# baseline (speedup 1.0000x reference)
; #define STA(P, br, kt) STAGE(P, A, aoff0, aoff1, lda, br, kt)
; #define STB(P, br, kt) STAGE(P, Bt, boff0, boff1, ldb, br, kt)
; #define WAIT_V(n) asm volatile("s_waitcnt vmcnt(" #n ")" ::: "memory")
; #define BAR __builtin_amdgcn_s_barrier()
; __device__ __forceinline__ void gemm256(const u16* __restrict__ A, int lda, const u16* __restrict__ Bt, int ldb, int K,
;                                         f32x4 (&acc)[2][2][4][2], const int g_wid) {
;     ...
;   STB(SB(0, 0), 0, 0); STA(SA(0, 0), 0, 0);
;   STB(SB(0, 1), HALF, 0); STA(SA(0, 1), HALF, 0);
;   if (wr == 1) BAR;
;   WAIT_V(4); BAR;
;   STB(SB(1, 0), 0, 1); STA(SA(1, 0), 0, 1); STB(SB(1, 1), HALF, 1);
;   WAIT_V(6); BAR;
.LBB0_108:
	s_or_b64 exec, exec, s[36:37]
	v_readlane_b32 s11, v254, 42
	s_mov_b64 vcc, 0x80
	v_lshl_add_u64 v[2:3], v[2:3], 0, vcc
	v_add_u32_e32 v170, s11, v16
	v_add_u32_e32 v171, 0x2000, v170
	v_readfirstlane_b32 s36, v170
	s_mov_b32 m0, s36
	v_readfirstlane_b32 s36, v171
	v_add_u32_e32 v172, 0x8000, v163
	s_waitcnt vmcnt(4)
	s_barrier
	global_load_lds_dwordx4 v[2:3], off
	v_lshl_add_u64 v[2:3], v[6:7], 0, vcc
	s_mov_b32 m0, s36
	v_readfirstlane_b32 s36, v172
	v_add_u32_e32 v173, 0xa000, v163
	v_readlane_b32 s37, v254, 43
	global_load_lds_dwordx4 v[2:3], off
	v_lshl_add_u64 v[2:3], v[8:9], 0, vcc
	s_mov_b32 m0, s36
	v_readfirstlane_b32 s36, v173
	v_add_u32_e32 v174, s37, v16
	global_load_lds_dwordx4 v[2:3], off
	v_lshl_add_u64 v[2:3], v[4:5], 0, vcc
	s_mov_b32 m0, s36
	v_readfirstlane_b32 s36, v174
	v_add_u32_e32 v175, 0x2000, v174
	global_load_lds_dwordx4 v[2:3], off
	v_lshl_add_u64 v[2:3], v[132:133], 1, s[28:29]
	s_mov_b32 m0, s36
	v_readfirstlane_b32 s36, v175
	global_load_lds_dwordx4 v[2:3], off
	v_lshl_add_u64 v[2:3], v[130:131], 1, s[28:29]
	s_mov_b32 m0, s36
	v_and_b32_e32 v20, 15, v0
	global_load_lds_dwordx4 v[2:3], off
	v_lshlrev_b32_e32 v3, 2, v0
	v_and_b32_e32 v21, 48, v0
	v_lshlrev_b32_e32 v2, 6, v20
	v_and_b32_e32 v3, 32, v3
	v_bitop3_b32 v2, v2, v3, v21 bitop3:0x36
	v_readlane_b32 s10, v254, 40
	v_lshlrev_b32_e32 v4, 6, v0
	v_add_u32_e32 v8, s11, v2
	v_add_u32_e32 v6, s10, v2
	v_readlane_b32 s10, v254, 41
	v_add_u32_e32 v9, s37, v2
	v_add_u32_e32 v20, 0, v2
	v_add_u32_e32 v7, s10, v2
	s_movk_i32 s10, 0x3c0
	v_and_or_b32 v2, v4, s10, v21
	v_xad_u32 v21, v2, v3, 0
	v_lshlrev_b32_e32 v2, 13, v15
	v_and_b32_e32 v16, 0x3000, v4
	v_and_b32_e32 v2, 0xffffc000, v2
	v_lshlrev_b32_e32 v4, 13, v10
	v_lshl_add_u32 v2, v17, 10, v2
	v_and_b32_e32 v4, 0xffffc000, v4
	v_or_b32_e32 v2, v2, v18
	v_lshl_add_u32 v4, v12, 10, v4
	v_add_u32_sdwa v2, v2, sext(v19) dst_sel:DWORD dst_unused:UNUSED_PAD src0_sel:DWORD src1_sel:WORD_0
	v_or_b32_e32 v4, v4, v13
	v_ashrrev_i32_e32 v3, 31, v2
	v_add_u32_sdwa v4, v4, sext(v14) dst_sel:DWORD dst_unused:UNUSED_PAD src0_sel:DWORD src1_sel:WORD_0
	s_waitcnt vmcnt(6)
	v_lshlrev_b32_e32 v11, 13, v11
	v_lshlrev_b64 v[2:3], 1, v[2:3]
	v_ashrrev_i32_e32 v5, 31, v4
	v_or_b32_e32 v22, 0x800, v11
	v_or_b32_e32 v23, 0x1000, v11
	v_or_b32_e32 v24, 0x1800, v11
	v_lshl_add_u64 v[134:135], s[24:25], 0, v[2:3]
	v_lshlrev_b64 v[4:5], 1, v[4:5]
	v_lshl_add_u64 v[138:139], s[30:31], 0, v[2:3]
	v_mov_b32_e32 v2, 0
	v_lshl_add_u64 v[136:137], s[24:25], 0, v[4:5]
	v_lshl_add_u64 v[142:143], s[30:31], 0, v[4:5]
	s_mov_b32 s54, -2
	s_mov_b64 s[36:37], 0
	v_add_u32_e32 v177, v6, v16
	v_add_u32_e32 v159, v20, v11
	v_add_u32_e32 v147, v21, v22
	v_add_u32_e32 v146, v21, v23
	v_add_u32_e32 v145, v21, v24
	v_add_u32_e32 v176, v7, v16
	v_add_u32_e32 v167, v8, v16
	v_add_u32_e32 v160, v9, v16
	v_mov_b32_e32 v3, v2
	v_mov_b32_e32 v4, v2
	v_mov_b32_e32 v5, v2
	v_mov_b32_e32 v6, v2
	v_mov_b32_e32 v7, v2
	v_mov_b32_e32 v8, v2
	v_mov_b32_e32 v9, v2
	v_mov_b32_e32 v10, v2
	v_mov_b32_e32 v11, v2
	v_mov_b32_e32 v12, v2
	v_mov_b32_e32 v13, v2
	v_mov_b32_e32 v14, v2
	v_mov_b32_e32 v15, v2
	v_mov_b32_e32 v16, v2
	v_mov_b32_e32 v17, v2
	v_mov_b32_e32 v18, v2
	v_mov_b32_e32 v19, v2
	v_mov_b32_e32 v20, v2
	v_mov_b32_e32 v21, v2
	v_mov_b32_e32 v22, v2
	v_mov_b32_e32 v23, v2
	v_mov_b32_e32 v24, v2
	v_mov_b32_e32 v25, v2
	v_mov_b32_e32 v26, v2
	v_mov_b32_e32 v27, v2
	v_mov_b32_e32 v28, v2
	v_mov_b32_e32 v29, v2
	v_mov_b32_e32 v30, v2
	v_mov_b32_e32 v31, v2
	v_mov_b32_e32 v32, v2
	v_mov_b32_e32 v33, v2
	v_mov_b32_e32 v34, v2
	v_mov_b32_e32 v35, v2
	v_mov_b32_e32 v36, v2
	v_mov_b32_e32 v37, v2
	v_mov_b32_e32 v38, v2
	v_mov_b32_e32 v39, v2
	v_mov_b32_e32 v40, v2
	v_mov_b32_e32 v41, v2
	v_mov_b32_e32 v42, v2
	v_mov_b32_e32 v43, v2
	v_mov_b32_e32 v44, v2
	v_mov_b32_e32 v45, v2
	v_mov_b32_e32 v46, v2
	v_mov_b32_e32 v47, v2
	v_mov_b32_e32 v48, v2
	v_mov_b32_e32 v49, v2
	v_mov_b32_e32 v50, v2
	v_mov_b32_e32 v51, v2
	v_mov_b32_e32 v52, v2
	v_mov_b32_e32 v53, v2
	v_mov_b32_e32 v54, v2
	v_mov_b32_e32 v55, v2
	v_mov_b32_e32 v56, v2
	v_mov_b32_e32 v57, v2
	v_mov_b32_e32 v58, v2
	v_mov_b32_e32 v59, v2
	v_mov_b32_e32 v60, v2
	v_mov_b32_e32 v61, v2
	v_mov_b32_e32 v62, v2
	v_mov_b32_e32 v63, v2
	v_mov_b32_e32 v64, v2
	v_mov_b32_e32 v65, v2
	v_mov_b32_e32 v66, v2
	v_mov_b32_e32 v67, v2
	v_mov_b32_e32 v68, v2
	v_mov_b32_e32 v69, v2
	v_mov_b32_e32 v70, v2
	v_mov_b32_e32 v71, v2
	v_mov_b32_e32 v72, v2
	v_mov_b32_e32 v73, v2
	v_mov_b32_e32 v74, v2
	v_mov_b32_e32 v75, v2
	v_mov_b32_e32 v76, v2
	v_mov_b32_e32 v77, v2
	v_mov_b32_e32 v78, v2
	v_mov_b32_e32 v79, v2
	v_mov_b32_e32 v80, v2
	v_mov_b32_e32 v81, v2
	v_mov_b32_e32 v82, v2
	v_mov_b32_e32 v83, v2
	v_mov_b32_e32 v84, v2
	v_mov_b32_e32 v85, v2
	v_mov_b32_e32 v86, v2
	v_mov_b32_e32 v87, v2
	v_mov_b32_e32 v88, v2
	v_mov_b32_e32 v89, v2
	v_mov_b32_e32 v90, v2
	v_mov_b32_e32 v91, v2
	v_mov_b32_e32 v92, v2
	v_mov_b32_e32 v93, v2
	v_mov_b32_e32 v94, v2
	v_mov_b32_e32 v95, v2
	v_mov_b32_e32 v96, v2
	v_mov_b32_e32 v97, v2
	v_mov_b32_e32 v98, v2
	v_mov_b32_e32 v99, v2
	v_mov_b32_e32 v100, v2
	v_mov_b32_e32 v101, v2
	v_mov_b32_e32 v102, v2
	v_mov_b32_e32 v103, v2
	v_mov_b32_e32 v104, v2
	v_mov_b32_e32 v105, v2
	v_mov_b32_e32 v106, v2
	v_mov_b32_e32 v107, v2
	v_mov_b32_e32 v108, v2
	v_mov_b32_e32 v109, v2
	v_mov_b32_e32 v110, v2
	v_mov_b32_e32 v111, v2
	v_mov_b32_e32 v112, v2
	v_mov_b32_e32 v113, v2
	v_mov_b32_e32 v114, v2
	v_mov_b32_e32 v115, v2
	v_mov_b32_e32 v116, v2
	v_mov_b32_e32 v117, v2
	v_mov_b32_e32 v118, v2
	v_mov_b32_e32 v119, v2
	v_mov_b32_e32 v120, v2
	v_mov_b32_e32 v121, v2
	v_mov_b32_e32 v122, v2
	v_mov_b32_e32 v123, v2
	v_mov_b32_e32 v124, v2
	v_mov_b32_e32 v125, v2
	v_mov_b32_e32 v126, v2
	v_mov_b32_e32 v127, v2
	v_mov_b32_e32 v128, v2
	v_mov_b32_e32 v129, v2
	.p2align 6
; #define STA(P, br, kt) STAGE(P, A, aoff0, aoff1, lda, br, kt)
; #define STB(P, br, kt) STAGE(P, Bt, boff0, boff1, ldb, br, kt)
; #define LDA(dst, b, h) _Pragma("unroll") for (int m = 0; m < 4; ++m) _Pragma("unroll") for (int k = 0; k < 2; ++k) \
;     dst[m][k] = *reinterpret_cast<const bf16x8*>((char*)SA(b, h) + lds_byte(wr * 64 + m * 16 + fr, k * 32 + fq * 8))
; #define LDB(dst, b, h) _Pragma("unroll") for (int n = 0; n < 2; ++n) _Pragma("unroll") for (int k = 0; k < 2; ++k) \
;     dst[n][k] = *reinterpret_cast<const bf16x8*>((char*)SB(b, h) + lds_byte(wc * 32 + n * 16 + fr, k * 32 + fq * 8))
; #define MMA(ai, bj, At, Bq) do { __builtin_amdgcn_s_setprio(1); \
;     _Pragma("unroll") for (int m = 0; m < 4; ++m) _Pragma("unroll") for (int n = 0; n < 2; ++n) _Pragma("unroll") for (int k = 0; k < 2; ++k) \
;       acc[ai][bj][m][n] = __builtin_amdgcn_mfma_f32_16x16x32_bf16(At[m][k], Bq[n][k], acc[ai][bj][m][n], 0, 0, 0); \
;     __builtin_amdgcn_s_setprio(0); } while (0)
; #define WAIT_V(n) asm volatile("s_waitcnt vmcnt(" #n ")" ::: "memory")
; #define WAIT_L(n) asm volatile("s_waitcnt lgkmcnt(" #n ")" ::: "memory")
; #define BAR __builtin_amdgcn_s_barrier()
; #define SCHED __builtin_amdgcn_sched_barrier(0)
; __device__ __forceinline__ void gemm256(const u16* __restrict__ A, int lda, const u16* __restrict__ Bt, int ldb, int K,
;                                         f32x4 (&acc)[2][2][4][2], const int g_wid) {
;     ...
;   for (int t = 0; t < nt - 2; t += 2) {
;     LDB(B0, 0, 0); SCHED; LDA(At, 0, 0); STA(SA(1, 1), HALF, t + 1);
;     WAIT_L(8); BAR; WAIT_L(0); MMA(0, 0, At, B0); BAR; SCHED;
;     LDB(B1, 0, 1); STB(SB(0, 0), 0, t + 2);
;     BAR; WAIT_L(0); MMA(0, 1, At, B1); BAR;
;     LDA(At, 0, 1); STA(SA(0, 0), 0, t + 2);
;     BAR; WAIT_L(0); MMA(1, 0, At, B0); BAR; SCHED;
;     STB(SB(0, 1), HALF, t + 2);
;     WAIT_V(6); BAR; MMA(1, 1, At, B1); BAR;
.LBB0_109:
	s_barrier
	ds_read_b128 v[180:183], v177
	ds_read_b128 v[184:187], v177 offset:1024
	ds_read_b128 v[188:191], v177 offset:2048
	ds_read_b128 v[192:195], v177 offset:3072
	v_add_u32_e32 v178, 0xc000, v163
	v_lshl_add_u64 v[244:245], v[142:143], 0, s[36:37]
	v_readfirstlane_b32 s10, v178
	v_add_u32_e32 v179, 0xe000, v163
	v_lshl_add_u64 v[228:229], v[244:245], 0, s[72:73]
	s_mov_b32 m0, s10
	v_lshl_add_u64 v[246:247], v[138:139], 0, s[36:37]
	v_readfirstlane_b32 s10, v179
	ds_read_b128 v[196:199], v159
	ds_read_b128 v[200:203], v159 offset:1024
	ds_read_b128 v[204:207], v147
	ds_read_b128 v[208:211], v147 offset:1024
	ds_read_b128 v[212:215], v146
	ds_read_b128 v[216:219], v146 offset:1024
	ds_read_b128 v[220:223], v145
	ds_read_b128 v[224:227], v145 offset:1024
	global_load_lds_dwordx4 v[228:229], off
	v_lshl_add_u64 v[228:229], v[246:247], 0, s[72:73]
	s_mov_b32 m0, s10
	s_nop 0
	global_load_lds_dwordx4 v[228:229], off
	s_waitcnt lgkmcnt(8)
	s_barrier
	s_waitcnt lgkmcnt(0)
	v_mfma_f32_16x16x32_bf16 v[126:129], v[196:199], v[180:183], v[126:129]
	v_mfma_f32_16x16x32_bf16 v[122:125], v[196:199], v[188:191], v[122:125]
	v_mfma_f32_16x16x32_bf16 v[118:121], v[204:207], v[180:183], v[118:121]
	v_mfma_f32_16x16x32_bf16 v[114:117], v[204:207], v[188:191], v[114:117]
	v_mfma_f32_16x16x32_bf16 v[110:113], v[212:215], v[180:183], v[110:113]
	v_mfma_f32_16x16x32_bf16 v[106:109], v[212:215], v[188:191], v[106:109]
	v_mfma_f32_16x16x32_bf16 v[102:105], v[220:223], v[180:183], v[102:105]
	v_mfma_f32_16x16x32_bf16 v[98:101], v[220:223], v[188:191], v[98:101]
	v_mfma_f32_16x16x32_bf16 v[126:129], v[200:203], v[184:187], v[126:129]
	v_mfma_f32_16x16x32_bf16 v[122:125], v[200:203], v[192:195], v[122:125]
	v_mfma_f32_16x16x32_bf16 v[118:121], v[208:211], v[184:187], v[118:121]
	v_mfma_f32_16x16x32_bf16 v[114:117], v[208:211], v[192:195], v[114:117]
	v_mfma_f32_16x16x32_bf16 v[110:113], v[216:219], v[184:187], v[110:113]
	v_mfma_f32_16x16x32_bf16 v[106:109], v[216:219], v[192:195], v[106:109]
	v_mfma_f32_16x16x32_bf16 v[102:105], v[224:227], v[184:187], v[102:105]
	v_mfma_f32_16x16x32_bf16 v[98:101], v[224:227], v[192:195], v[98:101]
	s_barrier
	v_lshl_add_u64 v[248:249], v[136:137], 0, s[36:37]
	v_readfirstlane_b32 s10, v161
	v_lshl_add_u64 v[250:251], v[248:249], 0, s[74:75]
	s_mov_b32 m0, s10
	ds_read_b128 v[228:231], v176
	ds_read_b128 v[232:235], v176 offset:1024
	ds_read_b128 v[236:239], v176 offset:2048
	ds_read_b128 v[240:243], v176 offset:3072
	global_load_lds_dwordx4 v[250:251], off
	v_lshl_add_u64 v[250:251], v[134:135], 0, s[36:37]
	v_readfirstlane_b32 s10, v162
	v_lshl_add_u64 v[252:253], v[250:251], 0, s[74:75]
	s_mov_b32 m0, s10
	s_nop 0
	global_load_lds_dwordx4 v[252:253], off
	s_barrier
	s_waitcnt lgkmcnt(0)
	v_mfma_f32_16x16x32_bf16 v[94:97], v[196:199], v[228:231], v[94:97]
	v_mfma_f32_16x16x32_bf16 v[90:93], v[196:199], v[236:239], v[90:93]
	v_mfma_f32_16x16x32_bf16 v[86:89], v[204:207], v[228:231], v[86:89]
	v_mfma_f32_16x16x32_bf16 v[82:85], v[204:207], v[236:239], v[82:85]
	v_mfma_f32_16x16x32_bf16 v[78:81], v[212:215], v[228:231], v[78:81]
	v_mfma_f32_16x16x32_bf16 v[74:77], v[212:215], v[236:239], v[74:77]
	v_mfma_f32_16x16x32_bf16 v[70:73], v[220:223], v[228:231], v[70:73]
	v_mfma_f32_16x16x32_bf16 v[66:69], v[220:223], v[236:239], v[66:69]
	v_mfma_f32_16x16x32_bf16 v[94:97], v[200:203], v[232:235], v[94:97]
	v_mfma_f32_16x16x32_bf16 v[90:93], v[200:203], v[240:243], v[90:93]
	v_mfma_f32_16x16x32_bf16 v[86:89], v[208:211], v[232:235], v[86:89]
	v_mfma_f32_16x16x32_bf16 v[82:85], v[208:211], v[240:243], v[82:85]
	v_mfma_f32_16x16x32_bf16 v[78:81], v[216:219], v[232:235], v[78:81]
	v_mfma_f32_16x16x32_bf16 v[74:77], v[216:219], v[240:243], v[74:77]
	v_mfma_f32_16x16x32_bf16 v[70:73], v[224:227], v[232:235], v[70:73]
	v_mfma_f32_16x16x32_bf16 v[66:69], v[224:227], v[240:243], v[66:69]
	v_readfirstlane_b32 s10, v163
	v_lshl_add_u64 v[252:253], v[244:245], 0, s[76:77]
	s_mov_b32 m0, s10
	v_readfirstlane_b32 s10, v164
	s_barrier
	ds_read_b128 v[196:199], v159 offset:16384
	ds_read_b128 v[200:203], v159 offset:17408
	ds_read_b128 v[204:207], v147 offset:16384
	ds_read_b128 v[208:211], v147 offset:17408
	ds_read_b128 v[212:215], v146 offset:16384
	ds_read_b128 v[216:219], v146 offset:17408
	ds_read_b128 v[220:223], v145 offset:16384
	ds_read_b128 v[224:227], v145 offset:17408
	global_load_lds_dwordx4 v[252:253], off
	v_lshl_add_u64 v[252:253], v[246:247], 0, s[76:77]
	s_mov_b32 m0, s10
	s_nop 0
	global_load_lds_dwordx4 v[252:253], off
	s_barrier
	s_waitcnt lgkmcnt(0)
	v_mfma_f32_16x16x32_bf16 v[62:65], v[196:199], v[180:183], v[62:65]
	v_mfma_f32_16x16x32_bf16 v[58:61], v[196:199], v[188:191], v[58:61]
	v_mfma_f32_16x16x32_bf16 v[54:57], v[204:207], v[180:183], v[54:57]
	v_mfma_f32_16x16x32_bf16 v[50:53], v[204:207], v[188:191], v[50:53]
	v_mfma_f32_16x16x32_bf16 v[46:49], v[212:215], v[180:183], v[46:49]
	v_mfma_f32_16x16x32_bf16 v[42:45], v[212:215], v[188:191], v[42:45]
	v_mfma_f32_16x16x32_bf16 v[38:41], v[220:223], v[180:183], v[38:41]
	v_mfma_f32_16x16x32_bf16 v[34:37], v[220:223], v[188:191], v[34:37]
	v_mfma_f32_16x16x32_bf16 v[62:65], v[200:203], v[184:187], v[62:65]
	v_mfma_f32_16x16x32_bf16 v[58:61], v[200:203], v[192:195], v[58:61]
	v_mfma_f32_16x16x32_bf16 v[54:57], v[208:211], v[184:187], v[54:57]
	v_mfma_f32_16x16x32_bf16 v[50:53], v[208:211], v[192:195], v[50:53]
	v_mfma_f32_16x16x32_bf16 v[46:49], v[216:219], v[184:187], v[46:49]
	v_mfma_f32_16x16x32_bf16 v[42:45], v[216:219], v[192:195], v[42:45]
	v_mfma_f32_16x16x32_bf16 v[38:41], v[224:227], v[184:187], v[38:41]
	v_mfma_f32_16x16x32_bf16 v[34:37], v[224:227], v[192:195], v[34:37]
	s_barrier
; #define STA(P, br, kt) STAGE(P, A, aoff0, aoff1, lda, br, kt)
; #define STB(P, br, kt) STAGE(P, Bt, boff0, boff1, ldb, br, kt)
; #define LDA(dst, b, h) _Pragma("unroll") for (int m = 0; m < 4; ++m) _Pragma("unroll") for (int k = 0; k < 2; ++k) \
;     dst[m][k] = *reinterpret_cast<const bf16x8*>((char*)SA(b, h) + lds_byte(wr * 64 + m * 16 + fr, k * 32 + fq * 8))
; #define LDB(dst, b, h) _Pragma("unroll") for (int n = 0; n < 2; ++n) _Pragma("unroll") for (int k = 0; k < 2; ++k) \
;     dst[n][k] = *reinterpret_cast<const bf16x8*>((char*)SB(b, h) + lds_byte(wc * 32 + n * 16 + fr, k * 32 + fq * 8))
; #define MMA(ai, bj, At, Bq) do { __builtin_amdgcn_s_setprio(1); \
;     _Pragma("unroll") for (int m = 0; m < 4; ++m) _Pragma("unroll") for (int n = 0; n < 2; ++n) _Pragma("unroll") for (int k = 0; k < 2; ++k) \
;       acc[ai][bj][m][n] = __builtin_amdgcn_mfma_f32_16x16x32_bf16(At[m][k], Bq[n][k], acc[ai][bj][m][n], 0, 0, 0); \
;     __builtin_amdgcn_s_setprio(0); } while (0)
; #define WAIT_V(n) asm volatile("s_waitcnt vmcnt(" #n ")" ::: "memory")
; #define WAIT_L(n) asm volatile("s_waitcnt lgkmcnt(" #n ")" ::: "memory")
; #define BAR __builtin_amdgcn_s_barrier()
; #define SCHED __builtin_amdgcn_sched_barrier(0)
; __device__ __forceinline__ void gemm256(const u16* __restrict__ A, int lda, const u16* __restrict__ Bt, int ldb, int K,
;                                         f32x4 (&acc)[2][2][4][2], const int g_wid) {
;     ...
;     STB(SB(0, 1), HALF, t + 2);
;     WAIT_V(6); BAR; MMA(1, 1, At, B1); BAR;
;     LDB(B0, 1, 0); SCHED; LDA(At, 1, 0); STA(SA(0, 1), HALF, t + 2);
;     WAIT_L(8); BAR; WAIT_L(0); MMA(0, 0, At, B0); BAR; SCHED;
;     LDB(B1, 1, 1); STB(SB(1, 0), 0, t + 3);
;     BAR; WAIT_L(0); MMA(0, 1, At, B1); BAR;
;     LDA(At, 1, 1); STA(SA(1, 0), 0, t + 3);
	v_readfirstlane_b32 s10, v165
	v_lshl_add_u64 v[180:181], v[248:249], 0, s[78:79]
	s_mov_b32 m0, s10
	v_readfirstlane_b32 s10, v166
	global_load_lds_dwordx4 v[180:181], off
	v_lshl_add_u64 v[180:181], v[250:251], 0, s[78:79]
	s_mov_b32 m0, s10
	s_nop 0
	global_load_lds_dwordx4 v[180:181], off
	s_waitcnt vmcnt(6)
	s_barrier
	v_mfma_f32_16x16x32_bf16 v[30:33], v[196:199], v[228:231], v[30:33]
	v_mfma_f32_16x16x32_bf16 v[26:29], v[196:199], v[236:239], v[26:29]
	v_mfma_f32_16x16x32_bf16 v[22:25], v[204:207], v[228:231], v[22:25]
	v_mfma_f32_16x16x32_bf16 v[18:21], v[204:207], v[236:239], v[18:21]
	v_mfma_f32_16x16x32_bf16 v[14:17], v[212:215], v[228:231], v[14:17]
	v_mfma_f32_16x16x32_bf16 v[10:13], v[212:215], v[236:239], v[10:13]
	v_mfma_f32_16x16x32_bf16 v[6:9], v[220:223], v[228:231], v[6:9]
	v_mfma_f32_16x16x32_bf16 v[2:5], v[220:223], v[236:239], v[2:5]
	v_mfma_f32_16x16x32_bf16 v[30:33], v[200:203], v[232:235], v[30:33]
	v_mfma_f32_16x16x32_bf16 v[26:29], v[200:203], v[240:243], v[26:29]
	v_mfma_f32_16x16x32_bf16 v[22:25], v[208:211], v[232:235], v[22:25]
	v_mfma_f32_16x16x32_bf16 v[18:21], v[208:211], v[240:243], v[18:21]
	v_mfma_f32_16x16x32_bf16 v[14:17], v[216:219], v[232:235], v[14:17]
	v_mfma_f32_16x16x32_bf16 v[10:13], v[216:219], v[240:243], v[10:13]
	v_mfma_f32_16x16x32_bf16 v[6:9], v[224:227], v[232:235], v[6:9]
	v_mfma_f32_16x16x32_bf16 v[2:5], v[224:227], v[240:243], v[2:5]
	s_barrier
	ds_read_b128 v[180:183], v167
	ds_read_b128 v[184:187], v167 offset:1024
	ds_read_b128 v[188:191], v167 offset:2048
	ds_read_b128 v[192:195], v167 offset:3072
	v_readfirstlane_b32 s10, v168
	v_lshl_add_u64 v[228:229], v[244:245], 0, s[80:81]
	s_mov_b32 m0, s10
	v_readfirstlane_b32 s10, v169
	ds_read_b128 v[196:199], v159 offset:32768
	ds_read_b128 v[200:203], v159 offset:33792
	ds_read_b128 v[204:207], v147 offset:32768
	ds_read_b128 v[208:211], v147 offset:33792
	ds_read_b128 v[212:215], v146 offset:32768
	ds_read_b128 v[216:219], v146 offset:33792
	ds_read_b128 v[220:223], v145 offset:32768
	ds_read_b128 v[224:227], v145 offset:33792
	global_load_lds_dwordx4 v[228:229], off
	v_lshl_add_u64 v[228:229], v[246:247], 0, s[80:81]
	s_mov_b32 m0, s10
	s_nop 0
	global_load_lds_dwordx4 v[228:229], off
	s_waitcnt lgkmcnt(8)
	s_barrier
	s_waitcnt lgkmcnt(0)
	v_mfma_f32_16x16x32_bf16 v[126:129], v[196:199], v[180:183], v[126:129]
	v_mfma_f32_16x16x32_bf16 v[122:125], v[196:199], v[188:191], v[122:125]
	v_mfma_f32_16x16x32_bf16 v[118:121], v[204:207], v[180:183], v[118:121]
	v_mfma_f32_16x16x32_bf16 v[114:117], v[204:207], v[188:191], v[114:117]
	v_mfma_f32_16x16x32_bf16 v[110:113], v[212:215], v[180:183], v[110:113]
	v_mfma_f32_16x16x32_bf16 v[106:109], v[212:215], v[188:191], v[106:109]
	v_mfma_f32_16x16x32_bf16 v[102:105], v[220:223], v[180:183], v[102:105]
	v_mfma_f32_16x16x32_bf16 v[98:101], v[220:223], v[188:191], v[98:101]
	v_mfma_f32_16x16x32_bf16 v[126:129], v[200:203], v[184:187], v[126:129]
	v_mfma_f32_16x16x32_bf16 v[122:125], v[200:203], v[192:195], v[122:125]
	v_mfma_f32_16x16x32_bf16 v[118:121], v[208:211], v[184:187], v[118:121]
	v_mfma_f32_16x16x32_bf16 v[114:117], v[208:211], v[192:195], v[114:117]
	v_mfma_f32_16x16x32_bf16 v[110:113], v[216:219], v[184:187], v[110:113]
	v_mfma_f32_16x16x32_bf16 v[106:109], v[216:219], v[192:195], v[106:109]
	v_mfma_f32_16x16x32_bf16 v[102:105], v[224:227], v[184:187], v[102:105]
	v_mfma_f32_16x16x32_bf16 v[98:101], v[224:227], v[192:195], v[98:101]
	s_barrier
	v_readfirstlane_b32 s10, v170
	v_lshl_add_u64 v[252:253], v[248:249], 0, s[82:83]
	s_mov_b32 m0, s10
	v_readfirstlane_b32 s10, v171
	ds_read_b128 v[228:231], v160
	ds_read_b128 v[232:235], v160 offset:1024
	ds_read_b128 v[236:239], v160 offset:2048
	ds_read_b128 v[240:243], v160 offset:3072
	global_load_lds_dwordx4 v[252:253], off
	v_lshl_add_u64 v[252:253], v[250:251], 0, s[82:83]
	s_mov_b32 m0, s10
	s_nop 0
	global_load_lds_dwordx4 v[252:253], off
	s_barrier
	s_waitcnt lgkmcnt(0)
	v_mfma_f32_16x16x32_bf16 v[94:97], v[196:199], v[228:231], v[94:97]
	v_mfma_f32_16x16x32_bf16 v[90:93], v[196:199], v[236:239], v[90:93]
	v_mfma_f32_16x16x32_bf16 v[86:89], v[204:207], v[228:231], v[86:89]
	v_mfma_f32_16x16x32_bf16 v[82:85], v[204:207], v[236:239], v[82:85]
	v_mfma_f32_16x16x32_bf16 v[78:81], v[212:215], v[228:231], v[78:81]
	v_mfma_f32_16x16x32_bf16 v[74:77], v[212:215], v[236:239], v[74:77]
	v_mfma_f32_16x16x32_bf16 v[70:73], v[220:223], v[228:231], v[70:73]
	v_mfma_f32_16x16x32_bf16 v[66:69], v[220:223], v[236:239], v[66:69]
	v_mfma_f32_16x16x32_bf16 v[94:97], v[200:203], v[232:235], v[94:97]
	v_mfma_f32_16x16x32_bf16 v[90:93], v[200:203], v[240:243], v[90:93]
	v_mfma_f32_16x16x32_bf16 v[86:89], v[208:211], v[232:235], v[86:89]
	v_mfma_f32_16x16x32_bf16 v[82:85], v[208:211], v[240:243], v[82:85]
	v_mfma_f32_16x16x32_bf16 v[78:81], v[216:219], v[232:235], v[78:81]
	v_mfma_f32_16x16x32_bf16 v[74:77], v[216:219], v[240:243], v[74:77]
	v_mfma_f32_16x16x32_bf16 v[70:73], v[224:227], v[232:235], v[70:73]
	v_mfma_f32_16x16x32_bf16 v[66:69], v[224:227], v[240:243], v[66:69]
	v_readfirstlane_b32 s10, v172
	v_lshl_add_u64 v[244:245], v[244:245], 0, s[84:85]
	s_mov_b32 m0, s10
	v_readfirstlane_b32 s10, v173
	s_barrier
	ds_read_b128 v[196:199], v159 offset:49152
	ds_read_b128 v[200:203], v159 offset:50176
	ds_read_b128 v[204:207], v147 offset:49152
	ds_read_b128 v[208:211], v147 offset:50176
	ds_read_b128 v[212:215], v146 offset:49152
	ds_read_b128 v[216:219], v146 offset:50176
	ds_read_b128 v[220:223], v145 offset:49152
	ds_read_b128 v[224:227], v145 offset:50176
	global_load_lds_dwordx4 v[244:245], off
	v_lshl_add_u64 v[244:245], v[246:247], 0, s[84:85]
	s_mov_b32 m0, s10
	s_nop 0
	global_load_lds_dwordx4 v[244:245], off
	s_barrier
; #define STA(P, br, kt) STAGE(P, A, aoff0, aoff1, lda, br, kt)
; #define STB(P, br, kt) STAGE(P, Bt, boff0, boff1, ldb, br, kt)
; #define LDA(dst, b, h) _Pragma("unroll") for (int m = 0; m < 4; ++m) _Pragma("unroll") for (int k = 0; k < 2; ++k) \
;     dst[m][k] = *reinterpret_cast<const bf16x8*>((char*)SA(b, h) + lds_byte(wr * 64 + m * 16 + fr, k * 32 + fq * 8))
; #define LDB(dst, b, h) _Pragma("unroll") for (int n = 0; n < 2; ++n) _Pragma("unroll") for (int k = 0; k < 2; ++k) \
;     dst[n][k] = *reinterpret_cast<const bf16x8*>((char*)SB(b, h) + lds_byte(wc * 32 + n * 16 + fr, k * 32 + fq * 8))
; #define MMA(ai, bj, At, Bq) do { __builtin_amdgcn_s_setprio(1); \
;     _Pragma("unroll") for (int m = 0; m < 4; ++m) _Pragma("unroll") for (int n = 0; n < 2; ++n) _Pragma("unroll") for (int k = 0; k < 2; ++k) \
;       acc[ai][bj][m][n] = __builtin_amdgcn_mfma_f32_16x16x32_bf16(At[m][k], Bq[n][k], acc[ai][bj][m][n], 0, 0, 0); \
;     __builtin_amdgcn_s_setprio(0); } while (0)
; #define WAIT_V(n) asm volatile("s_waitcnt vmcnt(" #n ")" ::: "memory")
; #define WAIT_L(n) asm volatile("s_waitcnt lgkmcnt(" #n ")" ::: "memory")
; #define BAR __builtin_amdgcn_s_barrier()
; #define SCHED __builtin_amdgcn_sched_barrier(0)
; __device__ __forceinline__ void gemm256(const u16* __restrict__ A, int lda, const u16* __restrict__ Bt, int ldb, int K,
;                                         f32x4 (&acc)[2][2][4][2], const int g_wid) {
;     ...
;     BAR; WAIT_L(0); MMA(1, 0, At, B0); BAR; SCHED;
;     STB(SB(1, 1), HALF, t + 3);
;     WAIT_V(6); BAR; MMA(1, 1, At, B1); BAR;
;   }
;   { LDB(B0, 0, 0); LDA(At, 0, 0); STA(SA(1, 1), HALF, nt - 1);
;     BAR; WAIT_L(0); MMA(0, 0, At, B0); BAR;
	s_waitcnt lgkmcnt(0)
	v_mfma_f32_16x16x32_bf16 v[62:65], v[196:199], v[180:183], v[62:65]
	v_mfma_f32_16x16x32_bf16 v[58:61], v[196:199], v[188:191], v[58:61]
	v_mfma_f32_16x16x32_bf16 v[54:57], v[204:207], v[180:183], v[54:57]
	v_mfma_f32_16x16x32_bf16 v[50:53], v[204:207], v[188:191], v[50:53]
	v_mfma_f32_16x16x32_bf16 v[46:49], v[212:215], v[180:183], v[46:49]
	v_mfma_f32_16x16x32_bf16 v[42:45], v[212:215], v[188:191], v[42:45]
	v_mfma_f32_16x16x32_bf16 v[38:41], v[220:223], v[180:183], v[38:41]
	v_mfma_f32_16x16x32_bf16 v[34:37], v[220:223], v[188:191], v[34:37]
	v_mfma_f32_16x16x32_bf16 v[62:65], v[200:203], v[184:187], v[62:65]
	v_mfma_f32_16x16x32_bf16 v[58:61], v[200:203], v[192:195], v[58:61]
	v_mfma_f32_16x16x32_bf16 v[54:57], v[208:211], v[184:187], v[54:57]
	v_mfma_f32_16x16x32_bf16 v[50:53], v[208:211], v[192:195], v[50:53]
	v_mfma_f32_16x16x32_bf16 v[46:49], v[216:219], v[184:187], v[46:49]
	v_mfma_f32_16x16x32_bf16 v[42:45], v[216:219], v[192:195], v[42:45]
	v_mfma_f32_16x16x32_bf16 v[38:41], v[224:227], v[184:187], v[38:41]
	v_mfma_f32_16x16x32_bf16 v[34:37], v[224:227], v[192:195], v[34:37]
	s_barrier
	v_readfirstlane_b32 s10, v174
	v_lshl_add_u64 v[180:181], v[248:249], 0, s[86:87]
	s_mov_b32 m0, s10
	v_readfirstlane_b32 s10, v175
	global_load_lds_dwordx4 v[180:181], off
	v_lshl_add_u64 v[180:181], v[250:251], 0, s[86:87]
	s_mov_b32 m0, s10
	s_nop 0
	global_load_lds_dwordx4 v[180:181], off
	s_waitcnt vmcnt(6)
	s_barrier
	v_mfma_f32_16x16x32_bf16 v[30:33], v[196:199], v[228:231], v[30:33]
	v_mfma_f32_16x16x32_bf16 v[26:29], v[196:199], v[236:239], v[26:29]
	v_mfma_f32_16x16x32_bf16 v[22:25], v[204:207], v[228:231], v[22:25]
	v_mfma_f32_16x16x32_bf16 v[18:21], v[204:207], v[236:239], v[18:21]
	v_mfma_f32_16x16x32_bf16 v[14:17], v[212:215], v[228:231], v[14:17]
	v_mfma_f32_16x16x32_bf16 v[10:13], v[212:215], v[236:239], v[10:13]
	v_mfma_f32_16x16x32_bf16 v[6:9], v[220:223], v[228:231], v[6:9]
	v_mfma_f32_16x16x32_bf16 v[2:5], v[220:223], v[236:239], v[2:5]
	v_mfma_f32_16x16x32_bf16 v[30:33], v[200:203], v[232:235], v[30:33]
	v_mfma_f32_16x16x32_bf16 v[26:29], v[200:203], v[240:243], v[26:29]
	v_mfma_f32_16x16x32_bf16 v[22:25], v[208:211], v[232:235], v[22:25]
	v_mfma_f32_16x16x32_bf16 v[18:21], v[208:211], v[240:243], v[18:21]
	v_mfma_f32_16x16x32_bf16 v[14:17], v[216:219], v[232:235], v[14:17]
	v_mfma_f32_16x16x32_bf16 v[10:13], v[216:219], v[240:243], v[10:13]
	v_mfma_f32_16x16x32_bf16 v[6:9], v[224:227], v[232:235], v[6:9]
	v_mfma_f32_16x16x32_bf16 v[2:5], v[224:227], v[240:243], v[2:5]
	s_add_i32 s54, s54, 2
	s_add_u32 s36, s36, 0x100
	s_addc_u32 s37, s37, 0
	s_cmp_lt_u32 s54, 12
	s_cbranch_scc1 .LBB0_109
	s_barrier
	s_add_u32 s34, s34, 0x40780
	s_addc_u32 s35, s35, 0
	v_readfirstlane_b32 s10, v178
	v_lshl_add_u64 v[132:133], v[132:133], 1, s[34:35]
	s_mov_b32 m0, s10
	v_readfirstlane_b32 s10, v179
	ds_read_b128 v[134:137], v177
	ds_read_b128 v[162:165], v177 offset:1024
	ds_read_b128 v[168:171], v177 offset:2048
	ds_read_b128 v[172:175], v177 offset:3072
	ds_read_b128 v[180:183], v159
	ds_read_b128 v[184:187], v159 offset:1024
	ds_read_b128 v[188:191], v147
	ds_read_b128 v[192:195], v147 offset:1024
	ds_read_b128 v[196:199], v146
	ds_read_b128 v[200:203], v146 offset:1024
	ds_read_b128 v[204:207], v145
	ds_read_b128 v[208:211], v145 offset:1024
	global_load_lds_dwordx4 v[132:133], off
	v_lshl_add_u64 v[130:131], v[130:131], 1, s[34:35]
	s_mov_b32 m0, s10
	s_nop 0
	global_load_lds_dwordx4 v[130:131], off
	s_barrier
	s_waitcnt lgkmcnt(0)
	v_mfma_f32_16x16x32_bf16 v[126:129], v[180:183], v[134:137], v[126:129]
	v_mfma_f32_16x16x32_bf16 v[122:125], v[180:183], v[168:171], v[122:125]
	v_mfma_f32_16x16x32_bf16 v[118:121], v[188:191], v[134:137], v[118:121]
	v_mfma_f32_16x16x32_bf16 v[114:117], v[188:191], v[168:171], v[114:117]
	v_mfma_f32_16x16x32_bf16 v[110:113], v[196:199], v[134:137], v[110:113]
	v_mfma_f32_16x16x32_bf16 v[106:109], v[196:199], v[168:171], v[106:109]
	v_mfma_f32_16x16x32_bf16 v[102:105], v[204:207], v[134:137], v[102:105]
	v_mfma_f32_16x16x32_bf16 v[98:101], v[204:207], v[168:171], v[98:101]
	v_mfma_f32_16x16x32_bf16 v[126:129], v[184:187], v[162:165], v[126:129]
	v_mfma_f32_16x16x32_bf16 v[122:125], v[184:187], v[172:175], v[122:125]
	v_mfma_f32_16x16x32_bf16 v[118:121], v[192:195], v[162:165], v[118:121]
	v_mfma_f32_16x16x32_bf16 v[114:117], v[192:195], v[172:175], v[114:117]
	v_mfma_f32_16x16x32_bf16 v[110:113], v[200:203], v[162:165], v[110:113]
	v_mfma_f32_16x16x32_bf16 v[106:109], v[200:203], v[172:175], v[106:109]
	v_mfma_f32_16x16x32_bf16 v[102:105], v[208:211], v[162:165], v[102:105]
	v_mfma_f32_16x16x32_bf16 v[98:101], v[208:211], v[172:175], v[98:101]
	s_barrier
	ds_read_b128 v[130:133], v176
	ds_read_b128 v[212:215], v176 offset:1024
	ds_read_b128 v[216:219], v176 offset:2048
	ds_read_b128 v[176:179], v176 offset:3072
	s_barrier
	s_waitcnt lgkmcnt(0)
	v_mfma_f32_16x16x32_bf16 v[94:97], v[180:183], v[130:133], v[94:97]
	v_mfma_f32_16x16x32_bf16 v[90:93], v[180:183], v[216:219], v[90:93]
	v_mfma_f32_16x16x32_bf16 v[86:89], v[188:191], v[130:133], v[86:89]
	v_mfma_f32_16x16x32_bf16 v[82:85], v[188:191], v[216:219], v[82:85]
	v_mfma_f32_16x16x32_bf16 v[78:81], v[196:199], v[130:133], v[78:81]
	v_mfma_f32_16x16x32_bf16 v[74:77], v[196:199], v[216:219], v[74:77]
	v_mfma_f32_16x16x32_bf16 v[70:73], v[204:207], v[130:133], v[70:73]
	v_mfma_f32_16x16x32_bf16 v[66:69], v[204:207], v[216:219], v[66:69]
	v_mfma_f32_16x16x32_bf16 v[94:97], v[184:187], v[212:215], v[94:97]
	v_mfma_f32_16x16x32_bf16 v[90:93], v[184:187], v[176:179], v[90:93]
	v_mfma_f32_16x16x32_bf16 v[86:89], v[192:195], v[212:215], v[86:89]
	v_mfma_f32_16x16x32_bf16 v[82:85], v[192:195], v[176:179], v[82:85]
	v_mfma_f32_16x16x32_bf16 v[78:81], v[200:203], v[212:215], v[78:81]
	v_mfma_f32_16x16x32_bf16 v[74:77], v[200:203], v[176:179], v[74:77]
	v_mfma_f32_16x16x32_bf16 v[70:73], v[208:211], v[212:215], v[70:73]
	v_mfma_f32_16x16x32_bf16 v[66:69], v[208:211], v[176:179], v[66:69]
	s_barrier
; #define LDA(dst, b, h) _Pragma("unroll") for (int m = 0; m < 4; ++m) _Pragma("unroll") for (int k = 0; k < 2; ++k) \
;     dst[m][k] = *reinterpret_cast<const bf16x8*>((char*)SA(b, h) + lds_byte(wr * 64 + m * 16 + fr, k * 32 + fq * 8))
; #define LDB(dst, b, h) _Pragma("unroll") for (int n = 0; n < 2; ++n) _Pragma("unroll") for (int k = 0; k < 2; ++k) \
;     dst[n][k] = *reinterpret_cast<const bf16x8*>((char*)SB(b, h) + lds_byte(wc * 32 + n * 16 + fr, k * 32 + fq * 8))
; #define MMA(ai, bj, At, Bq) do { __builtin_amdgcn_s_setprio(1); \
;     _Pragma("unroll") for (int m = 0; m < 4; ++m) _Pragma("unroll") for (int n = 0; n < 2; ++n) _Pragma("unroll") for (int k = 0; k < 2; ++k) \
;       acc[ai][bj][m][n] = __builtin_amdgcn_mfma_f32_16x16x32_bf16(At[m][k], Bq[n][k], acc[ai][bj][m][n], 0, 0, 0); \
;     __builtin_amdgcn_s_setprio(0); } while (0)
; #define WAIT_V(n) asm volatile("s_waitcnt vmcnt(" #n ")" ::: "memory")
; #define WAIT_L(n) asm volatile("s_waitcnt lgkmcnt(" #n ")" ::: "memory")
; #define BAR __builtin_amdgcn_s_barrier()
; __device__ __forceinline__ void gemm256(const u16* __restrict__ A, int lda, const u16* __restrict__ Bt, int ldb, int K,
;                                         f32x4 (&acc)[2][2][4][2], const int g_wid) {
;     ...
;     LDA(At, 0, 1); WAIT_V(4); BAR; WAIT_L(0); MMA(1, 0, At, B0); MMA(1, 1, At, B1); BAR; }
;   { LDB(B0, 1, 0); LDA(At, 1, 0); WAIT_V(2); BAR; WAIT_L(0); MMA(0, 0, At, B0); BAR;
	ds_read_b128 v[180:183], v159 offset:16384
	ds_read_b128 v[184:187], v159 offset:17408
	ds_read_b128 v[188:191], v147 offset:16384
	ds_read_b128 v[192:195], v147 offset:17408
	ds_read_b128 v[196:199], v146 offset:16384
	ds_read_b128 v[200:203], v146 offset:17408
	ds_read_b128 v[204:207], v145 offset:16384
	ds_read_b128 v[208:211], v145 offset:17408
	s_waitcnt vmcnt(4)
	s_barrier
	s_waitcnt lgkmcnt(0)
	v_mfma_f32_16x16x32_bf16 v[62:65], v[180:183], v[134:137], v[62:65]
	v_mfma_f32_16x16x32_bf16 v[58:61], v[180:183], v[168:171], v[58:61]
	v_mfma_f32_16x16x32_bf16 v[54:57], v[188:191], v[134:137], v[54:57]
	v_mfma_f32_16x16x32_bf16 v[50:53], v[188:191], v[168:171], v[50:53]
	v_mfma_f32_16x16x32_bf16 v[46:49], v[196:199], v[134:137], v[46:49]
	v_mfma_f32_16x16x32_bf16 v[42:45], v[196:199], v[168:171], v[42:45]
	v_mfma_f32_16x16x32_bf16 v[38:41], v[204:207], v[134:137], v[38:41]
	v_mfma_f32_16x16x32_bf16 v[34:37], v[204:207], v[168:171], v[34:37]
	v_mfma_f32_16x16x32_bf16 v[220:223], v[184:187], v[162:165], v[62:65]
	v_mfma_f32_16x16x32_bf16 v[224:227], v[184:187], v[172:175], v[58:61]
	v_mfma_f32_16x16x32_bf16 v[228:231], v[192:195], v[162:165], v[54:57]
	v_mfma_f32_16x16x32_bf16 v[232:235], v[192:195], v[172:175], v[50:53]
	v_mfma_f32_16x16x32_bf16 v[236:239], v[200:203], v[162:165], v[46:49]
	v_mfma_f32_16x16x32_bf16 v[240:243], v[200:203], v[172:175], v[42:45]
	v_mfma_f32_16x16x32_bf16 v[134:137], v[208:211], v[162:165], v[38:41]
	v_mfma_f32_16x16x32_bf16 v[162:165], v[208:211], v[172:175], v[34:37]
	v_mfma_f32_16x16x32_bf16 v[30:33], v[180:183], v[130:133], v[30:33]
	v_mfma_f32_16x16x32_bf16 v[26:29], v[180:183], v[216:219], v[26:29]
	v_mfma_f32_16x16x32_bf16 v[22:25], v[188:191], v[130:133], v[22:25]
	v_mfma_f32_16x16x32_bf16 v[18:21], v[188:191], v[216:219], v[18:21]
	v_mfma_f32_16x16x32_bf16 v[14:17], v[196:199], v[130:133], v[14:17]
	v_mfma_f32_16x16x32_bf16 v[10:13], v[196:199], v[216:219], v[10:13]
	v_mfma_f32_16x16x32_bf16 v[6:9], v[204:207], v[130:133], v[6:9]
	v_mfma_f32_16x16x32_bf16 v[2:5], v[204:207], v[216:219], v[2:5]
	v_mfma_f32_16x16x32_bf16 v[30:33], v[184:187], v[212:215], v[30:33]
	v_mfma_f32_16x16x32_bf16 v[26:29], v[184:187], v[176:179], v[26:29]
	v_mfma_f32_16x16x32_bf16 v[22:25], v[192:195], v[212:215], v[22:25]
	v_mfma_f32_16x16x32_bf16 v[18:21], v[192:195], v[176:179], v[18:21]
	v_mfma_f32_16x16x32_bf16 v[14:17], v[200:203], v[212:215], v[14:17]
	v_mfma_f32_16x16x32_bf16 v[10:13], v[200:203], v[176:179], v[10:13]
	v_mfma_f32_16x16x32_bf16 v[6:9], v[208:211], v[212:215], v[6:9]
	v_mfma_f32_16x16x32_bf16 v[2:5], v[208:211], v[176:179], v[2:5]
	s_barrier
	ds_read_b128 v[130:133], v167
	ds_read_b128 v[168:171], v167 offset:1024
	ds_read_b128 v[172:175], v167 offset:2048
	ds_read_b128 v[176:179], v167 offset:3072
	ds_read_b128 v[34:37], v159 offset:32768
	ds_read_b128 v[38:41], v159 offset:33792
	ds_read_b128 v[42:45], v147 offset:32768
	ds_read_b128 v[46:49], v147 offset:33792
	ds_read_b128 v[180:183], v146 offset:32768
	ds_read_b128 v[184:187], v146 offset:33792
	ds_read_b128 v[188:191], v145 offset:32768
	ds_read_b128 v[192:195], v145 offset:33792
	s_waitcnt vmcnt(2)
	s_barrier
	s_waitcnt lgkmcnt(0)
	v_mfma_f32_16x16x32_bf16 v[50:53], v[34:37], v[130:133], v[126:129]
	v_mfma_f32_16x16x32_bf16 v[126:129], v[38:41], v[168:171], v[50:53]
	v_mfma_f32_16x16x32_bf16 v[50:53], v[34:37], v[172:175], v[122:125]
	v_mfma_f32_16x16x32_bf16 v[122:125], v[38:41], v[176:179], v[50:53]
	v_mfma_f32_16x16x32_bf16 v[50:53], v[42:45], v[130:133], v[118:121]
	v_mfma_f32_16x16x32_bf16 v[118:121], v[46:49], v[168:171], v[50:53]
	v_mfma_f32_16x16x32_bf16 v[50:53], v[42:45], v[172:175], v[114:117]
	v_mfma_f32_16x16x32_bf16 v[114:117], v[46:49], v[176:179], v[50:53]
	v_mfma_f32_16x16x32_bf16 v[50:53], v[180:183], v[130:133], v[110:113]
	v_mfma_f32_16x16x32_bf16 v[110:113], v[184:187], v[168:171], v[50:53]
	v_mfma_f32_16x16x32_bf16 v[50:53], v[180:183], v[172:175], v[106:109]
	v_mfma_f32_16x16x32_bf16 v[106:109], v[184:187], v[176:179], v[50:53]
	v_mfma_f32_16x16x32_bf16 v[50:53], v[188:191], v[130:133], v[102:105]
	v_mfma_f32_16x16x32_bf16 v[102:105], v[192:195], v[168:171], v[50:53]
	v_mfma_f32_16x16x32_bf16 v[50:53], v[188:191], v[172:175], v[98:101]
	v_mfma_f32_16x16x32_bf16 v[98:101], v[192:195], v[176:179], v[50:53]
	s_barrier
; #define LDA(dst, b, h) _Pragma("unroll") for (int m = 0; m < 4; ++m) _Pragma("unroll") for (int k = 0; k < 2; ++k) \
;     dst[m][k] = *reinterpret_cast<const bf16x8*>((char*)SA(b, h) + lds_byte(wr * 64 + m * 16 + fr, k * 32 + fq * 8))
; #define LDB(dst, b, h) _Pragma("unroll") for (int n = 0; n < 2; ++n) _Pragma("unroll") for (int k = 0; k < 2; ++k) \
;     dst[n][k] = *reinterpret_cast<const bf16x8*>((char*)SB(b, h) + lds_byte(wc * 32 + n * 16 + fr, k * 32 + fq * 8))
; #define MMA(ai, bj, At, Bq) do { __builtin_amdgcn_s_setprio(1); \
;     _Pragma("unroll") for (int m = 0; m < 4; ++m) _Pragma("unroll") for (int n = 0; n < 2; ++n) _Pragma("unroll") for (int k = 0; k < 2; ++k) \
;       acc[ai][bj][m][n] = __builtin_amdgcn_mfma_f32_16x16x32_bf16(At[m][k], Bq[n][k], acc[ai][bj][m][n], 0, 0, 0); \
;     __builtin_amdgcn_s_setprio(0); } while (0)
; #define WAIT_V(n) asm volatile("s_waitcnt vmcnt(" #n ")" ::: "memory")
; #define WAIT_L(n) asm volatile("s_waitcnt lgkmcnt(" #n ")" ::: "memory")
; #define BAR __builtin_amdgcn_s_barrier()
; __device__ __forceinline__ void gemm256(const u16* __restrict__ A, int lda, const u16* __restrict__ Bt, int ldb, int K,
;                                         f32x4 (&acc)[2][2][4][2], const int g_wid) {
;     ...
;     LDB(B1, 1, 1); WAIT_V(0); BAR; WAIT_L(0); MMA(0, 1, At, B1); BAR;
;     LDA(At, 1, 1); BAR; WAIT_L(0); MMA(1, 0, At, B0); MMA(1, 1, At, B1); BAR; }
;   if (wr == 0) BAR;
	ds_read_b128 v[196:199], v160
	ds_read_b128 v[200:203], v160 offset:1024
	ds_read_b128 v[204:207], v160 offset:2048
	ds_read_b128 v[208:211], v160 offset:3072
	s_waitcnt vmcnt(0)
	s_barrier
	s_waitcnt lgkmcnt(0)
	v_mfma_f32_16x16x32_bf16 v[50:53], v[34:37], v[196:199], v[94:97]
	v_mfma_f32_16x16x32_bf16 v[34:37], v[34:37], v[204:207], v[90:93]
	v_mfma_f32_16x16x32_bf16 v[58:61], v[38:41], v[208:211], v[34:37]
	v_mfma_f32_16x16x32_bf16 v[34:37], v[42:45], v[196:199], v[86:89]
	v_mfma_f32_16x16x32_bf16 v[54:57], v[46:49], v[200:203], v[34:37]
	v_mfma_f32_16x16x32_bf16 v[34:37], v[42:45], v[204:207], v[82:85]
	v_mfma_f32_16x16x32_bf16 v[62:65], v[38:41], v[200:203], v[50:53]
	v_mfma_f32_16x16x32_bf16 v[50:53], v[46:49], v[208:211], v[34:37]
	v_mfma_f32_16x16x32_bf16 v[34:37], v[180:183], v[196:199], v[78:81]
	v_mfma_f32_16x16x32_bf16 v[46:49], v[184:187], v[200:203], v[34:37]
	v_mfma_f32_16x16x32_bf16 v[34:37], v[180:183], v[204:207], v[74:77]
	v_mfma_f32_16x16x32_bf16 v[42:45], v[184:187], v[208:211], v[34:37]
	v_mfma_f32_16x16x32_bf16 v[34:37], v[188:191], v[196:199], v[70:73]
	v_mfma_f32_16x16x32_bf16 v[38:41], v[192:195], v[200:203], v[34:37]
	v_mfma_f32_16x16x32_bf16 v[34:37], v[188:191], v[204:207], v[66:69]
	v_mfma_f32_16x16x32_bf16 v[34:37], v[192:195], v[208:211], v[34:37]
	s_barrier
	ds_read_b128 v[180:183], v159 offset:49152
	ds_read_b128 v[184:187], v159 offset:50176
	ds_read_b128 v[188:191], v147 offset:49152
	ds_read_b128 v[192:195], v147 offset:50176
	ds_read_b128 v[212:215], v146 offset:49152
	ds_read_b128 v[216:219], v146 offset:50176
	ds_read_b128 v[244:247], v145 offset:49152
	ds_read_b128 v[248:251], v145 offset:50176
	s_barrier
	s_waitcnt lgkmcnt(0)
	v_mfma_f32_16x16x32_bf16 v[66:69], v[180:183], v[130:133], v[220:223]
	v_mfma_f32_16x16x32_bf16 v[94:97], v[184:187], v[168:171], v[66:69]
	v_mfma_f32_16x16x32_bf16 v[66:69], v[180:183], v[172:175], v[224:227]
	v_mfma_f32_16x16x32_bf16 v[90:93], v[184:187], v[176:179], v[66:69]
	v_mfma_f32_16x16x32_bf16 v[66:69], v[188:191], v[130:133], v[228:231]
	v_mfma_f32_16x16x32_bf16 v[86:89], v[192:195], v[168:171], v[66:69]
	v_mfma_f32_16x16x32_bf16 v[66:69], v[188:191], v[172:175], v[232:235]
	v_mfma_f32_16x16x32_bf16 v[82:85], v[192:195], v[176:179], v[66:69]
	v_mfma_f32_16x16x32_bf16 v[66:69], v[212:215], v[130:133], v[236:239]
	v_mfma_f32_16x16x32_bf16 v[78:81], v[216:219], v[168:171], v[66:69]
	v_mfma_f32_16x16x32_bf16 v[66:69], v[212:215], v[172:175], v[240:243]
	v_mfma_f32_16x16x32_bf16 v[74:77], v[216:219], v[176:179], v[66:69]
	v_mfma_f32_16x16x32_bf16 v[66:69], v[244:247], v[130:133], v[134:137]
	v_mfma_f32_16x16x32_bf16 v[70:73], v[248:251], v[168:171], v[66:69]
	v_mfma_f32_16x16x32_bf16 v[66:69], v[244:247], v[172:175], v[162:165]
	v_mfma_f32_16x16x32_bf16 v[66:69], v[248:251], v[176:179], v[66:69]
	v_mfma_f32_16x16x32_bf16 v[30:33], v[180:183], v[196:199], v[30:33]
	v_mfma_f32_16x16x32_bf16 v[26:29], v[180:183], v[204:207], v[26:29]
	v_mfma_f32_16x16x32_bf16 v[22:25], v[188:191], v[196:199], v[22:25]
	v_mfma_f32_16x16x32_bf16 v[18:21], v[188:191], v[204:207], v[18:21]
	v_mfma_f32_16x16x32_bf16 v[14:17], v[212:215], v[196:199], v[14:17]
	v_mfma_f32_16x16x32_bf16 v[10:13], v[212:215], v[204:207], v[10:13]
	v_mfma_f32_16x16x32_bf16 v[6:9], v[244:247], v[196:199], v[6:9]
	v_mfma_f32_16x16x32_bf16 v[2:5], v[244:247], v[204:207], v[2:5]
	v_mfma_f32_16x16x32_bf16 v[30:33], v[184:187], v[200:203], v[30:33]
	v_mfma_f32_16x16x32_bf16 v[26:29], v[184:187], v[208:211], v[26:29]
	v_mfma_f32_16x16x32_bf16 v[22:25], v[192:195], v[200:203], v[22:25]
	v_mfma_f32_16x16x32_bf16 v[18:21], v[192:195], v[208:211], v[18:21]
	v_mfma_f32_16x16x32_bf16 v[14:17], v[216:219], v[200:203], v[14:17]
	v_mfma_f32_16x16x32_bf16 v[10:13], v[216:219], v[208:211], v[10:13]
	v_mfma_f32_16x16x32_bf16 v[6:9], v[248:251], v[200:203], v[6:9]
	v_mfma_f32_16x16x32_bf16 v[2:5], v[248:251], v[208:211], v[2:5]
	s_setprio 0
	s_movk_i32 s10, 0x100
	v_cmp_gt_u32_e32 vcc, s10, v0
	s_barrier
	s_and_saveexec_b64 s[34:35], vcc
	s_cbranch_execz .LBB0_105
	s_barrier
	s_branch .LBB0_105

; #define STA(P, br, kt) STAGE(P, A, aoff0, aoff1, lda, br, kt)
; #define STB(P, br, kt) STAGE(P, Bt, boff0, boff1, ldb, br, kt)
; #define LDA(dst, b, h) _Pragma("unroll") for (int m = 0; m < 4; ++m) _Pragma("unroll") for (int k = 0; k < 2; ++k) \
;     dst[m][k] = *reinterpret_cast<const bf16x8*>((char*)SA(b, h) + lds_byte(wr * 64 + m * 16 + fr, k * 32 + fq * 8))
; #define LDB(dst, b, h) _Pragma("unroll") for (int n = 0; n < 2; ++n) _Pragma("unroll") for (int k = 0; k < 2; ++k) \
;     dst[n][k] = *reinterpret_cast<const bf16x8*>((char*)SB(b, h) + lds_byte(wc * 32 + n * 16 + fr, k * 32 + fq * 8))
; #define MMA(ai, bj, At, Bq) do { __builtin_amdgcn_s_setprio(1); \
;     _Pragma("unroll") for (int m = 0; m < 4; ++m) _Pragma("unroll") for (int n = 0; n < 2; ++n) _Pragma("unroll") for (int k = 0; k < 2; ++k) \
;       acc[ai][bj][m][n] = __builtin_amdgcn_mfma_f32_16x16x32_bf16(At[m][k], Bq[n][k], acc[ai][bj][m][n], 0, 0, 0); \
;     __builtin_amdgcn_s_setprio(0); } while (0)
; #define WAIT_V(n) asm volatile("s_waitcnt vmcnt(" #n ")" ::: "memory")
; #define WAIT_L(n) asm volatile("s_waitcnt lgkmcnt(" #n ")" ::: "memory")
; #define BAR __builtin_amdgcn_s_barrier()
; #define SCHED __builtin_amdgcn_sched_barrier(0)
; __device__ __forceinline__ void gemm256(const u16* __restrict__ A, int lda, const u16* __restrict__ Bt, int ldb, int K,
;                                         f32x4 (&acc)[2][2][4][2], const int g_wid) {
;     ...
;   STB(SB(0, 0), 0, 0); STA(SA(0, 0), 0, 0);
;   STB(SB(0, 1), HALF, 0); STA(SA(0, 1), HALF, 0);
;   if (wr == 1) BAR;
;   WAIT_V(4); BAR;
;   STB(SB(1, 0), 0, 1); STA(SA(1, 0), 0, 1); STB(SB(1, 1), HALF, 1);
;   WAIT_V(6); BAR;
;   for (int t = 0; t < nt - 2; t += 2) {
;     LDB(B0, 0, 0); SCHED; LDA(At, 0, 0); STA(SA(1, 1), HALF, t + 1);
;     WAIT_L(8); BAR; WAIT_L(0); MMA(0, 0, At, B0); BAR; SCHED;
;     LDB(B1, 0, 1); STB(SB(0, 0), 0, t + 2);
;     BAR; WAIT_L(0); MMA(0, 1, At, B1); BAR;
;     LDA(At, 0, 1); STA(SA(0, 0), 0, t + 2);
;     BAR; WAIT_L(0); MMA(1, 0, At, B0); BAR; SCHED;
;     STB(SB(0, 1), HALF, t + 2);
;     WAIT_V(6); BAR; MMA(1, 1, At, B1); BAR;
.LBB0_116:
	s_or_b64 exec, exec, s[28:29]
	v_readlane_b32 s11, v254, 42
	s_mov_b64 s[28:29], 0x80
	v_lshl_add_u64 v[138:139], v[138:139], 0, s[28:29]
	v_add_u32_e32 v169, s11, v173
	v_add_u32_e32 v170, 0x2000, v169
	v_readfirstlane_b32 s10, v169
	s_mov_b32 m0, s10
	v_readfirstlane_b32 s10, v170
	v_add_u32_e32 v171, 0x8000, v161
	s_waitcnt vmcnt(4)
	s_barrier
	global_load_lds_dwordx4 v[138:139], off
	v_lshl_add_u64 v[138:139], v[142:143], 0, s[28:29]
	s_mov_b32 m0, s10
	v_readfirstlane_b32 s10, v171
	global_load_lds_dwordx4 v[138:139], off
	v_lshl_add_u64 v[138:139], v[144:145], 0, s[28:29]
	s_mov_b32 m0, s10
	v_add_u32_e32 v172, 0xa000, v161
	global_load_lds_dwordx4 v[138:139], off
	v_lshl_add_u64 v[138:139], v[146:147], 0, s[28:29]
	v_readlane_b32 s28, v254, 43
	v_readfirstlane_b32 s10, v172
	s_add_u32 s26, s26, 0x60080
	v_add_u32_e32 v173, s28, v173
	s_mov_b32 m0, s10
	s_addc_u32 s27, s27, 0
	v_readfirstlane_b32 s10, v173
	v_add_u32_e32 v174, 0x2000, v173
	global_load_lds_dwordx4 v[138:139], off
	v_lshl_add_u64 v[136:137], v[136:137], 1, s[26:27]
	s_mov_b32 m0, s10
	v_readfirstlane_b32 s10, v174
	global_load_lds_dwordx4 v[136:137], off
	v_lshl_add_u64 v[134:135], v[134:135], 1, s[26:27]
	s_mov_b32 m0, s10
	v_lshlrev_b32_e32 v136, 2, v0
	global_load_lds_dwordx4 v[134:135], off
	v_and_b32_e32 v134, 15, v0
	v_and_b32_e32 v135, 48, v0
	v_lshlrev_b32_e32 v134, 6, v134
	v_and_b32_e32 v136, 32, v136
	v_bitop3_b32 v134, v134, v136, v135 bitop3:0x36
	v_readlane_b32 s10, v254, 40
	v_lshlrev_b32_e32 v137, 6, v0
	v_add_u32_e32 v183, s11, v134
	v_add_u32_e32 v144, s10, v134
	v_readlane_b32 s10, v254, 41
	v_add_u32_e32 v184, s28, v134
	v_add_u32_e32 v146, 0, v134
	v_add_u32_e32 v182, s10, v134
	s_movk_i32 s10, 0x3c0
	v_and_or_b32 v134, v137, s10, v135
	s_movk_i32 s9, 0x600
	v_lshlrev_b32_e32 v145, 13, v181
	v_xad_u32 v181, v134, v136, 0
	v_lshrrev_b32_e32 v135, 1, v177
	v_mul_lo_u32 v134, v179, s9
	s_movk_i32 s10, 0x6000
	v_lshrrev_b32_e32 v142, 1, v162
	v_mul_lo_u32 v136, v168, s9
	v_lshlrev_b32_e32 v143, 9, v168
	v_and_b32_e32 v185, 0x3000, v137
	v_mad_u64_u32 v[134:135], s[26:27], v135, s10, v[134:135]
	v_mad_u64_u32 v[136:137], s[26:27], v142, s10, v[136:137]
	v_lshl_add_u32 v142, v142, 13, v143
	v_or_b32_e32 v134, v134, v178
	v_or_b32_e32 v136, v136, v175
	v_or_b32_e32 v142, v142, v175
	s_waitcnt vmcnt(6)
	v_add_u32_e32 v134, v134, v180
	v_add_u32_e32 v136, v136, v176
	v_add_u32_e32 v142, v142, v176
	v_or_b32_e32 v186, 0x800, v145
	v_or_b32_e32 v187, 0x1000, v145
	v_or_b32_e32 v188, 0x1800, v145
	v_ashrrev_i32_e32 v135, 31, v134
	v_ashrrev_i32_e32 v137, 31, v136
	v_ashrrev_i32_e32 v143, 31, v142
	v_lshl_add_u64 v[134:135], v[134:135], 1, s[20:21]
	v_lshl_add_u64 v[136:137], v[136:137], 1, s[20:21]
	v_lshl_add_u64 v[138:139], v[2:3], 1, s[22:23]
	v_lshl_add_u64 v[142:143], v[142:143], 1, s[22:23]
	s_mov_b32 s28, -2
	s_mov_b64 s[26:27], 0
	v_add_u32_e32 v176, v144, v185
	v_add_u32_e32 v147, v146, v145
	v_add_u32_e32 v146, v181, v186
	v_add_u32_e32 v145, v181, v187
	v_add_u32_e32 v144, v181, v188
	v_add_u32_e32 v175, v182, v185
	v_add_u32_e32 v168, v183, v185
	v_add_u32_e32 v162, v184, v185
	.p2align 6
.LBB0_117:
	s_barrier
	ds_read_b128 v[180:183], v176
	ds_read_b128 v[184:187], v176 offset:1024
	ds_read_b128 v[188:191], v176 offset:2048
	ds_read_b128 v[192:195], v176 offset:3072
	v_add_u32_e32 v177, 0xc000, v161
	v_lshl_add_u64 v[244:245], v[142:143], 0, s[26:27]
	v_readfirstlane_b32 s10, v177
	v_lshl_add_u64 v[178:179], v[244:245], 0, s[88:89]
	s_mov_b32 m0, s10
	ds_read_b128 v[196:199], v147
	ds_read_b128 v[200:203], v147 offset:1024
	ds_read_b128 v[204:207], v146
	ds_read_b128 v[208:211], v146 offset:1024
	ds_read_b128 v[212:215], v145
	ds_read_b128 v[216:219], v145 offset:1024
	ds_read_b128 v[220:223], v144
	ds_read_b128 v[224:227], v144 offset:1024
	global_load_lds_dwordx4 v[178:179], off
	v_add_u32_e32 v178, 0xe000, v161
	v_lshl_add_u64 v[246:247], v[138:139], 0, s[26:27]
	v_readfirstlane_b32 s10, v178
	v_lshl_add_u64 v[228:229], v[246:247], 0, s[88:89]
	s_mov_b32 m0, s10
	s_nop 0
	global_load_lds_dwordx4 v[228:229], off
	s_waitcnt lgkmcnt(8)
	s_barrier
	s_waitcnt lgkmcnt(0)
	v_mfma_f32_16x16x32_bf16 v[8:11], v[196:199], v[180:183], v[8:11]
	v_mfma_f32_16x16x32_bf16 v[4:7], v[196:199], v[188:191], v[4:7]
	v_mfma_f32_16x16x32_bf16 v[24:27], v[204:207], v[180:183], v[24:27]
	v_mfma_f32_16x16x32_bf16 v[20:23], v[204:207], v[188:191], v[20:23]
	v_mfma_f32_16x16x32_bf16 v[56:59], v[212:215], v[180:183], v[56:59]
	v_mfma_f32_16x16x32_bf16 v[52:55], v[212:215], v[188:191], v[52:55]
	v_mfma_f32_16x16x32_bf16 v[88:91], v[220:223], v[180:183], v[88:91]
	v_mfma_f32_16x16x32_bf16 v[84:87], v[220:223], v[188:191], v[84:87]
	v_mfma_f32_16x16x32_bf16 v[8:11], v[200:203], v[184:187], v[8:11]
	v_mfma_f32_16x16x32_bf16 v[4:7], v[200:203], v[192:195], v[4:7]
	v_mfma_f32_16x16x32_bf16 v[24:27], v[208:211], v[184:187], v[24:27]
	v_mfma_f32_16x16x32_bf16 v[20:23], v[208:211], v[192:195], v[20:23]
	v_mfma_f32_16x16x32_bf16 v[56:59], v[216:219], v[184:187], v[56:59]
	v_mfma_f32_16x16x32_bf16 v[52:55], v[216:219], v[192:195], v[52:55]
	v_mfma_f32_16x16x32_bf16 v[88:91], v[224:227], v[184:187], v[88:91]
	v_mfma_f32_16x16x32_bf16 v[84:87], v[224:227], v[192:195], v[84:87]
	s_barrier
	v_lshl_add_u64 v[248:249], v[136:137], 0, s[26:27]
	v_readfirstlane_b32 s10, v159
	v_lshl_add_u64 v[250:251], v[248:249], 0, s[90:91]
	s_mov_b32 m0, s10
	ds_read_b128 v[228:231], v175
	ds_read_b128 v[232:235], v175 offset:1024
	ds_read_b128 v[236:239], v175 offset:2048
	ds_read_b128 v[240:243], v175 offset:3072
	global_load_lds_dwordx4 v[250:251], off
	v_lshl_add_u64 v[250:251], v[134:135], 0, s[26:27]
	v_readfirstlane_b32 s10, v160
	v_lshl_add_u64 v[252:253], v[250:251], 0, s[90:91]
	s_mov_b32 m0, s10
	s_nop 0
	global_load_lds_dwordx4 v[252:253], off
	s_barrier
; #define STA(P, br, kt) STAGE(P, A, aoff0, aoff1, lda, br, kt)
; #define STB(P, br, kt) STAGE(P, Bt, boff0, boff1, ldb, br, kt)
; #define LDA(dst, b, h) _Pragma("unroll") for (int m = 0; m < 4; ++m) _Pragma("unroll") for (int k = 0; k < 2; ++k) \
;     dst[m][k] = *reinterpret_cast<const bf16x8*>((char*)SA(b, h) + lds_byte(wr * 64 + m * 16 + fr, k * 32 + fq * 8))
; #define LDB(dst, b, h) _Pragma("unroll") for (int n = 0; n < 2; ++n) _Pragma("unroll") for (int k = 0; k < 2; ++k) \
;     dst[n][k] = *reinterpret_cast<const bf16x8*>((char*)SB(b, h) + lds_byte(wc * 32 + n * 16 + fr, k * 32 + fq * 8))
; #define MMA(ai, bj, At, Bq) do { __builtin_amdgcn_s_setprio(1); \
;     _Pragma("unroll") for (int m = 0; m < 4; ++m) _Pragma("unroll") for (int n = 0; n < 2; ++n) _Pragma("unroll") for (int k = 0; k < 2; ++k) \
;       acc[ai][bj][m][n] = __builtin_amdgcn_mfma_f32_16x16x32_bf16(At[m][k], Bq[n][k], acc[ai][bj][m][n], 0, 0, 0); \
;     __builtin_amdgcn_s_setprio(0); } while (0)
; #define WAIT_V(n) asm volatile("s_waitcnt vmcnt(" #n ")" ::: "memory")
; #define WAIT_L(n) asm volatile("s_waitcnt lgkmcnt(" #n ")" ::: "memory")
; #define BAR __builtin_amdgcn_s_barrier()
; #define SCHED __builtin_amdgcn_sched_barrier(0)
; __device__ __forceinline__ void gemm256(const u16* __restrict__ A, int lda, const u16* __restrict__ Bt, int ldb, int K,
;                                         f32x4 (&acc)[2][2][4][2], const int g_wid) {
;     ...
;     BAR; WAIT_L(0); MMA(0, 1, At, B1); BAR;
;     LDA(At, 0, 1); STA(SA(0, 0), 0, t + 2);
;     BAR; WAIT_L(0); MMA(1, 0, At, B0); BAR; SCHED;
;     STB(SB(0, 1), HALF, t + 2);
;     WAIT_V(6); BAR; MMA(1, 1, At, B1); BAR;
;     LDB(B0, 1, 0); SCHED; LDA(At, 1, 0); STA(SA(0, 1), HALF, t + 2);
;     WAIT_L(8); BAR; WAIT_L(0); MMA(0, 0, At, B0); BAR; SCHED;
	s_waitcnt lgkmcnt(0)
	v_mfma_f32_16x16x32_bf16 v[16:19], v[196:199], v[228:231], v[16:19]
	v_mfma_f32_16x16x32_bf16 v[12:15], v[196:199], v[236:239], v[12:15]
	v_mfma_f32_16x16x32_bf16 v[40:43], v[204:207], v[228:231], v[40:43]
	v_mfma_f32_16x16x32_bf16 v[36:39], v[204:207], v[236:239], v[36:39]
	v_mfma_f32_16x16x32_bf16 v[72:75], v[212:215], v[228:231], v[72:75]
	v_mfma_f32_16x16x32_bf16 v[64:67], v[212:215], v[236:239], v[64:67]
	v_mfma_f32_16x16x32_bf16 v[104:107], v[220:223], v[228:231], v[104:107]
	v_mfma_f32_16x16x32_bf16 v[92:95], v[220:223], v[236:239], v[92:95]
	v_mfma_f32_16x16x32_bf16 v[16:19], v[200:203], v[232:235], v[16:19]
	v_mfma_f32_16x16x32_bf16 v[12:15], v[200:203], v[240:243], v[12:15]
	v_mfma_f32_16x16x32_bf16 v[40:43], v[208:211], v[232:235], v[40:43]
	v_mfma_f32_16x16x32_bf16 v[36:39], v[208:211], v[240:243], v[36:39]
	v_mfma_f32_16x16x32_bf16 v[72:75], v[216:219], v[232:235], v[72:75]
	v_mfma_f32_16x16x32_bf16 v[64:67], v[216:219], v[240:243], v[64:67]
	v_mfma_f32_16x16x32_bf16 v[104:107], v[224:227], v[232:235], v[104:107]
	v_mfma_f32_16x16x32_bf16 v[92:95], v[224:227], v[240:243], v[92:95]
	v_readfirstlane_b32 s10, v161
	v_lshl_add_u64 v[252:253], v[244:245], 0, s[92:93]
	s_mov_b32 m0, s10
	v_readfirstlane_b32 s10, v163
	s_barrier
	ds_read_b128 v[196:199], v147 offset:16384
	ds_read_b128 v[200:203], v147 offset:17408
	ds_read_b128 v[204:207], v146 offset:16384
	ds_read_b128 v[208:211], v146 offset:17408
	ds_read_b128 v[212:215], v145 offset:16384
	ds_read_b128 v[216:219], v145 offset:17408
	ds_read_b128 v[220:223], v144 offset:16384
	ds_read_b128 v[224:227], v144 offset:17408
	global_load_lds_dwordx4 v[252:253], off
	v_lshl_add_u64 v[252:253], v[246:247], 0, s[92:93]
	s_mov_b32 m0, s10
	s_nop 0
	global_load_lds_dwordx4 v[252:253], off
	s_barrier
	s_waitcnt lgkmcnt(0)
	v_mfma_f32_16x16x32_bf16 v[120:123], v[196:199], v[180:183], v[120:123]
	v_mfma_f32_16x16x32_bf16 v[116:119], v[196:199], v[188:191], v[116:119]
	v_mfma_f32_16x16x32_bf16 v[112:115], v[204:207], v[180:183], v[112:115]
	v_mfma_f32_16x16x32_bf16 v[108:111], v[204:207], v[188:191], v[108:111]
	v_mfma_f32_16x16x32_bf16 v[80:83], v[212:215], v[180:183], v[80:83]
	v_mfma_f32_16x16x32_bf16 v[76:79], v[212:215], v[188:191], v[76:79]
	v_mfma_f32_16x16x32_bf16 v[48:51], v[220:223], v[180:183], v[48:51]
	v_mfma_f32_16x16x32_bf16 v[44:47], v[220:223], v[188:191], v[44:47]
	v_mfma_f32_16x16x32_bf16 v[120:123], v[200:203], v[184:187], v[120:123]
	v_mfma_f32_16x16x32_bf16 v[116:119], v[200:203], v[192:195], v[116:119]
	v_mfma_f32_16x16x32_bf16 v[112:115], v[208:211], v[184:187], v[112:115]
	v_mfma_f32_16x16x32_bf16 v[108:111], v[208:211], v[192:195], v[108:111]
	v_mfma_f32_16x16x32_bf16 v[80:83], v[216:219], v[184:187], v[80:83]
	v_mfma_f32_16x16x32_bf16 v[76:79], v[216:219], v[192:195], v[76:79]
	v_mfma_f32_16x16x32_bf16 v[48:51], v[224:227], v[184:187], v[48:51]
	v_mfma_f32_16x16x32_bf16 v[44:47], v[224:227], v[192:195], v[44:47]
	s_barrier
	v_readfirstlane_b32 s10, v164
	v_lshl_add_u64 v[180:181], v[248:249], 0, s[94:95]
	s_mov_b32 m0, s10
	v_readfirstlane_b32 s10, v165
	global_load_lds_dwordx4 v[180:181], off
	v_lshl_add_u64 v[180:181], v[250:251], 0, s[94:95]
	s_mov_b32 m0, s10
	s_nop 0
	global_load_lds_dwordx4 v[180:181], off
	s_waitcnt vmcnt(6)
	s_barrier
	v_mfma_f32_16x16x32_bf16 v[128:131], v[196:199], v[228:231], v[128:131]
	v_mfma_f32_16x16x32_bf16 v[124:127], v[196:199], v[236:239], v[124:127]
	v_mfma_f32_16x16x32_bf16 v[100:103], v[204:207], v[228:231], v[100:103]
	v_mfma_f32_16x16x32_bf16 v[96:99], v[204:207], v[236:239], v[96:99]
	v_mfma_f32_16x16x32_bf16 v[68:71], v[212:215], v[228:231], v[68:71]
	v_mfma_f32_16x16x32_bf16 v[60:63], v[212:215], v[236:239], v[60:63]
	v_mfma_f32_16x16x32_bf16 v[32:35], v[220:223], v[228:231], v[32:35]
	v_mfma_f32_16x16x32_bf16 v[28:31], v[220:223], v[236:239], v[28:31]
	v_mfma_f32_16x16x32_bf16 v[128:131], v[200:203], v[232:235], v[128:131]
	v_mfma_f32_16x16x32_bf16 v[124:127], v[200:203], v[240:243], v[124:127]
	v_mfma_f32_16x16x32_bf16 v[100:103], v[208:211], v[232:235], v[100:103]
	v_mfma_f32_16x16x32_bf16 v[96:99], v[208:211], v[240:243], v[96:99]
	v_mfma_f32_16x16x32_bf16 v[68:71], v[216:219], v[232:235], v[68:71]
	v_mfma_f32_16x16x32_bf16 v[60:63], v[216:219], v[240:243], v[60:63]
	v_mfma_f32_16x16x32_bf16 v[32:35], v[224:227], v[232:235], v[32:35]
	v_mfma_f32_16x16x32_bf16 v[28:31], v[224:227], v[240:243], v[28:31]
	s_barrier
	ds_read_b128 v[180:183], v168
	ds_read_b128 v[184:187], v168 offset:1024
	ds_read_b128 v[188:191], v168 offset:2048
	ds_read_b128 v[192:195], v168 offset:3072
	v_readfirstlane_b32 s10, v166
	v_lshl_add_u64 v[228:229], v[244:245], 0, s[96:97]
	s_mov_b32 m0, s10
	v_readfirstlane_b32 s10, v167
	ds_read_b128 v[196:199], v147 offset:32768
	ds_read_b128 v[200:203], v147 offset:33792
	ds_read_b128 v[204:207], v146 offset:32768
	ds_read_b128 v[208:211], v146 offset:33792
	ds_read_b128 v[212:215], v145 offset:32768
	ds_read_b128 v[216:219], v145 offset:33792
	ds_read_b128 v[220:223], v144 offset:32768
	ds_read_b128 v[224:227], v144 offset:33792
	global_load_lds_dwordx4 v[228:229], off
	v_lshl_add_u64 v[228:229], v[246:247], 0, s[96:97]
	s_mov_b32 m0, s10
	s_nop 0
	global_load_lds_dwordx4 v[228:229], off
	s_waitcnt lgkmcnt(8)
	s_barrier
; #define STA(P, br, kt) STAGE(P, A, aoff0, aoff1, lda, br, kt)
; #define STB(P, br, kt) STAGE(P, Bt, boff0, boff1, ldb, br, kt)
; #define LDA(dst, b, h) _Pragma("unroll") for (int m = 0; m < 4; ++m) _Pragma("unroll") for (int k = 0; k < 2; ++k) \
;     dst[m][k] = *reinterpret_cast<const bf16x8*>((char*)SA(b, h) + lds_byte(wr * 64 + m * 16 + fr, k * 32 + fq * 8))
; #define LDB(dst, b, h) _Pragma("unroll") for (int n = 0; n < 2; ++n) _Pragma("unroll") for (int k = 0; k < 2; ++k) \
;     dst[n][k] = *reinterpret_cast<const bf16x8*>((char*)SB(b, h) + lds_byte(wc * 32 + n * 16 + fr, k * 32 + fq * 8))
; #define MMA(ai, bj, At, Bq) do { __builtin_amdgcn_s_setprio(1); \
;     _Pragma("unroll") for (int m = 0; m < 4; ++m) _Pragma("unroll") for (int n = 0; n < 2; ++n) _Pragma("unroll") for (int k = 0; k < 2; ++k) \
;       acc[ai][bj][m][n] = __builtin_amdgcn_mfma_f32_16x16x32_bf16(At[m][k], Bq[n][k], acc[ai][bj][m][n], 0, 0, 0); \
;     __builtin_amdgcn_s_setprio(0); } while (0)
; #define WAIT_V(n) asm volatile("s_waitcnt vmcnt(" #n ")" ::: "memory")
; #define WAIT_L(n) asm volatile("s_waitcnt lgkmcnt(" #n ")" ::: "memory")
; #define BAR __builtin_amdgcn_s_barrier()
; #define SCHED __builtin_amdgcn_sched_barrier(0)
; __device__ __forceinline__ void gemm256(const u16* __restrict__ A, int lda, const u16* __restrict__ Bt, int ldb, int K,
;                                         f32x4 (&acc)[2][2][4][2], const int g_wid) {
;     ...
;     WAIT_L(8); BAR; WAIT_L(0); MMA(0, 0, At, B0); BAR; SCHED;
;     LDB(B1, 1, 1); STB(SB(1, 0), 0, t + 3);
;     BAR; WAIT_L(0); MMA(0, 1, At, B1); BAR;
;     LDA(At, 1, 1); STA(SA(1, 0), 0, t + 3);
;     BAR; WAIT_L(0); MMA(1, 0, At, B0); BAR; SCHED;
;     STB(SB(1, 1), HALF, t + 3);
;     WAIT_V(6); BAR; MMA(1, 1, At, B1); BAR;
	s_waitcnt lgkmcnt(0)
	v_mfma_f32_16x16x32_bf16 v[8:11], v[196:199], v[180:183], v[8:11]
	v_mfma_f32_16x16x32_bf16 v[4:7], v[196:199], v[188:191], v[4:7]
	v_mfma_f32_16x16x32_bf16 v[24:27], v[204:207], v[180:183], v[24:27]
	v_mfma_f32_16x16x32_bf16 v[20:23], v[204:207], v[188:191], v[20:23]
	v_mfma_f32_16x16x32_bf16 v[56:59], v[212:215], v[180:183], v[56:59]
	v_mfma_f32_16x16x32_bf16 v[52:55], v[212:215], v[188:191], v[52:55]
	v_mfma_f32_16x16x32_bf16 v[88:91], v[220:223], v[180:183], v[88:91]
	v_mfma_f32_16x16x32_bf16 v[84:87], v[220:223], v[188:191], v[84:87]
	v_mfma_f32_16x16x32_bf16 v[8:11], v[200:203], v[184:187], v[8:11]
	v_mfma_f32_16x16x32_bf16 v[4:7], v[200:203], v[192:195], v[4:7]
	v_mfma_f32_16x16x32_bf16 v[24:27], v[208:211], v[184:187], v[24:27]
	v_mfma_f32_16x16x32_bf16 v[20:23], v[208:211], v[192:195], v[20:23]
	v_mfma_f32_16x16x32_bf16 v[56:59], v[216:219], v[184:187], v[56:59]
	v_mfma_f32_16x16x32_bf16 v[52:55], v[216:219], v[192:195], v[52:55]
	v_mfma_f32_16x16x32_bf16 v[88:91], v[224:227], v[184:187], v[88:91]
	v_mfma_f32_16x16x32_bf16 v[84:87], v[224:227], v[192:195], v[84:87]
	s_barrier
	v_readfirstlane_b32 s10, v169
	v_lshl_add_u64 v[252:253], v[248:249], 0, s[66:67]
	s_mov_b32 m0, s10
	v_readfirstlane_b32 s10, v170
	ds_read_b128 v[228:231], v162
	ds_read_b128 v[232:235], v162 offset:1024
	ds_read_b128 v[236:239], v162 offset:2048
	ds_read_b128 v[240:243], v162 offset:3072
	global_load_lds_dwordx4 v[252:253], off
	v_lshl_add_u64 v[252:253], v[250:251], 0, s[66:67]
	s_mov_b32 m0, s10
	s_nop 0
	global_load_lds_dwordx4 v[252:253], off
	s_barrier
	s_waitcnt lgkmcnt(0)
	v_mfma_f32_16x16x32_bf16 v[16:19], v[196:199], v[228:231], v[16:19]
	v_mfma_f32_16x16x32_bf16 v[12:15], v[196:199], v[236:239], v[12:15]
	v_mfma_f32_16x16x32_bf16 v[40:43], v[204:207], v[228:231], v[40:43]
	v_mfma_f32_16x16x32_bf16 v[36:39], v[204:207], v[236:239], v[36:39]
	v_mfma_f32_16x16x32_bf16 v[72:75], v[212:215], v[228:231], v[72:75]
	v_mfma_f32_16x16x32_bf16 v[64:67], v[212:215], v[236:239], v[64:67]
	v_mfma_f32_16x16x32_bf16 v[104:107], v[220:223], v[228:231], v[104:107]
	v_mfma_f32_16x16x32_bf16 v[92:95], v[220:223], v[236:239], v[92:95]
	v_mfma_f32_16x16x32_bf16 v[16:19], v[200:203], v[232:235], v[16:19]
	v_mfma_f32_16x16x32_bf16 v[12:15], v[200:203], v[240:243], v[12:15]
	v_mfma_f32_16x16x32_bf16 v[40:43], v[208:211], v[232:235], v[40:43]
	v_mfma_f32_16x16x32_bf16 v[36:39], v[208:211], v[240:243], v[36:39]
	v_mfma_f32_16x16x32_bf16 v[72:75], v[216:219], v[232:235], v[72:75]
	v_mfma_f32_16x16x32_bf16 v[64:67], v[216:219], v[240:243], v[64:67]
	v_mfma_f32_16x16x32_bf16 v[104:107], v[224:227], v[232:235], v[104:107]
	v_mfma_f32_16x16x32_bf16 v[92:95], v[224:227], v[240:243], v[92:95]
	v_readfirstlane_b32 s10, v171
	v_lshl_add_u64 v[244:245], v[244:245], 0, s[62:63]
	s_mov_b32 m0, s10
	v_readfirstlane_b32 s10, v172
	s_barrier
	ds_read_b128 v[196:199], v147 offset:49152
	ds_read_b128 v[200:203], v147 offset:50176
	ds_read_b128 v[204:207], v146 offset:49152
	ds_read_b128 v[208:211], v146 offset:50176
	ds_read_b128 v[212:215], v145 offset:49152
	ds_read_b128 v[216:219], v145 offset:50176
	ds_read_b128 v[220:223], v144 offset:49152
	ds_read_b128 v[224:227], v144 offset:50176
	global_load_lds_dwordx4 v[244:245], off
	v_lshl_add_u64 v[244:245], v[246:247], 0, s[62:63]
	s_mov_b32 m0, s10
	s_nop 0
	global_load_lds_dwordx4 v[244:245], off
	s_barrier
	s_waitcnt lgkmcnt(0)
	v_mfma_f32_16x16x32_bf16 v[120:123], v[196:199], v[180:183], v[120:123]
	v_mfma_f32_16x16x32_bf16 v[116:119], v[196:199], v[188:191], v[116:119]
	v_mfma_f32_16x16x32_bf16 v[112:115], v[204:207], v[180:183], v[112:115]
	v_mfma_f32_16x16x32_bf16 v[108:111], v[204:207], v[188:191], v[108:111]
	v_mfma_f32_16x16x32_bf16 v[80:83], v[212:215], v[180:183], v[80:83]
	v_mfma_f32_16x16x32_bf16 v[76:79], v[212:215], v[188:191], v[76:79]
	v_mfma_f32_16x16x32_bf16 v[48:51], v[220:223], v[180:183], v[48:51]
	v_mfma_f32_16x16x32_bf16 v[44:47], v[220:223], v[188:191], v[44:47]
	v_mfma_f32_16x16x32_bf16 v[120:123], v[200:203], v[184:187], v[120:123]
	v_mfma_f32_16x16x32_bf16 v[116:119], v[200:203], v[192:195], v[116:119]
	v_mfma_f32_16x16x32_bf16 v[112:115], v[208:211], v[184:187], v[112:115]
	v_mfma_f32_16x16x32_bf16 v[108:111], v[208:211], v[192:195], v[108:111]
	v_mfma_f32_16x16x32_bf16 v[80:83], v[216:219], v[184:187], v[80:83]
	v_mfma_f32_16x16x32_bf16 v[76:79], v[216:219], v[192:195], v[76:79]
	v_mfma_f32_16x16x32_bf16 v[48:51], v[224:227], v[184:187], v[48:51]
	v_mfma_f32_16x16x32_bf16 v[44:47], v[224:227], v[192:195], v[44:47]
	s_barrier
	v_readfirstlane_b32 s10, v173
	v_lshl_add_u64 v[180:181], v[248:249], 0, s[56:57]
	s_mov_b32 m0, s10
	v_readfirstlane_b32 s10, v174
	global_load_lds_dwordx4 v[180:181], off
	v_lshl_add_u64 v[180:181], v[250:251], 0, s[56:57]
	s_mov_b32 m0, s10
	s_nop 0
	global_load_lds_dwordx4 v[180:181], off
	s_waitcnt vmcnt(6)
	s_barrier
	v_mfma_f32_16x16x32_bf16 v[128:131], v[196:199], v[228:231], v[128:131]
	v_mfma_f32_16x16x32_bf16 v[124:127], v[196:199], v[236:239], v[124:127]
	v_mfma_f32_16x16x32_bf16 v[100:103], v[204:207], v[228:231], v[100:103]
	v_mfma_f32_16x16x32_bf16 v[96:99], v[204:207], v[236:239], v[96:99]
	v_mfma_f32_16x16x32_bf16 v[68:71], v[212:215], v[228:231], v[68:71]
	v_mfma_f32_16x16x32_bf16 v[60:63], v[212:215], v[236:239], v[60:63]
	v_mfma_f32_16x16x32_bf16 v[32:35], v[220:223], v[228:231], v[32:35]
	v_mfma_f32_16x16x32_bf16 v[28:31], v[220:223], v[236:239], v[28:31]
	v_mfma_f32_16x16x32_bf16 v[128:131], v[200:203], v[232:235], v[128:131]
	v_mfma_f32_16x16x32_bf16 v[124:127], v[200:203], v[240:243], v[124:127]
	v_mfma_f32_16x16x32_bf16 v[100:103], v[208:211], v[232:235], v[100:103]
	v_mfma_f32_16x16x32_bf16 v[96:99], v[208:211], v[240:243], v[96:99]
	v_mfma_f32_16x16x32_bf16 v[68:71], v[216:219], v[232:235], v[68:71]
	v_mfma_f32_16x16x32_bf16 v[60:63], v[216:219], v[240:243], v[60:63]
	v_mfma_f32_16x16x32_bf16 v[32:35], v[224:227], v[232:235], v[32:35]
	v_mfma_f32_16x16x32_bf16 v[28:31], v[224:227], v[240:243], v[28:31]
	s_add_i32 s28, s28, 2
	s_add_u32 s26, s26, 0x100
	s_addc_u32 s27, s27, 0
	s_cmp_lt_u32 s28, 4
	s_cbranch_scc1 .LBB0_117
; #define STA(P, br, kt) STAGE(P, A, aoff0, aoff1, lda, br, kt)
; #define LDA(dst, b, h) _Pragma("unroll") for (int m = 0; m < 4; ++m) _Pragma("unroll") for (int k = 0; k < 2; ++k) \
;     dst[m][k] = *reinterpret_cast<const bf16x8*>((char*)SA(b, h) + lds_byte(wr * 64 + m * 16 + fr, k * 32 + fq * 8))
; #define LDB(dst, b, h) _Pragma("unroll") for (int n = 0; n < 2; ++n) _Pragma("unroll") for (int k = 0; k < 2; ++k) \
;     dst[n][k] = *reinterpret_cast<const bf16x8*>((char*)SB(b, h) + lds_byte(wc * 32 + n * 16 + fr, k * 32 + fq * 8))
; #define MMA(ai, bj, At, Bq) do { __builtin_amdgcn_s_setprio(1); \
;     _Pragma("unroll") for (int m = 0; m < 4; ++m) _Pragma("unroll") for (int n = 0; n < 2; ++n) _Pragma("unroll") for (int k = 0; k < 2; ++k) \
;       acc[ai][bj][m][n] = __builtin_amdgcn_mfma_f32_16x16x32_bf16(At[m][k], Bq[n][k], acc[ai][bj][m][n], 0, 0, 0); \
;     __builtin_amdgcn_s_setprio(0); } while (0)
; #define WAIT_V(n) asm volatile("s_waitcnt vmcnt(" #n ")" ::: "memory")
; #define WAIT_L(n) asm volatile("s_waitcnt lgkmcnt(" #n ")" ::: "memory")
; #define BAR __builtin_amdgcn_s_barrier()
; __device__ __forceinline__ void gemm256(const u16* __restrict__ A, int lda, const u16* __restrict__ Bt, int ldb, int K,
;                                         f32x4 (&acc)[2][2][4][2], const int g_wid) {
;     ...
;     WAIT_V(6); BAR; MMA(1, 1, At, B1); BAR;
;   }
;   { LDB(B0, 0, 0); LDA(At, 0, 0); STA(SA(1, 1), HALF, nt - 1);
;     BAR; WAIT_L(0); MMA(0, 0, At, B0); BAR;
;     LDB(B1, 0, 1); BAR; WAIT_L(0); MMA(0, 1, At, B1); BAR;
;     LDA(At, 0, 1); WAIT_V(4); BAR; WAIT_L(0); MMA(1, 0, At, B0); MMA(1, 1, At, B1); BAR; }
	s_barrier
	s_add_u32 s24, s24, 0x20380
	s_addc_u32 s25, s25, 0
	v_readfirstlane_b32 s10, v177
	v_lshl_add_u64 v[132:133], v[132:133], 1, s[24:25]
	s_mov_b32 m0, s10
	v_readfirstlane_b32 s10, v178
	ds_read_b128 v[134:137], v176
	ds_read_b128 v[164:167], v176 offset:1024
	ds_read_b128 v[170:173], v176 offset:2048
	ds_read_b128 v[180:183], v176 offset:3072
	ds_read_b128 v[184:187], v147
	ds_read_b128 v[188:191], v147 offset:1024
	ds_read_b128 v[192:195], v146
	ds_read_b128 v[196:199], v146 offset:1024
	ds_read_b128 v[200:203], v145
	ds_read_b128 v[204:207], v145 offset:1024
	ds_read_b128 v[208:211], v144
	ds_read_b128 v[212:215], v144 offset:1024
	global_load_lds_dwordx4 v[132:133], off
	v_lshl_add_u64 v[2:3], v[2:3], 1, s[24:25]
	s_mov_b32 m0, s10
	s_nop 0
	global_load_lds_dwordx4 v[2:3], off
	s_barrier
	s_waitcnt lgkmcnt(0)
	v_mfma_f32_16x16x32_bf16 v[8:11], v[184:187], v[134:137], v[8:11]
	v_mfma_f32_16x16x32_bf16 v[2:5], v[184:187], v[170:173], v[4:7]
	v_mfma_f32_16x16x32_bf16 v[24:27], v[192:195], v[134:137], v[24:27]
	v_mfma_f32_16x16x32_bf16 v[20:23], v[192:195], v[170:173], v[20:23]
	v_mfma_f32_16x16x32_bf16 v[56:59], v[200:203], v[134:137], v[56:59]
	v_mfma_f32_16x16x32_bf16 v[52:55], v[200:203], v[170:173], v[52:55]
	v_mfma_f32_16x16x32_bf16 v[88:91], v[208:211], v[134:137], v[88:91]
	v_mfma_f32_16x16x32_bf16 v[84:87], v[208:211], v[170:173], v[84:87]
	v_mfma_f32_16x16x32_bf16 v[8:11], v[188:191], v[164:167], v[8:11]
	v_mfma_f32_16x16x32_bf16 v[2:5], v[188:191], v[180:183], v[2:5]
	v_mfma_f32_16x16x32_bf16 v[24:27], v[196:199], v[164:167], v[24:27]
	v_mfma_f32_16x16x32_bf16 v[20:23], v[196:199], v[180:183], v[20:23]
	v_mfma_f32_16x16x32_bf16 v[56:59], v[204:207], v[164:167], v[56:59]
	v_mfma_f32_16x16x32_bf16 v[52:55], v[204:207], v[180:183], v[52:55]
	v_mfma_f32_16x16x32_bf16 v[88:91], v[212:215], v[164:167], v[88:91]
	v_mfma_f32_16x16x32_bf16 v[84:87], v[212:215], v[180:183], v[84:87]
	s_barrier
	ds_read_b128 v[176:179], v175
	ds_read_b128 v[216:219], v175 offset:1024
	ds_read_b128 v[220:223], v175 offset:2048
	ds_read_b128 v[224:227], v175 offset:3072
	s_barrier
	s_waitcnt lgkmcnt(0)
	v_mfma_f32_16x16x32_bf16 v[16:19], v[184:187], v[176:179], v[16:19]
	v_mfma_f32_16x16x32_bf16 v[12:15], v[184:187], v[220:223], v[12:15]
	v_mfma_f32_16x16x32_bf16 v[40:43], v[192:195], v[176:179], v[40:43]
	v_mfma_f32_16x16x32_bf16 v[36:39], v[192:195], v[220:223], v[36:39]
	v_mfma_f32_16x16x32_bf16 v[72:75], v[200:203], v[176:179], v[72:75]
	v_mfma_f32_16x16x32_bf16 v[64:67], v[200:203], v[220:223], v[64:67]
	v_mfma_f32_16x16x32_bf16 v[104:107], v[208:211], v[176:179], v[104:107]
	v_mfma_f32_16x16x32_bf16 v[92:95], v[208:211], v[220:223], v[92:95]
	v_mfma_f32_16x16x32_bf16 v[16:19], v[188:191], v[216:219], v[16:19]
	v_mfma_f32_16x16x32_bf16 v[12:15], v[188:191], v[224:227], v[12:15]
	v_mfma_f32_16x16x32_bf16 v[40:43], v[196:199], v[216:219], v[40:43]
	v_mfma_f32_16x16x32_bf16 v[36:39], v[196:199], v[224:227], v[36:39]
	v_mfma_f32_16x16x32_bf16 v[72:75], v[204:207], v[216:219], v[72:75]
	v_mfma_f32_16x16x32_bf16 v[64:67], v[204:207], v[224:227], v[64:67]
	v_mfma_f32_16x16x32_bf16 v[104:107], v[212:215], v[216:219], v[104:107]
	v_mfma_f32_16x16x32_bf16 v[92:95], v[212:215], v[224:227], v[92:95]
	s_barrier
	ds_read_b128 v[184:187], v147 offset:16384
	ds_read_b128 v[188:191], v147 offset:17408
	ds_read_b128 v[192:195], v146 offset:16384
	ds_read_b128 v[196:199], v146 offset:17408
	ds_read_b128 v[200:203], v145 offset:16384
	ds_read_b128 v[204:207], v145 offset:17408
	ds_read_b128 v[208:211], v144 offset:16384
	ds_read_b128 v[212:215], v144 offset:17408
	s_waitcnt vmcnt(4)
	s_barrier
	s_waitcnt lgkmcnt(0)
	v_mfma_f32_16x16x32_bf16 v[120:123], v[184:187], v[134:137], v[120:123]
	v_mfma_f32_16x16x32_bf16 v[116:119], v[184:187], v[170:173], v[116:119]
	v_mfma_f32_16x16x32_bf16 v[112:115], v[192:195], v[134:137], v[112:115]
	v_mfma_f32_16x16x32_bf16 v[108:111], v[192:195], v[170:173], v[108:111]
	v_mfma_f32_16x16x32_bf16 v[80:83], v[200:203], v[134:137], v[80:83]
	v_mfma_f32_16x16x32_bf16 v[76:79], v[200:203], v[170:173], v[76:79]
	v_mfma_f32_16x16x32_bf16 v[48:51], v[208:211], v[134:137], v[48:51]
	v_mfma_f32_16x16x32_bf16 v[44:47], v[208:211], v[170:173], v[44:47]
	v_mfma_f32_16x16x32_bf16 v[120:123], v[188:191], v[164:167], v[120:123]
	v_mfma_f32_16x16x32_bf16 v[116:119], v[188:191], v[180:183], v[116:119]
	v_mfma_f32_16x16x32_bf16 v[112:115], v[196:199], v[164:167], v[112:115]
	v_mfma_f32_16x16x32_bf16 v[108:111], v[196:199], v[180:183], v[108:111]
	v_mfma_f32_16x16x32_bf16 v[80:83], v[204:207], v[164:167], v[80:83]
	v_mfma_f32_16x16x32_bf16 v[76:79], v[204:207], v[180:183], v[76:79]
	v_mfma_f32_16x16x32_bf16 v[48:51], v[212:215], v[164:167], v[48:51]
	v_mfma_f32_16x16x32_bf16 v[44:47], v[212:215], v[180:183], v[44:47]
	v_mfma_f32_16x16x32_bf16 v[128:131], v[184:187], v[176:179], v[128:131]
	v_mfma_f32_16x16x32_bf16 v[124:127], v[184:187], v[220:223], v[124:127]
	v_mfma_f32_16x16x32_bf16 v[100:103], v[192:195], v[176:179], v[100:103]
	v_mfma_f32_16x16x32_bf16 v[96:99], v[192:195], v[220:223], v[96:99]
	v_mfma_f32_16x16x32_bf16 v[68:71], v[200:203], v[176:179], v[68:71]
	v_mfma_f32_16x16x32_bf16 v[60:63], v[200:203], v[220:223], v[60:63]
	v_mfma_f32_16x16x32_bf16 v[32:35], v[208:211], v[176:179], v[32:35]
	v_mfma_f32_16x16x32_bf16 v[28:31], v[208:211], v[220:223], v[28:31]
	v_mfma_f32_16x16x32_bf16 v[128:131], v[188:191], v[216:219], v[128:131]
	v_mfma_f32_16x16x32_bf16 v[124:127], v[188:191], v[224:227], v[124:127]
	v_mfma_f32_16x16x32_bf16 v[100:103], v[196:199], v[216:219], v[100:103]
	v_mfma_f32_16x16x32_bf16 v[96:99], v[196:199], v[224:227], v[96:99]
	v_mfma_f32_16x16x32_bf16 v[68:71], v[204:207], v[216:219], v[68:71]
	v_mfma_f32_16x16x32_bf16 v[60:63], v[204:207], v[224:227], v[60:63]
	v_mfma_f32_16x16x32_bf16 v[32:35], v[212:215], v[216:219], v[32:35]
	v_mfma_f32_16x16x32_bf16 v[28:31], v[212:215], v[224:227], v[28:31]
	s_barrier
; #define LDA(dst, b, h) _Pragma("unroll") for (int m = 0; m < 4; ++m) _Pragma("unroll") for (int k = 0; k < 2; ++k) \
;     dst[m][k] = *reinterpret_cast<const bf16x8*>((char*)SA(b, h) + lds_byte(wr * 64 + m * 16 + fr, k * 32 + fq * 8))
; #define LDB(dst, b, h) _Pragma("unroll") for (int n = 0; n < 2; ++n) _Pragma("unroll") for (int k = 0; k < 2; ++k) \
;     dst[n][k] = *reinterpret_cast<const bf16x8*>((char*)SB(b, h) + lds_byte(wc * 32 + n * 16 + fr, k * 32 + fq * 8))
; #define MMA(ai, bj, At, Bq) do { __builtin_amdgcn_s_setprio(1); \
;     _Pragma("unroll") for (int m = 0; m < 4; ++m) _Pragma("unroll") for (int n = 0; n < 2; ++n) _Pragma("unroll") for (int k = 0; k < 2; ++k) \
;       acc[ai][bj][m][n] = __builtin_amdgcn_mfma_f32_16x16x32_bf16(At[m][k], Bq[n][k], acc[ai][bj][m][n], 0, 0, 0); \
;     __builtin_amdgcn_s_setprio(0); } while (0)
; #define WAIT_V(n) asm volatile("s_waitcnt vmcnt(" #n ")" ::: "memory")
; #define WAIT_L(n) asm volatile("s_waitcnt lgkmcnt(" #n ")" ::: "memory")
; #define BAR __builtin_amdgcn_s_barrier()
; __device__ __forceinline__ void gemm256(const u16* __restrict__ A, int lda, const u16* __restrict__ Bt, int ldb, int K,
;                                         f32x4 (&acc)[2][2][4][2], const int g_wid) {
;     ...
;   { LDB(B0, 1, 0); LDA(At, 1, 0); WAIT_V(2); BAR; WAIT_L(0); MMA(0, 0, At, B0); BAR;
;     LDB(B1, 1, 1); WAIT_V(0); BAR; WAIT_L(0); MMA(0, 1, At, B1); BAR;
;     LDA(At, 1, 1); BAR; WAIT_L(0); MMA(1, 0, At, B0); MMA(1, 1, At, B1); BAR; }
;   if (wr == 0) BAR;
	ds_read_b128 v[132:135], v168
	ds_read_b128 v[136:139], v168 offset:1024
	ds_read_b128 v[164:167], v168 offset:2048
	ds_read_b128 v[168:171], v168 offset:3072
	ds_read_b128 v[172:175], v147 offset:32768
	ds_read_b128 v[176:179], v147 offset:33792
	ds_read_b128 v[180:183], v146 offset:32768
	ds_read_b128 v[184:187], v146 offset:33792
	ds_read_b128 v[188:191], v145 offset:32768
	ds_read_b128 v[192:195], v145 offset:33792
	ds_read_b128 v[196:199], v144 offset:32768
	ds_read_b128 v[200:203], v144 offset:33792
	s_waitcnt vmcnt(2)
	s_barrier
	s_waitcnt lgkmcnt(0)
	v_mfma_f32_16x16x32_bf16 v[6:9], v[172:175], v[132:135], v[8:11]
	v_mfma_f32_16x16x32_bf16 v[2:5], v[172:175], v[164:167], v[2:5]
	v_mfma_f32_16x16x32_bf16 v[24:27], v[180:183], v[132:135], v[24:27]
	v_mfma_f32_16x16x32_bf16 v[20:23], v[180:183], v[164:167], v[20:23]
	v_mfma_f32_16x16x32_bf16 v[56:59], v[188:191], v[132:135], v[56:59]
	v_mfma_f32_16x16x32_bf16 v[52:55], v[188:191], v[164:167], v[52:55]
	v_mfma_f32_16x16x32_bf16 v[88:91], v[196:199], v[132:135], v[88:91]
	v_mfma_f32_16x16x32_bf16 v[84:87], v[196:199], v[164:167], v[84:87]
	v_mfma_f32_16x16x32_bf16 v[8:11], v[176:179], v[136:139], v[6:9]
	v_mfma_f32_16x16x32_bf16 v[4:7], v[176:179], v[168:171], v[2:5]
	v_mfma_f32_16x16x32_bf16 v[24:27], v[184:187], v[136:139], v[24:27]
	v_mfma_f32_16x16x32_bf16 v[20:23], v[184:187], v[168:171], v[20:23]
	v_mfma_f32_16x16x32_bf16 v[56:59], v[192:195], v[136:139], v[56:59]
	v_mfma_f32_16x16x32_bf16 v[52:55], v[192:195], v[168:171], v[52:55]
	v_mfma_f32_16x16x32_bf16 v[88:91], v[200:203], v[136:139], v[88:91]
	v_mfma_f32_16x16x32_bf16 v[84:87], v[200:203], v[168:171], v[84:87]
	s_barrier
	ds_read_b128 v[204:207], v162
	ds_read_b128 v[208:211], v162 offset:1024
	ds_read_b128 v[212:215], v162 offset:2048
	ds_read_b128 v[160:163], v162 offset:3072
	s_waitcnt vmcnt(0)
	s_barrier
	s_waitcnt lgkmcnt(0)
	v_mfma_f32_16x16x32_bf16 v[16:19], v[172:175], v[204:207], v[16:19]
	v_mfma_f32_16x16x32_bf16 v[12:15], v[172:175], v[212:215], v[12:15]
	v_mfma_f32_16x16x32_bf16 v[40:43], v[180:183], v[204:207], v[40:43]
	v_mfma_f32_16x16x32_bf16 v[36:39], v[180:183], v[212:215], v[36:39]
	v_mfma_f32_16x16x32_bf16 v[72:75], v[188:191], v[204:207], v[72:75]
	v_mfma_f32_16x16x32_bf16 v[64:67], v[188:191], v[212:215], v[64:67]
	v_mfma_f32_16x16x32_bf16 v[104:107], v[196:199], v[204:207], v[104:107]
	v_mfma_f32_16x16x32_bf16 v[92:95], v[196:199], v[212:215], v[92:95]
	v_mfma_f32_16x16x32_bf16 v[16:19], v[176:179], v[208:211], v[16:19]
	v_mfma_f32_16x16x32_bf16 v[12:15], v[176:179], v[160:163], v[12:15]
	v_mfma_f32_16x16x32_bf16 v[40:43], v[184:187], v[208:211], v[40:43]
	v_mfma_f32_16x16x32_bf16 v[36:39], v[184:187], v[160:163], v[36:39]
	v_mfma_f32_16x16x32_bf16 v[72:75], v[192:195], v[208:211], v[72:75]
	v_mfma_f32_16x16x32_bf16 v[64:67], v[192:195], v[160:163], v[64:67]
	v_mfma_f32_16x16x32_bf16 v[104:107], v[200:203], v[208:211], v[104:107]
	v_mfma_f32_16x16x32_bf16 v[92:95], v[200:203], v[160:163], v[92:95]
	s_barrier
	ds_read_b128 v[172:175], v147 offset:49152
	ds_read_b128 v[176:179], v147 offset:50176
	ds_read_b128 v[180:183], v146 offset:49152
	ds_read_b128 v[184:187], v146 offset:50176
	ds_read_b128 v[188:191], v145 offset:49152
	ds_read_b128 v[192:195], v145 offset:50176
	ds_read_b128 v[196:199], v144 offset:49152
	ds_read_b128 v[142:145], v144 offset:50176
	s_barrier
	s_waitcnt lgkmcnt(0)
	v_mfma_f32_16x16x32_bf16 v[120:123], v[172:175], v[132:135], v[120:123]
	v_mfma_f32_16x16x32_bf16 v[116:119], v[172:175], v[164:167], v[116:119]
	v_mfma_f32_16x16x32_bf16 v[112:115], v[180:183], v[132:135], v[112:115]
	v_mfma_f32_16x16x32_bf16 v[108:111], v[180:183], v[164:167], v[108:111]
	v_mfma_f32_16x16x32_bf16 v[80:83], v[188:191], v[132:135], v[80:83]
	v_mfma_f32_16x16x32_bf16 v[76:79], v[188:191], v[164:167], v[76:79]
	v_mfma_f32_16x16x32_bf16 v[48:51], v[196:199], v[132:135], v[48:51]
	v_mfma_f32_16x16x32_bf16 v[44:47], v[196:199], v[164:167], v[44:47]
	v_mfma_f32_16x16x32_bf16 v[120:123], v[176:179], v[136:139], v[120:123]
	v_mfma_f32_16x16x32_bf16 v[116:119], v[176:179], v[168:171], v[116:119]
	v_mfma_f32_16x16x32_bf16 v[112:115], v[184:187], v[136:139], v[112:115]
	v_mfma_f32_16x16x32_bf16 v[108:111], v[184:187], v[168:171], v[108:111]
	v_mfma_f32_16x16x32_bf16 v[80:83], v[192:195], v[136:139], v[80:83]
	v_mfma_f32_16x16x32_bf16 v[76:79], v[192:195], v[168:171], v[76:79]
	v_mfma_f32_16x16x32_bf16 v[48:51], v[142:145], v[136:139], v[48:51]
	v_mfma_f32_16x16x32_bf16 v[44:47], v[142:145], v[168:171], v[44:47]
	v_mfma_f32_16x16x32_bf16 v[128:131], v[172:175], v[204:207], v[128:131]
	v_mfma_f32_16x16x32_bf16 v[124:127], v[172:175], v[212:215], v[124:127]
	v_mfma_f32_16x16x32_bf16 v[100:103], v[180:183], v[204:207], v[100:103]
	v_mfma_f32_16x16x32_bf16 v[96:99], v[180:183], v[212:215], v[96:99]
	v_mfma_f32_16x16x32_bf16 v[68:71], v[188:191], v[204:207], v[68:71]
	v_mfma_f32_16x16x32_bf16 v[60:63], v[188:191], v[212:215], v[60:63]
	v_mfma_f32_16x16x32_bf16 v[32:35], v[196:199], v[204:207], v[32:35]
	v_mfma_f32_16x16x32_bf16 v[28:31], v[196:199], v[212:215], v[28:31]
	v_mfma_f32_16x16x32_bf16 v[128:131], v[176:179], v[208:211], v[128:131]
	v_mfma_f32_16x16x32_bf16 v[124:127], v[176:179], v[160:163], v[124:127]
	v_mfma_f32_16x16x32_bf16 v[100:103], v[184:187], v[208:211], v[100:103]
	v_mfma_f32_16x16x32_bf16 v[96:99], v[184:187], v[160:163], v[96:99]
	v_mfma_f32_16x16x32_bf16 v[68:71], v[192:195], v[208:211], v[68:71]
	v_mfma_f32_16x16x32_bf16 v[60:63], v[192:195], v[160:163], v[60:63]
	v_mfma_f32_16x16x32_bf16 v[32:35], v[142:145], v[208:211], v[32:35]
	v_mfma_f32_16x16x32_bf16 v[28:31], v[142:145], v[160:163], v[28:31]
	s_setprio 0
	s_movk_i32 s10, 0x100
	v_cmp_gt_u32_e32 vcc, s10, v0
	s_barrier
	s_and_saveexec_b64 s[24:25], vcc
	s_cbranch_execz .LBB0_113
	s_barrier
	s_branch .LBB0_113

; #define STA(P, br, kt) STAGE(P, A, aoff0, aoff1, lda, br, kt)
; #define STB(P, br, kt) STAGE(P, Bt, boff0, boff1, ldb, br, kt)
; #define WAIT_V(n) asm volatile("s_waitcnt vmcnt(" #n ")" ::: "memory")
; #define BAR __builtin_amdgcn_s_barrier()
; __device__ __forceinline__ void gemm256(const u16* __restrict__ A, int lda, const u16* __restrict__ Bt, int ldb, int K,
;                                         f32x4 (&acc)[2][2][4][2], const int g_wid) {
;     ...
;   STB(SB(0, 0), 0, 0); STA(SA(0, 0), 0, 0);
;   STB(SB(0, 1), HALF, 0); STA(SA(0, 1), HALF, 0);
;   if (wr == 1) BAR;
;   WAIT_V(4); BAR;
;   STB(SB(1, 0), 0, 1); STA(SA(1, 0), 0, 1); STB(SB(1, 1), HALF, 1);
;   WAIT_V(6); BAR;
; __device__ __forceinline__ void phase_g4(PP p, const int g_wid) {
;     ...
;     f32x4 acc[2][2][4][2]; ZERO_ACC;
;     const bool isg = pass < 3;
;     if (isg) gemm256(p->Wm + (long)(4352 + pass * 1024 + pn * 256) * 1024, 1024, p->hb + (long)192 * 256 * 1024, 1024, 1024, acc, g_wid);
;     else gemm256(p->Wm + 7602176L + (long)(pass - 3) * 524288 + (long)pn * 256 * 512, 512, p->X + X_BO + (long)192 * 256 * 1536 + (pass - 3) * 512, 1536, 512, acc, g_wid);
.LBB0_127:
	s_or_b64 exec, exec, s[20:21]
	v_readlane_b32 s11, v254, 42
	s_mov_b64 s[8:9], 0x80
	v_lshl_add_u64 v[6:7], v[6:7], 0, s[8:9]
	v_add_u32_e32 v167, s11, v20
	v_add_u32_e32 v168, 0x2000, v167
	v_readfirstlane_b32 s10, v167
	s_mov_b32 m0, s10
	v_readfirstlane_b32 s10, v168
	v_add_u32_e32 v169, 0x8000, v159
	s_waitcnt vmcnt(4)
	s_barrier
	global_load_lds_dwordx4 v[6:7], off
	v_lshl_add_u64 v[6:7], v[8:9], 0, s[8:9]
	s_mov_b32 m0, s10
	v_readfirstlane_b32 s10, v169
	v_add_u32_e32 v170, 0xa000, v159
	v_readlane_b32 s20, v254, 43
	global_load_lds_dwordx4 v[6:7], off
	v_lshl_add_u64 v[6:7], v[10:11], 0, s[8:9]
	s_mov_b32 m0, s10
	v_readfirstlane_b32 s10, v170
	s_add_u32 s18, s18, 0x60080
	v_add_u32_e32 v171, s20, v20
	global_load_lds_dwordx4 v[6:7], off
	v_lshl_add_u64 v[6:7], v[12:13], 0, s[8:9]
	s_mov_b32 m0, s10
	s_addc_u32 s19, s19, 0
	v_readfirstlane_b32 s10, v171
	v_add_u32_e32 v172, 0x2000, v171
	global_load_lds_dwordx4 v[6:7], off
	v_lshl_add_u64 v[4:5], v[4:5], 1, s[18:19]
	s_mov_b32 m0, s10
	v_readfirstlane_b32 s10, v172
	global_load_lds_dwordx4 v[4:5], off
	v_lshl_add_u64 v[2:3], v[2:3], 1, s[18:19]
	s_mov_b32 m0, s10
	v_and_b32_e32 v24, 15, v0
	global_load_lds_dwordx4 v[2:3], off
	v_lshlrev_b32_e32 v3, 2, v0
	v_and_b32_e32 v25, 48, v0
	v_lshlrev_b32_e32 v2, 6, v24
	v_and_b32_e32 v3, 32, v3
	v_bitop3_b32 v2, v2, v3, v25 bitop3:0x36
	v_readlane_b32 s10, v254, 40
	v_lshlrev_b32_e32 v8, 6, v0
	v_add_u32_e32 v6, s11, v2
	v_add_u32_e32 v4, s10, v2
	v_readlane_b32 s10, v254, 41
	v_add_u32_e32 v7, s20, v2
	v_add_u32_e32 v11, 0, v2
	v_add_u32_e32 v5, s10, v2
	s_movk_i32 s10, 0x3c0
	v_and_or_b32 v2, v8, s10, v25
	s_movk_i32 s8, 0x600
	v_and_b32_e32 v9, 0x3000, v8
	v_xad_u32 v8, v2, v3, 0
	v_lshrrev_b32_e32 v3, 1, v19
	v_mul_lo_u32 v2, v22, s8
	s_movk_i32 s10, 0x6000
	v_mad_u64_u32 v[2:3], s[18:19], v3, s10, v[2:3]
	v_or_b32_e32 v2, v2, v21
	v_readlane_b32 s18, v255, 2
	v_add_u32_e32 v2, v2, v23
	v_readlane_b32 s19, v255, 3
	s_add_u32 s16, s18, s16
	v_ashrrev_i32_e32 v3, 31, v2
	s_addc_u32 s17, s19, s17
	v_lshl_add_u64 v[134:135], v[2:3], 1, s[16:17]
	v_lshrrev_b32_e32 v17, 1, v17
	v_mul_lo_u32 v2, v14, s8
	v_mad_u64_u32 v[2:3], s[18:19], v17, s10, v[2:3]
	v_or_b32_e32 v2, v2, v15
	v_add_u32_e32 v2, v2, v16
	v_ashrrev_i32_e32 v3, 31, v2
	v_lshl_add_u64 v[136:137], v[2:3], 1, s[16:17]
	v_lshlrev_b32_e32 v2, 9, v14
	s_add_u32 s10, s14, s25
	v_lshl_add_u32 v2, v17, 13, v2
	s_addc_u32 s11, s15, 0
	v_or_b32_e32 v2, v2, v15
	s_add_u32 s14, s6, s10
	v_add_u32_e32 v2, v2, v16
	s_waitcnt vmcnt(6)
	v_lshlrev_b32_e32 v10, 13, v18
	s_addc_u32 s15, s7, s11
	v_ashrrev_i32_e32 v3, 31, v2
	v_or_b32_e32 v12, 0x800, v10
	v_or_b32_e32 v13, 0x1000, v10
	v_or_b32_e32 v18, 0x1800, v10
	v_lshl_add_u64 v[140:141], v[2:3], 1, s[14:15]
	v_mov_b32_e32 v2, 0
	v_lshl_add_u64 v[138:139], v[130:131], 1, s[14:15]
	s_mov_b32 s16, -2
	s_mov_b64 s[14:15], 0
	v_add_u32_e32 v174, v4, v9
	v_add_u32_e32 v146, v11, v10
	v_add_u32_e32 v145, v8, v12
	v_add_u32_e32 v144, v8, v13
	v_add_u32_e32 v143, v8, v18
	v_add_u32_e32 v173, v5, v9
	v_add_u32_e32 v166, v6, v9
	v_add_u32_e32 v161, v7, v9
	v_mov_b32_e32 v3, v2
	v_mov_b32_e32 v4, v2
	v_mov_b32_e32 v5, v2
	v_mov_b32_e32 v6, v2
	v_mov_b32_e32 v7, v2
	v_mov_b32_e32 v8, v2
	v_mov_b32_e32 v9, v2
	v_mov_b32_e32 v10, v2
	v_mov_b32_e32 v11, v2
	v_mov_b32_e32 v12, v2
	v_mov_b32_e32 v13, v2
	v_mov_b32_e32 v14, v2
	v_mov_b32_e32 v15, v2
	v_mov_b32_e32 v16, v2
	v_mov_b32_e32 v17, v2
	v_mov_b32_e32 v18, v2
	v_mov_b32_e32 v19, v2
	v_mov_b32_e32 v20, v2
	v_mov_b32_e32 v21, v2
	v_mov_b32_e32 v22, v2
	v_mov_b32_e32 v23, v2
	v_mov_b32_e32 v24, v2
	v_mov_b32_e32 v25, v2
	v_mov_b32_e32 v26, v2
	v_mov_b32_e32 v27, v2
	v_mov_b32_e32 v28, v2
	v_mov_b32_e32 v29, v2
	v_mov_b32_e32 v30, v2
	v_mov_b32_e32 v31, v2
	v_mov_b32_e32 v32, v2
	v_mov_b32_e32 v33, v2
	v_mov_b32_e32 v34, v2
	v_mov_b32_e32 v35, v2
	v_mov_b32_e32 v36, v2
	v_mov_b32_e32 v37, v2
	v_mov_b32_e32 v38, v2
	v_mov_b32_e32 v39, v2
	v_mov_b32_e32 v40, v2
	v_mov_b32_e32 v41, v2
	v_mov_b32_e32 v42, v2
	v_mov_b32_e32 v43, v2
	v_mov_b32_e32 v44, v2
	v_mov_b32_e32 v45, v2
	v_mov_b32_e32 v46, v2
	v_mov_b32_e32 v47, v2
	v_mov_b32_e32 v48, v2
	v_mov_b32_e32 v49, v2
	v_mov_b32_e32 v50, v2
	v_mov_b32_e32 v51, v2
	v_mov_b32_e32 v52, v2
	v_mov_b32_e32 v53, v2
	v_mov_b32_e32 v54, v2
	v_mov_b32_e32 v55, v2
	v_mov_b32_e32 v56, v2
	v_mov_b32_e32 v57, v2
	v_mov_b32_e32 v58, v2
	v_mov_b32_e32 v59, v2
	v_mov_b32_e32 v60, v2
	v_mov_b32_e32 v61, v2
	v_mov_b32_e32 v62, v2
	v_mov_b32_e32 v63, v2
	v_mov_b32_e32 v64, v2
	v_mov_b32_e32 v65, v2
	v_mov_b32_e32 v66, v2
	v_mov_b32_e32 v67, v2
	v_mov_b32_e32 v68, v2
	v_mov_b32_e32 v69, v2
	v_mov_b32_e32 v70, v2
	v_mov_b32_e32 v71, v2
	v_mov_b32_e32 v72, v2
	v_mov_b32_e32 v73, v2
	v_mov_b32_e32 v74, v2
	v_mov_b32_e32 v75, v2
	v_mov_b32_e32 v76, v2
	v_mov_b32_e32 v77, v2
	v_mov_b32_e32 v78, v2
	v_mov_b32_e32 v79, v2
	v_mov_b32_e32 v80, v2
	v_mov_b32_e32 v81, v2
	v_mov_b32_e32 v82, v2
	v_mov_b32_e32 v83, v2
	v_mov_b32_e32 v84, v2
	v_mov_b32_e32 v85, v2
	v_mov_b32_e32 v86, v2
	v_mov_b32_e32 v87, v2
	v_mov_b32_e32 v88, v2
	v_mov_b32_e32 v89, v2
	v_mov_b32_e32 v90, v2
	v_mov_b32_e32 v91, v2
	v_mov_b32_e32 v92, v2
	v_mov_b32_e32 v93, v2
	v_mov_b32_e32 v94, v2
	v_mov_b32_e32 v95, v2
	v_mov_b32_e32 v96, v2
	v_mov_b32_e32 v97, v2
	v_mov_b32_e32 v98, v2
	v_mov_b32_e32 v99, v2
	v_mov_b32_e32 v100, v2
	v_mov_b32_e32 v101, v2
	v_mov_b32_e32 v102, v2
	v_mov_b32_e32 v103, v2
	v_mov_b32_e32 v104, v2
	v_mov_b32_e32 v105, v2
	v_mov_b32_e32 v106, v2
	v_mov_b32_e32 v107, v2
	v_mov_b32_e32 v108, v2
	v_mov_b32_e32 v109, v2
	v_mov_b32_e32 v110, v2
	v_mov_b32_e32 v111, v2
	v_mov_b32_e32 v112, v2
	v_mov_b32_e32 v113, v2
	v_mov_b32_e32 v114, v2
	v_mov_b32_e32 v115, v2
	v_mov_b32_e32 v116, v2
	v_mov_b32_e32 v117, v2
	v_mov_b32_e32 v118, v2
	v_mov_b32_e32 v119, v2
	v_mov_b32_e32 v120, v2
	v_mov_b32_e32 v121, v2
	v_mov_b32_e32 v122, v2
	v_mov_b32_e32 v123, v2
	v_mov_b32_e32 v124, v2
	v_mov_b32_e32 v125, v2
	v_mov_b32_e32 v126, v2
	v_mov_b32_e32 v127, v2
	v_mov_b32_e32 v128, v2
	v_mov_b32_e32 v129, v2
	s_mov_b64 s[8:9], 0x16920100
	s_mov_b64 s[18:19], 0x16980100
	s_mov_b64 s[20:21], 0x16920180
	s_mov_b64 s[26:27], 0x16980180
	.p2align 6
; #define STA(P, br, kt) STAGE(P, A, aoff0, aoff1, lda, br, kt)
; #define STB(P, br, kt) STAGE(P, Bt, boff0, boff1, ldb, br, kt)
; #define LDA(dst, b, h) _Pragma("unroll") for (int m = 0; m < 4; ++m) _Pragma("unroll") for (int k = 0; k < 2; ++k) \
;     dst[m][k] = *reinterpret_cast<const bf16x8*>((char*)SA(b, h) + lds_byte(wr * 64 + m * 16 + fr, k * 32 + fq * 8))
; #define LDB(dst, b, h) _Pragma("unroll") for (int n = 0; n < 2; ++n) _Pragma("unroll") for (int k = 0; k < 2; ++k) \
;     dst[n][k] = *reinterpret_cast<const bf16x8*>((char*)SB(b, h) + lds_byte(wc * 32 + n * 16 + fr, k * 32 + fq * 8))
; #define MMA(ai, bj, At, Bq) do { __builtin_amdgcn_s_setprio(1); \
;     _Pragma("unroll") for (int m = 0; m < 4; ++m) _Pragma("unroll") for (int n = 0; n < 2; ++n) _Pragma("unroll") for (int k = 0; k < 2; ++k) \
;       acc[ai][bj][m][n] = __builtin_amdgcn_mfma_f32_16x16x32_bf16(At[m][k], Bq[n][k], acc[ai][bj][m][n], 0, 0, 0); \
;     __builtin_amdgcn_s_setprio(0); } while (0)
; #define WAIT_V(n) asm volatile("s_waitcnt vmcnt(" #n ")" ::: "memory")
; #define WAIT_L(n) asm volatile("s_waitcnt lgkmcnt(" #n ")" ::: "memory")
; #define BAR __builtin_amdgcn_s_barrier()
; #define SCHED __builtin_amdgcn_sched_barrier(0)
; __device__ __forceinline__ void gemm256(const u16* __restrict__ A, int lda, const u16* __restrict__ Bt, int ldb, int K,
;                                         f32x4 (&acc)[2][2][4][2], const int g_wid) {
;     ...
;   for (int t = 0; t < nt - 2; t += 2) {
;     LDB(B0, 0, 0); SCHED; LDA(At, 0, 0); STA(SA(1, 1), HALF, t + 1);
;     WAIT_L(8); BAR; WAIT_L(0); MMA(0, 0, At, B0); BAR; SCHED;
;     LDB(B1, 0, 1); STB(SB(0, 0), 0, t + 2);
;     BAR; WAIT_L(0); MMA(0, 1, At, B1); BAR;
;     LDA(At, 0, 1); STA(SA(0, 0), 0, t + 2);
;     BAR; WAIT_L(0); MMA(1, 0, At, B0); BAR; SCHED;
;     STB(SB(0, 1), HALF, t + 2);
;     WAIT_V(6); BAR; MMA(1, 1, At, B1); BAR;
.LBB0_128:
	s_barrier
	ds_read_b128 v[178:181], v174
	ds_read_b128 v[182:185], v174 offset:1024
	ds_read_b128 v[186:189], v174 offset:2048
	ds_read_b128 v[190:193], v174 offset:3072
	v_add_u32_e32 v175, 0xc000, v159
	v_lshl_add_u64 v[242:243], v[140:141], 0, s[14:15]
	v_readfirstlane_b32 s10, v175
	v_lshl_add_u64 v[176:177], v[242:243], 0, s[88:89]
	s_mov_b32 m0, s10
	ds_read_b128 v[194:197], v146
	ds_read_b128 v[198:201], v146 offset:1024
	ds_read_b128 v[202:205], v145
	ds_read_b128 v[206:209], v145 offset:1024
	ds_read_b128 v[210:213], v144
	ds_read_b128 v[214:217], v144 offset:1024
	ds_read_b128 v[218:221], v143
	ds_read_b128 v[222:225], v143 offset:1024
	global_load_lds_dwordx4 v[176:177], off
	v_add_u32_e32 v176, 0xe000, v159
	v_lshl_add_u64 v[244:245], v[138:139], 0, s[14:15]
	v_readfirstlane_b32 s10, v176
	v_lshl_add_u64 v[226:227], v[244:245], 0, s[88:89]
	s_mov_b32 m0, s10
	s_nop 0
	global_load_lds_dwordx4 v[226:227], off
	s_waitcnt lgkmcnt(8)
	s_barrier
	s_waitcnt lgkmcnt(0)
	v_mfma_f32_16x16x32_bf16 v[126:129], v[194:197], v[178:181], v[126:129]
	v_mfma_f32_16x16x32_bf16 v[122:125], v[194:197], v[186:189], v[122:125]
	v_mfma_f32_16x16x32_bf16 v[118:121], v[202:205], v[178:181], v[118:121]
	v_mfma_f32_16x16x32_bf16 v[114:117], v[202:205], v[186:189], v[114:117]
	v_mfma_f32_16x16x32_bf16 v[110:113], v[210:213], v[178:181], v[110:113]
	v_mfma_f32_16x16x32_bf16 v[106:109], v[210:213], v[186:189], v[106:109]
	v_mfma_f32_16x16x32_bf16 v[102:105], v[218:221], v[178:181], v[102:105]
	v_mfma_f32_16x16x32_bf16 v[98:101], v[218:221], v[186:189], v[98:101]
	v_mfma_f32_16x16x32_bf16 v[126:129], v[198:201], v[182:185], v[126:129]
	v_mfma_f32_16x16x32_bf16 v[122:125], v[198:201], v[190:193], v[122:125]
	v_mfma_f32_16x16x32_bf16 v[118:121], v[206:209], v[182:185], v[118:121]
	v_mfma_f32_16x16x32_bf16 v[114:117], v[206:209], v[190:193], v[114:117]
	v_mfma_f32_16x16x32_bf16 v[110:113], v[214:217], v[182:185], v[110:113]
	v_mfma_f32_16x16x32_bf16 v[106:109], v[214:217], v[190:193], v[106:109]
	v_mfma_f32_16x16x32_bf16 v[102:105], v[222:225], v[182:185], v[102:105]
	v_mfma_f32_16x16x32_bf16 v[98:101], v[222:225], v[190:193], v[98:101]
	s_barrier
	v_lshl_add_u64 v[246:247], v[136:137], 0, s[14:15]
	v_readfirstlane_b32 s10, v142
	v_lshl_add_u64 v[248:249], v[246:247], 0, s[8:9]
	s_mov_b32 m0, s10
	ds_read_b128 v[226:229], v173
	ds_read_b128 v[230:233], v173 offset:1024
	ds_read_b128 v[234:237], v173 offset:2048
	ds_read_b128 v[238:241], v173 offset:3072
	global_load_lds_dwordx4 v[248:249], off
	v_lshl_add_u64 v[248:249], v[134:135], 0, s[14:15]
	v_readfirstlane_b32 s10, v147
	v_lshl_add_u64 v[250:251], v[248:249], 0, s[8:9]
	s_mov_b32 m0, s10
	s_nop 0
	global_load_lds_dwordx4 v[250:251], off
	s_barrier
	s_waitcnt lgkmcnt(0)
	v_mfma_f32_16x16x32_bf16 v[94:97], v[194:197], v[226:229], v[94:97]
	v_mfma_f32_16x16x32_bf16 v[90:93], v[194:197], v[234:237], v[90:93]
	v_mfma_f32_16x16x32_bf16 v[86:89], v[202:205], v[226:229], v[86:89]
	v_mfma_f32_16x16x32_bf16 v[82:85], v[202:205], v[234:237], v[82:85]
	v_mfma_f32_16x16x32_bf16 v[78:81], v[210:213], v[226:229], v[78:81]
	v_mfma_f32_16x16x32_bf16 v[74:77], v[210:213], v[234:237], v[74:77]
	v_mfma_f32_16x16x32_bf16 v[70:73], v[218:221], v[226:229], v[70:73]
	v_mfma_f32_16x16x32_bf16 v[66:69], v[218:221], v[234:237], v[66:69]
	v_mfma_f32_16x16x32_bf16 v[94:97], v[198:201], v[230:233], v[94:97]
	v_mfma_f32_16x16x32_bf16 v[90:93], v[198:201], v[238:241], v[90:93]
	v_mfma_f32_16x16x32_bf16 v[86:89], v[206:209], v[230:233], v[86:89]
	v_mfma_f32_16x16x32_bf16 v[82:85], v[206:209], v[238:241], v[82:85]
	v_mfma_f32_16x16x32_bf16 v[78:81], v[214:217], v[230:233], v[78:81]
	v_mfma_f32_16x16x32_bf16 v[74:77], v[214:217], v[238:241], v[74:77]
	v_mfma_f32_16x16x32_bf16 v[70:73], v[222:225], v[230:233], v[70:73]
	v_mfma_f32_16x16x32_bf16 v[66:69], v[222:225], v[238:241], v[66:69]
	v_readfirstlane_b32 s10, v159
	v_lshl_add_u64 v[250:251], v[242:243], 0, s[92:93]
	s_mov_b32 m0, s10
	v_readfirstlane_b32 s10, v160
	s_barrier
	ds_read_b128 v[194:197], v146 offset:16384
	ds_read_b128 v[198:201], v146 offset:17408
	ds_read_b128 v[202:205], v145 offset:16384
	ds_read_b128 v[206:209], v145 offset:17408
	ds_read_b128 v[210:213], v144 offset:16384
	ds_read_b128 v[214:217], v144 offset:17408
	ds_read_b128 v[218:221], v143 offset:16384
	ds_read_b128 v[222:225], v143 offset:17408
	global_load_lds_dwordx4 v[250:251], off
	v_lshl_add_u64 v[250:251], v[244:245], 0, s[92:93]
	s_mov_b32 m0, s10
	s_nop 0
	global_load_lds_dwordx4 v[250:251], off
	s_barrier
	s_waitcnt lgkmcnt(0)
	v_mfma_f32_16x16x32_bf16 v[62:65], v[194:197], v[178:181], v[62:65]
	v_mfma_f32_16x16x32_bf16 v[58:61], v[194:197], v[186:189], v[58:61]
	v_mfma_f32_16x16x32_bf16 v[54:57], v[202:205], v[178:181], v[54:57]
	v_mfma_f32_16x16x32_bf16 v[50:53], v[202:205], v[186:189], v[50:53]
	v_mfma_f32_16x16x32_bf16 v[46:49], v[210:213], v[178:181], v[46:49]
	v_mfma_f32_16x16x32_bf16 v[42:45], v[210:213], v[186:189], v[42:45]
	v_mfma_f32_16x16x32_bf16 v[38:41], v[218:221], v[178:181], v[38:41]
	v_mfma_f32_16x16x32_bf16 v[34:37], v[218:221], v[186:189], v[34:37]
	v_mfma_f32_16x16x32_bf16 v[62:65], v[198:201], v[182:185], v[62:65]
	v_mfma_f32_16x16x32_bf16 v[58:61], v[198:201], v[190:193], v[58:61]
	v_mfma_f32_16x16x32_bf16 v[54:57], v[206:209], v[182:185], v[54:57]
	v_mfma_f32_16x16x32_bf16 v[50:53], v[206:209], v[190:193], v[50:53]
	v_mfma_f32_16x16x32_bf16 v[46:49], v[214:217], v[182:185], v[46:49]
	v_mfma_f32_16x16x32_bf16 v[42:45], v[214:217], v[190:193], v[42:45]
	v_mfma_f32_16x16x32_bf16 v[38:41], v[222:225], v[182:185], v[38:41]
	v_mfma_f32_16x16x32_bf16 v[34:37], v[222:225], v[190:193], v[34:37]
	s_barrier
; #define STA(P, br, kt) STAGE(P, A, aoff0, aoff1, lda, br, kt)
; #define STB(P, br, kt) STAGE(P, Bt, boff0, boff1, ldb, br, kt)
; #define LDA(dst, b, h) _Pragma("unroll") for (int m = 0; m < 4; ++m) _Pragma("unroll") for (int k = 0; k < 2; ++k) \
;     dst[m][k] = *reinterpret_cast<const bf16x8*>((char*)SA(b, h) + lds_byte(wr * 64 + m * 16 + fr, k * 32 + fq * 8))
; #define LDB(dst, b, h) _Pragma("unroll") for (int n = 0; n < 2; ++n) _Pragma("unroll") for (int k = 0; k < 2; ++k) \
;     dst[n][k] = *reinterpret_cast<const bf16x8*>((char*)SB(b, h) + lds_byte(wc * 32 + n * 16 + fr, k * 32 + fq * 8))
; #define MMA(ai, bj, At, Bq) do { __builtin_amdgcn_s_setprio(1); \
;     _Pragma("unroll") for (int m = 0; m < 4; ++m) _Pragma("unroll") for (int n = 0; n < 2; ++n) _Pragma("unroll") for (int k = 0; k < 2; ++k) \
;       acc[ai][bj][m][n] = __builtin_amdgcn_mfma_f32_16x16x32_bf16(At[m][k], Bq[n][k], acc[ai][bj][m][n], 0, 0, 0); \
;     __builtin_amdgcn_s_setprio(0); } while (0)
; #define WAIT_V(n) asm volatile("s_waitcnt vmcnt(" #n ")" ::: "memory")
; #define WAIT_L(n) asm volatile("s_waitcnt lgkmcnt(" #n ")" ::: "memory")
; #define BAR __builtin_amdgcn_s_barrier()
; #define SCHED __builtin_amdgcn_sched_barrier(0)
; __device__ __forceinline__ void gemm256(const u16* __restrict__ A, int lda, const u16* __restrict__ Bt, int ldb, int K,
;                                         f32x4 (&acc)[2][2][4][2], const int g_wid) {
;     ...
;     STB(SB(0, 1), HALF, t + 2);
;     WAIT_V(6); BAR; MMA(1, 1, At, B1); BAR;
;     LDB(B0, 1, 0); SCHED; LDA(At, 1, 0); STA(SA(0, 1), HALF, t + 2);
;     WAIT_L(8); BAR; WAIT_L(0); MMA(0, 0, At, B0); BAR; SCHED;
;     LDB(B1, 1, 1); STB(SB(1, 0), 0, t + 3);
;     BAR; WAIT_L(0); MMA(0, 1, At, B1); BAR;
;     LDA(At, 1, 1); STA(SA(1, 0), 0, t + 3);
	v_readfirstlane_b32 s10, v162
	v_lshl_add_u64 v[178:179], v[246:247], 0, s[18:19]
	s_mov_b32 m0, s10
	v_readfirstlane_b32 s10, v163
	global_load_lds_dwordx4 v[178:179], off
	v_lshl_add_u64 v[178:179], v[248:249], 0, s[18:19]
	s_mov_b32 m0, s10
	s_nop 0
	global_load_lds_dwordx4 v[178:179], off
	s_waitcnt vmcnt(6)
	s_barrier
	v_mfma_f32_16x16x32_bf16 v[30:33], v[194:197], v[226:229], v[30:33]
	v_mfma_f32_16x16x32_bf16 v[26:29], v[194:197], v[234:237], v[26:29]
	v_mfma_f32_16x16x32_bf16 v[22:25], v[202:205], v[226:229], v[22:25]
	v_mfma_f32_16x16x32_bf16 v[18:21], v[202:205], v[234:237], v[18:21]
	v_mfma_f32_16x16x32_bf16 v[14:17], v[210:213], v[226:229], v[14:17]
	v_mfma_f32_16x16x32_bf16 v[10:13], v[210:213], v[234:237], v[10:13]
	v_mfma_f32_16x16x32_bf16 v[6:9], v[218:221], v[226:229], v[6:9]
	v_mfma_f32_16x16x32_bf16 v[2:5], v[218:221], v[234:237], v[2:5]
	v_mfma_f32_16x16x32_bf16 v[30:33], v[198:201], v[230:233], v[30:33]
	v_mfma_f32_16x16x32_bf16 v[26:29], v[198:201], v[238:241], v[26:29]
	v_mfma_f32_16x16x32_bf16 v[22:25], v[206:209], v[230:233], v[22:25]
	v_mfma_f32_16x16x32_bf16 v[18:21], v[206:209], v[238:241], v[18:21]
	v_mfma_f32_16x16x32_bf16 v[14:17], v[214:217], v[230:233], v[14:17]
	v_mfma_f32_16x16x32_bf16 v[10:13], v[214:217], v[238:241], v[10:13]
	v_mfma_f32_16x16x32_bf16 v[6:9], v[222:225], v[230:233], v[6:9]
	v_mfma_f32_16x16x32_bf16 v[2:5], v[222:225], v[238:241], v[2:5]
	s_barrier
	ds_read_b128 v[178:181], v166
	ds_read_b128 v[182:185], v166 offset:1024
	ds_read_b128 v[186:189], v166 offset:2048
	ds_read_b128 v[190:193], v166 offset:3072
	v_readfirstlane_b32 s10, v164
	v_lshl_add_u64 v[226:227], v[242:243], 0, s[96:97]
	s_mov_b32 m0, s10
	v_readfirstlane_b32 s10, v165
	ds_read_b128 v[194:197], v146 offset:32768
	ds_read_b128 v[198:201], v146 offset:33792
	ds_read_b128 v[202:205], v145 offset:32768
	ds_read_b128 v[206:209], v145 offset:33792
	ds_read_b128 v[210:213], v144 offset:32768
	ds_read_b128 v[214:217], v144 offset:33792
	ds_read_b128 v[218:221], v143 offset:32768
	ds_read_b128 v[222:225], v143 offset:33792
	global_load_lds_dwordx4 v[226:227], off
	v_lshl_add_u64 v[226:227], v[244:245], 0, s[96:97]
	s_mov_b32 m0, s10
	s_nop 0
	global_load_lds_dwordx4 v[226:227], off
	s_waitcnt lgkmcnt(8)
	s_barrier
	s_waitcnt lgkmcnt(0)
	v_mfma_f32_16x16x32_bf16 v[126:129], v[194:197], v[178:181], v[126:129]
	v_mfma_f32_16x16x32_bf16 v[122:125], v[194:197], v[186:189], v[122:125]
	v_mfma_f32_16x16x32_bf16 v[118:121], v[202:205], v[178:181], v[118:121]
	v_mfma_f32_16x16x32_bf16 v[114:117], v[202:205], v[186:189], v[114:117]
	v_mfma_f32_16x16x32_bf16 v[110:113], v[210:213], v[178:181], v[110:113]
	v_mfma_f32_16x16x32_bf16 v[106:109], v[210:213], v[186:189], v[106:109]
	v_mfma_f32_16x16x32_bf16 v[102:105], v[218:221], v[178:181], v[102:105]
	v_mfma_f32_16x16x32_bf16 v[98:101], v[218:221], v[186:189], v[98:101]
	v_mfma_f32_16x16x32_bf16 v[126:129], v[198:201], v[182:185], v[126:129]
	v_mfma_f32_16x16x32_bf16 v[122:125], v[198:201], v[190:193], v[122:125]
	v_mfma_f32_16x16x32_bf16 v[118:121], v[206:209], v[182:185], v[118:121]
	v_mfma_f32_16x16x32_bf16 v[114:117], v[206:209], v[190:193], v[114:117]
	v_mfma_f32_16x16x32_bf16 v[110:113], v[214:217], v[182:185], v[110:113]
	v_mfma_f32_16x16x32_bf16 v[106:109], v[214:217], v[190:193], v[106:109]
	v_mfma_f32_16x16x32_bf16 v[102:105], v[222:225], v[182:185], v[102:105]
	v_mfma_f32_16x16x32_bf16 v[98:101], v[222:225], v[190:193], v[98:101]
	s_barrier
	v_readfirstlane_b32 s10, v167
	v_lshl_add_u64 v[250:251], v[246:247], 0, s[20:21]
	s_mov_b32 m0, s10
	v_readfirstlane_b32 s10, v168
	ds_read_b128 v[226:229], v161
	ds_read_b128 v[230:233], v161 offset:1024
	ds_read_b128 v[234:237], v161 offset:2048
	ds_read_b128 v[238:241], v161 offset:3072
	global_load_lds_dwordx4 v[250:251], off
	v_lshl_add_u64 v[250:251], v[248:249], 0, s[20:21]
	s_mov_b32 m0, s10
	s_nop 0
	global_load_lds_dwordx4 v[250:251], off
	s_barrier
	s_waitcnt lgkmcnt(0)
	v_mfma_f32_16x16x32_bf16 v[94:97], v[194:197], v[226:229], v[94:97]
	v_mfma_f32_16x16x32_bf16 v[90:93], v[194:197], v[234:237], v[90:93]
	v_mfma_f32_16x16x32_bf16 v[86:89], v[202:205], v[226:229], v[86:89]
	v_mfma_f32_16x16x32_bf16 v[82:85], v[202:205], v[234:237], v[82:85]
	v_mfma_f32_16x16x32_bf16 v[78:81], v[210:213], v[226:229], v[78:81]
	v_mfma_f32_16x16x32_bf16 v[74:77], v[210:213], v[234:237], v[74:77]
	v_mfma_f32_16x16x32_bf16 v[70:73], v[218:221], v[226:229], v[70:73]
	v_mfma_f32_16x16x32_bf16 v[66:69], v[218:221], v[234:237], v[66:69]
	v_mfma_f32_16x16x32_bf16 v[94:97], v[198:201], v[230:233], v[94:97]
	v_mfma_f32_16x16x32_bf16 v[90:93], v[198:201], v[238:241], v[90:93]
	v_mfma_f32_16x16x32_bf16 v[86:89], v[206:209], v[230:233], v[86:89]
	v_mfma_f32_16x16x32_bf16 v[82:85], v[206:209], v[238:241], v[82:85]
	v_mfma_f32_16x16x32_bf16 v[78:81], v[214:217], v[230:233], v[78:81]
	v_mfma_f32_16x16x32_bf16 v[74:77], v[214:217], v[238:241], v[74:77]
	v_mfma_f32_16x16x32_bf16 v[70:73], v[222:225], v[230:233], v[70:73]
	v_mfma_f32_16x16x32_bf16 v[66:69], v[222:225], v[238:241], v[66:69]
	v_readfirstlane_b32 s10, v169
	v_lshl_add_u64 v[242:243], v[242:243], 0, s[62:63]
	s_mov_b32 m0, s10
	v_readfirstlane_b32 s10, v170
	s_barrier
	ds_read_b128 v[194:197], v146 offset:49152
	ds_read_b128 v[198:201], v146 offset:50176
	ds_read_b128 v[202:205], v145 offset:49152
	ds_read_b128 v[206:209], v145 offset:50176
	ds_read_b128 v[210:213], v144 offset:49152
	ds_read_b128 v[214:217], v144 offset:50176
	ds_read_b128 v[218:221], v143 offset:49152
	ds_read_b128 v[222:225], v143 offset:50176
	global_load_lds_dwordx4 v[242:243], off
	v_lshl_add_u64 v[242:243], v[244:245], 0, s[62:63]
	s_mov_b32 m0, s10
	s_nop 0
	global_load_lds_dwordx4 v[242:243], off
	s_barrier
; #define STA(P, br, kt) STAGE(P, A, aoff0, aoff1, lda, br, kt)
; #define STB(P, br, kt) STAGE(P, Bt, boff0, boff1, ldb, br, kt)
; #define LDA(dst, b, h) _Pragma("unroll") for (int m = 0; m < 4; ++m) _Pragma("unroll") for (int k = 0; k < 2; ++k) \
;     dst[m][k] = *reinterpret_cast<const bf16x8*>((char*)SA(b, h) + lds_byte(wr * 64 + m * 16 + fr, k * 32 + fq * 8))
; #define LDB(dst, b, h) _Pragma("unroll") for (int n = 0; n < 2; ++n) _Pragma("unroll") for (int k = 0; k < 2; ++k) \
;     dst[n][k] = *reinterpret_cast<const bf16x8*>((char*)SB(b, h) + lds_byte(wc * 32 + n * 16 + fr, k * 32 + fq * 8))
; #define MMA(ai, bj, At, Bq) do { __builtin_amdgcn_s_setprio(1); \
;     _Pragma("unroll") for (int m = 0; m < 4; ++m) _Pragma("unroll") for (int n = 0; n < 2; ++n) _Pragma("unroll") for (int k = 0; k < 2; ++k) \
;       acc[ai][bj][m][n] = __builtin_amdgcn_mfma_f32_16x16x32_bf16(At[m][k], Bq[n][k], acc[ai][bj][m][n], 0, 0, 0); \
;     __builtin_amdgcn_s_setprio(0); } while (0)
; #define WAIT_V(n) asm volatile("s_waitcnt vmcnt(" #n ")" ::: "memory")
; #define WAIT_L(n) asm volatile("s_waitcnt lgkmcnt(" #n ")" ::: "memory")
; #define BAR __builtin_amdgcn_s_barrier()
; #define SCHED __builtin_amdgcn_sched_barrier(0)
; __device__ __forceinline__ void gemm256(const u16* __restrict__ A, int lda, const u16* __restrict__ Bt, int ldb, int K,
;                                         f32x4 (&acc)[2][2][4][2], const int g_wid) {
;     ...
;     BAR; WAIT_L(0); MMA(1, 0, At, B0); BAR; SCHED;
;     STB(SB(1, 1), HALF, t + 3);
;     WAIT_V(6); BAR; MMA(1, 1, At, B1); BAR;
;   }
;   { LDB(B0, 0, 0); LDA(At, 0, 0); STA(SA(1, 1), HALF, nt - 1);
;     BAR; WAIT_L(0); MMA(0, 0, At, B0); BAR;
;     LDB(B1, 0, 1); BAR; WAIT_L(0); MMA(0, 1, At, B1); BAR;
	s_waitcnt lgkmcnt(0)
	v_mfma_f32_16x16x32_bf16 v[62:65], v[194:197], v[178:181], v[62:65]
	v_mfma_f32_16x16x32_bf16 v[58:61], v[194:197], v[186:189], v[58:61]
	v_mfma_f32_16x16x32_bf16 v[54:57], v[202:205], v[178:181], v[54:57]
	v_mfma_f32_16x16x32_bf16 v[50:53], v[202:205], v[186:189], v[50:53]
	v_mfma_f32_16x16x32_bf16 v[46:49], v[210:213], v[178:181], v[46:49]
	v_mfma_f32_16x16x32_bf16 v[42:45], v[210:213], v[186:189], v[42:45]
	v_mfma_f32_16x16x32_bf16 v[38:41], v[218:221], v[178:181], v[38:41]
	v_mfma_f32_16x16x32_bf16 v[34:37], v[218:221], v[186:189], v[34:37]
	v_mfma_f32_16x16x32_bf16 v[62:65], v[198:201], v[182:185], v[62:65]
	v_mfma_f32_16x16x32_bf16 v[58:61], v[198:201], v[190:193], v[58:61]
	v_mfma_f32_16x16x32_bf16 v[54:57], v[206:209], v[182:185], v[54:57]
	v_mfma_f32_16x16x32_bf16 v[50:53], v[206:209], v[190:193], v[50:53]
	v_mfma_f32_16x16x32_bf16 v[46:49], v[214:217], v[182:185], v[46:49]
	v_mfma_f32_16x16x32_bf16 v[42:45], v[214:217], v[190:193], v[42:45]
	v_mfma_f32_16x16x32_bf16 v[38:41], v[222:225], v[182:185], v[38:41]
	v_mfma_f32_16x16x32_bf16 v[34:37], v[222:225], v[190:193], v[34:37]
	s_barrier
	v_readfirstlane_b32 s10, v171
	v_lshl_add_u64 v[178:179], v[246:247], 0, s[26:27]
	s_mov_b32 m0, s10
	v_readfirstlane_b32 s10, v172
	global_load_lds_dwordx4 v[178:179], off
	v_lshl_add_u64 v[178:179], v[248:249], 0, s[26:27]
	s_mov_b32 m0, s10
	s_nop 0
	global_load_lds_dwordx4 v[178:179], off
	s_waitcnt vmcnt(6)
	s_barrier
	v_mfma_f32_16x16x32_bf16 v[30:33], v[194:197], v[226:229], v[30:33]
	v_mfma_f32_16x16x32_bf16 v[26:29], v[194:197], v[234:237], v[26:29]
	v_mfma_f32_16x16x32_bf16 v[22:25], v[202:205], v[226:229], v[22:25]
	v_mfma_f32_16x16x32_bf16 v[18:21], v[202:205], v[234:237], v[18:21]
	v_mfma_f32_16x16x32_bf16 v[14:17], v[210:213], v[226:229], v[14:17]
	v_mfma_f32_16x16x32_bf16 v[10:13], v[210:213], v[234:237], v[10:13]
	v_mfma_f32_16x16x32_bf16 v[6:9], v[218:221], v[226:229], v[6:9]
	v_mfma_f32_16x16x32_bf16 v[2:5], v[218:221], v[234:237], v[2:5]
	v_mfma_f32_16x16x32_bf16 v[30:33], v[198:201], v[230:233], v[30:33]
	v_mfma_f32_16x16x32_bf16 v[26:29], v[198:201], v[238:241], v[26:29]
	v_mfma_f32_16x16x32_bf16 v[22:25], v[206:209], v[230:233], v[22:25]
	v_mfma_f32_16x16x32_bf16 v[18:21], v[206:209], v[238:241], v[18:21]
	v_mfma_f32_16x16x32_bf16 v[14:17], v[214:217], v[230:233], v[14:17]
	v_mfma_f32_16x16x32_bf16 v[10:13], v[214:217], v[238:241], v[10:13]
	v_mfma_f32_16x16x32_bf16 v[6:9], v[222:225], v[230:233], v[6:9]
	v_mfma_f32_16x16x32_bf16 v[2:5], v[222:225], v[238:241], v[2:5]
	s_add_i32 s16, s16, 2
	s_add_u32 s14, s14, 0x100
	s_addc_u32 s15, s15, 0
	s_cmp_lt_u32 s16, 4
	s_cbranch_scc1 .LBB0_128
	s_barrier
	s_add_u32 s12, s12, 0x20380
	s_addc_u32 s13, s13, 0
	v_readfirstlane_b32 s10, v175
	v_lshl_add_u64 v[132:133], v[132:133], 1, s[12:13]
	s_mov_b32 m0, s10
	v_readfirstlane_b32 s10, v176
	ds_read_b128 v[134:137], v174
	ds_read_b128 v[138:141], v174 offset:1024
	ds_read_b128 v[162:165], v174 offset:2048
	ds_read_b128 v[168:171], v174 offset:3072
	ds_read_b128 v[178:181], v146
	ds_read_b128 v[182:185], v146 offset:1024
	ds_read_b128 v[186:189], v145
	ds_read_b128 v[190:193], v145 offset:1024
	ds_read_b128 v[194:197], v144
	ds_read_b128 v[198:201], v144 offset:1024
	ds_read_b128 v[202:205], v143
	ds_read_b128 v[206:209], v143 offset:1024
	global_load_lds_dwordx4 v[132:133], off
	v_lshl_add_u64 v[130:131], v[130:131], 1, s[12:13]
	s_mov_b32 m0, s10
	s_nop 0
	global_load_lds_dwordx4 v[130:131], off
	s_barrier
	s_waitcnt lgkmcnt(0)
	v_mfma_f32_16x16x32_bf16 v[126:129], v[178:181], v[134:137], v[126:129]
	v_mfma_f32_16x16x32_bf16 v[122:125], v[178:181], v[162:165], v[122:125]
	v_mfma_f32_16x16x32_bf16 v[118:121], v[186:189], v[134:137], v[118:121]
	v_mfma_f32_16x16x32_bf16 v[114:117], v[186:189], v[162:165], v[114:117]
	v_mfma_f32_16x16x32_bf16 v[110:113], v[194:197], v[134:137], v[110:113]
	v_mfma_f32_16x16x32_bf16 v[106:109], v[194:197], v[162:165], v[106:109]
	v_mfma_f32_16x16x32_bf16 v[102:105], v[202:205], v[134:137], v[102:105]
	v_mfma_f32_16x16x32_bf16 v[98:101], v[202:205], v[162:165], v[98:101]
	v_mfma_f32_16x16x32_bf16 v[126:129], v[182:185], v[138:141], v[126:129]
	v_mfma_f32_16x16x32_bf16 v[122:125], v[182:185], v[168:171], v[122:125]
	v_mfma_f32_16x16x32_bf16 v[118:121], v[190:193], v[138:141], v[118:121]
	v_mfma_f32_16x16x32_bf16 v[114:117], v[190:193], v[168:171], v[114:117]
	v_mfma_f32_16x16x32_bf16 v[110:113], v[198:201], v[138:141], v[110:113]
	v_mfma_f32_16x16x32_bf16 v[106:109], v[198:201], v[168:171], v[106:109]
	v_mfma_f32_16x16x32_bf16 v[102:105], v[206:209], v[138:141], v[102:105]
	v_mfma_f32_16x16x32_bf16 v[98:101], v[206:209], v[168:171], v[98:101]
	s_barrier
	ds_read_b128 v[130:133], v173
	ds_read_b128 v[174:177], v173 offset:1024
	ds_read_b128 v[210:213], v173 offset:2048
	ds_read_b128 v[214:217], v173 offset:3072
	s_barrier
	s_waitcnt lgkmcnt(0)
	v_mfma_f32_16x16x32_bf16 v[86:89], v[186:189], v[130:133], v[86:89]
	v_mfma_f32_16x16x32_bf16 v[74:77], v[194:197], v[210:213], v[74:77]
	v_mfma_f32_16x16x32_bf16 v[70:73], v[202:205], v[130:133], v[70:73]
	v_mfma_f32_16x16x32_bf16 v[66:69], v[202:205], v[210:213], v[66:69]
	v_mfma_f32_16x16x32_bf16 v[94:97], v[178:181], v[130:133], v[94:97]
	v_mfma_f32_16x16x32_bf16 v[90:93], v[178:181], v[210:213], v[90:93]
	v_mfma_f32_16x16x32_bf16 v[86:89], v[190:193], v[174:177], v[86:89]
	v_mfma_f32_16x16x32_bf16 v[82:85], v[186:189], v[210:213], v[82:85]
	v_mfma_f32_16x16x32_bf16 v[78:81], v[194:197], v[130:133], v[78:81]
	v_mfma_f32_16x16x32_bf16 v[74:77], v[198:201], v[214:217], v[74:77]
	v_mfma_f32_16x16x32_bf16 v[70:73], v[206:209], v[174:177], v[70:73]
	v_mfma_f32_16x16x32_bf16 v[66:69], v[206:209], v[214:217], v[66:69]
	v_mfma_f32_16x16x32_bf16 v[218:221], v[182:185], v[174:177], v[94:97]
	v_mfma_f32_16x16x32_bf16 v[178:181], v[182:185], v[214:217], v[90:93]
	v_mfma_f32_16x16x32_bf16 v[182:185], v[190:193], v[214:217], v[82:85]
	v_mfma_f32_16x16x32_bf16 v[186:189], v[198:201], v[174:177], v[78:81]
	s_barrier
; #define LDA(dst, b, h) _Pragma("unroll") for (int m = 0; m < 4; ++m) _Pragma("unroll") for (int k = 0; k < 2; ++k) \
;     dst[m][k] = *reinterpret_cast<const bf16x8*>((char*)SA(b, h) + lds_byte(wr * 64 + m * 16 + fr, k * 32 + fq * 8))
; #define LDB(dst, b, h) _Pragma("unroll") for (int n = 0; n < 2; ++n) _Pragma("unroll") for (int k = 0; k < 2; ++k) \
;     dst[n][k] = *reinterpret_cast<const bf16x8*>((char*)SB(b, h) + lds_byte(wc * 32 + n * 16 + fr, k * 32 + fq * 8))
; #define MMA(ai, bj, At, Bq) do { __builtin_amdgcn_s_setprio(1); \
;     _Pragma("unroll") for (int m = 0; m < 4; ++m) _Pragma("unroll") for (int n = 0; n < 2; ++n) _Pragma("unroll") for (int k = 0; k < 2; ++k) \
;       acc[ai][bj][m][n] = __builtin_amdgcn_mfma_f32_16x16x32_bf16(At[m][k], Bq[n][k], acc[ai][bj][m][n], 0, 0, 0); \
;     __builtin_amdgcn_s_setprio(0); } while (0)
; #define WAIT_V(n) asm volatile("s_waitcnt vmcnt(" #n ")" ::: "memory")
; #define WAIT_L(n) asm volatile("s_waitcnt lgkmcnt(" #n ")" ::: "memory")
; #define BAR __builtin_amdgcn_s_barrier()
; __device__ __forceinline__ void gemm256(const u16* __restrict__ A, int lda, const u16* __restrict__ Bt, int ldb, int K,
;                                         f32x4 (&acc)[2][2][4][2], const int g_wid) {
;     ...
;     LDA(At, 0, 1); WAIT_V(4); BAR; WAIT_L(0); MMA(1, 0, At, B0); MMA(1, 1, At, B1); BAR; }
;   { LDB(B0, 1, 0); LDA(At, 1, 0); WAIT_V(2); BAR; WAIT_L(0); MMA(0, 0, At, B0); BAR;
	s_nop 0
	ds_read_b128 v[78:81], v146 offset:16384
	ds_read_b128 v[82:85], v146 offset:17408
	ds_read_b128 v[90:93], v145 offset:16384
	ds_read_b128 v[94:97], v145 offset:17408
	ds_read_b128 v[190:193], v144 offset:16384
	ds_read_b128 v[194:197], v144 offset:17408
	ds_read_b128 v[198:201], v143 offset:16384
	ds_read_b128 v[202:205], v143 offset:17408
	s_waitcnt vmcnt(4)
	s_barrier
	s_waitcnt lgkmcnt(0)
	v_mfma_f32_16x16x32_bf16 v[54:57], v[90:93], v[134:137], v[54:57]
	v_mfma_f32_16x16x32_bf16 v[42:45], v[190:193], v[162:165], v[42:45]
	v_mfma_f32_16x16x32_bf16 v[38:41], v[198:201], v[134:137], v[38:41]
	v_mfma_f32_16x16x32_bf16 v[34:37], v[198:201], v[162:165], v[34:37]
	v_mfma_f32_16x16x32_bf16 v[62:65], v[78:81], v[134:137], v[62:65]
	v_mfma_f32_16x16x32_bf16 v[58:61], v[78:81], v[162:165], v[58:61]
	v_mfma_f32_16x16x32_bf16 v[54:57], v[94:97], v[138:141], v[54:57]
	v_mfma_f32_16x16x32_bf16 v[50:53], v[90:93], v[162:165], v[50:53]
	v_mfma_f32_16x16x32_bf16 v[46:49], v[190:193], v[134:137], v[46:49]
	v_mfma_f32_16x16x32_bf16 v[42:45], v[194:197], v[168:171], v[42:45]
	v_mfma_f32_16x16x32_bf16 v[38:41], v[202:205], v[138:141], v[38:41]
	v_mfma_f32_16x16x32_bf16 v[34:37], v[202:205], v[168:171], v[34:37]
	v_mfma_f32_16x16x32_bf16 v[206:209], v[82:85], v[138:141], v[62:65]
	v_mfma_f32_16x16x32_bf16 v[222:225], v[82:85], v[168:171], v[58:61]
	v_mfma_f32_16x16x32_bf16 v[226:229], v[94:97], v[168:171], v[50:53]
	v_mfma_f32_16x16x32_bf16 v[230:233], v[194:197], v[138:141], v[46:49]
	v_mfma_f32_16x16x32_bf16 v[2:5], v[198:201], v[210:213], v[2:5]
	v_mfma_f32_16x16x32_bf16 v[30:33], v[78:81], v[130:133], v[30:33]
	v_mfma_f32_16x16x32_bf16 v[26:29], v[78:81], v[210:213], v[26:29]
	v_mfma_f32_16x16x32_bf16 v[22:25], v[90:93], v[130:133], v[22:25]
	v_mfma_f32_16x16x32_bf16 v[18:21], v[90:93], v[210:213], v[18:21]
	v_mfma_f32_16x16x32_bf16 v[14:17], v[190:193], v[130:133], v[14:17]
	v_mfma_f32_16x16x32_bf16 v[10:13], v[190:193], v[210:213], v[10:13]
	v_mfma_f32_16x16x32_bf16 v[6:9], v[198:201], v[130:133], v[6:9]
	v_mfma_f32_16x16x32_bf16 v[2:5], v[202:205], v[214:217], v[2:5]
	v_mfma_f32_16x16x32_bf16 v[134:137], v[82:85], v[174:177], v[30:33]
	v_mfma_f32_16x16x32_bf16 v[138:141], v[82:85], v[214:217], v[26:29]
	v_mfma_f32_16x16x32_bf16 v[162:165], v[94:97], v[174:177], v[22:25]
	v_mfma_f32_16x16x32_bf16 v[168:171], v[94:97], v[214:217], v[18:21]
	v_mfma_f32_16x16x32_bf16 v[234:237], v[194:197], v[174:177], v[14:17]
	v_mfma_f32_16x16x32_bf16 v[190:193], v[194:197], v[214:217], v[10:13]
	v_mfma_f32_16x16x32_bf16 v[130:133], v[202:205], v[174:177], v[6:9]
	s_barrier
	s_nop 0
	ds_read_b128 v[6:9], v166
	ds_read_b128 v[10:13], v166 offset:1024
	ds_read_b128 v[22:25], v166 offset:2048
	ds_read_b128 v[172:175], v166 offset:3072
	ds_read_b128 v[14:17], v146 offset:32768
	ds_read_b128 v[18:21], v146 offset:33792
	ds_read_b128 v[26:29], v145 offset:32768
	ds_read_b128 v[46:49], v145 offset:33792
	ds_read_b128 v[194:197], v144 offset:32768
	ds_read_b128 v[198:201], v144 offset:33792
	ds_read_b128 v[202:205], v143 offset:32768
	ds_read_b128 v[210:213], v143 offset:33792
	s_waitcnt vmcnt(2)
	s_barrier
	s_waitcnt lgkmcnt(0)
	v_mfma_f32_16x16x32_bf16 v[30:33], v[14:17], v[6:9], v[126:129]
	v_mfma_f32_16x16x32_bf16 v[126:129], v[18:21], v[10:13], v[30:33]
	v_mfma_f32_16x16x32_bf16 v[30:33], v[14:17], v[22:25], v[122:125]
	v_mfma_f32_16x16x32_bf16 v[94:97], v[18:21], v[172:175], v[30:33]
	v_mfma_f32_16x16x32_bf16 v[30:33], v[26:29], v[6:9], v[118:121]
	v_mfma_f32_16x16x32_bf16 v[122:125], v[46:49], v[10:13], v[30:33]
	v_mfma_f32_16x16x32_bf16 v[30:33], v[26:29], v[22:25], v[114:117]
	v_mfma_f32_16x16x32_bf16 v[90:93], v[46:49], v[172:175], v[30:33]
	v_mfma_f32_16x16x32_bf16 v[30:33], v[194:197], v[6:9], v[110:113]
	v_mfma_f32_16x16x32_bf16 v[114:117], v[198:201], v[10:13], v[30:33]
	v_mfma_f32_16x16x32_bf16 v[30:33], v[194:197], v[22:25], v[106:109]
	v_mfma_f32_16x16x32_bf16 v[82:85], v[198:201], v[172:175], v[30:33]
	v_mfma_f32_16x16x32_bf16 v[30:33], v[202:205], v[6:9], v[102:105]
	v_mfma_f32_16x16x32_bf16 v[110:113], v[210:213], v[10:13], v[30:33]
	v_mfma_f32_16x16x32_bf16 v[30:33], v[202:205], v[22:25], v[98:101]
	v_mfma_f32_16x16x32_bf16 v[78:81], v[210:213], v[172:175], v[30:33]
	s_barrier
; #define LDA(dst, b, h) _Pragma("unroll") for (int m = 0; m < 4; ++m) _Pragma("unroll") for (int k = 0; k < 2; ++k) \
;     dst[m][k] = *reinterpret_cast<const bf16x8*>((char*)SA(b, h) + lds_byte(wr * 64 + m * 16 + fr, k * 32 + fq * 8))
; #define LDB(dst, b, h) _Pragma("unroll") for (int n = 0; n < 2; ++n) _Pragma("unroll") for (int k = 0; k < 2; ++k) \
;     dst[n][k] = *reinterpret_cast<const bf16x8*>((char*)SB(b, h) + lds_byte(wc * 32 + n * 16 + fr, k * 32 + fq * 8))
; #define MMA(ai, bj, At, Bq) do { __builtin_amdgcn_s_setprio(1); \
;     _Pragma("unroll") for (int m = 0; m < 4; ++m) _Pragma("unroll") for (int n = 0; n < 2; ++n) _Pragma("unroll") for (int k = 0; k < 2; ++k) \
;       acc[ai][bj][m][n] = __builtin_amdgcn_mfma_f32_16x16x32_bf16(At[m][k], Bq[n][k], acc[ai][bj][m][n], 0, 0, 0); \
;     __builtin_amdgcn_s_setprio(0); } while (0)
; #define WAIT_V(n) asm volatile("s_waitcnt vmcnt(" #n ")" ::: "memory")
; #define WAIT_L(n) asm volatile("s_waitcnt lgkmcnt(" #n ")" ::: "memory")
; #define BAR __builtin_amdgcn_s_barrier()
; __device__ __forceinline__ void gemm256(const u16* __restrict__ A, int lda, const u16* __restrict__ Bt, int ldb, int K,
;                                         f32x4 (&acc)[2][2][4][2], const int g_wid) {
;     ...
;   { LDB(B0, 1, 0); LDA(At, 1, 0); WAIT_V(2); BAR; WAIT_L(0); MMA(0, 0, At, B0); BAR;
;     LDB(B1, 1, 1); WAIT_V(0); BAR; WAIT_L(0); MMA(0, 1, At, B1); BAR;
;     LDA(At, 1, 1); BAR; WAIT_L(0); MMA(1, 0, At, B0); MMA(1, 1, At, B1); BAR; }
;   if (wr == 0) BAR;
	ds_read_b128 v[214:217], v161
	ds_read_b128 v[238:241], v161 offset:1024
	ds_read_b128 v[242:245], v161 offset:2048
	ds_read_b128 v[246:249], v161 offset:3072
	s_waitcnt vmcnt(0)
	s_barrier
	s_waitcnt lgkmcnt(0)
	v_mfma_f32_16x16x32_bf16 v[30:33], v[14:17], v[214:217], v[218:221]
	v_mfma_f32_16x16x32_bf16 v[14:17], v[14:17], v[242:245], v[178:181]
	v_mfma_f32_16x16x32_bf16 v[62:65], v[18:21], v[238:241], v[30:33]
	v_mfma_f32_16x16x32_bf16 v[30:33], v[18:21], v[246:249], v[14:17]
	v_mfma_f32_16x16x32_bf16 v[14:17], v[26:29], v[214:217], v[86:89]
	v_mfma_f32_16x16x32_bf16 v[58:61], v[46:49], v[238:241], v[14:17]
	v_mfma_f32_16x16x32_bf16 v[14:17], v[26:29], v[242:245], v[182:185]
	v_mfma_f32_16x16x32_bf16 v[26:29], v[46:49], v[246:249], v[14:17]
	v_mfma_f32_16x16x32_bf16 v[14:17], v[194:197], v[214:217], v[186:189]
	v_mfma_f32_16x16x32_bf16 v[50:53], v[198:201], v[238:241], v[14:17]
	v_mfma_f32_16x16x32_bf16 v[14:17], v[194:197], v[242:245], v[74:77]
	v_mfma_f32_16x16x32_bf16 v[18:21], v[198:201], v[246:249], v[14:17]
	v_mfma_f32_16x16x32_bf16 v[14:17], v[202:205], v[214:217], v[70:73]
	v_mfma_f32_16x16x32_bf16 v[46:49], v[210:213], v[238:241], v[14:17]
	v_mfma_f32_16x16x32_bf16 v[14:17], v[202:205], v[242:245], v[66:69]
	v_mfma_f32_16x16x32_bf16 v[14:17], v[210:213], v[246:249], v[14:17]
	s_barrier
	ds_read_b128 v[176:179], v146 offset:49152
	ds_read_b128 v[180:183], v146 offset:50176
	ds_read_b128 v[184:187], v145 offset:49152
	ds_read_b128 v[194:197], v145 offset:50176
	ds_read_b128 v[198:201], v144 offset:49152
	ds_read_b128 v[144:147], v144 offset:50176
	ds_read_b128 v[202:205], v143 offset:49152
	ds_read_b128 v[210:213], v143 offset:50176
	s_barrier
	s_waitcnt lgkmcnt(0)
	v_mfma_f32_16x16x32_bf16 v[54:57], v[184:187], v[6:9], v[54:57]
	v_mfma_f32_16x16x32_bf16 v[106:109], v[194:197], v[10:13], v[54:57]
	v_mfma_f32_16x16x32_bf16 v[54:57], v[184:187], v[22:25], v[226:229]
	v_mfma_f32_16x16x32_bf16 v[66:69], v[176:179], v[6:9], v[206:209]
	v_mfma_f32_16x16x32_bf16 v[74:77], v[194:197], v[172:175], v[54:57]
	v_mfma_f32_16x16x32_bf16 v[54:57], v[198:201], v[6:9], v[230:233]
	v_mfma_f32_16x16x32_bf16 v[6:9], v[202:205], v[6:9], v[38:41]
	v_mfma_f32_16x16x32_bf16 v[118:121], v[180:183], v[10:13], v[66:69]
	v_mfma_f32_16x16x32_bf16 v[66:69], v[176:179], v[22:25], v[222:225]
	v_mfma_f32_16x16x32_bf16 v[42:45], v[198:201], v[22:25], v[42:45]
	v_mfma_f32_16x16x32_bf16 v[98:101], v[210:213], v[10:13], v[6:9]
	v_mfma_f32_16x16x32_bf16 v[6:9], v[202:205], v[22:25], v[34:37]
	v_mfma_f32_16x16x32_bf16 v[86:89], v[180:183], v[172:175], v[66:69]
	v_mfma_f32_16x16x32_bf16 v[102:105], v[144:147], v[10:13], v[54:57]
	v_mfma_f32_16x16x32_bf16 v[70:73], v[144:147], v[172:175], v[42:45]
	v_mfma_f32_16x16x32_bf16 v[66:69], v[210:213], v[172:175], v[6:9]
	v_mfma_f32_16x16x32_bf16 v[6:9], v[176:179], v[214:217], v[134:137]
	v_mfma_f32_16x16x32_bf16 v[54:57], v[180:183], v[238:241], v[6:9]
	v_mfma_f32_16x16x32_bf16 v[6:9], v[176:179], v[242:245], v[138:141]
	v_mfma_f32_16x16x32_bf16 v[22:25], v[180:183], v[246:249], v[6:9]
	v_mfma_f32_16x16x32_bf16 v[6:9], v[184:187], v[214:217], v[162:165]
	v_mfma_f32_16x16x32_bf16 v[42:45], v[194:197], v[238:241], v[6:9]
	v_mfma_f32_16x16x32_bf16 v[6:9], v[184:187], v[242:245], v[168:171]
	v_mfma_f32_16x16x32_bf16 v[10:13], v[194:197], v[246:249], v[6:9]
	v_mfma_f32_16x16x32_bf16 v[6:9], v[198:201], v[214:217], v[234:237]
	v_mfma_f32_16x16x32_bf16 v[38:41], v[144:147], v[238:241], v[6:9]
	v_mfma_f32_16x16x32_bf16 v[6:9], v[198:201], v[242:245], v[190:193]
	v_mfma_f32_16x16x32_bf16 v[34:37], v[202:205], v[214:217], v[130:133]
	v_mfma_f32_16x16x32_bf16 v[2:5], v[202:205], v[242:245], v[2:5]
	v_mfma_f32_16x16x32_bf16 v[6:9], v[144:147], v[246:249], v[6:9]
	v_mfma_f32_16x16x32_bf16 v[34:37], v[210:213], v[238:241], v[34:37]
	v_mfma_f32_16x16x32_bf16 v[2:5], v[210:213], v[246:249], v[2:5]
	s_setprio 0
	s_movk_i32 s10, 0x100
	v_cmp_gt_u32_e32 vcc, s10, v0
	s_barrier
	s_and_saveexec_b64 s[12:13], vcc
	s_cbranch_execz .LBB0_131
	s_barrier

; #define hw_tid() ((g_wid << 6) | hw_lane())
; #define STA(P, br, kt) STAGE(P, A, aoff0, aoff1, lda, br, kt)
; #define STB(P, br, kt) STAGE(P, Bt, boff0, boff1, ldb, br, kt)
; #define WAIT_V(n) asm volatile("s_waitcnt vmcnt(" #n ")" ::: "memory")
; #define BAR __builtin_amdgcn_s_barrier()
; __device__ __forceinline__ void gemm256(const u16* __restrict__ A, int lda, const u16* __restrict__ Bt, int ldb, int K,
;                                         f32x4 (&acc)[2][2][4][2], const int g_wid) {
;   int tid = hw_tid(); asm volatile("" : "+v"(tid));
;   const int wid = tid >> 6, lane = tid & 63, wr = wid >> 2, wc = wid & 3, fr = lane & 15, fq = lane >> 4;
;   int r0, c0, r1, c1;
;   stage_rc(tid * 16, r0, c0);
;   stage_rc(tid * 16 + 8192, r1, c1);
;   const int aoff0 = r0 * lda + c0, aoff1 = r1 * lda + c1, boff0 = r0 * ldb + c0, boff1 = r1 * ldb + c1;
;   bf16x8 At[4][2], B0[2][2], B1[2][2];
;   const int nt = K / BK;
;   STB(SB(0, 0), 0, 0); STA(SA(0, 0), 0, 0);
;   STB(SB(0, 1), HALF, 0); STA(SA(0, 1), HALF, 0);
;   if (wr == 1) BAR;
;   WAIT_V(4); BAR;
;   STB(SB(1, 0), 0, 1); STA(SA(1, 0), 0, 1); STB(SB(1, 1), HALF, 1);
;   WAIT_V(6); BAR;
.LBB0_135:
	s_or_b64 exec, exec, s[18:19]
	v_readlane_b32 s11, v254, 42
	s_add_u32 s18, s16, 0x6000080
	s_addc_u32 s19, s17, 0
	v_add_u32_e32 v167, s11, v16
	v_add_u32_e32 v168, 0x2000, v167
	v_readfirstlane_b32 s10, v167
	v_lshl_add_u64 v[20:21], s[18:19], 0, v[2:3]
	s_mov_b32 m0, s10
	v_readfirstlane_b32 s10, v168
	v_add_u32_e32 v169, 0x8000, v160
	s_waitcnt vmcnt(4)
	s_barrier
	global_load_lds_dwordx4 v[20:21], off
	v_lshl_add_u64 v[20:21], s[18:19], 0, v[4:5]
	s_mov_b32 m0, s10
	s_mov_b64 s[8:9], 0x80
	v_readfirstlane_b32 s10, v169
	v_add_u32_e32 v170, 0xa000, v160
	v_readlane_b32 s20, v254, 43
	global_load_lds_dwordx4 v[20:21], off
	v_lshl_add_u64 v[8:9], v[8:9], 0, s[8:9]
	s_mov_b32 m0, s10
	v_readfirstlane_b32 s10, v170
	s_add_u32 s18, s16, 0x6040080
	v_add_u32_e32 v171, s20, v16
	global_load_lds_dwordx4 v[8:9], off
	v_lshl_add_u64 v[6:7], v[6:7], 0, s[8:9]
	s_mov_b32 m0, s10
	s_addc_u32 s19, s17, 0
	v_readfirstlane_b32 s10, v171
	v_add_u32_e32 v172, 0x2000, v171
	global_load_lds_dwordx4 v[6:7], off
	v_lshl_add_u64 v[2:3], s[18:19], 0, v[2:3]
	s_mov_b32 m0, s10
	v_readfirstlane_b32 s10, v172
	global_load_lds_dwordx4 v[2:3], off
	v_lshl_add_u64 v[2:3], s[18:19], 0, v[4:5]
	s_mov_b32 m0, s10
	v_and_b32_e32 v22, 15, v0
	global_load_lds_dwordx4 v[2:3], off
	v_lshlrev_b32_e32 v3, 2, v0
	v_and_b32_e32 v23, 48, v0
	v_lshlrev_b32_e32 v2, 6, v22
	v_and_b32_e32 v3, 32, v3
	v_bitop3_b32 v2, v2, v3, v23 bitop3:0x36
	v_readlane_b32 s10, v254, 40
	v_lshlrev_b32_e32 v4, 6, v0
	v_add_u32_e32 v8, s11, v2
	v_add_u32_e32 v6, s10, v2
	v_readlane_b32 s10, v254, 41
	v_add_u32_e32 v9, s20, v2
	v_add_u32_e32 v20, 0, v2
	v_add_u32_e32 v7, s10, v2
	s_movk_i32 s10, 0x3c0
	v_and_or_b32 v2, v4, s10, v23
	v_xad_u32 v21, v2, v3, 0
	v_lshlrev_b32_e32 v2, 13, v15
	v_and_b32_e32 v16, 0x3000, v4
	v_and_b32_e32 v2, 0xffffc000, v2
	v_lshlrev_b32_e32 v4, 13, v10
	v_lshl_add_u32 v2, v17, 10, v2
	v_and_b32_e32 v4, 0xffffc000, v4
	v_or_b32_e32 v2, v2, v18
	v_lshl_add_u32 v4, v12, 10, v4
	v_add_u32_sdwa v2, v2, sext(v19) dst_sel:DWORD dst_unused:UNUSED_PAD src0_sel:DWORD src1_sel:WORD_0
	v_or_b32_e32 v4, v4, v13
	v_ashrrev_i32_e32 v3, 31, v2
	v_add_u32_sdwa v4, v4, sext(v14) dst_sel:DWORD dst_unused:UNUSED_PAD src0_sel:DWORD src1_sel:WORD_0
	s_add_u32 s6, s6, s14
	s_waitcnt vmcnt(6)
	v_lshlrev_b32_e32 v11, 13, v11
	v_lshlrev_b64 v[2:3], 1, v[2:3]
	v_ashrrev_i32_e32 v5, 31, v4
	s_addc_u32 s7, s7, s15
	v_or_b32_e32 v22, 0x800, v11
	v_or_b32_e32 v23, 0x1000, v11
	v_or_b32_e32 v24, 0x1800, v11
	v_lshl_add_u64 v[134:135], s[16:17], 0, v[2:3]
	v_lshlrev_b64 v[4:5], 1, v[4:5]
	v_lshl_add_u64 v[138:139], s[6:7], 0, v[2:3]
	v_mov_b32_e32 v2, 0
	v_lshl_add_u64 v[136:137], s[16:17], 0, v[4:5]
	v_lshl_add_u64 v[140:141], s[6:7], 0, v[4:5]
	s_mov_b32 s14, -2
	s_mov_b64 s[6:7], 0
	v_add_u32_e32 v174, v6, v16
	v_add_u32_e32 v145, v20, v11
	v_add_u32_e32 v144, v21, v22
	v_add_u32_e32 v143, v21, v23
	v_add_u32_e32 v142, v21, v24
	v_add_u32_e32 v173, v7, v16
	v_add_u32_e32 v165, v8, v16
	v_add_u32_e32 v159, v9, v16
	v_mov_b32_e32 v3, v2
	v_mov_b32_e32 v4, v2
	v_mov_b32_e32 v5, v2
	v_mov_b32_e32 v6, v2
	v_mov_b32_e32 v7, v2
	v_mov_b32_e32 v8, v2
	v_mov_b32_e32 v9, v2
	v_mov_b32_e32 v10, v2
	v_mov_b32_e32 v11, v2
	v_mov_b32_e32 v12, v2
	v_mov_b32_e32 v13, v2
	v_mov_b32_e32 v14, v2
	v_mov_b32_e32 v15, v2
	v_mov_b32_e32 v16, v2
	v_mov_b32_e32 v17, v2
	v_mov_b32_e32 v18, v2
	v_mov_b32_e32 v19, v2
	v_mov_b32_e32 v20, v2
	v_mov_b32_e32 v21, v2
	v_mov_b32_e32 v22, v2
	v_mov_b32_e32 v23, v2
	v_mov_b32_e32 v24, v2
	v_mov_b32_e32 v25, v2
	v_mov_b32_e32 v26, v2
	v_mov_b32_e32 v27, v2
	v_mov_b32_e32 v28, v2
	v_mov_b32_e32 v29, v2
	v_mov_b32_e32 v30, v2
	v_mov_b32_e32 v31, v2
	v_mov_b32_e32 v32, v2
	v_mov_b32_e32 v33, v2
	v_mov_b32_e32 v34, v2
	v_mov_b32_e32 v35, v2
	v_mov_b32_e32 v36, v2
	v_mov_b32_e32 v37, v2
	v_mov_b32_e32 v38, v2
	v_mov_b32_e32 v39, v2
	v_mov_b32_e32 v40, v2
	v_mov_b32_e32 v41, v2
	v_mov_b32_e32 v42, v2
	v_mov_b32_e32 v43, v2
	v_mov_b32_e32 v44, v2
	v_mov_b32_e32 v45, v2
	v_mov_b32_e32 v46, v2
	v_mov_b32_e32 v47, v2
	v_mov_b32_e32 v48, v2
	v_mov_b32_e32 v49, v2
	v_mov_b32_e32 v50, v2
	v_mov_b32_e32 v51, v2
	v_mov_b32_e32 v52, v2
	v_mov_b32_e32 v53, v2
	v_mov_b32_e32 v54, v2
	v_mov_b32_e32 v55, v2
	v_mov_b32_e32 v56, v2
	v_mov_b32_e32 v57, v2
	v_mov_b32_e32 v58, v2
	v_mov_b32_e32 v59, v2
	v_mov_b32_e32 v60, v2
	v_mov_b32_e32 v61, v2
	v_mov_b32_e32 v62, v2
	v_mov_b32_e32 v63, v2
	v_mov_b32_e32 v64, v2
	v_mov_b32_e32 v65, v2
	v_mov_b32_e32 v66, v2
	v_mov_b32_e32 v67, v2
	v_mov_b32_e32 v68, v2
	v_mov_b32_e32 v69, v2
	v_mov_b32_e32 v70, v2
	v_mov_b32_e32 v71, v2
	v_mov_b32_e32 v72, v2
	v_mov_b32_e32 v73, v2
	v_mov_b32_e32 v74, v2
	v_mov_b32_e32 v75, v2
	v_mov_b32_e32 v76, v2
	v_mov_b32_e32 v77, v2
	v_mov_b32_e32 v78, v2
	v_mov_b32_e32 v79, v2
	v_mov_b32_e32 v80, v2
	v_mov_b32_e32 v81, v2
	v_mov_b32_e32 v82, v2
	v_mov_b32_e32 v83, v2
	v_mov_b32_e32 v84, v2
	v_mov_b32_e32 v85, v2
	v_mov_b32_e32 v86, v2
	v_mov_b32_e32 v87, v2
	v_mov_b32_e32 v88, v2
	v_mov_b32_e32 v89, v2
	v_mov_b32_e32 v90, v2
	v_mov_b32_e32 v91, v2
	v_mov_b32_e32 v92, v2
	v_mov_b32_e32 v93, v2
	v_mov_b32_e32 v94, v2
	v_mov_b32_e32 v95, v2
	v_mov_b32_e32 v96, v2
	v_mov_b32_e32 v97, v2
	v_mov_b32_e32 v98, v2
	v_mov_b32_e32 v99, v2
	v_mov_b32_e32 v100, v2
	v_mov_b32_e32 v101, v2
	v_mov_b32_e32 v102, v2
	v_mov_b32_e32 v103, v2
	v_mov_b32_e32 v104, v2
	v_mov_b32_e32 v105, v2
	v_mov_b32_e32 v106, v2
	v_mov_b32_e32 v107, v2
	v_mov_b32_e32 v108, v2
	v_mov_b32_e32 v109, v2
	v_mov_b32_e32 v110, v2
	v_mov_b32_e32 v111, v2
	v_mov_b32_e32 v112, v2
	v_mov_b32_e32 v113, v2
	v_mov_b32_e32 v114, v2
	v_mov_b32_e32 v115, v2
	v_mov_b32_e32 v116, v2
	v_mov_b32_e32 v117, v2
	v_mov_b32_e32 v118, v2
	v_mov_b32_e32 v119, v2
	v_mov_b32_e32 v120, v2
	v_mov_b32_e32 v121, v2
	v_mov_b32_e32 v122, v2
	v_mov_b32_e32 v123, v2
	v_mov_b32_e32 v124, v2
	v_mov_b32_e32 v125, v2
	v_mov_b32_e32 v126, v2
	v_mov_b32_e32 v127, v2
	v_mov_b32_e32 v128, v2
	v_mov_b32_e32 v129, v2
	s_mov_b64 s[8:9], 0x6000100
	s_mov_b64 s[16:17], 0x6040100
	s_mov_b64 s[18:19], 0x6000180
	s_mov_b64 s[20:21], 0x6040180
	.p2align 6
; #define STA(P, br, kt) STAGE(P, A, aoff0, aoff1, lda, br, kt)
; #define STB(P, br, kt) STAGE(P, Bt, boff0, boff1, ldb, br, kt)
; #define LDA(dst, b, h) _Pragma("unroll") for (int m = 0; m < 4; ++m) _Pragma("unroll") for (int k = 0; k < 2; ++k) \
;     dst[m][k] = *reinterpret_cast<const bf16x8*>((char*)SA(b, h) + lds_byte(wr * 64 + m * 16 + fr, k * 32 + fq * 8))
; #define LDB(dst, b, h) _Pragma("unroll") for (int n = 0; n < 2; ++n) _Pragma("unroll") for (int k = 0; k < 2; ++k) \
;     dst[n][k] = *reinterpret_cast<const bf16x8*>((char*)SB(b, h) + lds_byte(wc * 32 + n * 16 + fr, k * 32 + fq * 8))
; #define MMA(ai, bj, At, Bq) do { __builtin_amdgcn_s_setprio(1); \
;     _Pragma("unroll") for (int m = 0; m < 4; ++m) _Pragma("unroll") for (int n = 0; n < 2; ++n) _Pragma("unroll") for (int k = 0; k < 2; ++k) \
;       acc[ai][bj][m][n] = __builtin_amdgcn_mfma_f32_16x16x32_bf16(At[m][k], Bq[n][k], acc[ai][bj][m][n], 0, 0, 0); \
;     __builtin_amdgcn_s_setprio(0); } while (0)
; #define WAIT_L(n) asm volatile("s_waitcnt lgkmcnt(" #n ")" ::: "memory")
; #define BAR __builtin_amdgcn_s_barrier()
; #define SCHED __builtin_amdgcn_sched_barrier(0)
; __device__ __forceinline__ void gemm256(const u16* __restrict__ A, int lda, const u16* __restrict__ Bt, int ldb, int K,
;                                         f32x4 (&acc)[2][2][4][2], const int g_wid) {
;     ...
;     LDB(B0, 0, 0); SCHED; LDA(At, 0, 0); STA(SA(1, 1), HALF, t + 1);
;     WAIT_L(8); BAR; WAIT_L(0); MMA(0, 0, At, B0); BAR; SCHED;
;     LDB(B1, 0, 1); STB(SB(0, 0), 0, t + 2);
;     BAR; WAIT_L(0); MMA(0, 1, At, B1); BAR;
;     LDA(At, 0, 1); STA(SA(0, 0), 0, t + 2);
;     BAR; WAIT_L(0); MMA(1, 0, At, B0); BAR; SCHED;
.LBB0_136:
	s_barrier
	ds_read_b128 v[178:181], v174
	ds_read_b128 v[182:185], v174 offset:1024
	ds_read_b128 v[186:189], v174 offset:2048
	ds_read_b128 v[190:193], v174 offset:3072
	v_add_u32_e32 v175, 0xc000, v160
	v_lshl_add_u64 v[242:243], v[140:141], 0, s[6:7]
	v_readfirstlane_b32 s10, v175
	v_lshl_add_u64 v[176:177], v[242:243], 0, s[68:69]
	s_mov_b32 m0, s10
	ds_read_b128 v[194:197], v145
	ds_read_b128 v[198:201], v145 offset:1024
	ds_read_b128 v[202:205], v144
	ds_read_b128 v[206:209], v144 offset:1024
	ds_read_b128 v[210:213], v143
	ds_read_b128 v[214:217], v143 offset:1024
	ds_read_b128 v[218:221], v142
	ds_read_b128 v[222:225], v142 offset:1024
	global_load_lds_dwordx4 v[176:177], off
	v_add_u32_e32 v176, 0xe000, v160
	v_lshl_add_u64 v[244:245], v[138:139], 0, s[6:7]
	v_readfirstlane_b32 s10, v176
	v_lshl_add_u64 v[226:227], v[244:245], 0, s[68:69]
	s_mov_b32 m0, s10
	s_nop 0
	global_load_lds_dwordx4 v[226:227], off
	s_waitcnt lgkmcnt(8)
	s_barrier
	s_waitcnt lgkmcnt(0)
	v_mfma_f32_16x16x32_bf16 v[126:129], v[194:197], v[178:181], v[126:129]
	v_mfma_f32_16x16x32_bf16 v[122:125], v[194:197], v[186:189], v[122:125]
	v_mfma_f32_16x16x32_bf16 v[118:121], v[202:205], v[178:181], v[118:121]
	v_mfma_f32_16x16x32_bf16 v[114:117], v[202:205], v[186:189], v[114:117]
	v_mfma_f32_16x16x32_bf16 v[110:113], v[210:213], v[178:181], v[110:113]
	v_mfma_f32_16x16x32_bf16 v[106:109], v[210:213], v[186:189], v[106:109]
	v_mfma_f32_16x16x32_bf16 v[102:105], v[218:221], v[178:181], v[102:105]
	v_mfma_f32_16x16x32_bf16 v[98:101], v[218:221], v[186:189], v[98:101]
	v_mfma_f32_16x16x32_bf16 v[126:129], v[198:201], v[182:185], v[126:129]
	v_mfma_f32_16x16x32_bf16 v[122:125], v[198:201], v[190:193], v[122:125]
	v_mfma_f32_16x16x32_bf16 v[118:121], v[206:209], v[182:185], v[118:121]
	v_mfma_f32_16x16x32_bf16 v[114:117], v[206:209], v[190:193], v[114:117]
	v_mfma_f32_16x16x32_bf16 v[110:113], v[214:217], v[182:185], v[110:113]
	v_mfma_f32_16x16x32_bf16 v[106:109], v[214:217], v[190:193], v[106:109]
	v_mfma_f32_16x16x32_bf16 v[102:105], v[222:225], v[182:185], v[102:105]
	v_mfma_f32_16x16x32_bf16 v[98:101], v[222:225], v[190:193], v[98:101]
	s_barrier
	v_lshl_add_u64 v[246:247], v[136:137], 0, s[6:7]
	v_readfirstlane_b32 s10, v146
	v_lshl_add_u64 v[248:249], v[246:247], 0, s[8:9]
	s_mov_b32 m0, s10
	ds_read_b128 v[226:229], v173
	ds_read_b128 v[230:233], v173 offset:1024
	ds_read_b128 v[234:237], v173 offset:2048
	ds_read_b128 v[238:241], v173 offset:3072
	global_load_lds_dwordx4 v[248:249], off
	v_lshl_add_u64 v[248:249], v[134:135], 0, s[6:7]
	v_readfirstlane_b32 s10, v147
	v_lshl_add_u64 v[250:251], v[248:249], 0, s[8:9]
	s_mov_b32 m0, s10
	s_nop 0
	global_load_lds_dwordx4 v[250:251], off
	s_barrier
	s_waitcnt lgkmcnt(0)
	v_mfma_f32_16x16x32_bf16 v[94:97], v[194:197], v[226:229], v[94:97]
	v_mfma_f32_16x16x32_bf16 v[90:93], v[194:197], v[234:237], v[90:93]
	v_mfma_f32_16x16x32_bf16 v[86:89], v[202:205], v[226:229], v[86:89]
	v_mfma_f32_16x16x32_bf16 v[82:85], v[202:205], v[234:237], v[82:85]
	v_mfma_f32_16x16x32_bf16 v[78:81], v[210:213], v[226:229], v[78:81]
	v_mfma_f32_16x16x32_bf16 v[74:77], v[210:213], v[234:237], v[74:77]
	v_mfma_f32_16x16x32_bf16 v[70:73], v[218:221], v[226:229], v[70:73]
	v_mfma_f32_16x16x32_bf16 v[66:69], v[218:221], v[234:237], v[66:69]
	v_mfma_f32_16x16x32_bf16 v[94:97], v[198:201], v[230:233], v[94:97]
	v_mfma_f32_16x16x32_bf16 v[90:93], v[198:201], v[238:241], v[90:93]
	v_mfma_f32_16x16x32_bf16 v[86:89], v[206:209], v[230:233], v[86:89]
	v_mfma_f32_16x16x32_bf16 v[82:85], v[206:209], v[238:241], v[82:85]
	v_mfma_f32_16x16x32_bf16 v[78:81], v[214:217], v[230:233], v[78:81]
	v_mfma_f32_16x16x32_bf16 v[74:77], v[214:217], v[238:241], v[74:77]
	v_mfma_f32_16x16x32_bf16 v[70:73], v[222:225], v[230:233], v[70:73]
	v_mfma_f32_16x16x32_bf16 v[66:69], v[222:225], v[238:241], v[66:69]
	v_readfirstlane_b32 s10, v160
	v_lshl_add_u64 v[250:251], v[242:243], 0, s[74:75]
	s_mov_b32 m0, s10
	v_readfirstlane_b32 s10, v161
	s_barrier
	ds_read_b128 v[194:197], v145 offset:16384
	ds_read_b128 v[198:201], v145 offset:17408
	ds_read_b128 v[202:205], v144 offset:16384
	ds_read_b128 v[206:209], v144 offset:17408
	ds_read_b128 v[210:213], v143 offset:16384
	ds_read_b128 v[214:217], v143 offset:17408
	ds_read_b128 v[218:221], v142 offset:16384
	ds_read_b128 v[222:225], v142 offset:17408
	global_load_lds_dwordx4 v[250:251], off
	v_lshl_add_u64 v[250:251], v[244:245], 0, s[74:75]
	s_mov_b32 m0, s10
	s_nop 0
	global_load_lds_dwordx4 v[250:251], off
	s_barrier
	s_waitcnt lgkmcnt(0)
	v_mfma_f32_16x16x32_bf16 v[62:65], v[194:197], v[178:181], v[62:65]
	v_mfma_f32_16x16x32_bf16 v[58:61], v[194:197], v[186:189], v[58:61]
	v_mfma_f32_16x16x32_bf16 v[54:57], v[202:205], v[178:181], v[54:57]
	v_mfma_f32_16x16x32_bf16 v[50:53], v[202:205], v[186:189], v[50:53]
	v_mfma_f32_16x16x32_bf16 v[46:49], v[210:213], v[178:181], v[46:49]
	v_mfma_f32_16x16x32_bf16 v[42:45], v[210:213], v[186:189], v[42:45]
	v_mfma_f32_16x16x32_bf16 v[38:41], v[218:221], v[178:181], v[38:41]
	v_mfma_f32_16x16x32_bf16 v[34:37], v[218:221], v[186:189], v[34:37]
	v_mfma_f32_16x16x32_bf16 v[62:65], v[198:201], v[182:185], v[62:65]
	v_mfma_f32_16x16x32_bf16 v[58:61], v[198:201], v[190:193], v[58:61]
	v_mfma_f32_16x16x32_bf16 v[54:57], v[206:209], v[182:185], v[54:57]
	v_mfma_f32_16x16x32_bf16 v[50:53], v[206:209], v[190:193], v[50:53]
	v_mfma_f32_16x16x32_bf16 v[46:49], v[214:217], v[182:185], v[46:49]
	v_mfma_f32_16x16x32_bf16 v[42:45], v[214:217], v[190:193], v[42:45]
	v_mfma_f32_16x16x32_bf16 v[38:41], v[222:225], v[182:185], v[38:41]
	v_mfma_f32_16x16x32_bf16 v[34:37], v[222:225], v[190:193], v[34:37]
	s_barrier
; #define STA(P, br, kt) STAGE(P, A, aoff0, aoff1, lda, br, kt)
; #define STB(P, br, kt) STAGE(P, Bt, boff0, boff1, ldb, br, kt)
; #define LDA(dst, b, h) _Pragma("unroll") for (int m = 0; m < 4; ++m) _Pragma("unroll") for (int k = 0; k < 2; ++k) \
;     dst[m][k] = *reinterpret_cast<const bf16x8*>((char*)SA(b, h) + lds_byte(wr * 64 + m * 16 + fr, k * 32 + fq * 8))
; #define LDB(dst, b, h) _Pragma("unroll") for (int n = 0; n < 2; ++n) _Pragma("unroll") for (int k = 0; k < 2; ++k) \
;     dst[n][k] = *reinterpret_cast<const bf16x8*>((char*)SB(b, h) + lds_byte(wc * 32 + n * 16 + fr, k * 32 + fq * 8))
; #define MMA(ai, bj, At, Bq) do { __builtin_amdgcn_s_setprio(1); \
;     _Pragma("unroll") for (int m = 0; m < 4; ++m) _Pragma("unroll") for (int n = 0; n < 2; ++n) _Pragma("unroll") for (int k = 0; k < 2; ++k) \
;       acc[ai][bj][m][n] = __builtin_amdgcn_mfma_f32_16x16x32_bf16(At[m][k], Bq[n][k], acc[ai][bj][m][n], 0, 0, 0); \
;     __builtin_amdgcn_s_setprio(0); } while (0)
; #define WAIT_V(n) asm volatile("s_waitcnt vmcnt(" #n ")" ::: "memory")
; #define WAIT_L(n) asm volatile("s_waitcnt lgkmcnt(" #n ")" ::: "memory")
; #define BAR __builtin_amdgcn_s_barrier()
; #define SCHED __builtin_amdgcn_sched_barrier(0)
; __device__ __forceinline__ void gemm256(const u16* __restrict__ A, int lda, const u16* __restrict__ Bt, int ldb, int K,
;                                         f32x4 (&acc)[2][2][4][2], const int g_wid) {
;     ...
;     STB(SB(0, 1), HALF, t + 2);
;     WAIT_V(6); BAR; MMA(1, 1, At, B1); BAR;
;     LDB(B0, 1, 0); SCHED; LDA(At, 1, 0); STA(SA(0, 1), HALF, t + 2);
;     WAIT_L(8); BAR; WAIT_L(0); MMA(0, 0, At, B0); BAR; SCHED;
;     LDB(B1, 1, 1); STB(SB(1, 0), 0, t + 3);
;     BAR; WAIT_L(0); MMA(0, 1, At, B1); BAR;
;     LDA(At, 1, 1); STA(SA(1, 0), 0, t + 3);
;     BAR; WAIT_L(0); MMA(1, 0, At, B0); BAR; SCHED;
	v_readfirstlane_b32 s10, v162
	v_lshl_add_u64 v[178:179], v[246:247], 0, s[16:17]
	s_mov_b32 m0, s10
	v_readfirstlane_b32 s10, v163
	global_load_lds_dwordx4 v[178:179], off
	v_lshl_add_u64 v[178:179], v[248:249], 0, s[16:17]
	s_mov_b32 m0, s10
	s_nop 0
	global_load_lds_dwordx4 v[178:179], off
	s_waitcnt vmcnt(6)
	s_barrier
	v_mfma_f32_16x16x32_bf16 v[30:33], v[194:197], v[226:229], v[30:33]
	v_mfma_f32_16x16x32_bf16 v[26:29], v[194:197], v[234:237], v[26:29]
	v_mfma_f32_16x16x32_bf16 v[22:25], v[202:205], v[226:229], v[22:25]
	v_mfma_f32_16x16x32_bf16 v[18:21], v[202:205], v[234:237], v[18:21]
	v_mfma_f32_16x16x32_bf16 v[14:17], v[210:213], v[226:229], v[14:17]
	v_mfma_f32_16x16x32_bf16 v[10:13], v[210:213], v[234:237], v[10:13]
	v_mfma_f32_16x16x32_bf16 v[6:9], v[218:221], v[226:229], v[6:9]
	v_mfma_f32_16x16x32_bf16 v[2:5], v[218:221], v[234:237], v[2:5]
	v_mfma_f32_16x16x32_bf16 v[30:33], v[198:201], v[230:233], v[30:33]
	v_mfma_f32_16x16x32_bf16 v[26:29], v[198:201], v[238:241], v[26:29]
	v_mfma_f32_16x16x32_bf16 v[22:25], v[206:209], v[230:233], v[22:25]
	v_mfma_f32_16x16x32_bf16 v[18:21], v[206:209], v[238:241], v[18:21]
	v_mfma_f32_16x16x32_bf16 v[14:17], v[214:217], v[230:233], v[14:17]
	v_mfma_f32_16x16x32_bf16 v[10:13], v[214:217], v[238:241], v[10:13]
	v_mfma_f32_16x16x32_bf16 v[6:9], v[222:225], v[230:233], v[6:9]
	v_mfma_f32_16x16x32_bf16 v[2:5], v[222:225], v[238:241], v[2:5]
	s_barrier
	ds_read_b128 v[178:181], v165
	ds_read_b128 v[182:185], v165 offset:1024
	ds_read_b128 v[186:189], v165 offset:2048
	ds_read_b128 v[190:193], v165 offset:3072
	v_readfirstlane_b32 s10, v164
	v_lshl_add_u64 v[226:227], v[242:243], 0, s[78:79]
	s_mov_b32 m0, s10
	v_readfirstlane_b32 s10, v166
	ds_read_b128 v[194:197], v145 offset:32768
	ds_read_b128 v[198:201], v145 offset:33792
	ds_read_b128 v[202:205], v144 offset:32768
	ds_read_b128 v[206:209], v144 offset:33792
	ds_read_b128 v[210:213], v143 offset:32768
	ds_read_b128 v[214:217], v143 offset:33792
	ds_read_b128 v[218:221], v142 offset:32768
	ds_read_b128 v[222:225], v142 offset:33792
	global_load_lds_dwordx4 v[226:227], off
	v_lshl_add_u64 v[226:227], v[244:245], 0, s[78:79]
	s_mov_b32 m0, s10
	s_nop 0
	global_load_lds_dwordx4 v[226:227], off
	s_waitcnt lgkmcnt(8)
	s_barrier
	s_waitcnt lgkmcnt(0)
	v_mfma_f32_16x16x32_bf16 v[126:129], v[194:197], v[178:181], v[126:129]
	v_mfma_f32_16x16x32_bf16 v[122:125], v[194:197], v[186:189], v[122:125]
	v_mfma_f32_16x16x32_bf16 v[118:121], v[202:205], v[178:181], v[118:121]
	v_mfma_f32_16x16x32_bf16 v[114:117], v[202:205], v[186:189], v[114:117]
	v_mfma_f32_16x16x32_bf16 v[110:113], v[210:213], v[178:181], v[110:113]
	v_mfma_f32_16x16x32_bf16 v[106:109], v[210:213], v[186:189], v[106:109]
	v_mfma_f32_16x16x32_bf16 v[102:105], v[218:221], v[178:181], v[102:105]
	v_mfma_f32_16x16x32_bf16 v[98:101], v[218:221], v[186:189], v[98:101]
	v_mfma_f32_16x16x32_bf16 v[126:129], v[198:201], v[182:185], v[126:129]
	v_mfma_f32_16x16x32_bf16 v[122:125], v[198:201], v[190:193], v[122:125]
	v_mfma_f32_16x16x32_bf16 v[118:121], v[206:209], v[182:185], v[118:121]
	v_mfma_f32_16x16x32_bf16 v[114:117], v[206:209], v[190:193], v[114:117]
	v_mfma_f32_16x16x32_bf16 v[110:113], v[214:217], v[182:185], v[110:113]
	v_mfma_f32_16x16x32_bf16 v[106:109], v[214:217], v[190:193], v[106:109]
	v_mfma_f32_16x16x32_bf16 v[102:105], v[222:225], v[182:185], v[102:105]
	v_mfma_f32_16x16x32_bf16 v[98:101], v[222:225], v[190:193], v[98:101]
	s_barrier
	v_readfirstlane_b32 s10, v167
	v_lshl_add_u64 v[250:251], v[246:247], 0, s[18:19]
	s_mov_b32 m0, s10
	v_readfirstlane_b32 s10, v168
	ds_read_b128 v[226:229], v159
	ds_read_b128 v[230:233], v159 offset:1024
	ds_read_b128 v[234:237], v159 offset:2048
	ds_read_b128 v[238:241], v159 offset:3072
	global_load_lds_dwordx4 v[250:251], off
	v_lshl_add_u64 v[250:251], v[248:249], 0, s[18:19]
	s_mov_b32 m0, s10
	s_nop 0
	global_load_lds_dwordx4 v[250:251], off
	s_barrier
	s_waitcnt lgkmcnt(0)
	v_mfma_f32_16x16x32_bf16 v[94:97], v[194:197], v[226:229], v[94:97]
	v_mfma_f32_16x16x32_bf16 v[90:93], v[194:197], v[234:237], v[90:93]
	v_mfma_f32_16x16x32_bf16 v[86:89], v[202:205], v[226:229], v[86:89]
	v_mfma_f32_16x16x32_bf16 v[82:85], v[202:205], v[234:237], v[82:85]
	v_mfma_f32_16x16x32_bf16 v[78:81], v[210:213], v[226:229], v[78:81]
	v_mfma_f32_16x16x32_bf16 v[74:77], v[210:213], v[234:237], v[74:77]
	v_mfma_f32_16x16x32_bf16 v[70:73], v[218:221], v[226:229], v[70:73]
	v_mfma_f32_16x16x32_bf16 v[66:69], v[218:221], v[234:237], v[66:69]
	v_mfma_f32_16x16x32_bf16 v[94:97], v[198:201], v[230:233], v[94:97]
	v_mfma_f32_16x16x32_bf16 v[90:93], v[198:201], v[238:241], v[90:93]
	v_mfma_f32_16x16x32_bf16 v[86:89], v[206:209], v[230:233], v[86:89]
	v_mfma_f32_16x16x32_bf16 v[82:85], v[206:209], v[238:241], v[82:85]
	v_mfma_f32_16x16x32_bf16 v[78:81], v[214:217], v[230:233], v[78:81]
	v_mfma_f32_16x16x32_bf16 v[74:77], v[214:217], v[238:241], v[74:77]
	v_mfma_f32_16x16x32_bf16 v[70:73], v[222:225], v[230:233], v[70:73]
	v_mfma_f32_16x16x32_bf16 v[66:69], v[222:225], v[238:241], v[66:69]
	v_readfirstlane_b32 s10, v169
	v_lshl_add_u64 v[242:243], v[242:243], 0, s[82:83]
	s_mov_b32 m0, s10
	v_readfirstlane_b32 s10, v170
	s_barrier
	ds_read_b128 v[194:197], v145 offset:49152
	ds_read_b128 v[198:201], v145 offset:50176
	ds_read_b128 v[202:205], v144 offset:49152
	ds_read_b128 v[206:209], v144 offset:50176
	ds_read_b128 v[210:213], v143 offset:49152
	ds_read_b128 v[214:217], v143 offset:50176
	ds_read_b128 v[218:221], v142 offset:49152
	ds_read_b128 v[222:225], v142 offset:50176
	global_load_lds_dwordx4 v[242:243], off
	v_lshl_add_u64 v[242:243], v[244:245], 0, s[82:83]
	s_mov_b32 m0, s10
	s_nop 0
	global_load_lds_dwordx4 v[242:243], off
	s_barrier
; #define STA(P, br, kt) STAGE(P, A, aoff0, aoff1, lda, br, kt)
; #define STB(P, br, kt) STAGE(P, Bt, boff0, boff1, ldb, br, kt)
; #define LDA(dst, b, h) _Pragma("unroll") for (int m = 0; m < 4; ++m) _Pragma("unroll") for (int k = 0; k < 2; ++k) \
;     dst[m][k] = *reinterpret_cast<const bf16x8*>((char*)SA(b, h) + lds_byte(wr * 64 + m * 16 + fr, k * 32 + fq * 8))
; #define LDB(dst, b, h) _Pragma("unroll") for (int n = 0; n < 2; ++n) _Pragma("unroll") for (int k = 0; k < 2; ++k) \
;     dst[n][k] = *reinterpret_cast<const bf16x8*>((char*)SB(b, h) + lds_byte(wc * 32 + n * 16 + fr, k * 32 + fq * 8))
; #define MMA(ai, bj, At, Bq) do { __builtin_amdgcn_s_setprio(1); \
;     _Pragma("unroll") for (int m = 0; m < 4; ++m) _Pragma("unroll") for (int n = 0; n < 2; ++n) _Pragma("unroll") for (int k = 0; k < 2; ++k) \
;       acc[ai][bj][m][n] = __builtin_amdgcn_mfma_f32_16x16x32_bf16(At[m][k], Bq[n][k], acc[ai][bj][m][n], 0, 0, 0); \
;     __builtin_amdgcn_s_setprio(0); } while (0)
; #define WAIT_V(n) asm volatile("s_waitcnt vmcnt(" #n ")" ::: "memory")
; #define WAIT_L(n) asm volatile("s_waitcnt lgkmcnt(" #n ")" ::: "memory")
; #define BAR __builtin_amdgcn_s_barrier()
; #define SCHED __builtin_amdgcn_sched_barrier(0)
; __device__ __forceinline__ void gemm256(const u16* __restrict__ A, int lda, const u16* __restrict__ Bt, int ldb, int K,
;                                         f32x4 (&acc)[2][2][4][2], const int g_wid) {
;     ...
;     BAR; WAIT_L(0); MMA(1, 0, At, B0); BAR; SCHED;
;     STB(SB(1, 1), HALF, t + 3);
;     WAIT_V(6); BAR; MMA(1, 1, At, B1); BAR;
;   }
;   { LDB(B0, 0, 0); LDA(At, 0, 0); STA(SA(1, 1), HALF, nt - 1);
;     BAR; WAIT_L(0); MMA(0, 0, At, B0); BAR;
;     LDB(B1, 0, 1); BAR; WAIT_L(0); MMA(0, 1, At, B1); BAR;
	s_waitcnt lgkmcnt(0)
	v_mfma_f32_16x16x32_bf16 v[62:65], v[194:197], v[178:181], v[62:65]
	v_mfma_f32_16x16x32_bf16 v[58:61], v[194:197], v[186:189], v[58:61]
	v_mfma_f32_16x16x32_bf16 v[54:57], v[202:205], v[178:181], v[54:57]
	v_mfma_f32_16x16x32_bf16 v[50:53], v[202:205], v[186:189], v[50:53]
	v_mfma_f32_16x16x32_bf16 v[46:49], v[210:213], v[178:181], v[46:49]
	v_mfma_f32_16x16x32_bf16 v[42:45], v[210:213], v[186:189], v[42:45]
	v_mfma_f32_16x16x32_bf16 v[38:41], v[218:221], v[178:181], v[38:41]
	v_mfma_f32_16x16x32_bf16 v[34:37], v[218:221], v[186:189], v[34:37]
	v_mfma_f32_16x16x32_bf16 v[62:65], v[198:201], v[182:185], v[62:65]
	v_mfma_f32_16x16x32_bf16 v[58:61], v[198:201], v[190:193], v[58:61]
	v_mfma_f32_16x16x32_bf16 v[54:57], v[206:209], v[182:185], v[54:57]
	v_mfma_f32_16x16x32_bf16 v[50:53], v[206:209], v[190:193], v[50:53]
	v_mfma_f32_16x16x32_bf16 v[46:49], v[214:217], v[182:185], v[46:49]
	v_mfma_f32_16x16x32_bf16 v[42:45], v[214:217], v[190:193], v[42:45]
	v_mfma_f32_16x16x32_bf16 v[38:41], v[222:225], v[182:185], v[38:41]
	v_mfma_f32_16x16x32_bf16 v[34:37], v[222:225], v[190:193], v[34:37]
	s_barrier
	v_readfirstlane_b32 s10, v171
	v_lshl_add_u64 v[178:179], v[246:247], 0, s[20:21]
	s_mov_b32 m0, s10
	v_readfirstlane_b32 s10, v172
	global_load_lds_dwordx4 v[178:179], off
	v_lshl_add_u64 v[178:179], v[248:249], 0, s[20:21]
	s_mov_b32 m0, s10
	s_nop 0
	global_load_lds_dwordx4 v[178:179], off
	s_waitcnt vmcnt(6)
	s_barrier
	v_mfma_f32_16x16x32_bf16 v[30:33], v[194:197], v[226:229], v[30:33]
	v_mfma_f32_16x16x32_bf16 v[26:29], v[194:197], v[234:237], v[26:29]
	v_mfma_f32_16x16x32_bf16 v[22:25], v[202:205], v[226:229], v[22:25]
	v_mfma_f32_16x16x32_bf16 v[18:21], v[202:205], v[234:237], v[18:21]
	v_mfma_f32_16x16x32_bf16 v[14:17], v[210:213], v[226:229], v[14:17]
	v_mfma_f32_16x16x32_bf16 v[10:13], v[210:213], v[234:237], v[10:13]
	v_mfma_f32_16x16x32_bf16 v[6:9], v[218:221], v[226:229], v[6:9]
	v_mfma_f32_16x16x32_bf16 v[2:5], v[218:221], v[234:237], v[2:5]
	v_mfma_f32_16x16x32_bf16 v[30:33], v[198:201], v[230:233], v[30:33]
	v_mfma_f32_16x16x32_bf16 v[26:29], v[198:201], v[238:241], v[26:29]
	v_mfma_f32_16x16x32_bf16 v[22:25], v[206:209], v[230:233], v[22:25]
	v_mfma_f32_16x16x32_bf16 v[18:21], v[206:209], v[238:241], v[18:21]
	v_mfma_f32_16x16x32_bf16 v[14:17], v[214:217], v[230:233], v[14:17]
	v_mfma_f32_16x16x32_bf16 v[10:13], v[214:217], v[238:241], v[10:13]
	v_mfma_f32_16x16x32_bf16 v[6:9], v[222:225], v[230:233], v[6:9]
	v_mfma_f32_16x16x32_bf16 v[2:5], v[222:225], v[238:241], v[2:5]
	s_add_i32 s14, s14, 2
	s_add_u32 s6, s6, 0x100
	s_addc_u32 s7, s7, 0
	s_cmp_lt_u32 s14, 12
	s_cbranch_scc1 .LBB0_136
	s_barrier
	s_add_u32 s6, s12, 0x40780
	s_addc_u32 s7, s13, 0
	v_readfirstlane_b32 s10, v175
	v_lshl_add_u64 v[132:133], v[132:133], 1, s[6:7]
	s_mov_b32 m0, s10
	v_lshl_add_u64 v[130:131], v[130:131], 1, s[6:7]
	v_readfirstlane_b32 s6, v176
	ds_read_b128 v[134:137], v174
	ds_read_b128 v[138:141], v174 offset:1024
	ds_read_b128 v[160:163], v174 offset:2048
	ds_read_b128 v[166:169], v174 offset:3072
	ds_read_b128 v[178:181], v145
	ds_read_b128 v[182:185], v145 offset:1024
	ds_read_b128 v[186:189], v144
	ds_read_b128 v[190:193], v144 offset:1024
	ds_read_b128 v[194:197], v143
	ds_read_b128 v[198:201], v143 offset:1024
	ds_read_b128 v[202:205], v142
	ds_read_b128 v[206:209], v142 offset:1024
	global_load_lds_dwordx4 v[132:133], off
	s_mov_b32 m0, s6
	s_nop 0
	global_load_lds_dwordx4 v[130:131], off
	s_barrier
	s_waitcnt lgkmcnt(0)
	v_mfma_f32_16x16x32_bf16 v[126:129], v[178:181], v[134:137], v[126:129]
	v_mfma_f32_16x16x32_bf16 v[122:125], v[178:181], v[160:163], v[122:125]
	v_mfma_f32_16x16x32_bf16 v[118:121], v[186:189], v[134:137], v[118:121]
	v_mfma_f32_16x16x32_bf16 v[114:117], v[186:189], v[160:163], v[114:117]
	v_mfma_f32_16x16x32_bf16 v[110:113], v[194:197], v[134:137], v[110:113]
	v_mfma_f32_16x16x32_bf16 v[106:109], v[194:197], v[160:163], v[106:109]
	v_mfma_f32_16x16x32_bf16 v[102:105], v[202:205], v[134:137], v[102:105]
	v_mfma_f32_16x16x32_bf16 v[98:101], v[202:205], v[160:163], v[98:101]
	v_mfma_f32_16x16x32_bf16 v[126:129], v[182:185], v[138:141], v[126:129]
	v_mfma_f32_16x16x32_bf16 v[122:125], v[182:185], v[166:169], v[122:125]
	v_mfma_f32_16x16x32_bf16 v[118:121], v[190:193], v[138:141], v[118:121]
	v_mfma_f32_16x16x32_bf16 v[114:117], v[190:193], v[166:169], v[114:117]
	v_mfma_f32_16x16x32_bf16 v[110:113], v[198:201], v[138:141], v[110:113]
	v_mfma_f32_16x16x32_bf16 v[106:109], v[198:201], v[166:169], v[106:109]
	v_mfma_f32_16x16x32_bf16 v[102:105], v[206:209], v[138:141], v[102:105]
	v_mfma_f32_16x16x32_bf16 v[98:101], v[206:209], v[166:169], v[98:101]
	s_barrier
	ds_read_b128 v[130:133], v173
	ds_read_b128 v[174:177], v173 offset:1024
	ds_read_b128 v[210:213], v173 offset:2048
	ds_read_b128 v[170:173], v173 offset:3072
	s_barrier
	s_waitcnt lgkmcnt(0)
	v_mfma_f32_16x16x32_bf16 v[86:89], v[186:189], v[130:133], v[86:89]
	v_mfma_f32_16x16x32_bf16 v[74:77], v[194:197], v[210:213], v[74:77]
	v_mfma_f32_16x16x32_bf16 v[70:73], v[202:205], v[130:133], v[70:73]
	v_mfma_f32_16x16x32_bf16 v[66:69], v[202:205], v[210:213], v[66:69]
	v_mfma_f32_16x16x32_bf16 v[94:97], v[178:181], v[130:133], v[94:97]
	v_mfma_f32_16x16x32_bf16 v[90:93], v[178:181], v[210:213], v[90:93]
	v_mfma_f32_16x16x32_bf16 v[86:89], v[190:193], v[174:177], v[86:89]
	v_mfma_f32_16x16x32_bf16 v[82:85], v[186:189], v[210:213], v[82:85]
	v_mfma_f32_16x16x32_bf16 v[78:81], v[194:197], v[130:133], v[78:81]
	v_mfma_f32_16x16x32_bf16 v[74:77], v[198:201], v[170:173], v[74:77]
	v_mfma_f32_16x16x32_bf16 v[70:73], v[206:209], v[174:177], v[70:73]
	v_mfma_f32_16x16x32_bf16 v[66:69], v[206:209], v[170:173], v[66:69]
	v_mfma_f32_16x16x32_bf16 v[214:217], v[182:185], v[174:177], v[94:97]
	v_mfma_f32_16x16x32_bf16 v[178:181], v[182:185], v[170:173], v[90:93]
	v_mfma_f32_16x16x32_bf16 v[182:185], v[190:193], v[170:173], v[82:85]
	v_mfma_f32_16x16x32_bf16 v[186:189], v[198:201], v[174:177], v[78:81]
	s_barrier
; #define LDA(dst, b, h) _Pragma("unroll") for (int m = 0; m < 4; ++m) _Pragma("unroll") for (int k = 0; k < 2; ++k) \
;     dst[m][k] = *reinterpret_cast<const bf16x8*>((char*)SA(b, h) + lds_byte(wr * 64 + m * 16 + fr, k * 32 + fq * 8))
; #define LDB(dst, b, h) _Pragma("unroll") for (int n = 0; n < 2; ++n) _Pragma("unroll") for (int k = 0; k < 2; ++k) \
;     dst[n][k] = *reinterpret_cast<const bf16x8*>((char*)SB(b, h) + lds_byte(wc * 32 + n * 16 + fr, k * 32 + fq * 8))
; #define MMA(ai, bj, At, Bq) do { __builtin_amdgcn_s_setprio(1); \
;     _Pragma("unroll") for (int m = 0; m < 4; ++m) _Pragma("unroll") for (int n = 0; n < 2; ++n) _Pragma("unroll") for (int k = 0; k < 2; ++k) \
;       acc[ai][bj][m][n] = __builtin_amdgcn_mfma_f32_16x16x32_bf16(At[m][k], Bq[n][k], acc[ai][bj][m][n], 0, 0, 0); \
;     __builtin_amdgcn_s_setprio(0); } while (0)
; #define WAIT_V(n) asm volatile("s_waitcnt vmcnt(" #n ")" ::: "memory")
; #define WAIT_L(n) asm volatile("s_waitcnt lgkmcnt(" #n ")" ::: "memory")
; #define BAR __builtin_amdgcn_s_barrier()
; __device__ __forceinline__ void gemm256(const u16* __restrict__ A, int lda, const u16* __restrict__ Bt, int ldb, int K,
;                                         f32x4 (&acc)[2][2][4][2], const int g_wid) {
;     ...
;     LDA(At, 0, 1); WAIT_V(4); BAR; WAIT_L(0); MMA(1, 0, At, B0); MMA(1, 1, At, B1); BAR; }
;   { LDB(B0, 1, 0); LDA(At, 1, 0); WAIT_V(2); BAR; WAIT_L(0); MMA(0, 0, At, B0); BAR;
	s_nop 0
	ds_read_b128 v[78:81], v145 offset:16384
	ds_read_b128 v[82:85], v145 offset:17408
	ds_read_b128 v[90:93], v144 offset:16384
	ds_read_b128 v[94:97], v144 offset:17408
	ds_read_b128 v[190:193], v143 offset:16384
	ds_read_b128 v[194:197], v143 offset:17408
	ds_read_b128 v[198:201], v142 offset:16384
	ds_read_b128 v[202:205], v142 offset:17408
	s_waitcnt vmcnt(4)
	s_barrier
	s_waitcnt lgkmcnt(0)
	v_mfma_f32_16x16x32_bf16 v[54:57], v[90:93], v[134:137], v[54:57]
	v_mfma_f32_16x16x32_bf16 v[42:45], v[190:193], v[160:163], v[42:45]
	v_mfma_f32_16x16x32_bf16 v[38:41], v[198:201], v[134:137], v[38:41]
	v_mfma_f32_16x16x32_bf16 v[34:37], v[198:201], v[160:163], v[34:37]
	v_mfma_f32_16x16x32_bf16 v[62:65], v[78:81], v[134:137], v[62:65]
	v_mfma_f32_16x16x32_bf16 v[58:61], v[78:81], v[160:163], v[58:61]
	v_mfma_f32_16x16x32_bf16 v[54:57], v[94:97], v[138:141], v[54:57]
	v_mfma_f32_16x16x32_bf16 v[50:53], v[90:93], v[160:163], v[50:53]
	v_mfma_f32_16x16x32_bf16 v[46:49], v[190:193], v[134:137], v[46:49]
	v_mfma_f32_16x16x32_bf16 v[42:45], v[194:197], v[166:169], v[42:45]
	v_mfma_f32_16x16x32_bf16 v[38:41], v[202:205], v[138:141], v[38:41]
	v_mfma_f32_16x16x32_bf16 v[34:37], v[202:205], v[166:169], v[34:37]
	v_mfma_f32_16x16x32_bf16 v[206:209], v[82:85], v[138:141], v[62:65]
	v_mfma_f32_16x16x32_bf16 v[218:221], v[82:85], v[166:169], v[58:61]
	v_mfma_f32_16x16x32_bf16 v[222:225], v[94:97], v[166:169], v[50:53]
	v_mfma_f32_16x16x32_bf16 v[226:229], v[194:197], v[138:141], v[46:49]
	v_mfma_f32_16x16x32_bf16 v[2:5], v[198:201], v[210:213], v[2:5]
	v_mfma_f32_16x16x32_bf16 v[30:33], v[78:81], v[130:133], v[30:33]
	v_mfma_f32_16x16x32_bf16 v[26:29], v[78:81], v[210:213], v[26:29]
	v_mfma_f32_16x16x32_bf16 v[22:25], v[90:93], v[130:133], v[22:25]
	v_mfma_f32_16x16x32_bf16 v[18:21], v[90:93], v[210:213], v[18:21]
	v_mfma_f32_16x16x32_bf16 v[14:17], v[190:193], v[130:133], v[14:17]
	v_mfma_f32_16x16x32_bf16 v[10:13], v[190:193], v[210:213], v[10:13]
	v_mfma_f32_16x16x32_bf16 v[6:9], v[198:201], v[130:133], v[6:9]
	v_mfma_f32_16x16x32_bf16 v[2:5], v[202:205], v[170:173], v[2:5]
	v_mfma_f32_16x16x32_bf16 v[134:137], v[82:85], v[174:177], v[30:33]
	v_mfma_f32_16x16x32_bf16 v[138:141], v[82:85], v[170:173], v[26:29]
	v_mfma_f32_16x16x32_bf16 v[160:163], v[94:97], v[174:177], v[22:25]
	v_mfma_f32_16x16x32_bf16 v[166:169], v[94:97], v[170:173], v[18:21]
	v_mfma_f32_16x16x32_bf16 v[230:233], v[194:197], v[174:177], v[14:17]
	v_mfma_f32_16x16x32_bf16 v[190:193], v[194:197], v[170:173], v[10:13]
	v_mfma_f32_16x16x32_bf16 v[130:133], v[202:205], v[174:177], v[6:9]
	s_barrier
	s_nop 0
	ds_read_b128 v[6:9], v165
	ds_read_b128 v[10:13], v165 offset:1024
	ds_read_b128 v[22:25], v165 offset:2048
	ds_read_b128 v[170:173], v165 offset:3072
	ds_read_b128 v[14:17], v145 offset:32768
	ds_read_b128 v[18:21], v145 offset:33792
	ds_read_b128 v[26:29], v144 offset:32768
	ds_read_b128 v[46:49], v144 offset:33792
	ds_read_b128 v[174:177], v143 offset:32768
	ds_read_b128 v[194:197], v143 offset:33792
	ds_read_b128 v[198:201], v142 offset:32768
	ds_read_b128 v[202:205], v142 offset:33792
	s_waitcnt vmcnt(2)
	s_barrier
	s_waitcnt lgkmcnt(0)
	v_mfma_f32_16x16x32_bf16 v[30:33], v[14:17], v[6:9], v[126:129]
	v_mfma_f32_16x16x32_bf16 v[126:129], v[18:21], v[10:13], v[30:33]
	v_mfma_f32_16x16x32_bf16 v[30:33], v[14:17], v[22:25], v[122:125]
	v_mfma_f32_16x16x32_bf16 v[94:97], v[18:21], v[170:173], v[30:33]
	v_mfma_f32_16x16x32_bf16 v[30:33], v[26:29], v[6:9], v[118:121]
	v_mfma_f32_16x16x32_bf16 v[122:125], v[46:49], v[10:13], v[30:33]
	v_mfma_f32_16x16x32_bf16 v[30:33], v[26:29], v[22:25], v[114:117]
	v_mfma_f32_16x16x32_bf16 v[90:93], v[46:49], v[170:173], v[30:33]
	v_mfma_f32_16x16x32_bf16 v[30:33], v[174:177], v[6:9], v[110:113]
	v_mfma_f32_16x16x32_bf16 v[114:117], v[194:197], v[10:13], v[30:33]
	v_mfma_f32_16x16x32_bf16 v[30:33], v[174:177], v[22:25], v[106:109]
	v_mfma_f32_16x16x32_bf16 v[82:85], v[194:197], v[170:173], v[30:33]
	v_mfma_f32_16x16x32_bf16 v[30:33], v[198:201], v[6:9], v[102:105]
	v_mfma_f32_16x16x32_bf16 v[110:113], v[202:205], v[10:13], v[30:33]
	v_mfma_f32_16x16x32_bf16 v[30:33], v[198:201], v[22:25], v[98:101]
	v_mfma_f32_16x16x32_bf16 v[78:81], v[202:205], v[170:173], v[30:33]
	s_barrier
; #define LDA(dst, b, h) _Pragma("unroll") for (int m = 0; m < 4; ++m) _Pragma("unroll") for (int k = 0; k < 2; ++k) \
;     dst[m][k] = *reinterpret_cast<const bf16x8*>((char*)SA(b, h) + lds_byte(wr * 64 + m * 16 + fr, k * 32 + fq * 8))
; #define LDB(dst, b, h) _Pragma("unroll") for (int n = 0; n < 2; ++n) _Pragma("unroll") for (int k = 0; k < 2; ++k) \
;     dst[n][k] = *reinterpret_cast<const bf16x8*>((char*)SB(b, h) + lds_byte(wc * 32 + n * 16 + fr, k * 32 + fq * 8))
; #define MMA(ai, bj, At, Bq) do { __builtin_amdgcn_s_setprio(1); \
;     _Pragma("unroll") for (int m = 0; m < 4; ++m) _Pragma("unroll") for (int n = 0; n < 2; ++n) _Pragma("unroll") for (int k = 0; k < 2; ++k) \
;       acc[ai][bj][m][n] = __builtin_amdgcn_mfma_f32_16x16x32_bf16(At[m][k], Bq[n][k], acc[ai][bj][m][n], 0, 0, 0); \
;     __builtin_amdgcn_s_setprio(0); } while (0)
; #define WAIT_V(n) asm volatile("s_waitcnt vmcnt(" #n ")" ::: "memory")
; #define WAIT_L(n) asm volatile("s_waitcnt lgkmcnt(" #n ")" ::: "memory")
; #define BAR __builtin_amdgcn_s_barrier()
; __device__ __forceinline__ void gemm256(const u16* __restrict__ A, int lda, const u16* __restrict__ Bt, int ldb, int K,
;                                         f32x4 (&acc)[2][2][4][2], const int g_wid) {
;     ...
;     LDB(B1, 1, 1); WAIT_V(0); BAR; WAIT_L(0); MMA(0, 1, At, B1); BAR;
;     LDA(At, 1, 1); BAR; WAIT_L(0); MMA(1, 0, At, B0); MMA(1, 1, At, B1); BAR; }
;   if (wr == 0) BAR;
	ds_read_b128 v[210:213], v159
	ds_read_b128 v[234:237], v159 offset:1024
	ds_read_b128 v[238:241], v159 offset:2048
	ds_read_b128 v[242:245], v159 offset:3072
	s_waitcnt vmcnt(0)
	s_barrier
	s_waitcnt lgkmcnt(0)
	v_mfma_f32_16x16x32_bf16 v[30:33], v[14:17], v[210:213], v[214:217]
	v_mfma_f32_16x16x32_bf16 v[14:17], v[14:17], v[238:241], v[178:181]
	v_mfma_f32_16x16x32_bf16 v[62:65], v[18:21], v[234:237], v[30:33]
	v_mfma_f32_16x16x32_bf16 v[30:33], v[18:21], v[242:245], v[14:17]
	v_mfma_f32_16x16x32_bf16 v[14:17], v[26:29], v[210:213], v[86:89]
	v_mfma_f32_16x16x32_bf16 v[58:61], v[46:49], v[234:237], v[14:17]
	v_mfma_f32_16x16x32_bf16 v[14:17], v[26:29], v[238:241], v[182:185]
	v_mfma_f32_16x16x32_bf16 v[26:29], v[46:49], v[242:245], v[14:17]
	v_mfma_f32_16x16x32_bf16 v[14:17], v[174:177], v[210:213], v[186:189]
	v_mfma_f32_16x16x32_bf16 v[50:53], v[194:197], v[234:237], v[14:17]
	v_mfma_f32_16x16x32_bf16 v[14:17], v[174:177], v[238:241], v[74:77]
	v_mfma_f32_16x16x32_bf16 v[18:21], v[194:197], v[242:245], v[14:17]
	v_mfma_f32_16x16x32_bf16 v[14:17], v[198:201], v[210:213], v[70:73]
	v_mfma_f32_16x16x32_bf16 v[46:49], v[202:205], v[234:237], v[14:17]
	v_mfma_f32_16x16x32_bf16 v[14:17], v[198:201], v[238:241], v[66:69]
	v_mfma_f32_16x16x32_bf16 v[14:17], v[202:205], v[242:245], v[14:17]
	s_barrier
	ds_read_b128 v[174:177], v145 offset:49152
	ds_read_b128 v[178:181], v145 offset:50176
	ds_read_b128 v[182:185], v144 offset:49152
	ds_read_b128 v[144:147], v144 offset:50176
	ds_read_b128 v[186:189], v143 offset:49152
	ds_read_b128 v[194:197], v143 offset:50176
	ds_read_b128 v[198:201], v142 offset:49152
	ds_read_b128 v[202:205], v142 offset:50176
	s_barrier
	s_waitcnt lgkmcnt(0)
	v_mfma_f32_16x16x32_bf16 v[54:57], v[182:185], v[6:9], v[54:57]
	v_mfma_f32_16x16x32_bf16 v[106:109], v[144:147], v[10:13], v[54:57]
	v_mfma_f32_16x16x32_bf16 v[54:57], v[182:185], v[22:25], v[222:225]
	v_mfma_f32_16x16x32_bf16 v[66:69], v[174:177], v[6:9], v[206:209]
	v_mfma_f32_16x16x32_bf16 v[74:77], v[144:147], v[170:173], v[54:57]
	v_mfma_f32_16x16x32_bf16 v[54:57], v[186:189], v[6:9], v[226:229]
	v_mfma_f32_16x16x32_bf16 v[6:9], v[198:201], v[6:9], v[38:41]
	v_mfma_f32_16x16x32_bf16 v[118:121], v[178:181], v[10:13], v[66:69]
	v_mfma_f32_16x16x32_bf16 v[66:69], v[174:177], v[22:25], v[218:221]
	v_mfma_f32_16x16x32_bf16 v[42:45], v[186:189], v[22:25], v[42:45]
	v_mfma_f32_16x16x32_bf16 v[98:101], v[202:205], v[10:13], v[6:9]
	v_mfma_f32_16x16x32_bf16 v[6:9], v[198:201], v[22:25], v[34:37]
	v_mfma_f32_16x16x32_bf16 v[86:89], v[178:181], v[170:173], v[66:69]
	v_mfma_f32_16x16x32_bf16 v[102:105], v[194:197], v[10:13], v[54:57]
	v_mfma_f32_16x16x32_bf16 v[70:73], v[194:197], v[170:173], v[42:45]
	v_mfma_f32_16x16x32_bf16 v[66:69], v[202:205], v[170:173], v[6:9]
	v_mfma_f32_16x16x32_bf16 v[6:9], v[174:177], v[210:213], v[134:137]
	v_mfma_f32_16x16x32_bf16 v[54:57], v[178:181], v[234:237], v[6:9]
	v_mfma_f32_16x16x32_bf16 v[6:9], v[174:177], v[238:241], v[138:141]
	v_mfma_f32_16x16x32_bf16 v[22:25], v[178:181], v[242:245], v[6:9]
	v_mfma_f32_16x16x32_bf16 v[6:9], v[182:185], v[210:213], v[160:163]
	v_mfma_f32_16x16x32_bf16 v[42:45], v[144:147], v[234:237], v[6:9]
	v_mfma_f32_16x16x32_bf16 v[6:9], v[182:185], v[238:241], v[166:169]
	v_mfma_f32_16x16x32_bf16 v[10:13], v[144:147], v[242:245], v[6:9]
	v_mfma_f32_16x16x32_bf16 v[6:9], v[186:189], v[210:213], v[230:233]
	v_mfma_f32_16x16x32_bf16 v[38:41], v[194:197], v[234:237], v[6:9]
	v_mfma_f32_16x16x32_bf16 v[6:9], v[186:189], v[238:241], v[190:193]
	v_mfma_f32_16x16x32_bf16 v[34:37], v[198:201], v[210:213], v[130:133]
	v_mfma_f32_16x16x32_bf16 v[2:5], v[198:201], v[238:241], v[2:5]
	v_mfma_f32_16x16x32_bf16 v[6:9], v[194:197], v[242:245], v[6:9]
	v_mfma_f32_16x16x32_bf16 v[34:37], v[202:205], v[234:237], v[34:37]
	v_mfma_f32_16x16x32_bf16 v[2:5], v[202:205], v[242:245], v[2:5]
	s_setprio 0
	s_movk_i32 s6, 0x100
	v_cmp_gt_u32_e32 vcc, s6, v0
	s_barrier
	s_and_saveexec_b64 s[6:7], vcc
	s_cbranch_execz .LBB0_139
	s_barrier

; #define hw_tid() ((g_wid << 6) | hw_lane())
; #define STA(P, br, kt) STAGE(P, A, aoff0, aoff1, lda, br, kt)
; #define STB(P, br, kt) STAGE(P, Bt, boff0, boff1, ldb, br, kt)
; #define WAIT_V(n) asm volatile("s_waitcnt vmcnt(" #n ")" ::: "memory")
; #define BAR __builtin_amdgcn_s_barrier()
; __device__ __forceinline__ void gemm256(const u16* __restrict__ A, int lda, const u16* __restrict__ Bt, int ldb, int K,
;                                         f32x4 (&acc)[2][2][4][2], const int g_wid) {
;   int tid = hw_tid(); asm volatile("" : "+v"(tid));
;   const int wid = tid >> 6, lane = tid & 63, wr = wid >> 2, wc = wid & 3, fr = lane & 15, fq = lane >> 4;
;   int r0, c0, r1, c1;
;   stage_rc(tid * 16, r0, c0);
;   stage_rc(tid * 16 + 8192, r1, c1);
;   const int aoff0 = r0 * lda + c0, aoff1 = r1 * lda + c1, boff0 = r0 * ldb + c0, boff1 = r1 * ldb + c1;
;   bf16x8 At[4][2], B0[2][2], B1[2][2];
;   const int nt = K / BK;
;   STB(SB(0, 0), 0, 0); STA(SA(0, 0), 0, 0);
;   STB(SB(0, 1), HALF, 0); STA(SA(0, 1), HALF, 0);
;   if (wr == 1) BAR;
;   WAIT_V(4); BAR;
;   STB(SB(1, 0), 0, 1); STA(SA(1, 0), 0, 1); STB(SB(1, 1), HALF, 1);
;   WAIT_V(6); BAR;
.LBB0_318:
	s_or_b64 exec, exec, s[24:25]
	v_readlane_b32 s13, v254, 42
	s_mov_b64 s[24:25], 0x80
	v_lshl_add_u64 v[2:3], v[2:3], 0, s[24:25]
	v_add_u32_e32 v169, s13, v16
	v_add_u32_e32 v170, 0x2000, v169
	v_readfirstlane_b32 s11, v169
	s_mov_b32 m0, s11
	v_readfirstlane_b32 s11, v170
	v_add_u32_e32 v171, 0x8000, v161
	s_waitcnt vmcnt(4)
	s_barrier
	global_load_lds_dwordx4 v[2:3], off
	v_lshl_add_u64 v[2:3], v[6:7], 0, s[24:25]
	s_mov_b32 m0, s11
	v_readfirstlane_b32 s11, v171
	v_add_u32_e32 v172, 0xa000, v161
	v_readlane_b32 s15, v254, 43
	global_load_lds_dwordx4 v[2:3], off
	v_lshl_add_u64 v[2:3], v[8:9], 0, s[24:25]
	s_mov_b32 m0, s11
	v_readfirstlane_b32 s11, v172
	s_add_u32 s22, s22, 0x40080
	v_add_u32_e32 v173, s15, v16
	global_load_lds_dwordx4 v[2:3], off
	v_lshl_add_u64 v[2:3], v[4:5], 0, s[24:25]
	s_mov_b32 m0, s11
	s_addc_u32 s23, s23, 0
	v_readfirstlane_b32 s11, v173
	v_add_u32_e32 v174, 0x2000, v173
	global_load_lds_dwordx4 v[2:3], off
	v_lshl_add_u64 v[2:3], v[132:133], 1, s[22:23]
	s_mov_b32 m0, s11
	v_readfirstlane_b32 s11, v174
	global_load_lds_dwordx4 v[2:3], off
	v_lshl_add_u64 v[2:3], v[130:131], 1, s[22:23]
	s_mov_b32 m0, s11
	v_and_b32_e32 v20, 15, v0
	global_load_lds_dwordx4 v[2:3], off
	v_lshlrev_b32_e32 v3, 2, v0
	v_and_b32_e32 v21, 48, v0
	v_lshlrev_b32_e32 v2, 6, v20
	v_and_b32_e32 v3, 32, v3
	v_bitop3_b32 v2, v2, v3, v21 bitop3:0x36
	v_readlane_b32 s11, v254, 40
	v_lshlrev_b32_e32 v4, 6, v0
	v_add_u32_e32 v8, s13, v2
	v_add_u32_e32 v6, s11, v2
	v_readlane_b32 s11, v254, 41
	v_add_u32_e32 v9, s15, v2
	v_add_u32_e32 v20, 0, v2
	v_add_u32_e32 v7, s11, v2
	s_movk_i32 s11, 0x3c0
	v_and_or_b32 v2, v4, s11, v21
	v_xad_u32 v21, v2, v3, 0
	v_lshlrev_b32_e32 v2, 13, v15
	v_and_b32_e32 v16, 0x3000, v4
	v_and_b32_e32 v2, 0xffffc000, v2
	v_lshlrev_b32_e32 v4, 13, v10
	v_lshl_add_u32 v2, v17, 10, v2
	v_and_b32_e32 v4, 0xffffc000, v4
	v_or_b32_e32 v2, v2, v18
	s_add_u32 s20, s6, s20
	v_lshl_add_u32 v4, v11, 10, v4
	v_add_u32_sdwa v2, v2, sext(v19) dst_sel:DWORD dst_unused:UNUSED_PAD src0_sel:DWORD src1_sel:WORD_0
	s_addc_u32 s21, s7, s21
	v_or_b32_e32 v4, v4, v13
	v_ashrrev_i32_e32 v3, 31, v2
	v_add_u32_sdwa v4, v4, sext(v14) dst_sel:DWORD dst_unused:UNUSED_PAD src0_sel:DWORD src1_sel:WORD_0
	s_add_u32 s18, s4, s18
	s_waitcnt vmcnt(6)
	v_lshlrev_b32_e32 v12, 13, v12
	v_lshlrev_b64 v[2:3], 1, v[2:3]
	v_ashrrev_i32_e32 v5, 31, v4
	s_addc_u32 s19, s5, s19
	v_or_b32_e32 v22, 0x800, v12
	v_or_b32_e32 v23, 0x1000, v12
	v_or_b32_e32 v24, 0x1800, v12
	v_lshl_add_u64 v[134:135], s[20:21], 0, v[2:3]
	v_lshlrev_b64 v[4:5], 1, v[4:5]
	v_lshl_add_u64 v[138:139], s[18:19], 0, v[2:3]
	v_mov_b32_e32 v2, 0
	v_lshl_add_u64 v[136:137], s[20:21], 0, v[4:5]
	v_lshl_add_u64 v[140:141], s[18:19], 0, v[4:5]
	s_mov_b32 s11, -2
	s_mov_b64 s[18:19], 0
	v_add_u32_e32 v176, v6, v16
	v_add_u32_e32 v147, v20, v12
	v_add_u32_e32 v146, v21, v22
	v_add_u32_e32 v145, v21, v23
	v_add_u32_e32 v144, v21, v24
	v_add_u32_e32 v175, v7, v16
	v_add_u32_e32 v168, v8, v16
	v_add_u32_e32 v162, v9, v16
	v_mov_b32_e32 v3, v2
	v_mov_b32_e32 v4, v2
	v_mov_b32_e32 v5, v2
	v_mov_b32_e32 v6, v2
	v_mov_b32_e32 v7, v2
	v_mov_b32_e32 v8, v2
	v_mov_b32_e32 v9, v2
	v_mov_b32_e32 v10, v2
	v_mov_b32_e32 v11, v2
	v_mov_b32_e32 v12, v2
	v_mov_b32_e32 v13, v2
	v_mov_b32_e32 v14, v2
	v_mov_b32_e32 v15, v2
	v_mov_b32_e32 v16, v2
	v_mov_b32_e32 v17, v2
	v_mov_b32_e32 v18, v2
	v_mov_b32_e32 v19, v2
	v_mov_b32_e32 v20, v2
	v_mov_b32_e32 v21, v2
	v_mov_b32_e32 v22, v2
	v_mov_b32_e32 v23, v2
	v_mov_b32_e32 v24, v2
	v_mov_b32_e32 v25, v2
	v_mov_b32_e32 v26, v2
	v_mov_b32_e32 v27, v2
	v_mov_b32_e32 v28, v2
	v_mov_b32_e32 v29, v2
	v_mov_b32_e32 v30, v2
	v_mov_b32_e32 v31, v2
	v_mov_b32_e32 v32, v2
	v_mov_b32_e32 v33, v2
	v_mov_b32_e32 v34, v2
	v_mov_b32_e32 v35, v2
	v_mov_b32_e32 v36, v2
	v_mov_b32_e32 v37, v2
	v_mov_b32_e32 v38, v2
	v_mov_b32_e32 v39, v2
	v_mov_b32_e32 v40, v2
	v_mov_b32_e32 v41, v2
	v_mov_b32_e32 v42, v2
	v_mov_b32_e32 v43, v2
	v_mov_b32_e32 v44, v2
	v_mov_b32_e32 v45, v2
	v_mov_b32_e32 v46, v2
	v_mov_b32_e32 v47, v2
	v_mov_b32_e32 v48, v2
	v_mov_b32_e32 v49, v2
	v_mov_b32_e32 v50, v2
	v_mov_b32_e32 v51, v2
	v_mov_b32_e32 v52, v2
	v_mov_b32_e32 v53, v2
	v_mov_b32_e32 v54, v2
	v_mov_b32_e32 v55, v2
	v_mov_b32_e32 v56, v2
	v_mov_b32_e32 v57, v2
	v_mov_b32_e32 v58, v2
	v_mov_b32_e32 v59, v2
	v_mov_b32_e32 v60, v2
	v_mov_b32_e32 v61, v2
	v_mov_b32_e32 v62, v2
	v_mov_b32_e32 v63, v2
	v_mov_b32_e32 v64, v2
	v_mov_b32_e32 v65, v2
	v_mov_b32_e32 v66, v2
	v_mov_b32_e32 v67, v2
	v_mov_b32_e32 v68, v2
	v_mov_b32_e32 v69, v2
	v_mov_b32_e32 v70, v2
	v_mov_b32_e32 v71, v2
	v_mov_b32_e32 v72, v2
	v_mov_b32_e32 v73, v2
	v_mov_b32_e32 v74, v2
	v_mov_b32_e32 v75, v2
	v_mov_b32_e32 v76, v2
	v_mov_b32_e32 v77, v2
	v_mov_b32_e32 v78, v2
	v_mov_b32_e32 v79, v2
	v_mov_b32_e32 v80, v2
	v_mov_b32_e32 v81, v2
	v_mov_b32_e32 v82, v2
	v_mov_b32_e32 v83, v2
	v_mov_b32_e32 v84, v2
	v_mov_b32_e32 v85, v2
	v_mov_b32_e32 v86, v2
	v_mov_b32_e32 v87, v2
	v_mov_b32_e32 v88, v2
	v_mov_b32_e32 v89, v2
	v_mov_b32_e32 v90, v2
	v_mov_b32_e32 v91, v2
	v_mov_b32_e32 v92, v2
	v_mov_b32_e32 v93, v2
	v_mov_b32_e32 v94, v2
	v_mov_b32_e32 v95, v2
	v_mov_b32_e32 v96, v2
	v_mov_b32_e32 v97, v2
	v_mov_b32_e32 v98, v2
	v_mov_b32_e32 v99, v2
	v_mov_b32_e32 v100, v2
	v_mov_b32_e32 v101, v2
	v_mov_b32_e32 v102, v2
	v_mov_b32_e32 v103, v2
	v_mov_b32_e32 v104, v2
	v_mov_b32_e32 v105, v2
	v_mov_b32_e32 v106, v2
	v_mov_b32_e32 v107, v2
	v_mov_b32_e32 v108, v2
	v_mov_b32_e32 v109, v2
	v_mov_b32_e32 v110, v2
	v_mov_b32_e32 v111, v2
	v_mov_b32_e32 v112, v2
	v_mov_b32_e32 v113, v2
	v_mov_b32_e32 v114, v2
	v_mov_b32_e32 v115, v2
	v_mov_b32_e32 v116, v2
	v_mov_b32_e32 v117, v2
	v_mov_b32_e32 v118, v2
	v_mov_b32_e32 v119, v2
	v_mov_b32_e32 v120, v2
	v_mov_b32_e32 v121, v2
	v_mov_b32_e32 v122, v2
	v_mov_b32_e32 v123, v2
	v_mov_b32_e32 v124, v2
	v_mov_b32_e32 v125, v2
	v_mov_b32_e32 v126, v2
	v_mov_b32_e32 v127, v2
	v_mov_b32_e32 v128, v2
	v_mov_b32_e32 v129, v2
	.p2align 6
; #define STA(P, br, kt) STAGE(P, A, aoff0, aoff1, lda, br, kt)
; #define STB(P, br, kt) STAGE(P, Bt, boff0, boff1, ldb, br, kt)
; #define LDA(dst, b, h) _Pragma("unroll") for (int m = 0; m < 4; ++m) _Pragma("unroll") for (int k = 0; k < 2; ++k) \
;     dst[m][k] = *reinterpret_cast<const bf16x8*>((char*)SA(b, h) + lds_byte(wr * 64 + m * 16 + fr, k * 32 + fq * 8))
; #define LDB(dst, b, h) _Pragma("unroll") for (int n = 0; n < 2; ++n) _Pragma("unroll") for (int k = 0; k < 2; ++k) \
;     dst[n][k] = *reinterpret_cast<const bf16x8*>((char*)SB(b, h) + lds_byte(wc * 32 + n * 16 + fr, k * 32 + fq * 8))
; #define MMA(ai, bj, At, Bq) do { __builtin_amdgcn_s_setprio(1); \
;     _Pragma("unroll") for (int m = 0; m < 4; ++m) _Pragma("unroll") for (int n = 0; n < 2; ++n) _Pragma("unroll") for (int k = 0; k < 2; ++k) \
;       acc[ai][bj][m][n] = __builtin_amdgcn_mfma_f32_16x16x32_bf16(At[m][k], Bq[n][k], acc[ai][bj][m][n], 0, 0, 0); \
;     __builtin_amdgcn_s_setprio(0); } while (0)
; #define WAIT_L(n) asm volatile("s_waitcnt lgkmcnt(" #n ")" ::: "memory")
; #define BAR __builtin_amdgcn_s_barrier()
; #define SCHED __builtin_amdgcn_sched_barrier(0)
; __device__ __forceinline__ void gemm256(const u16* __restrict__ A, int lda, const u16* __restrict__ Bt, int ldb, int K,
;                                         f32x4 (&acc)[2][2][4][2], const int g_wid) {
;     ...
;     LDB(B0, 0, 0); SCHED; LDA(At, 0, 0); STA(SA(1, 1), HALF, t + 1);
;     WAIT_L(8); BAR; WAIT_L(0); MMA(0, 0, At, B0); BAR; SCHED;
;     LDB(B1, 0, 1); STB(SB(0, 0), 0, t + 2);
;     BAR; WAIT_L(0); MMA(0, 1, At, B1); BAR;
;     LDA(At, 0, 1); STA(SA(0, 0), 0, t + 2);
;     BAR; WAIT_L(0); MMA(1, 0, At, B0); BAR; SCHED;
.LBB0_319:
	s_barrier
	ds_read_b128 v[180:183], v176
	ds_read_b128 v[184:187], v176 offset:1024
	ds_read_b128 v[188:191], v176 offset:2048
	ds_read_b128 v[192:195], v176 offset:3072
	v_add_u32_e32 v177, 0xc000, v161
	v_lshl_add_u64 v[244:245], v[140:141], 0, s[18:19]
	v_readfirstlane_b32 s13, v177
	v_lshl_add_u64 v[178:179], v[244:245], 0, s[68:69]
	s_mov_b32 m0, s13
	ds_read_b128 v[196:199], v147
	ds_read_b128 v[200:203], v147 offset:1024
	ds_read_b128 v[204:207], v146
	ds_read_b128 v[208:211], v146 offset:1024
	ds_read_b128 v[212:215], v145
	ds_read_b128 v[216:219], v145 offset:1024
	ds_read_b128 v[220:223], v144
	ds_read_b128 v[224:227], v144 offset:1024
	global_load_lds_dwordx4 v[178:179], off
	v_add_u32_e32 v178, 0xe000, v161
	v_lshl_add_u64 v[246:247], v[138:139], 0, s[18:19]
	v_readfirstlane_b32 s13, v178
	v_lshl_add_u64 v[228:229], v[246:247], 0, s[68:69]
	s_mov_b32 m0, s13
	s_nop 0
	global_load_lds_dwordx4 v[228:229], off
	s_waitcnt lgkmcnt(8)
	s_barrier
	s_waitcnt lgkmcnt(0)
	v_mfma_f32_16x16x32_bf16 v[126:129], v[196:199], v[180:183], v[126:129]
	v_mfma_f32_16x16x32_bf16 v[122:125], v[196:199], v[188:191], v[122:125]
	v_mfma_f32_16x16x32_bf16 v[118:121], v[204:207], v[180:183], v[118:121]
	v_mfma_f32_16x16x32_bf16 v[114:117], v[204:207], v[188:191], v[114:117]
	v_mfma_f32_16x16x32_bf16 v[110:113], v[212:215], v[180:183], v[110:113]
	v_mfma_f32_16x16x32_bf16 v[106:109], v[212:215], v[188:191], v[106:109]
	v_mfma_f32_16x16x32_bf16 v[102:105], v[220:223], v[180:183], v[102:105]
	v_mfma_f32_16x16x32_bf16 v[98:101], v[220:223], v[188:191], v[98:101]
	v_mfma_f32_16x16x32_bf16 v[126:129], v[200:203], v[184:187], v[126:129]
	v_mfma_f32_16x16x32_bf16 v[122:125], v[200:203], v[192:195], v[122:125]
	v_mfma_f32_16x16x32_bf16 v[118:121], v[208:211], v[184:187], v[118:121]
	v_mfma_f32_16x16x32_bf16 v[114:117], v[208:211], v[192:195], v[114:117]
	v_mfma_f32_16x16x32_bf16 v[110:113], v[216:219], v[184:187], v[110:113]
	v_mfma_f32_16x16x32_bf16 v[106:109], v[216:219], v[192:195], v[106:109]
	v_mfma_f32_16x16x32_bf16 v[102:105], v[224:227], v[184:187], v[102:105]
	v_mfma_f32_16x16x32_bf16 v[98:101], v[224:227], v[192:195], v[98:101]
	s_barrier
	v_lshl_add_u64 v[248:249], v[136:137], 0, s[18:19]
	v_readfirstlane_b32 s13, v159
	v_lshl_add_u64 v[250:251], v[248:249], 0, s[74:75]
	s_mov_b32 m0, s13
	ds_read_b128 v[228:231], v175
	ds_read_b128 v[232:235], v175 offset:1024
	ds_read_b128 v[236:239], v175 offset:2048
	ds_read_b128 v[240:243], v175 offset:3072
	global_load_lds_dwordx4 v[250:251], off
	v_lshl_add_u64 v[250:251], v[134:135], 0, s[18:19]
	v_readfirstlane_b32 s13, v160
	v_lshl_add_u64 v[252:253], v[250:251], 0, s[74:75]
	s_mov_b32 m0, s13
	s_nop 0
	global_load_lds_dwordx4 v[252:253], off
	s_barrier
	s_waitcnt lgkmcnt(0)
	v_mfma_f32_16x16x32_bf16 v[94:97], v[196:199], v[228:231], v[94:97]
	v_mfma_f32_16x16x32_bf16 v[90:93], v[196:199], v[236:239], v[90:93]
	v_mfma_f32_16x16x32_bf16 v[86:89], v[204:207], v[228:231], v[86:89]
	v_mfma_f32_16x16x32_bf16 v[82:85], v[204:207], v[236:239], v[82:85]
	v_mfma_f32_16x16x32_bf16 v[78:81], v[212:215], v[228:231], v[78:81]
	v_mfma_f32_16x16x32_bf16 v[74:77], v[212:215], v[236:239], v[74:77]
	v_mfma_f32_16x16x32_bf16 v[70:73], v[220:223], v[228:231], v[70:73]
	v_mfma_f32_16x16x32_bf16 v[66:69], v[220:223], v[236:239], v[66:69]
	v_mfma_f32_16x16x32_bf16 v[94:97], v[200:203], v[232:235], v[94:97]
	v_mfma_f32_16x16x32_bf16 v[90:93], v[200:203], v[240:243], v[90:93]
	v_mfma_f32_16x16x32_bf16 v[86:89], v[208:211], v[232:235], v[86:89]
	v_mfma_f32_16x16x32_bf16 v[82:85], v[208:211], v[240:243], v[82:85]
	v_mfma_f32_16x16x32_bf16 v[78:81], v[216:219], v[232:235], v[78:81]
	v_mfma_f32_16x16x32_bf16 v[74:77], v[216:219], v[240:243], v[74:77]
	v_mfma_f32_16x16x32_bf16 v[70:73], v[224:227], v[232:235], v[70:73]
	v_mfma_f32_16x16x32_bf16 v[66:69], v[224:227], v[240:243], v[66:69]
	v_readfirstlane_b32 s13, v161
	v_lshl_add_u64 v[252:253], v[244:245], 0, s[74:75]
	s_mov_b32 m0, s13
	v_readfirstlane_b32 s13, v163
	s_barrier
	ds_read_b128 v[196:199], v147 offset:16384
	ds_read_b128 v[200:203], v147 offset:17408
	ds_read_b128 v[204:207], v146 offset:16384
	ds_read_b128 v[208:211], v146 offset:17408
	ds_read_b128 v[212:215], v145 offset:16384
	ds_read_b128 v[216:219], v145 offset:17408
	ds_read_b128 v[220:223], v144 offset:16384
	ds_read_b128 v[224:227], v144 offset:17408
	global_load_lds_dwordx4 v[252:253], off
	v_lshl_add_u64 v[252:253], v[246:247], 0, s[74:75]
	s_mov_b32 m0, s13
	s_nop 0
	global_load_lds_dwordx4 v[252:253], off
	s_barrier
	s_waitcnt lgkmcnt(0)
	v_mfma_f32_16x16x32_bf16 v[62:65], v[196:199], v[180:183], v[62:65]
	v_mfma_f32_16x16x32_bf16 v[58:61], v[196:199], v[188:191], v[58:61]
	v_mfma_f32_16x16x32_bf16 v[54:57], v[204:207], v[180:183], v[54:57]
	v_mfma_f32_16x16x32_bf16 v[50:53], v[204:207], v[188:191], v[50:53]
	v_mfma_f32_16x16x32_bf16 v[46:49], v[212:215], v[180:183], v[46:49]
	v_mfma_f32_16x16x32_bf16 v[42:45], v[212:215], v[188:191], v[42:45]
	v_mfma_f32_16x16x32_bf16 v[38:41], v[220:223], v[180:183], v[38:41]
	v_mfma_f32_16x16x32_bf16 v[34:37], v[220:223], v[188:191], v[34:37]
	v_mfma_f32_16x16x32_bf16 v[62:65], v[200:203], v[184:187], v[62:65]
	v_mfma_f32_16x16x32_bf16 v[58:61], v[200:203], v[192:195], v[58:61]
	v_mfma_f32_16x16x32_bf16 v[54:57], v[208:211], v[184:187], v[54:57]
	v_mfma_f32_16x16x32_bf16 v[50:53], v[208:211], v[192:195], v[50:53]
	v_mfma_f32_16x16x32_bf16 v[46:49], v[216:219], v[184:187], v[46:49]
	v_mfma_f32_16x16x32_bf16 v[42:45], v[216:219], v[192:195], v[42:45]
	v_mfma_f32_16x16x32_bf16 v[38:41], v[224:227], v[184:187], v[38:41]
	v_mfma_f32_16x16x32_bf16 v[34:37], v[224:227], v[192:195], v[34:37]
	s_barrier
; #define STA(P, br, kt) STAGE(P, A, aoff0, aoff1, lda, br, kt)
; #define STB(P, br, kt) STAGE(P, Bt, boff0, boff1, ldb, br, kt)
; #define LDA(dst, b, h) _Pragma("unroll") for (int m = 0; m < 4; ++m) _Pragma("unroll") for (int k = 0; k < 2; ++k) \
;     dst[m][k] = *reinterpret_cast<const bf16x8*>((char*)SA(b, h) + lds_byte(wr * 64 + m * 16 + fr, k * 32 + fq * 8))
; #define LDB(dst, b, h) _Pragma("unroll") for (int n = 0; n < 2; ++n) _Pragma("unroll") for (int k = 0; k < 2; ++k) \
;     dst[n][k] = *reinterpret_cast<const bf16x8*>((char*)SB(b, h) + lds_byte(wc * 32 + n * 16 + fr, k * 32 + fq * 8))
; #define MMA(ai, bj, At, Bq) do { __builtin_amdgcn_s_setprio(1); \
;     _Pragma("unroll") for (int m = 0; m < 4; ++m) _Pragma("unroll") for (int n = 0; n < 2; ++n) _Pragma("unroll") for (int k = 0; k < 2; ++k) \
;       acc[ai][bj][m][n] = __builtin_amdgcn_mfma_f32_16x16x32_bf16(At[m][k], Bq[n][k], acc[ai][bj][m][n], 0, 0, 0); \
;     __builtin_amdgcn_s_setprio(0); } while (0)
; #define WAIT_V(n) asm volatile("s_waitcnt vmcnt(" #n ")" ::: "memory")
; #define WAIT_L(n) asm volatile("s_waitcnt lgkmcnt(" #n ")" ::: "memory")
; #define BAR __builtin_amdgcn_s_barrier()
; #define SCHED __builtin_amdgcn_sched_barrier(0)
; __device__ __forceinline__ void gemm256(const u16* __restrict__ A, int lda, const u16* __restrict__ Bt, int ldb, int K,
;                                         f32x4 (&acc)[2][2][4][2], const int g_wid) {
;     ...
;     STB(SB(0, 1), HALF, t + 2);
;     WAIT_V(6); BAR; MMA(1, 1, At, B1); BAR;
;     LDB(B0, 1, 0); SCHED; LDA(At, 1, 0); STA(SA(0, 1), HALF, t + 2);
;     WAIT_L(8); BAR; WAIT_L(0); MMA(0, 0, At, B0); BAR; SCHED;
;     LDB(B1, 1, 1); STB(SB(1, 0), 0, t + 3);
;     BAR; WAIT_L(0); MMA(0, 1, At, B1); BAR;
;     LDA(At, 1, 1); STA(SA(1, 0), 0, t + 3);
;     BAR; WAIT_L(0); MMA(1, 0, At, B0); BAR; SCHED;
	v_readfirstlane_b32 s13, v164
	v_lshl_add_u64 v[180:181], v[248:249], 0, s[78:79]
	s_mov_b32 m0, s13
	v_readfirstlane_b32 s13, v165
	global_load_lds_dwordx4 v[180:181], off
	v_lshl_add_u64 v[180:181], v[250:251], 0, s[78:79]
	s_mov_b32 m0, s13
	s_nop 0
	global_load_lds_dwordx4 v[180:181], off
	s_waitcnt vmcnt(6)
	s_barrier
	v_mfma_f32_16x16x32_bf16 v[30:33], v[196:199], v[228:231], v[30:33]
	v_mfma_f32_16x16x32_bf16 v[26:29], v[196:199], v[236:239], v[26:29]
	v_mfma_f32_16x16x32_bf16 v[22:25], v[204:207], v[228:231], v[22:25]
	v_mfma_f32_16x16x32_bf16 v[18:21], v[204:207], v[236:239], v[18:21]
	v_mfma_f32_16x16x32_bf16 v[14:17], v[212:215], v[228:231], v[14:17]
	v_mfma_f32_16x16x32_bf16 v[10:13], v[212:215], v[236:239], v[10:13]
	v_mfma_f32_16x16x32_bf16 v[6:9], v[220:223], v[228:231], v[6:9]
	v_mfma_f32_16x16x32_bf16 v[2:5], v[220:223], v[236:239], v[2:5]
	v_mfma_f32_16x16x32_bf16 v[30:33], v[200:203], v[232:235], v[30:33]
	v_mfma_f32_16x16x32_bf16 v[26:29], v[200:203], v[240:243], v[26:29]
	v_mfma_f32_16x16x32_bf16 v[22:25], v[208:211], v[232:235], v[22:25]
	v_mfma_f32_16x16x32_bf16 v[18:21], v[208:211], v[240:243], v[18:21]
	v_mfma_f32_16x16x32_bf16 v[14:17], v[216:219], v[232:235], v[14:17]
	v_mfma_f32_16x16x32_bf16 v[10:13], v[216:219], v[240:243], v[10:13]
	v_mfma_f32_16x16x32_bf16 v[6:9], v[224:227], v[232:235], v[6:9]
	v_mfma_f32_16x16x32_bf16 v[2:5], v[224:227], v[240:243], v[2:5]
	s_barrier
	ds_read_b128 v[180:183], v168
	ds_read_b128 v[184:187], v168 offset:1024
	ds_read_b128 v[188:191], v168 offset:2048
	ds_read_b128 v[192:195], v168 offset:3072
	v_readfirstlane_b32 s13, v166
	v_lshl_add_u64 v[228:229], v[244:245], 0, s[78:79]
	s_mov_b32 m0, s13
	v_readfirstlane_b32 s13, v167
	ds_read_b128 v[196:199], v147 offset:32768
	ds_read_b128 v[200:203], v147 offset:33792
	ds_read_b128 v[204:207], v146 offset:32768
	ds_read_b128 v[208:211], v146 offset:33792
	ds_read_b128 v[212:215], v145 offset:32768
	ds_read_b128 v[216:219], v145 offset:33792
	ds_read_b128 v[220:223], v144 offset:32768
	ds_read_b128 v[224:227], v144 offset:33792
	global_load_lds_dwordx4 v[228:229], off
	v_lshl_add_u64 v[228:229], v[246:247], 0, s[78:79]
	s_mov_b32 m0, s13
	s_nop 0
	global_load_lds_dwordx4 v[228:229], off
	s_waitcnt lgkmcnt(8)
	s_barrier
	s_waitcnt lgkmcnt(0)
	v_mfma_f32_16x16x32_bf16 v[126:129], v[196:199], v[180:183], v[126:129]
	v_mfma_f32_16x16x32_bf16 v[122:125], v[196:199], v[188:191], v[122:125]
	v_mfma_f32_16x16x32_bf16 v[118:121], v[204:207], v[180:183], v[118:121]
	v_mfma_f32_16x16x32_bf16 v[114:117], v[204:207], v[188:191], v[114:117]
	v_mfma_f32_16x16x32_bf16 v[110:113], v[212:215], v[180:183], v[110:113]
	v_mfma_f32_16x16x32_bf16 v[106:109], v[212:215], v[188:191], v[106:109]
	v_mfma_f32_16x16x32_bf16 v[102:105], v[220:223], v[180:183], v[102:105]
	v_mfma_f32_16x16x32_bf16 v[98:101], v[220:223], v[188:191], v[98:101]
	v_mfma_f32_16x16x32_bf16 v[126:129], v[200:203], v[184:187], v[126:129]
	v_mfma_f32_16x16x32_bf16 v[122:125], v[200:203], v[192:195], v[122:125]
	v_mfma_f32_16x16x32_bf16 v[118:121], v[208:211], v[184:187], v[118:121]
	v_mfma_f32_16x16x32_bf16 v[114:117], v[208:211], v[192:195], v[114:117]
	v_mfma_f32_16x16x32_bf16 v[110:113], v[216:219], v[184:187], v[110:113]
	v_mfma_f32_16x16x32_bf16 v[106:109], v[216:219], v[192:195], v[106:109]
	v_mfma_f32_16x16x32_bf16 v[102:105], v[224:227], v[184:187], v[102:105]
	v_mfma_f32_16x16x32_bf16 v[98:101], v[224:227], v[192:195], v[98:101]
	s_barrier
	v_readfirstlane_b32 s13, v169
	v_lshl_add_u64 v[252:253], v[248:249], 0, s[82:83]
	s_mov_b32 m0, s13
	v_readfirstlane_b32 s13, v170
	ds_read_b128 v[228:231], v162
	ds_read_b128 v[232:235], v162 offset:1024
	ds_read_b128 v[236:239], v162 offset:2048
	ds_read_b128 v[240:243], v162 offset:3072
	global_load_lds_dwordx4 v[252:253], off
	v_lshl_add_u64 v[252:253], v[250:251], 0, s[82:83]
	s_mov_b32 m0, s13
	s_nop 0
	global_load_lds_dwordx4 v[252:253], off
	s_barrier
	s_waitcnt lgkmcnt(0)
	v_mfma_f32_16x16x32_bf16 v[94:97], v[196:199], v[228:231], v[94:97]
	v_mfma_f32_16x16x32_bf16 v[90:93], v[196:199], v[236:239], v[90:93]
	v_mfma_f32_16x16x32_bf16 v[86:89], v[204:207], v[228:231], v[86:89]
	v_mfma_f32_16x16x32_bf16 v[82:85], v[204:207], v[236:239], v[82:85]
	v_mfma_f32_16x16x32_bf16 v[78:81], v[212:215], v[228:231], v[78:81]
	v_mfma_f32_16x16x32_bf16 v[74:77], v[212:215], v[236:239], v[74:77]
	v_mfma_f32_16x16x32_bf16 v[70:73], v[220:223], v[228:231], v[70:73]
	v_mfma_f32_16x16x32_bf16 v[66:69], v[220:223], v[236:239], v[66:69]
	v_mfma_f32_16x16x32_bf16 v[94:97], v[200:203], v[232:235], v[94:97]
	v_mfma_f32_16x16x32_bf16 v[90:93], v[200:203], v[240:243], v[90:93]
	v_mfma_f32_16x16x32_bf16 v[86:89], v[208:211], v[232:235], v[86:89]
	v_mfma_f32_16x16x32_bf16 v[82:85], v[208:211], v[240:243], v[82:85]
	v_mfma_f32_16x16x32_bf16 v[78:81], v[216:219], v[232:235], v[78:81]
	v_mfma_f32_16x16x32_bf16 v[74:77], v[216:219], v[240:243], v[74:77]
	v_mfma_f32_16x16x32_bf16 v[70:73], v[224:227], v[232:235], v[70:73]
	v_mfma_f32_16x16x32_bf16 v[66:69], v[224:227], v[240:243], v[66:69]
	v_readfirstlane_b32 s13, v171
	v_lshl_add_u64 v[244:245], v[244:245], 0, s[82:83]
	s_mov_b32 m0, s13
	v_readfirstlane_b32 s13, v172
	s_barrier
	ds_read_b128 v[196:199], v147 offset:49152
	ds_read_b128 v[200:203], v147 offset:50176
	ds_read_b128 v[204:207], v146 offset:49152
	ds_read_b128 v[208:211], v146 offset:50176
	ds_read_b128 v[212:215], v145 offset:49152
	ds_read_b128 v[216:219], v145 offset:50176
	ds_read_b128 v[220:223], v144 offset:49152
	ds_read_b128 v[224:227], v144 offset:50176
	global_load_lds_dwordx4 v[244:245], off
	v_lshl_add_u64 v[244:245], v[246:247], 0, s[82:83]
	s_mov_b32 m0, s13
	s_nop 0
	global_load_lds_dwordx4 v[244:245], off
	s_barrier
; #define STA(P, br, kt) STAGE(P, A, aoff0, aoff1, lda, br, kt)
; #define STB(P, br, kt) STAGE(P, Bt, boff0, boff1, ldb, br, kt)
; #define LDA(dst, b, h) _Pragma("unroll") for (int m = 0; m < 4; ++m) _Pragma("unroll") for (int k = 0; k < 2; ++k) \
;     dst[m][k] = *reinterpret_cast<const bf16x8*>((char*)SA(b, h) + lds_byte(wr * 64 + m * 16 + fr, k * 32 + fq * 8))
; #define LDB(dst, b, h) _Pragma("unroll") for (int n = 0; n < 2; ++n) _Pragma("unroll") for (int k = 0; k < 2; ++k) \
;     dst[n][k] = *reinterpret_cast<const bf16x8*>((char*)SB(b, h) + lds_byte(wc * 32 + n * 16 + fr, k * 32 + fq * 8))
; #define MMA(ai, bj, At, Bq) do { __builtin_amdgcn_s_setprio(1); \
;     _Pragma("unroll") for (int m = 0; m < 4; ++m) _Pragma("unroll") for (int n = 0; n < 2; ++n) _Pragma("unroll") for (int k = 0; k < 2; ++k) \
;       acc[ai][bj][m][n] = __builtin_amdgcn_mfma_f32_16x16x32_bf16(At[m][k], Bq[n][k], acc[ai][bj][m][n], 0, 0, 0); \
;     __builtin_amdgcn_s_setprio(0); } while (0)
; #define WAIT_V(n) asm volatile("s_waitcnt vmcnt(" #n ")" ::: "memory")
; #define WAIT_L(n) asm volatile("s_waitcnt lgkmcnt(" #n ")" ::: "memory")
; #define BAR __builtin_amdgcn_s_barrier()
; #define SCHED __builtin_amdgcn_sched_barrier(0)
; __device__ __forceinline__ void gemm256(const u16* __restrict__ A, int lda, const u16* __restrict__ Bt, int ldb, int K,
;                                         f32x4 (&acc)[2][2][4][2], const int g_wid) {
;     ...
;     BAR; WAIT_L(0); MMA(1, 0, At, B0); BAR; SCHED;
;     STB(SB(1, 1), HALF, t + 3);
;     WAIT_V(6); BAR; MMA(1, 1, At, B1); BAR;
;   }
;   { LDB(B0, 0, 0); LDA(At, 0, 0); STA(SA(1, 1), HALF, nt - 1);
;     BAR; WAIT_L(0); MMA(0, 0, At, B0); BAR;
;     LDB(B1, 0, 1); BAR; WAIT_L(0); MMA(0, 1, At, B1); BAR;
	s_waitcnt lgkmcnt(0)
	v_mfma_f32_16x16x32_bf16 v[62:65], v[196:199], v[180:183], v[62:65]
	v_mfma_f32_16x16x32_bf16 v[58:61], v[196:199], v[188:191], v[58:61]
	v_mfma_f32_16x16x32_bf16 v[54:57], v[204:207], v[180:183], v[54:57]
	v_mfma_f32_16x16x32_bf16 v[50:53], v[204:207], v[188:191], v[50:53]
	v_mfma_f32_16x16x32_bf16 v[46:49], v[212:215], v[180:183], v[46:49]
	v_mfma_f32_16x16x32_bf16 v[42:45], v[212:215], v[188:191], v[42:45]
	v_mfma_f32_16x16x32_bf16 v[38:41], v[220:223], v[180:183], v[38:41]
	v_mfma_f32_16x16x32_bf16 v[34:37], v[220:223], v[188:191], v[34:37]
	v_mfma_f32_16x16x32_bf16 v[62:65], v[200:203], v[184:187], v[62:65]
	v_mfma_f32_16x16x32_bf16 v[58:61], v[200:203], v[192:195], v[58:61]
	v_mfma_f32_16x16x32_bf16 v[54:57], v[208:211], v[184:187], v[54:57]
	v_mfma_f32_16x16x32_bf16 v[50:53], v[208:211], v[192:195], v[50:53]
	v_mfma_f32_16x16x32_bf16 v[46:49], v[216:219], v[184:187], v[46:49]
	v_mfma_f32_16x16x32_bf16 v[42:45], v[216:219], v[192:195], v[42:45]
	v_mfma_f32_16x16x32_bf16 v[38:41], v[224:227], v[184:187], v[38:41]
	v_mfma_f32_16x16x32_bf16 v[34:37], v[224:227], v[192:195], v[34:37]
	s_barrier
	v_readfirstlane_b32 s13, v173
	v_lshl_add_u64 v[180:181], v[248:249], 0, s[86:87]
	s_mov_b32 m0, s13
	v_readfirstlane_b32 s13, v174
	global_load_lds_dwordx4 v[180:181], off
	v_lshl_add_u64 v[180:181], v[250:251], 0, s[86:87]
	s_mov_b32 m0, s13
	s_nop 0
	global_load_lds_dwordx4 v[180:181], off
	s_waitcnt vmcnt(6)
	s_barrier
	v_mfma_f32_16x16x32_bf16 v[30:33], v[196:199], v[228:231], v[30:33]
	v_mfma_f32_16x16x32_bf16 v[26:29], v[196:199], v[236:239], v[26:29]
	v_mfma_f32_16x16x32_bf16 v[22:25], v[204:207], v[228:231], v[22:25]
	v_mfma_f32_16x16x32_bf16 v[18:21], v[204:207], v[236:239], v[18:21]
	v_mfma_f32_16x16x32_bf16 v[14:17], v[212:215], v[228:231], v[14:17]
	v_mfma_f32_16x16x32_bf16 v[10:13], v[212:215], v[236:239], v[10:13]
	v_mfma_f32_16x16x32_bf16 v[6:9], v[220:223], v[228:231], v[6:9]
	v_mfma_f32_16x16x32_bf16 v[2:5], v[220:223], v[236:239], v[2:5]
	v_mfma_f32_16x16x32_bf16 v[30:33], v[200:203], v[232:235], v[30:33]
	v_mfma_f32_16x16x32_bf16 v[26:29], v[200:203], v[240:243], v[26:29]
	v_mfma_f32_16x16x32_bf16 v[22:25], v[208:211], v[232:235], v[22:25]
	v_mfma_f32_16x16x32_bf16 v[18:21], v[208:211], v[240:243], v[18:21]
	v_mfma_f32_16x16x32_bf16 v[14:17], v[216:219], v[232:235], v[14:17]
	v_mfma_f32_16x16x32_bf16 v[10:13], v[216:219], v[240:243], v[10:13]
	v_mfma_f32_16x16x32_bf16 v[6:9], v[224:227], v[232:235], v[6:9]
	v_mfma_f32_16x16x32_bf16 v[2:5], v[224:227], v[240:243], v[2:5]
	s_add_i32 s11, s11, 2
	s_add_u32 s18, s18, 0x100
	s_addc_u32 s19, s19, 0
	s_cmp_lt_u32 s11, 12
	s_cbranch_scc1 .LBB0_319
	s_barrier
	s_add_u32 s16, s16, 0x40780
	s_addc_u32 s17, s17, 0
	v_readfirstlane_b32 s11, v177
	v_lshl_add_u64 v[132:133], v[132:133], 1, s[16:17]
	s_mov_b32 m0, s11
	v_readfirstlane_b32 s11, v178
	ds_read_b128 v[134:137], v176
	ds_read_b128 v[138:141], v176 offset:1024
	ds_read_b128 v[164:167], v176 offset:2048
	ds_read_b128 v[170:173], v176 offset:3072
	ds_read_b128 v[180:183], v147
	ds_read_b128 v[184:187], v147 offset:1024
	ds_read_b128 v[188:191], v146
	ds_read_b128 v[192:195], v146 offset:1024
	ds_read_b128 v[196:199], v145
	ds_read_b128 v[200:203], v145 offset:1024
	ds_read_b128 v[204:207], v144
	ds_read_b128 v[208:211], v144 offset:1024
	global_load_lds_dwordx4 v[132:133], off
	v_lshl_add_u64 v[130:131], v[130:131], 1, s[16:17]
	s_mov_b32 m0, s11
	s_nop 0
	global_load_lds_dwordx4 v[130:131], off
	s_barrier
	s_waitcnt lgkmcnt(0)
	v_mfma_f32_16x16x32_bf16 v[126:129], v[180:183], v[134:137], v[126:129]
	v_mfma_f32_16x16x32_bf16 v[122:125], v[180:183], v[164:167], v[122:125]
	v_mfma_f32_16x16x32_bf16 v[110:113], v[196:199], v[134:137], v[110:113]
	v_mfma_f32_16x16x32_bf16 v[106:109], v[196:199], v[164:167], v[106:109]
	v_mfma_f32_16x16x32_bf16 v[126:129], v[184:187], v[138:141], v[126:129]
	v_mfma_f32_16x16x32_bf16 v[122:125], v[184:187], v[170:173], v[122:125]
	v_mfma_f32_16x16x32_bf16 v[118:121], v[188:191], v[134:137], v[118:121]
	v_mfma_f32_16x16x32_bf16 v[114:117], v[188:191], v[164:167], v[114:117]
	v_mfma_f32_16x16x32_bf16 v[110:113], v[200:203], v[138:141], v[110:113]
	v_mfma_f32_16x16x32_bf16 v[106:109], v[200:203], v[170:173], v[106:109]
	v_mfma_f32_16x16x32_bf16 v[102:105], v[204:207], v[134:137], v[102:105]
	v_mfma_f32_16x16x32_bf16 v[98:101], v[204:207], v[164:167], v[98:101]
	v_mfma_f32_16x16x32_bf16 v[130:133], v[192:195], v[138:141], v[118:121]
	v_mfma_f32_16x16x32_bf16 v[176:179], v[192:195], v[170:173], v[114:117]
	v_mfma_f32_16x16x32_bf16 v[212:215], v[208:211], v[138:141], v[102:105]
	v_mfma_f32_16x16x32_bf16 v[216:219], v[208:211], v[170:173], v[98:101]
	s_barrier
	s_nop 1
	ds_read_b128 v[98:101], v175
	ds_read_b128 v[102:105], v175 offset:1024
	ds_read_b128 v[114:117], v175 offset:2048
	ds_read_b128 v[118:121], v175 offset:3072
	s_barrier
	s_waitcnt lgkmcnt(0)
	v_mfma_f32_16x16x32_bf16 v[94:97], v[180:183], v[98:101], v[94:97]
	v_mfma_f32_16x16x32_bf16 v[90:93], v[180:183], v[114:117], v[90:93]
	v_mfma_f32_16x16x32_bf16 v[78:81], v[196:199], v[98:101], v[78:81]
	v_mfma_f32_16x16x32_bf16 v[74:77], v[196:199], v[114:117], v[74:77]
	v_mfma_f32_16x16x32_bf16 v[94:97], v[184:187], v[102:105], v[94:97]
	v_mfma_f32_16x16x32_bf16 v[90:93], v[184:187], v[118:121], v[90:93]
	v_mfma_f32_16x16x32_bf16 v[86:89], v[188:191], v[98:101], v[86:89]
	v_mfma_f32_16x16x32_bf16 v[82:85], v[188:191], v[114:117], v[82:85]
	v_mfma_f32_16x16x32_bf16 v[78:81], v[200:203], v[102:105], v[78:81]
	v_mfma_f32_16x16x32_bf16 v[74:77], v[200:203], v[118:121], v[74:77]
	v_mfma_f32_16x16x32_bf16 v[70:73], v[204:207], v[98:101], v[70:73]
	v_mfma_f32_16x16x32_bf16 v[66:69], v[204:207], v[114:117], v[66:69]
	v_mfma_f32_16x16x32_bf16 v[180:183], v[192:195], v[102:105], v[86:89]
	v_mfma_f32_16x16x32_bf16 v[184:187], v[192:195], v[118:121], v[82:85]
	v_mfma_f32_16x16x32_bf16 v[188:191], v[208:211], v[102:105], v[70:73]
	v_mfma_f32_16x16x32_bf16 v[192:195], v[208:211], v[118:121], v[66:69]
	s_barrier
; #define LDA(dst, b, h) _Pragma("unroll") for (int m = 0; m < 4; ++m) _Pragma("unroll") for (int k = 0; k < 2; ++k) \
;     dst[m][k] = *reinterpret_cast<const bf16x8*>((char*)SA(b, h) + lds_byte(wr * 64 + m * 16 + fr, k * 32 + fq * 8))
; #define LDB(dst, b, h) _Pragma("unroll") for (int n = 0; n < 2; ++n) _Pragma("unroll") for (int k = 0; k < 2; ++k) \
;     dst[n][k] = *reinterpret_cast<const bf16x8*>((char*)SB(b, h) + lds_byte(wc * 32 + n * 16 + fr, k * 32 + fq * 8))
; #define MMA(ai, bj, At, Bq) do { __builtin_amdgcn_s_setprio(1); \
;     _Pragma("unroll") for (int m = 0; m < 4; ++m) _Pragma("unroll") for (int n = 0; n < 2; ++n) _Pragma("unroll") for (int k = 0; k < 2; ++k) \
;       acc[ai][bj][m][n] = __builtin_amdgcn_mfma_f32_16x16x32_bf16(At[m][k], Bq[n][k], acc[ai][bj][m][n], 0, 0, 0); \
;     __builtin_amdgcn_s_setprio(0); } while (0)
; #define WAIT_V(n) asm volatile("s_waitcnt vmcnt(" #n ")" ::: "memory")
; #define WAIT_L(n) asm volatile("s_waitcnt lgkmcnt(" #n ")" ::: "memory")
; #define BAR __builtin_amdgcn_s_barrier()
; __device__ __forceinline__ void gemm256(const u16* __restrict__ A, int lda, const u16* __restrict__ Bt, int ldb, int K,
;                                         f32x4 (&acc)[2][2][4][2], const int g_wid) {
;     ...
;     LDA(At, 0, 1); WAIT_V(4); BAR; WAIT_L(0); MMA(1, 0, At, B0); MMA(1, 1, At, B1); BAR; }
;   { LDB(B0, 1, 0); LDA(At, 1, 0); WAIT_V(2); BAR; WAIT_L(0); MMA(0, 0, At, B0); BAR;
	s_nop 1
	ds_read_b128 v[66:69], v147 offset:16384
	ds_read_b128 v[70:73], v147 offset:17408
	ds_read_b128 v[82:85], v146 offset:16384
	ds_read_b128 v[86:89], v146 offset:17408
	ds_read_b128 v[196:199], v145 offset:16384
	ds_read_b128 v[200:203], v145 offset:17408
	ds_read_b128 v[204:207], v144 offset:16384
	ds_read_b128 v[208:211], v144 offset:17408
	s_waitcnt vmcnt(4)
	s_barrier
	s_waitcnt lgkmcnt(0)
	v_mfma_f32_16x16x32_bf16 v[62:65], v[66:69], v[134:137], v[62:65]
	v_mfma_f32_16x16x32_bf16 v[54:57], v[82:85], v[134:137], v[54:57]
	v_mfma_f32_16x16x32_bf16 v[46:49], v[196:199], v[134:137], v[46:49]
	v_mfma_f32_16x16x32_bf16 v[38:41], v[204:207], v[134:137], v[38:41]
	v_mfma_f32_16x16x32_bf16 v[62:65], v[70:73], v[138:141], v[62:65]
	v_mfma_f32_16x16x32_bf16 v[58:61], v[66:69], v[164:167], v[58:61]
	v_mfma_f32_16x16x32_bf16 v[54:57], v[86:89], v[138:141], v[54:57]
	v_mfma_f32_16x16x32_bf16 v[50:53], v[82:85], v[164:167], v[50:53]
	v_mfma_f32_16x16x32_bf16 v[46:49], v[200:203], v[138:141], v[46:49]
	v_mfma_f32_16x16x32_bf16 v[42:45], v[196:199], v[164:167], v[42:45]
	v_mfma_f32_16x16x32_bf16 v[38:41], v[208:211], v[138:141], v[38:41]
	v_mfma_f32_16x16x32_bf16 v[34:37], v[204:207], v[164:167], v[34:37]
	v_mfma_f32_16x16x32_bf16 v[220:223], v[70:73], v[170:173], v[58:61]
	v_mfma_f32_16x16x32_bf16 v[224:227], v[86:89], v[170:173], v[50:53]
	v_mfma_f32_16x16x32_bf16 v[228:231], v[200:203], v[170:173], v[42:45]
	v_mfma_f32_16x16x32_bf16 v[134:137], v[208:211], v[170:173], v[34:37]
	v_mfma_f32_16x16x32_bf16 v[30:33], v[66:69], v[98:101], v[30:33]
	v_mfma_f32_16x16x32_bf16 v[22:25], v[82:85], v[98:101], v[22:25]
	v_mfma_f32_16x16x32_bf16 v[14:17], v[196:199], v[98:101], v[14:17]
	v_mfma_f32_16x16x32_bf16 v[6:9], v[204:207], v[98:101], v[6:9]
	v_mfma_f32_16x16x32_bf16 v[30:33], v[70:73], v[102:105], v[30:33]
	v_mfma_f32_16x16x32_bf16 v[26:29], v[66:69], v[114:117], v[26:29]
	v_mfma_f32_16x16x32_bf16 v[22:25], v[86:89], v[102:105], v[22:25]
	v_mfma_f32_16x16x32_bf16 v[18:21], v[82:85], v[114:117], v[18:21]
	v_mfma_f32_16x16x32_bf16 v[14:17], v[200:203], v[102:105], v[14:17]
	v_mfma_f32_16x16x32_bf16 v[10:13], v[196:199], v[114:117], v[10:13]
	v_mfma_f32_16x16x32_bf16 v[6:9], v[208:211], v[102:105], v[6:9]
	v_mfma_f32_16x16x32_bf16 v[2:5], v[204:207], v[114:117], v[2:5]
	v_mfma_f32_16x16x32_bf16 v[138:141], v[70:73], v[118:121], v[26:29]
	v_mfma_f32_16x16x32_bf16 v[164:167], v[86:89], v[118:121], v[18:21]
	v_mfma_f32_16x16x32_bf16 v[170:173], v[200:203], v[118:121], v[10:13]
	v_mfma_f32_16x16x32_bf16 v[196:199], v[208:211], v[118:121], v[2:5]
	s_barrier
	ds_read_b128 v[200:203], v168
	ds_read_b128 v[204:207], v168 offset:1024
	ds_read_b128 v[208:211], v168 offset:2048
	ds_read_b128 v[232:235], v168 offset:3072
	ds_read_b128 v[2:5], v147 offset:32768
	ds_read_b128 v[10:13], v147 offset:33792
	ds_read_b128 v[18:21], v146 offset:32768
	ds_read_b128 v[34:37], v146 offset:33792
	ds_read_b128 v[236:239], v145 offset:32768
	ds_read_b128 v[240:243], v145 offset:33792
	ds_read_b128 v[244:247], v144 offset:32768
	ds_read_b128 v[248:251], v144 offset:33792
	s_waitcnt vmcnt(2)
	s_barrier
	s_waitcnt lgkmcnt(0)
	v_mfma_f32_16x16x32_bf16 v[26:29], v[2:5], v[200:203], v[126:129]
	v_mfma_f32_16x16x32_bf16 v[118:121], v[10:13], v[204:207], v[26:29]
	v_mfma_f32_16x16x32_bf16 v[26:29], v[2:5], v[208:211], v[122:125]
	v_mfma_f32_16x16x32_bf16 v[86:89], v[10:13], v[232:235], v[26:29]
	v_mfma_f32_16x16x32_bf16 v[26:29], v[18:21], v[200:203], v[130:133]
	v_mfma_f32_16x16x32_bf16 v[114:117], v[34:37], v[204:207], v[26:29]
	v_mfma_f32_16x16x32_bf16 v[26:29], v[18:21], v[208:211], v[176:179]
	v_mfma_f32_16x16x32_bf16 v[82:85], v[34:37], v[232:235], v[26:29]
	v_mfma_f32_16x16x32_bf16 v[26:29], v[236:239], v[200:203], v[110:113]
	v_mfma_f32_16x16x32_bf16 v[102:105], v[240:243], v[204:207], v[26:29]
	v_mfma_f32_16x16x32_bf16 v[26:29], v[236:239], v[208:211], v[106:109]
	v_mfma_f32_16x16x32_bf16 v[70:73], v[240:243], v[232:235], v[26:29]
	v_mfma_f32_16x16x32_bf16 v[26:29], v[244:247], v[200:203], v[212:215]
	v_mfma_f32_16x16x32_bf16 v[98:101], v[248:251], v[204:207], v[26:29]
	v_mfma_f32_16x16x32_bf16 v[26:29], v[244:247], v[208:211], v[216:219]
	v_mfma_f32_16x16x32_bf16 v[66:69], v[248:251], v[232:235], v[26:29]
	s_barrier
; #define LDA(dst, b, h) _Pragma("unroll") for (int m = 0; m < 4; ++m) _Pragma("unroll") for (int k = 0; k < 2; ++k) \
;     dst[m][k] = *reinterpret_cast<const bf16x8*>((char*)SA(b, h) + lds_byte(wr * 64 + m * 16 + fr, k * 32 + fq * 8))
; #define LDB(dst, b, h) _Pragma("unroll") for (int n = 0; n < 2; ++n) _Pragma("unroll") for (int k = 0; k < 2; ++k) \
;     dst[n][k] = *reinterpret_cast<const bf16x8*>((char*)SB(b, h) + lds_byte(wc * 32 + n * 16 + fr, k * 32 + fq * 8))
; #define MMA(ai, bj, At, Bq) do { __builtin_amdgcn_s_setprio(1); \
;     _Pragma("unroll") for (int m = 0; m < 4; ++m) _Pragma("unroll") for (int n = 0; n < 2; ++n) _Pragma("unroll") for (int k = 0; k < 2; ++k) \
;       acc[ai][bj][m][n] = __builtin_amdgcn_mfma_f32_16x16x32_bf16(At[m][k], Bq[n][k], acc[ai][bj][m][n], 0, 0, 0); \
;     __builtin_amdgcn_s_setprio(0); } while (0)
; #define WAIT_V(n) asm volatile("s_waitcnt vmcnt(" #n ")" ::: "memory")
; #define WAIT_L(n) asm volatile("s_waitcnt lgkmcnt(" #n ")" ::: "memory")
; #define BAR __builtin_amdgcn_s_barrier()
; __device__ __forceinline__ void gemm256(const u16* __restrict__ A, int lda, const u16* __restrict__ Bt, int ldb, int K,
;                                         f32x4 (&acc)[2][2][4][2], const int g_wid) {
;     ...
;     LDB(B1, 1, 1); WAIT_V(0); BAR; WAIT_L(0); MMA(0, 1, At, B1); BAR;
;     LDA(At, 1, 1); BAR; WAIT_L(0); MMA(1, 0, At, B0); MMA(1, 1, At, B1); BAR; }
;   if (wr == 0) BAR;
	ds_read_b128 v[130:133], v162
	ds_read_b128 v[174:177], v162 offset:1024
	ds_read_b128 v[212:215], v162 offset:2048
	ds_read_b128 v[160:163], v162 offset:3072
	s_waitcnt vmcnt(0)
	s_barrier
	s_waitcnt lgkmcnt(0)
	v_mfma_f32_16x16x32_bf16 v[26:29], v[2:5], v[130:133], v[94:97]
	v_mfma_f32_16x16x32_bf16 v[2:5], v[2:5], v[212:215], v[90:93]
	v_mfma_f32_16x16x32_bf16 v[58:61], v[10:13], v[174:177], v[26:29]
	v_mfma_f32_16x16x32_bf16 v[26:29], v[10:13], v[160:163], v[2:5]
	v_mfma_f32_16x16x32_bf16 v[2:5], v[18:21], v[130:133], v[180:183]
	v_mfma_f32_16x16x32_bf16 v[50:53], v[34:37], v[174:177], v[2:5]
	v_mfma_f32_16x16x32_bf16 v[2:5], v[18:21], v[212:215], v[184:187]
	v_mfma_f32_16x16x32_bf16 v[18:21], v[34:37], v[160:163], v[2:5]
	v_mfma_f32_16x16x32_bf16 v[2:5], v[236:239], v[130:133], v[78:81]
	v_mfma_f32_16x16x32_bf16 v[42:45], v[240:243], v[174:177], v[2:5]
	v_mfma_f32_16x16x32_bf16 v[2:5], v[236:239], v[212:215], v[74:77]
	v_mfma_f32_16x16x32_bf16 v[10:13], v[240:243], v[160:163], v[2:5]
	v_mfma_f32_16x16x32_bf16 v[2:5], v[244:247], v[130:133], v[188:191]
	v_mfma_f32_16x16x32_bf16 v[34:37], v[248:251], v[174:177], v[2:5]
	v_mfma_f32_16x16x32_bf16 v[2:5], v[244:247], v[212:215], v[192:195]
	v_mfma_f32_16x16x32_bf16 v[2:5], v[248:251], v[160:163], v[2:5]
	s_barrier
	ds_read_b128 v[178:181], v147 offset:49152
	ds_read_b128 v[182:185], v147 offset:50176
	ds_read_b128 v[186:189], v146 offset:49152
	ds_read_b128 v[190:193], v146 offset:50176
	ds_read_b128 v[216:219], v145 offset:49152
	ds_read_b128 v[236:239], v145 offset:50176
	ds_read_b128 v[240:243], v144 offset:49152
	ds_read_b128 v[144:147], v144 offset:50176
	s_barrier
	s_waitcnt lgkmcnt(0)
	v_mfma_f32_16x16x32_bf16 v[62:65], v[178:181], v[200:203], v[62:65]
	v_mfma_f32_16x16x32_bf16 v[54:57], v[186:189], v[200:203], v[54:57]
	v_mfma_f32_16x16x32_bf16 v[46:49], v[216:219], v[200:203], v[46:49]
	v_mfma_f32_16x16x32_bf16 v[38:41], v[240:243], v[200:203], v[38:41]
	v_mfma_f32_16x16x32_bf16 v[126:129], v[182:185], v[204:207], v[62:65]
	v_mfma_f32_16x16x32_bf16 v[62:65], v[178:181], v[208:211], v[220:223]
	v_mfma_f32_16x16x32_bf16 v[122:125], v[190:193], v[204:207], v[54:57]
	v_mfma_f32_16x16x32_bf16 v[54:57], v[186:189], v[208:211], v[224:227]
	v_mfma_f32_16x16x32_bf16 v[110:113], v[236:239], v[204:207], v[46:49]
	v_mfma_f32_16x16x32_bf16 v[46:49], v[216:219], v[208:211], v[228:231]
	v_mfma_f32_16x16x32_bf16 v[106:109], v[144:147], v[204:207], v[38:41]
	v_mfma_f32_16x16x32_bf16 v[38:41], v[240:243], v[208:211], v[134:137]
	v_mfma_f32_16x16x32_bf16 v[94:97], v[182:185], v[232:235], v[62:65]
	v_mfma_f32_16x16x32_bf16 v[90:93], v[190:193], v[232:235], v[54:57]
	v_mfma_f32_16x16x32_bf16 v[78:81], v[236:239], v[232:235], v[46:49]
	v_mfma_f32_16x16x32_bf16 v[74:77], v[144:147], v[232:235], v[38:41]
	v_mfma_f32_16x16x32_bf16 v[30:33], v[178:181], v[130:133], v[30:33]
	v_mfma_f32_16x16x32_bf16 v[22:25], v[186:189], v[130:133], v[22:25]
	v_mfma_f32_16x16x32_bf16 v[14:17], v[216:219], v[130:133], v[14:17]
	v_mfma_f32_16x16x32_bf16 v[6:9], v[240:243], v[130:133], v[6:9]
	v_mfma_f32_16x16x32_bf16 v[62:65], v[182:185], v[174:177], v[30:33]
	v_mfma_f32_16x16x32_bf16 v[30:33], v[178:181], v[212:215], v[138:141]
	v_mfma_f32_16x16x32_bf16 v[54:57], v[190:193], v[174:177], v[22:25]
	v_mfma_f32_16x16x32_bf16 v[22:25], v[186:189], v[212:215], v[164:167]
	v_mfma_f32_16x16x32_bf16 v[46:49], v[236:239], v[174:177], v[14:17]
	v_mfma_f32_16x16x32_bf16 v[14:17], v[216:219], v[212:215], v[170:173]
	v_mfma_f32_16x16x32_bf16 v[38:41], v[144:147], v[174:177], v[6:9]
	v_mfma_f32_16x16x32_bf16 v[6:9], v[240:243], v[212:215], v[196:199]
	v_mfma_f32_16x16x32_bf16 v[30:33], v[182:185], v[160:163], v[30:33]
	v_mfma_f32_16x16x32_bf16 v[22:25], v[190:193], v[160:163], v[22:25]
	v_mfma_f32_16x16x32_bf16 v[14:17], v[236:239], v[160:163], v[14:17]
	v_mfma_f32_16x16x32_bf16 v[6:9], v[144:147], v[160:163], v[6:9]
	s_setprio 0
	s_movk_i32 s11, 0x100
	v_cmp_gt_u32_e32 vcc, s11, v0
	s_barrier
	s_and_saveexec_b64 s[16:17], vcc
	s_cbranch_execz .LBB0_309
	s_barrier
	s_branch .LBB0_309

; #define hw_tid() ((g_wid << 6) | hw_lane())
; #define STA(P, br, kt) STAGE(P, A, aoff0, aoff1, lda, br, kt)
; #define STB(P, br, kt) STAGE(P, Bt, boff0, boff1, ldb, br, kt)
; #define WAIT_V(n) asm volatile("s_waitcnt vmcnt(" #n ")" ::: "memory")
; #define BAR __builtin_amdgcn_s_barrier()
; __device__ __forceinline__ void gemm256(const u16* __restrict__ A, int lda, const u16* __restrict__ Bt, int ldb, int K,
;                                         f32x4 (&acc)[2][2][4][2], const int g_wid) {
;   int tid = hw_tid(); asm volatile("" : "+v"(tid));
;   const int wid = tid >> 6, lane = tid & 63, wr = wid >> 2, wc = wid & 3, fr = lane & 15, fq = lane >> 4;
;   int r0, c0, r1, c1;
;   stage_rc(tid * 16, r0, c0);
;   stage_rc(tid * 16 + 8192, r1, c1);
;   const int aoff0 = r0 * lda + c0, aoff1 = r1 * lda + c1, boff0 = r0 * ldb + c0, boff1 = r1 * ldb + c1;
;   bf16x8 At[4][2], B0[2][2], B1[2][2];
;   const int nt = K / BK;
;   STB(SB(0, 0), 0, 0); STA(SA(0, 0), 0, 0);
;   STB(SB(0, 1), HALF, 0); STA(SA(0, 1), HALF, 0);
;   if (wr == 1) BAR;
;   WAIT_V(4); BAR;
;   STB(SB(1, 0), 0, 1); STA(SA(1, 0), 0, 1); STB(SB(1, 1), HALF, 1);
;   WAIT_V(6); BAR;
.LBB0_340:
	s_or_b64 exec, exec, s[14:15]
	v_readlane_b32 s11, v254, 42
	s_mov_b64 s[24:25], 0x80
	v_lshl_add_u64 v[2:3], v[2:3], 0, s[24:25]
	v_add_u32_e32 v167, s11, v19
	v_add_u32_e32 v168, 0x2000, v167
	v_readfirstlane_b32 s14, v167
	s_mov_b32 m0, s14
	v_readfirstlane_b32 s14, v168
	v_add_u32_e32 v169, 0x8000, v159
	s_waitcnt vmcnt(4)
	s_barrier
	global_load_lds_dwordx4 v[2:3], off
	v_lshl_add_u64 v[2:3], v[6:7], 0, s[24:25]
	s_mov_b32 m0, s14
	v_readfirstlane_b32 s14, v169
	v_add_u32_e32 v170, 0xa000, v159
	v_readlane_b32 s15, v254, 43
	global_load_lds_dwordx4 v[2:3], off
	v_lshl_add_u64 v[2:3], v[8:9], 0, s[24:25]
	s_mov_b32 m0, s14
	v_readfirstlane_b32 s14, v170
	s_add_u32 s12, s12, 0xb0080
	v_add_u32_e32 v171, s15, v19
	global_load_lds_dwordx4 v[2:3], off
	v_lshl_add_u64 v[2:3], v[4:5], 0, s[24:25]
	s_mov_b32 m0, s14
	s_addc_u32 s13, s13, 0
	v_readfirstlane_b32 s14, v171
	global_load_lds_dwordx4 v[2:3], off
	v_lshl_add_u64 v[2:3], v[130:131], 1, s[12:13]
	s_mov_b32 m0, s14
	v_add_u32_e32 v172, 0x2000, v171
	global_load_lds_dwordx4 v[2:3], off
	v_lshl_add_u64 v[2:3], v[132:133], 1, s[12:13]
	v_readfirstlane_b32 s12, v172
	s_mov_b32 m0, s12
	v_and_b32_e32 v20, 15, v0
	global_load_lds_dwordx4 v[2:3], off
	v_lshlrev_b32_e32 v3, 2, v0
	v_and_b32_e32 v21, 48, v0
	v_lshlrev_b32_e32 v2, 6, v20
	v_and_b32_e32 v3, 32, v3
	v_bitop3_b32 v2, v2, v3, v21 bitop3:0x36
	v_readlane_b32 s10, v254, 40
	v_lshlrev_b32_e32 v4, 6, v0
	v_add_u32_e32 v8, s11, v2
	v_add_u32_e32 v6, s10, v2
	v_readlane_b32 s10, v254, 41
	v_add_u32_e32 v9, s15, v2
	v_add_u32_e32 v20, 0, v2
	v_add_u32_e32 v7, s10, v2
	s_movk_i32 s10, 0x3c0
	v_and_or_b32 v2, v4, s10, v21
	s_movk_i32 s10, 0xb00
	v_and_b32_e32 v19, 0x3000, v4
	v_xad_u32 v21, v2, v3, 0
	v_lshrrev_b32_e32 v3, 1, v11
	v_mul_lo_u32 v2, v14, s10
	s_mov_b32 s11, 0xb000
	v_lshrrev_b32_e32 v5, 1, v12
	v_mul_lo_u32 v4, v17, s10
	v_mad_u64_u32 v[2:3], s[12:13], v3, s11, v[2:3]
	v_mad_u64_u32 v[4:5], s[14:15], v5, s11, v[4:5]
	v_or_b32_e32 v2, v2, v13
	v_or_b32_e32 v4, v4, v16
	v_add_u32_sdwa v2, v2, sext(v15) dst_sel:DWORD dst_unused:UNUSED_PAD src0_sel:DWORD src1_sel:WORD_0
	v_add_u32_sdwa v4, v4, sext(v18) dst_sel:DWORD dst_unused:UNUSED_PAD src0_sel:DWORD src1_sel:WORD_0
	v_ashrrev_i32_e32 v3, 31, v2
	s_add_u32 s12, s4, s23
	v_ashrrev_i32_e32 v5, 31, v4
	v_lshlrev_b64 v[2:3], 1, v[2:3]
	s_addc_u32 s13, s5, s22
	v_lshlrev_b64 v[4:5], 1, v[4:5]
	v_lshl_add_u64 v[134:135], s[12:13], 0, v[2:3]
	v_lshl_add_u64 v[136:137], s[12:13], 0, v[4:5]
	s_add_u32 s12, s8, s21
	s_waitcnt vmcnt(6)
	v_lshlrev_b32_e32 v10, 13, v10
	s_addc_u32 s13, s9, s17
	v_or_b32_e32 v22, 0x800, v10
	v_or_b32_e32 v23, 0x1000, v10
	v_or_b32_e32 v24, 0x1800, v10
	v_lshl_add_u64 v[138:139], s[12:13], 0, v[2:3]
	v_mov_b32_e32 v2, 0
	v_lshl_add_u64 v[140:141], s[12:13], 0, v[4:5]
	s_mov_b32 s14, -2
	s_mov_b64 s[12:13], 0
	v_add_u32_e32 v174, v6, v19
	v_add_u32_e32 v145, v20, v10
	v_add_u32_e32 v144, v21, v22
	v_add_u32_e32 v143, v21, v23
	v_add_u32_e32 v142, v21, v24
	v_add_u32_e32 v173, v7, v19
	v_add_u32_e32 v166, v8, v19
	v_add_u32_e32 v160, v9, v19
	v_mov_b32_e32 v3, v2
	v_mov_b32_e32 v4, v2
	v_mov_b32_e32 v5, v2
	v_mov_b32_e32 v6, v2
	v_mov_b32_e32 v7, v2
	v_mov_b32_e32 v8, v2
	v_mov_b32_e32 v9, v2
	v_mov_b32_e32 v10, v2
	v_mov_b32_e32 v11, v2
	v_mov_b32_e32 v12, v2
	v_mov_b32_e32 v13, v2
	v_mov_b32_e32 v14, v2
	v_mov_b32_e32 v15, v2
	v_mov_b32_e32 v16, v2
	v_mov_b32_e32 v17, v2
	v_mov_b32_e32 v18, v2
	v_mov_b32_e32 v19, v2
	v_mov_b32_e32 v20, v2
	v_mov_b32_e32 v21, v2
	v_mov_b32_e32 v22, v2
	v_mov_b32_e32 v23, v2
	v_mov_b32_e32 v24, v2
	v_mov_b32_e32 v25, v2
	v_mov_b32_e32 v26, v2
	v_mov_b32_e32 v27, v2
	v_mov_b32_e32 v28, v2
	v_mov_b32_e32 v29, v2
	v_mov_b32_e32 v30, v2
	v_mov_b32_e32 v31, v2
	v_mov_b32_e32 v32, v2
	v_mov_b32_e32 v33, v2
	v_mov_b32_e32 v34, v2
	v_mov_b32_e32 v35, v2
	v_mov_b32_e32 v36, v2
	v_mov_b32_e32 v37, v2
	v_mov_b32_e32 v38, v2
	v_mov_b32_e32 v39, v2
	v_mov_b32_e32 v40, v2
	v_mov_b32_e32 v41, v2
	v_mov_b32_e32 v42, v2
	v_mov_b32_e32 v43, v2
	v_mov_b32_e32 v44, v2
	v_mov_b32_e32 v45, v2
	v_mov_b32_e32 v46, v2
	v_mov_b32_e32 v47, v2
	v_mov_b32_e32 v48, v2
	v_mov_b32_e32 v49, v2
	v_mov_b32_e32 v50, v2
	v_mov_b32_e32 v51, v2
	v_mov_b32_e32 v52, v2
	v_mov_b32_e32 v53, v2
	v_mov_b32_e32 v54, v2
	v_mov_b32_e32 v55, v2
	v_mov_b32_e32 v56, v2
	v_mov_b32_e32 v57, v2
	v_mov_b32_e32 v58, v2
	v_mov_b32_e32 v59, v2
	v_mov_b32_e32 v60, v2
	v_mov_b32_e32 v61, v2
	v_mov_b32_e32 v62, v2
	v_mov_b32_e32 v63, v2
	v_mov_b32_e32 v64, v2
	v_mov_b32_e32 v65, v2
	v_mov_b32_e32 v66, v2
	v_mov_b32_e32 v67, v2
	v_mov_b32_e32 v68, v2
	v_mov_b32_e32 v69, v2
	v_mov_b32_e32 v70, v2
	v_mov_b32_e32 v71, v2
	v_mov_b32_e32 v72, v2
	v_mov_b32_e32 v73, v2
	v_mov_b32_e32 v74, v2
	v_mov_b32_e32 v75, v2
	v_mov_b32_e32 v76, v2
	v_mov_b32_e32 v77, v2
	v_mov_b32_e32 v78, v2
	v_mov_b32_e32 v79, v2
	v_mov_b32_e32 v80, v2
	v_mov_b32_e32 v81, v2
	v_mov_b32_e32 v82, v2
	v_mov_b32_e32 v83, v2
	v_mov_b32_e32 v84, v2
	v_mov_b32_e32 v85, v2
	v_mov_b32_e32 v86, v2
	v_mov_b32_e32 v87, v2
	v_mov_b32_e32 v88, v2
	v_mov_b32_e32 v89, v2
	v_mov_b32_e32 v90, v2
	v_mov_b32_e32 v91, v2
	v_mov_b32_e32 v92, v2
	v_mov_b32_e32 v93, v2
	v_mov_b32_e32 v94, v2
	v_mov_b32_e32 v95, v2
	v_mov_b32_e32 v96, v2
	v_mov_b32_e32 v97, v2
	v_mov_b32_e32 v98, v2
	v_mov_b32_e32 v99, v2
	v_mov_b32_e32 v100, v2
	v_mov_b32_e32 v101, v2
	v_mov_b32_e32 v102, v2
	v_mov_b32_e32 v103, v2
	v_mov_b32_e32 v104, v2
	v_mov_b32_e32 v105, v2
	v_mov_b32_e32 v106, v2
	v_mov_b32_e32 v107, v2
	v_mov_b32_e32 v108, v2
	v_mov_b32_e32 v109, v2
	v_mov_b32_e32 v110, v2
	v_mov_b32_e32 v111, v2
	v_mov_b32_e32 v112, v2
	v_mov_b32_e32 v113, v2
	v_mov_b32_e32 v114, v2
	v_mov_b32_e32 v115, v2
	v_mov_b32_e32 v116, v2
	v_mov_b32_e32 v117, v2
	v_mov_b32_e32 v118, v2
	v_mov_b32_e32 v119, v2
	v_mov_b32_e32 v120, v2
	v_mov_b32_e32 v121, v2
	v_mov_b32_e32 v122, v2
	v_mov_b32_e32 v123, v2
	v_mov_b32_e32 v124, v2
	v_mov_b32_e32 v125, v2
	v_mov_b32_e32 v126, v2
	v_mov_b32_e32 v127, v2
	v_mov_b32_e32 v128, v2
	v_mov_b32_e32 v129, v2
	s_mov_b64 s[10:11], 0xbb0080
	s_mov_b64 s[22:23], 0xb00100
	s_mov_b64 s[24:25], 0xb0100
	s_mov_b64 s[26:27], 0xbb0100
	s_mov_b64 s[28:29], 0xb00180
	.p2align 6
; #define STA(P, br, kt) STAGE(P, A, aoff0, aoff1, lda, br, kt)
; #define STB(P, br, kt) STAGE(P, Bt, boff0, boff1, ldb, br, kt)
; #define LDA(dst, b, h) _Pragma("unroll") for (int m = 0; m < 4; ++m) _Pragma("unroll") for (int k = 0; k < 2; ++k) \
;     dst[m][k] = *reinterpret_cast<const bf16x8*>((char*)SA(b, h) + lds_byte(wr * 64 + m * 16 + fr, k * 32 + fq * 8))
; #define LDB(dst, b, h) _Pragma("unroll") for (int n = 0; n < 2; ++n) _Pragma("unroll") for (int k = 0; k < 2; ++k) \
;     dst[n][k] = *reinterpret_cast<const bf16x8*>((char*)SB(b, h) + lds_byte(wc * 32 + n * 16 + fr, k * 32 + fq * 8))
; #define MMA(ai, bj, At, Bq) do { __builtin_amdgcn_s_setprio(1); \
;     _Pragma("unroll") for (int m = 0; m < 4; ++m) _Pragma("unroll") for (int n = 0; n < 2; ++n) _Pragma("unroll") for (int k = 0; k < 2; ++k) \
;       acc[ai][bj][m][n] = __builtin_amdgcn_mfma_f32_16x16x32_bf16(At[m][k], Bq[n][k], acc[ai][bj][m][n], 0, 0, 0); \
;     __builtin_amdgcn_s_setprio(0); } while (0)
; #define WAIT_L(n) asm volatile("s_waitcnt lgkmcnt(" #n ")" ::: "memory")
; #define BAR __builtin_amdgcn_s_barrier()
; #define SCHED __builtin_amdgcn_sched_barrier(0)
; __device__ __forceinline__ void gemm256(const u16* __restrict__ A, int lda, const u16* __restrict__ Bt, int ldb, int K,
;                                         f32x4 (&acc)[2][2][4][2], const int g_wid) {
;     ...
;     LDB(B0, 0, 0); SCHED; LDA(At, 0, 0); STA(SA(1, 1), HALF, t + 1);
;     WAIT_L(8); BAR; WAIT_L(0); MMA(0, 0, At, B0); BAR; SCHED;
;     LDB(B1, 0, 1); STB(SB(0, 0), 0, t + 2);
;     BAR; WAIT_L(0); MMA(0, 1, At, B1); BAR;
;     LDA(At, 0, 1); STA(SA(0, 0), 0, t + 2);
;     BAR; WAIT_L(0); MMA(1, 0, At, B0); BAR; SCHED;
.LBB0_341:
	s_barrier
	ds_read_b128 v[178:181], v174
	ds_read_b128 v[182:185], v174 offset:1024
	ds_read_b128 v[186:189], v174 offset:2048
	ds_read_b128 v[190:193], v174 offset:3072
	v_add_u32_e32 v175, 0xc000, v159
	v_lshl_add_u64 v[242:243], v[138:139], 0, s[12:13]
	v_readfirstlane_b32 s15, v175
	v_lshl_add_u64 v[176:177], v[242:243], 0, s[10:11]
	s_mov_b32 m0, s15
	ds_read_b128 v[194:197], v145
	ds_read_b128 v[198:201], v145 offset:1024
	ds_read_b128 v[202:205], v144
	ds_read_b128 v[206:209], v144 offset:1024
	ds_read_b128 v[210:213], v143
	ds_read_b128 v[214:217], v143 offset:1024
	ds_read_b128 v[218:221], v142
	ds_read_b128 v[222:225], v142 offset:1024
	global_load_lds_dwordx4 v[176:177], off
	v_add_u32_e32 v176, 0xe000, v159
	v_lshl_add_u64 v[244:245], v[140:141], 0, s[12:13]
	v_readfirstlane_b32 s15, v176
	v_lshl_add_u64 v[226:227], v[244:245], 0, s[10:11]
	s_mov_b32 m0, s15
	s_nop 0
	global_load_lds_dwordx4 v[226:227], off
	s_waitcnt lgkmcnt(8)
	s_barrier
	s_waitcnt lgkmcnt(0)
	v_mfma_f32_16x16x32_bf16 v[126:129], v[194:197], v[178:181], v[126:129]
	v_mfma_f32_16x16x32_bf16 v[122:125], v[194:197], v[186:189], v[122:125]
	v_mfma_f32_16x16x32_bf16 v[118:121], v[202:205], v[178:181], v[118:121]
	v_mfma_f32_16x16x32_bf16 v[114:117], v[202:205], v[186:189], v[114:117]
	v_mfma_f32_16x16x32_bf16 v[110:113], v[210:213], v[178:181], v[110:113]
	v_mfma_f32_16x16x32_bf16 v[106:109], v[210:213], v[186:189], v[106:109]
	v_mfma_f32_16x16x32_bf16 v[102:105], v[218:221], v[178:181], v[102:105]
	v_mfma_f32_16x16x32_bf16 v[98:101], v[218:221], v[186:189], v[98:101]
	v_mfma_f32_16x16x32_bf16 v[126:129], v[198:201], v[182:185], v[126:129]
	v_mfma_f32_16x16x32_bf16 v[122:125], v[198:201], v[190:193], v[122:125]
	v_mfma_f32_16x16x32_bf16 v[118:121], v[206:209], v[182:185], v[118:121]
	v_mfma_f32_16x16x32_bf16 v[114:117], v[206:209], v[190:193], v[114:117]
	v_mfma_f32_16x16x32_bf16 v[110:113], v[214:217], v[182:185], v[110:113]
	v_mfma_f32_16x16x32_bf16 v[106:109], v[214:217], v[190:193], v[106:109]
	v_mfma_f32_16x16x32_bf16 v[102:105], v[222:225], v[182:185], v[102:105]
	v_mfma_f32_16x16x32_bf16 v[98:101], v[222:225], v[190:193], v[98:101]
	s_barrier
	v_lshl_add_u64 v[246:247], v[134:135], 0, s[12:13]
	v_readfirstlane_b32 s15, v146
	v_lshl_add_u64 v[248:249], v[246:247], 0, s[74:75]
	s_mov_b32 m0, s15
	ds_read_b128 v[226:229], v173
	ds_read_b128 v[230:233], v173 offset:1024
	ds_read_b128 v[234:237], v173 offset:2048
	ds_read_b128 v[238:241], v173 offset:3072
	global_load_lds_dwordx4 v[248:249], off
	v_lshl_add_u64 v[248:249], v[136:137], 0, s[12:13]
	v_readfirstlane_b32 s15, v147
	v_lshl_add_u64 v[250:251], v[248:249], 0, s[74:75]
	s_mov_b32 m0, s15
	s_nop 0
	global_load_lds_dwordx4 v[250:251], off
	s_barrier
	s_waitcnt lgkmcnt(0)
	v_mfma_f32_16x16x32_bf16 v[94:97], v[194:197], v[226:229], v[94:97]
	v_mfma_f32_16x16x32_bf16 v[90:93], v[194:197], v[234:237], v[90:93]
	v_mfma_f32_16x16x32_bf16 v[86:89], v[202:205], v[226:229], v[86:89]
	v_mfma_f32_16x16x32_bf16 v[82:85], v[202:205], v[234:237], v[82:85]
	v_mfma_f32_16x16x32_bf16 v[78:81], v[210:213], v[226:229], v[78:81]
	v_mfma_f32_16x16x32_bf16 v[74:77], v[210:213], v[234:237], v[74:77]
	v_mfma_f32_16x16x32_bf16 v[70:73], v[218:221], v[226:229], v[70:73]
	v_mfma_f32_16x16x32_bf16 v[66:69], v[218:221], v[234:237], v[66:69]
	v_mfma_f32_16x16x32_bf16 v[94:97], v[198:201], v[230:233], v[94:97]
	v_mfma_f32_16x16x32_bf16 v[90:93], v[198:201], v[238:241], v[90:93]
	v_mfma_f32_16x16x32_bf16 v[86:89], v[206:209], v[230:233], v[86:89]
	v_mfma_f32_16x16x32_bf16 v[82:85], v[206:209], v[238:241], v[82:85]
	v_mfma_f32_16x16x32_bf16 v[78:81], v[214:217], v[230:233], v[78:81]
	v_mfma_f32_16x16x32_bf16 v[74:77], v[214:217], v[238:241], v[74:77]
	v_mfma_f32_16x16x32_bf16 v[70:73], v[222:225], v[230:233], v[70:73]
	v_mfma_f32_16x16x32_bf16 v[66:69], v[222:225], v[238:241], v[66:69]
	v_readfirstlane_b32 s15, v159
	v_lshl_add_u64 v[250:251], v[242:243], 0, s[22:23]
	s_mov_b32 m0, s15
	v_readfirstlane_b32 s15, v161
	s_barrier
	ds_read_b128 v[194:197], v145 offset:16384
	ds_read_b128 v[198:201], v145 offset:17408
	ds_read_b128 v[202:205], v144 offset:16384
	ds_read_b128 v[206:209], v144 offset:17408
	ds_read_b128 v[210:213], v143 offset:16384
	ds_read_b128 v[214:217], v143 offset:17408
	ds_read_b128 v[218:221], v142 offset:16384
	ds_read_b128 v[222:225], v142 offset:17408
	global_load_lds_dwordx4 v[250:251], off
	v_lshl_add_u64 v[250:251], v[244:245], 0, s[22:23]
	s_mov_b32 m0, s15
	s_nop 0
	global_load_lds_dwordx4 v[250:251], off
	s_barrier
	s_waitcnt lgkmcnt(0)
	v_mfma_f32_16x16x32_bf16 v[62:65], v[194:197], v[178:181], v[62:65]
	v_mfma_f32_16x16x32_bf16 v[58:61], v[194:197], v[186:189], v[58:61]
	v_mfma_f32_16x16x32_bf16 v[54:57], v[202:205], v[178:181], v[54:57]
	v_mfma_f32_16x16x32_bf16 v[50:53], v[202:205], v[186:189], v[50:53]
	v_mfma_f32_16x16x32_bf16 v[46:49], v[210:213], v[178:181], v[46:49]
	v_mfma_f32_16x16x32_bf16 v[42:45], v[210:213], v[186:189], v[42:45]
	v_mfma_f32_16x16x32_bf16 v[38:41], v[218:221], v[178:181], v[38:41]
	v_mfma_f32_16x16x32_bf16 v[34:37], v[218:221], v[186:189], v[34:37]
	v_mfma_f32_16x16x32_bf16 v[62:65], v[198:201], v[182:185], v[62:65]
	v_mfma_f32_16x16x32_bf16 v[58:61], v[198:201], v[190:193], v[58:61]
	v_mfma_f32_16x16x32_bf16 v[54:57], v[206:209], v[182:185], v[54:57]
	v_mfma_f32_16x16x32_bf16 v[50:53], v[206:209], v[190:193], v[50:53]
	v_mfma_f32_16x16x32_bf16 v[46:49], v[214:217], v[182:185], v[46:49]
	v_mfma_f32_16x16x32_bf16 v[42:45], v[214:217], v[190:193], v[42:45]
	v_mfma_f32_16x16x32_bf16 v[38:41], v[222:225], v[182:185], v[38:41]
	v_mfma_f32_16x16x32_bf16 v[34:37], v[222:225], v[190:193], v[34:37]
	s_barrier
; #define STA(P, br, kt) STAGE(P, A, aoff0, aoff1, lda, br, kt)
; #define STB(P, br, kt) STAGE(P, Bt, boff0, boff1, ldb, br, kt)
; #define LDA(dst, b, h) _Pragma("unroll") for (int m = 0; m < 4; ++m) _Pragma("unroll") for (int k = 0; k < 2; ++k) \
;     dst[m][k] = *reinterpret_cast<const bf16x8*>((char*)SA(b, h) + lds_byte(wr * 64 + m * 16 + fr, k * 32 + fq * 8))
; #define LDB(dst, b, h) _Pragma("unroll") for (int n = 0; n < 2; ++n) _Pragma("unroll") for (int k = 0; k < 2; ++k) \
;     dst[n][k] = *reinterpret_cast<const bf16x8*>((char*)SB(b, h) + lds_byte(wc * 32 + n * 16 + fr, k * 32 + fq * 8))
; #define MMA(ai, bj, At, Bq) do { __builtin_amdgcn_s_setprio(1); \
;     _Pragma("unroll") for (int m = 0; m < 4; ++m) _Pragma("unroll") for (int n = 0; n < 2; ++n) _Pragma("unroll") for (int k = 0; k < 2; ++k) \
;       acc[ai][bj][m][n] = __builtin_amdgcn_mfma_f32_16x16x32_bf16(At[m][k], Bq[n][k], acc[ai][bj][m][n], 0, 0, 0); \
;     __builtin_amdgcn_s_setprio(0); } while (0)
; #define WAIT_V(n) asm volatile("s_waitcnt vmcnt(" #n ")" ::: "memory")
; #define WAIT_L(n) asm volatile("s_waitcnt lgkmcnt(" #n ")" ::: "memory")
; #define BAR __builtin_amdgcn_s_barrier()
; #define SCHED __builtin_amdgcn_sched_barrier(0)
; __device__ __forceinline__ void gemm256(const u16* __restrict__ A, int lda, const u16* __restrict__ Bt, int ldb, int K,
;                                         f32x4 (&acc)[2][2][4][2], const int g_wid) {
;     ...
;     STB(SB(0, 1), HALF, t + 2);
;     WAIT_V(6); BAR; MMA(1, 1, At, B1); BAR;
;     LDB(B0, 1, 0); SCHED; LDA(At, 1, 0); STA(SA(0, 1), HALF, t + 2);
;     WAIT_L(8); BAR; WAIT_L(0); MMA(0, 0, At, B0); BAR; SCHED;
;     LDB(B1, 1, 1); STB(SB(1, 0), 0, t + 3);
;     BAR; WAIT_L(0); MMA(0, 1, At, B1); BAR;
;     LDA(At, 1, 1); STA(SA(1, 0), 0, t + 3);
;     BAR; WAIT_L(0); MMA(1, 0, At, B0); BAR; SCHED;
	v_readfirstlane_b32 s15, v162
	v_lshl_add_u64 v[178:179], v[246:247], 0, s[24:25]
	s_mov_b32 m0, s15
	v_readfirstlane_b32 s15, v163
	global_load_lds_dwordx4 v[178:179], off
	v_lshl_add_u64 v[178:179], v[248:249], 0, s[24:25]
	s_mov_b32 m0, s15
	s_nop 0
	global_load_lds_dwordx4 v[178:179], off
	s_waitcnt vmcnt(6)
	s_barrier
	v_mfma_f32_16x16x32_bf16 v[30:33], v[194:197], v[226:229], v[30:33]
	v_mfma_f32_16x16x32_bf16 v[26:29], v[194:197], v[234:237], v[26:29]
	v_mfma_f32_16x16x32_bf16 v[22:25], v[202:205], v[226:229], v[22:25]
	v_mfma_f32_16x16x32_bf16 v[18:21], v[202:205], v[234:237], v[18:21]
	v_mfma_f32_16x16x32_bf16 v[14:17], v[210:213], v[226:229], v[14:17]
	v_mfma_f32_16x16x32_bf16 v[10:13], v[210:213], v[234:237], v[10:13]
	v_mfma_f32_16x16x32_bf16 v[6:9], v[218:221], v[226:229], v[6:9]
	v_mfma_f32_16x16x32_bf16 v[2:5], v[218:221], v[234:237], v[2:5]
	v_mfma_f32_16x16x32_bf16 v[30:33], v[198:201], v[230:233], v[30:33]
	v_mfma_f32_16x16x32_bf16 v[26:29], v[198:201], v[238:241], v[26:29]
	v_mfma_f32_16x16x32_bf16 v[22:25], v[206:209], v[230:233], v[22:25]
	v_mfma_f32_16x16x32_bf16 v[18:21], v[206:209], v[238:241], v[18:21]
	v_mfma_f32_16x16x32_bf16 v[14:17], v[214:217], v[230:233], v[14:17]
	v_mfma_f32_16x16x32_bf16 v[10:13], v[214:217], v[238:241], v[10:13]
	v_mfma_f32_16x16x32_bf16 v[6:9], v[222:225], v[230:233], v[6:9]
	v_mfma_f32_16x16x32_bf16 v[2:5], v[222:225], v[238:241], v[2:5]
	s_barrier
	ds_read_b128 v[178:181], v166
	ds_read_b128 v[182:185], v166 offset:1024
	ds_read_b128 v[186:189], v166 offset:2048
	ds_read_b128 v[190:193], v166 offset:3072
	v_readfirstlane_b32 s15, v164
	v_lshl_add_u64 v[226:227], v[242:243], 0, s[26:27]
	s_mov_b32 m0, s15
	v_readfirstlane_b32 s15, v165
	ds_read_b128 v[194:197], v145 offset:32768
	ds_read_b128 v[198:201], v145 offset:33792
	ds_read_b128 v[202:205], v144 offset:32768
	ds_read_b128 v[206:209], v144 offset:33792
	ds_read_b128 v[210:213], v143 offset:32768
	ds_read_b128 v[214:217], v143 offset:33792
	ds_read_b128 v[218:221], v142 offset:32768
	ds_read_b128 v[222:225], v142 offset:33792
	global_load_lds_dwordx4 v[226:227], off
	v_lshl_add_u64 v[226:227], v[244:245], 0, s[26:27]
	s_mov_b32 m0, s15
	s_nop 0
	global_load_lds_dwordx4 v[226:227], off
	s_waitcnt lgkmcnt(8)
	s_barrier
	s_waitcnt lgkmcnt(0)
	v_mfma_f32_16x16x32_bf16 v[126:129], v[194:197], v[178:181], v[126:129]
	v_mfma_f32_16x16x32_bf16 v[122:125], v[194:197], v[186:189], v[122:125]
	v_mfma_f32_16x16x32_bf16 v[118:121], v[202:205], v[178:181], v[118:121]
	v_mfma_f32_16x16x32_bf16 v[114:117], v[202:205], v[186:189], v[114:117]
	v_mfma_f32_16x16x32_bf16 v[110:113], v[210:213], v[178:181], v[110:113]
	v_mfma_f32_16x16x32_bf16 v[106:109], v[210:213], v[186:189], v[106:109]
	v_mfma_f32_16x16x32_bf16 v[102:105], v[218:221], v[178:181], v[102:105]
	v_mfma_f32_16x16x32_bf16 v[98:101], v[218:221], v[186:189], v[98:101]
	v_mfma_f32_16x16x32_bf16 v[126:129], v[198:201], v[182:185], v[126:129]
	v_mfma_f32_16x16x32_bf16 v[122:125], v[198:201], v[190:193], v[122:125]
	v_mfma_f32_16x16x32_bf16 v[118:121], v[206:209], v[182:185], v[118:121]
	v_mfma_f32_16x16x32_bf16 v[114:117], v[206:209], v[190:193], v[114:117]
	v_mfma_f32_16x16x32_bf16 v[110:113], v[214:217], v[182:185], v[110:113]
	v_mfma_f32_16x16x32_bf16 v[106:109], v[214:217], v[190:193], v[106:109]
	v_mfma_f32_16x16x32_bf16 v[102:105], v[222:225], v[182:185], v[102:105]
	v_mfma_f32_16x16x32_bf16 v[98:101], v[222:225], v[190:193], v[98:101]
	s_barrier
	v_readfirstlane_b32 s15, v167
	v_lshl_add_u64 v[250:251], v[246:247], 0, s[82:83]
	s_mov_b32 m0, s15
	v_readfirstlane_b32 s15, v168
	ds_read_b128 v[226:229], v160
	ds_read_b128 v[230:233], v160 offset:1024
	ds_read_b128 v[234:237], v160 offset:2048
	ds_read_b128 v[238:241], v160 offset:3072
	global_load_lds_dwordx4 v[250:251], off
	v_lshl_add_u64 v[250:251], v[248:249], 0, s[82:83]
	s_mov_b32 m0, s15
	s_nop 0
	global_load_lds_dwordx4 v[250:251], off
	s_barrier
	s_waitcnt lgkmcnt(0)
	v_mfma_f32_16x16x32_bf16 v[94:97], v[194:197], v[226:229], v[94:97]
	v_mfma_f32_16x16x32_bf16 v[90:93], v[194:197], v[234:237], v[90:93]
	v_mfma_f32_16x16x32_bf16 v[86:89], v[202:205], v[226:229], v[86:89]
	v_mfma_f32_16x16x32_bf16 v[82:85], v[202:205], v[234:237], v[82:85]
	v_mfma_f32_16x16x32_bf16 v[78:81], v[210:213], v[226:229], v[78:81]
	v_mfma_f32_16x16x32_bf16 v[74:77], v[210:213], v[234:237], v[74:77]
	v_mfma_f32_16x16x32_bf16 v[70:73], v[218:221], v[226:229], v[70:73]
	v_mfma_f32_16x16x32_bf16 v[66:69], v[218:221], v[234:237], v[66:69]
	v_mfma_f32_16x16x32_bf16 v[94:97], v[198:201], v[230:233], v[94:97]
	v_mfma_f32_16x16x32_bf16 v[90:93], v[198:201], v[238:241], v[90:93]
	v_mfma_f32_16x16x32_bf16 v[86:89], v[206:209], v[230:233], v[86:89]
	v_mfma_f32_16x16x32_bf16 v[82:85], v[206:209], v[238:241], v[82:85]
	v_mfma_f32_16x16x32_bf16 v[78:81], v[214:217], v[230:233], v[78:81]
	v_mfma_f32_16x16x32_bf16 v[74:77], v[214:217], v[238:241], v[74:77]
	v_mfma_f32_16x16x32_bf16 v[70:73], v[222:225], v[230:233], v[70:73]
	v_mfma_f32_16x16x32_bf16 v[66:69], v[222:225], v[238:241], v[66:69]
	v_readfirstlane_b32 s15, v169
	v_lshl_add_u64 v[242:243], v[242:243], 0, s[28:29]
	s_mov_b32 m0, s15
	v_readfirstlane_b32 s15, v170
	s_barrier
	ds_read_b128 v[194:197], v145 offset:49152
	ds_read_b128 v[198:201], v145 offset:50176
	ds_read_b128 v[202:205], v144 offset:49152
	ds_read_b128 v[206:209], v144 offset:50176
	ds_read_b128 v[210:213], v143 offset:49152
	ds_read_b128 v[214:217], v143 offset:50176
	ds_read_b128 v[218:221], v142 offset:49152
	ds_read_b128 v[222:225], v142 offset:50176
	global_load_lds_dwordx4 v[242:243], off
	v_lshl_add_u64 v[242:243], v[244:245], 0, s[28:29]
	s_mov_b32 m0, s15
	s_nop 0
	global_load_lds_dwordx4 v[242:243], off
	s_barrier
; #define STA(P, br, kt) STAGE(P, A, aoff0, aoff1, lda, br, kt)
; #define STB(P, br, kt) STAGE(P, Bt, boff0, boff1, ldb, br, kt)
; #define LDA(dst, b, h) _Pragma("unroll") for (int m = 0; m < 4; ++m) _Pragma("unroll") for (int k = 0; k < 2; ++k) \
;     dst[m][k] = *reinterpret_cast<const bf16x8*>((char*)SA(b, h) + lds_byte(wr * 64 + m * 16 + fr, k * 32 + fq * 8))
; #define LDB(dst, b, h) _Pragma("unroll") for (int n = 0; n < 2; ++n) _Pragma("unroll") for (int k = 0; k < 2; ++k) \
;     dst[n][k] = *reinterpret_cast<const bf16x8*>((char*)SB(b, h) + lds_byte(wc * 32 + n * 16 + fr, k * 32 + fq * 8))
; #define MMA(ai, bj, At, Bq) do { __builtin_amdgcn_s_setprio(1); \
;     _Pragma("unroll") for (int m = 0; m < 4; ++m) _Pragma("unroll") for (int n = 0; n < 2; ++n) _Pragma("unroll") for (int k = 0; k < 2; ++k) \
;       acc[ai][bj][m][n] = __builtin_amdgcn_mfma_f32_16x16x32_bf16(At[m][k], Bq[n][k], acc[ai][bj][m][n], 0, 0, 0); \
;     __builtin_amdgcn_s_setprio(0); } while (0)
; #define WAIT_V(n) asm volatile("s_waitcnt vmcnt(" #n ")" ::: "memory")
; #define WAIT_L(n) asm volatile("s_waitcnt lgkmcnt(" #n ")" ::: "memory")
; #define BAR __builtin_amdgcn_s_barrier()
; #define SCHED __builtin_amdgcn_sched_barrier(0)
; __device__ __forceinline__ void gemm256(const u16* __restrict__ A, int lda, const u16* __restrict__ Bt, int ldb, int K,
;                                         f32x4 (&acc)[2][2][4][2], const int g_wid) {
;     ...
;     BAR; WAIT_L(0); MMA(1, 0, At, B0); BAR; SCHED;
;     STB(SB(1, 1), HALF, t + 3);
;     WAIT_V(6); BAR; MMA(1, 1, At, B1); BAR;
;   }
;   { LDB(B0, 0, 0); LDA(At, 0, 0); STA(SA(1, 1), HALF, nt - 1);
;     BAR; WAIT_L(0); MMA(0, 0, At, B0); BAR;
;     LDB(B1, 0, 1); BAR; WAIT_L(0); MMA(0, 1, At, B1); BAR;
	s_waitcnt lgkmcnt(0)
	v_mfma_f32_16x16x32_bf16 v[62:65], v[194:197], v[178:181], v[62:65]
	v_mfma_f32_16x16x32_bf16 v[58:61], v[194:197], v[186:189], v[58:61]
	v_mfma_f32_16x16x32_bf16 v[54:57], v[202:205], v[178:181], v[54:57]
	v_mfma_f32_16x16x32_bf16 v[50:53], v[202:205], v[186:189], v[50:53]
	v_mfma_f32_16x16x32_bf16 v[46:49], v[210:213], v[178:181], v[46:49]
	v_mfma_f32_16x16x32_bf16 v[42:45], v[210:213], v[186:189], v[42:45]
	v_mfma_f32_16x16x32_bf16 v[38:41], v[218:221], v[178:181], v[38:41]
	v_mfma_f32_16x16x32_bf16 v[34:37], v[218:221], v[186:189], v[34:37]
	v_mfma_f32_16x16x32_bf16 v[62:65], v[198:201], v[182:185], v[62:65]
	v_mfma_f32_16x16x32_bf16 v[58:61], v[198:201], v[190:193], v[58:61]
	v_mfma_f32_16x16x32_bf16 v[54:57], v[206:209], v[182:185], v[54:57]
	v_mfma_f32_16x16x32_bf16 v[50:53], v[206:209], v[190:193], v[50:53]
	v_mfma_f32_16x16x32_bf16 v[46:49], v[214:217], v[182:185], v[46:49]
	v_mfma_f32_16x16x32_bf16 v[42:45], v[214:217], v[190:193], v[42:45]
	v_mfma_f32_16x16x32_bf16 v[38:41], v[222:225], v[182:185], v[38:41]
	v_mfma_f32_16x16x32_bf16 v[34:37], v[222:225], v[190:193], v[34:37]
	s_barrier
	v_readfirstlane_b32 s15, v171
	v_lshl_add_u64 v[178:179], v[246:247], 0, s[50:51]
	s_mov_b32 m0, s15
	v_readfirstlane_b32 s15, v172
	global_load_lds_dwordx4 v[178:179], off
	v_lshl_add_u64 v[178:179], v[248:249], 0, s[50:51]
	s_mov_b32 m0, s15
	s_nop 0
	global_load_lds_dwordx4 v[178:179], off
	s_waitcnt vmcnt(6)
	s_barrier
	v_mfma_f32_16x16x32_bf16 v[30:33], v[194:197], v[226:229], v[30:33]
	v_mfma_f32_16x16x32_bf16 v[26:29], v[194:197], v[234:237], v[26:29]
	v_mfma_f32_16x16x32_bf16 v[22:25], v[202:205], v[226:229], v[22:25]
	v_mfma_f32_16x16x32_bf16 v[18:21], v[202:205], v[234:237], v[18:21]
	v_mfma_f32_16x16x32_bf16 v[14:17], v[210:213], v[226:229], v[14:17]
	v_mfma_f32_16x16x32_bf16 v[10:13], v[210:213], v[234:237], v[10:13]
	v_mfma_f32_16x16x32_bf16 v[6:9], v[218:221], v[226:229], v[6:9]
	v_mfma_f32_16x16x32_bf16 v[2:5], v[218:221], v[234:237], v[2:5]
	v_mfma_f32_16x16x32_bf16 v[30:33], v[198:201], v[230:233], v[30:33]
	v_mfma_f32_16x16x32_bf16 v[26:29], v[198:201], v[238:241], v[26:29]
	v_mfma_f32_16x16x32_bf16 v[22:25], v[206:209], v[230:233], v[22:25]
	v_mfma_f32_16x16x32_bf16 v[18:21], v[206:209], v[238:241], v[18:21]
	v_mfma_f32_16x16x32_bf16 v[14:17], v[214:217], v[230:233], v[14:17]
	v_mfma_f32_16x16x32_bf16 v[10:13], v[214:217], v[238:241], v[10:13]
	v_mfma_f32_16x16x32_bf16 v[6:9], v[222:225], v[230:233], v[6:9]
	v_mfma_f32_16x16x32_bf16 v[2:5], v[222:225], v[238:241], v[2:5]
	s_add_i32 s14, s14, 2
	s_add_u32 s12, s12, 0x100
	s_addc_u32 s13, s13, 0
	s_cmp_lt_u32 s14, 40
	s_cbranch_scc1 .LBB0_341
	s_barrier
	s_add_u32 s2, s2, 0xb1580
	s_addc_u32 s3, s3, 0
	v_readfirstlane_b32 s12, v175
	v_lshl_add_u64 v[130:131], v[130:131], 1, s[2:3]
	s_mov_b32 m0, s12
	ds_read_b128 v[134:137], v174
	ds_read_b128 v[138:141], v174 offset:1024
	ds_read_b128 v[162:165], v174 offset:2048
	ds_read_b128 v[168:171], v174 offset:3072
	ds_read_b128 v[178:181], v145
	ds_read_b128 v[182:185], v145 offset:1024
	ds_read_b128 v[186:189], v144
	ds_read_b128 v[190:193], v144 offset:1024
	ds_read_b128 v[194:197], v143
	ds_read_b128 v[198:201], v143 offset:1024
	ds_read_b128 v[202:205], v142
	ds_read_b128 v[206:209], v142 offset:1024
	global_load_lds_dwordx4 v[130:131], off
	v_lshl_add_u64 v[130:131], v[132:133], 1, s[2:3]
	v_readfirstlane_b32 s2, v176
	s_mov_b32 m0, s2
	s_nop 0
	global_load_lds_dwordx4 v[130:131], off
	s_barrier
	s_waitcnt lgkmcnt(0)
	v_mfma_f32_16x16x32_bf16 v[126:129], v[178:181], v[134:137], v[126:129]
	v_mfma_f32_16x16x32_bf16 v[118:121], v[186:189], v[134:137], v[118:121]
	v_mfma_f32_16x16x32_bf16 v[114:117], v[186:189], v[162:165], v[114:117]
	v_mfma_f32_16x16x32_bf16 v[110:113], v[194:197], v[134:137], v[110:113]
	v_mfma_f32_16x16x32_bf16 v[106:109], v[194:197], v[162:165], v[106:109]
	v_mfma_f32_16x16x32_bf16 v[102:105], v[202:205], v[134:137], v[102:105]
	v_mfma_f32_16x16x32_bf16 v[98:101], v[202:205], v[162:165], v[98:101]
	v_mfma_f32_16x16x32_bf16 v[126:129], v[182:185], v[138:141], v[126:129]
	v_mfma_f32_16x16x32_bf16 v[122:125], v[178:181], v[162:165], v[122:125]
	v_mfma_f32_16x16x32_bf16 v[118:121], v[190:193], v[138:141], v[118:121]
	v_mfma_f32_16x16x32_bf16 v[114:117], v[190:193], v[168:171], v[114:117]
	v_mfma_f32_16x16x32_bf16 v[110:113], v[198:201], v[138:141], v[110:113]
	v_mfma_f32_16x16x32_bf16 v[106:109], v[198:201], v[168:171], v[106:109]
	v_mfma_f32_16x16x32_bf16 v[102:105], v[206:209], v[138:141], v[102:105]
	v_mfma_f32_16x16x32_bf16 v[98:101], v[206:209], v[168:171], v[98:101]
	v_mfma_f32_16x16x32_bf16 v[130:133], v[182:185], v[168:171], v[122:125]
	s_barrier
	s_nop 0
	ds_read_b128 v[122:125], v173
	ds_read_b128 v[174:177], v173 offset:1024
	ds_read_b128 v[210:213], v173 offset:2048
	ds_read_b128 v[214:217], v173 offset:3072
	s_barrier
	s_waitcnt lgkmcnt(0)
	v_mfma_f32_16x16x32_bf16 v[78:81], v[194:197], v[122:125], v[78:81]
	v_mfma_f32_16x16x32_bf16 v[74:77], v[194:197], v[210:213], v[74:77]
	v_mfma_f32_16x16x32_bf16 v[70:73], v[202:205], v[122:125], v[70:73]
	v_mfma_f32_16x16x32_bf16 v[66:69], v[202:205], v[210:213], v[66:69]
	v_mfma_f32_16x16x32_bf16 v[94:97], v[178:181], v[122:125], v[94:97]
	v_mfma_f32_16x16x32_bf16 v[90:93], v[178:181], v[210:213], v[90:93]
	v_mfma_f32_16x16x32_bf16 v[86:89], v[186:189], v[122:125], v[86:89]
	v_mfma_f32_16x16x32_bf16 v[82:85], v[186:189], v[210:213], v[82:85]
	v_mfma_f32_16x16x32_bf16 v[78:81], v[198:201], v[174:177], v[78:81]
	v_mfma_f32_16x16x32_bf16 v[74:77], v[198:201], v[214:217], v[74:77]
	v_mfma_f32_16x16x32_bf16 v[70:73], v[206:209], v[174:177], v[70:73]
	v_mfma_f32_16x16x32_bf16 v[66:69], v[206:209], v[214:217], v[66:69]
	v_mfma_f32_16x16x32_bf16 v[218:221], v[182:185], v[174:177], v[94:97]
	v_mfma_f32_16x16x32_bf16 v[178:181], v[182:185], v[214:217], v[90:93]
	v_mfma_f32_16x16x32_bf16 v[182:185], v[190:193], v[174:177], v[86:89]
	v_mfma_f32_16x16x32_bf16 v[186:189], v[190:193], v[214:217], v[82:85]
	s_barrier
; #define LDA(dst, b, h) _Pragma("unroll") for (int m = 0; m < 4; ++m) _Pragma("unroll") for (int k = 0; k < 2; ++k) \
;     dst[m][k] = *reinterpret_cast<const bf16x8*>((char*)SA(b, h) + lds_byte(wr * 64 + m * 16 + fr, k * 32 + fq * 8))
; #define LDB(dst, b, h) _Pragma("unroll") for (int n = 0; n < 2; ++n) _Pragma("unroll") for (int k = 0; k < 2; ++k) \
;     dst[n][k] = *reinterpret_cast<const bf16x8*>((char*)SB(b, h) + lds_byte(wc * 32 + n * 16 + fr, k * 32 + fq * 8))
; #define MMA(ai, bj, At, Bq) do { __builtin_amdgcn_s_setprio(1); \
;     _Pragma("unroll") for (int m = 0; m < 4; ++m) _Pragma("unroll") for (int n = 0; n < 2; ++n) _Pragma("unroll") for (int k = 0; k < 2; ++k) \
;       acc[ai][bj][m][n] = __builtin_amdgcn_mfma_f32_16x16x32_bf16(At[m][k], Bq[n][k], acc[ai][bj][m][n], 0, 0, 0); \
;     __builtin_amdgcn_s_setprio(0); } while (0)
; #define WAIT_V(n) asm volatile("s_waitcnt vmcnt(" #n ")" ::: "memory")
; #define WAIT_L(n) asm volatile("s_waitcnt lgkmcnt(" #n ")" ::: "memory")
; #define BAR __builtin_amdgcn_s_barrier()
; __device__ __forceinline__ void gemm256(const u16* __restrict__ A, int lda, const u16* __restrict__ Bt, int ldb, int K,
;                                         f32x4 (&acc)[2][2][4][2], const int g_wid) {
;     ...
;     LDA(At, 0, 1); WAIT_V(4); BAR; WAIT_L(0); MMA(1, 0, At, B0); MMA(1, 1, At, B1); BAR; }
;   { LDB(B0, 1, 0); LDA(At, 1, 0); WAIT_V(2); BAR; WAIT_L(0); MMA(0, 0, At, B0); BAR;
	s_nop 0
	ds_read_b128 v[82:85], v145 offset:16384
	ds_read_b128 v[86:89], v145 offset:17408
	ds_read_b128 v[90:93], v144 offset:16384
	ds_read_b128 v[94:97], v144 offset:17408
	ds_read_b128 v[190:193], v143 offset:16384
	ds_read_b128 v[194:197], v143 offset:17408
	ds_read_b128 v[198:201], v142 offset:16384
	ds_read_b128 v[202:205], v142 offset:17408
	s_waitcnt vmcnt(4)
	s_barrier
	s_waitcnt lgkmcnt(0)
	v_mfma_f32_16x16x32_bf16 v[46:49], v[190:193], v[134:137], v[46:49]
	v_mfma_f32_16x16x32_bf16 v[42:45], v[190:193], v[162:165], v[42:45]
	v_mfma_f32_16x16x32_bf16 v[38:41], v[198:201], v[134:137], v[38:41]
	v_mfma_f32_16x16x32_bf16 v[34:37], v[198:201], v[162:165], v[34:37]
	v_mfma_f32_16x16x32_bf16 v[62:65], v[82:85], v[134:137], v[62:65]
	v_mfma_f32_16x16x32_bf16 v[58:61], v[82:85], v[162:165], v[58:61]
	v_mfma_f32_16x16x32_bf16 v[54:57], v[90:93], v[134:137], v[54:57]
	v_mfma_f32_16x16x32_bf16 v[50:53], v[90:93], v[162:165], v[50:53]
	v_mfma_f32_16x16x32_bf16 v[46:49], v[194:197], v[138:141], v[46:49]
	v_mfma_f32_16x16x32_bf16 v[42:45], v[194:197], v[168:171], v[42:45]
	v_mfma_f32_16x16x32_bf16 v[38:41], v[202:205], v[138:141], v[38:41]
	v_mfma_f32_16x16x32_bf16 v[34:37], v[202:205], v[168:171], v[34:37]
	v_mfma_f32_16x16x32_bf16 v[206:209], v[86:89], v[138:141], v[62:65]
	v_mfma_f32_16x16x32_bf16 v[222:225], v[86:89], v[168:171], v[58:61]
	v_mfma_f32_16x16x32_bf16 v[226:229], v[94:97], v[138:141], v[54:57]
	v_mfma_f32_16x16x32_bf16 v[230:233], v[94:97], v[168:171], v[50:53]
	v_mfma_f32_16x16x32_bf16 v[2:5], v[198:201], v[210:213], v[2:5]
	v_mfma_f32_16x16x32_bf16 v[30:33], v[82:85], v[122:125], v[30:33]
	v_mfma_f32_16x16x32_bf16 v[26:29], v[82:85], v[210:213], v[26:29]
	v_mfma_f32_16x16x32_bf16 v[22:25], v[90:93], v[122:125], v[22:25]
	v_mfma_f32_16x16x32_bf16 v[18:21], v[90:93], v[210:213], v[18:21]
	v_mfma_f32_16x16x32_bf16 v[14:17], v[190:193], v[122:125], v[14:17]
	v_mfma_f32_16x16x32_bf16 v[10:13], v[190:193], v[210:213], v[10:13]
	v_mfma_f32_16x16x32_bf16 v[6:9], v[198:201], v[122:125], v[6:9]
	v_mfma_f32_16x16x32_bf16 v[2:5], v[202:205], v[214:217], v[2:5]
	v_mfma_f32_16x16x32_bf16 v[134:137], v[86:89], v[174:177], v[30:33]
	v_mfma_f32_16x16x32_bf16 v[138:141], v[86:89], v[214:217], v[26:29]
	v_mfma_f32_16x16x32_bf16 v[162:165], v[94:97], v[174:177], v[22:25]
	v_mfma_f32_16x16x32_bf16 v[168:171], v[94:97], v[214:217], v[18:21]
	v_mfma_f32_16x16x32_bf16 v[234:237], v[194:197], v[174:177], v[14:17]
	v_mfma_f32_16x16x32_bf16 v[190:193], v[194:197], v[214:217], v[10:13]
	v_mfma_f32_16x16x32_bf16 v[172:175], v[202:205], v[174:177], v[6:9]
	s_barrier
	s_nop 0
	ds_read_b128 v[6:9], v166
	ds_read_b128 v[10:13], v166 offset:1024
	ds_read_b128 v[14:17], v166 offset:2048
	ds_read_b128 v[194:197], v166 offset:3072
	ds_read_b128 v[18:21], v145 offset:32768
	ds_read_b128 v[22:25], v145 offset:33792
	ds_read_b128 v[30:33], v144 offset:32768
	ds_read_b128 v[50:53], v144 offset:33792
	ds_read_b128 v[198:201], v143 offset:32768
	ds_read_b128 v[202:205], v143 offset:33792
	ds_read_b128 v[210:213], v142 offset:32768
	ds_read_b128 v[214:217], v142 offset:33792
	s_waitcnt vmcnt(2)
	s_barrier
	s_waitcnt lgkmcnt(0)
	v_mfma_f32_16x16x32_bf16 v[26:29], v[18:21], v[6:9], v[126:129]
	v_mfma_f32_16x16x32_bf16 v[122:125], v[22:25], v[10:13], v[26:29]
	v_mfma_f32_16x16x32_bf16 v[26:29], v[18:21], v[14:17], v[130:133]
	v_mfma_f32_16x16x32_bf16 v[90:93], v[22:25], v[194:197], v[26:29]
	v_mfma_f32_16x16x32_bf16 v[26:29], v[30:33], v[6:9], v[118:121]
	v_mfma_f32_16x16x32_bf16 v[126:129], v[50:53], v[10:13], v[26:29]
	v_mfma_f32_16x16x32_bf16 v[26:29], v[30:33], v[14:17], v[114:117]
	v_mfma_f32_16x16x32_bf16 v[94:97], v[50:53], v[194:197], v[26:29]
	v_mfma_f32_16x16x32_bf16 v[26:29], v[198:201], v[6:9], v[110:113]
	v_mfma_f32_16x16x32_bf16 v[118:121], v[202:205], v[10:13], v[26:29]
	v_mfma_f32_16x16x32_bf16 v[26:29], v[198:201], v[14:17], v[106:109]
	v_mfma_f32_16x16x32_bf16 v[86:89], v[202:205], v[194:197], v[26:29]
	v_mfma_f32_16x16x32_bf16 v[26:29], v[210:213], v[6:9], v[102:105]
	v_mfma_f32_16x16x32_bf16 v[114:117], v[214:217], v[10:13], v[26:29]
	v_mfma_f32_16x16x32_bf16 v[26:29], v[210:213], v[14:17], v[98:101]
	v_mfma_f32_16x16x32_bf16 v[82:85], v[214:217], v[194:197], v[26:29]
	s_barrier
; #define LDA(dst, b, h) _Pragma("unroll") for (int m = 0; m < 4; ++m) _Pragma("unroll") for (int k = 0; k < 2; ++k) \
;     dst[m][k] = *reinterpret_cast<const bf16x8*>((char*)SA(b, h) + lds_byte(wr * 64 + m * 16 + fr, k * 32 + fq * 8))
; #define LDB(dst, b, h) _Pragma("unroll") for (int n = 0; n < 2; ++n) _Pragma("unroll") for (int k = 0; k < 2; ++k) \
;     dst[n][k] = *reinterpret_cast<const bf16x8*>((char*)SB(b, h) + lds_byte(wc * 32 + n * 16 + fr, k * 32 + fq * 8))
; #define MMA(ai, bj, At, Bq) do { __builtin_amdgcn_s_setprio(1); \
;     _Pragma("unroll") for (int m = 0; m < 4; ++m) _Pragma("unroll") for (int n = 0; n < 2; ++n) _Pragma("unroll") for (int k = 0; k < 2; ++k) \
;       acc[ai][bj][m][n] = __builtin_amdgcn_mfma_f32_16x16x32_bf16(At[m][k], Bq[n][k], acc[ai][bj][m][n], 0, 0, 0); \
;     __builtin_amdgcn_s_setprio(0); } while (0)
; #define WAIT_V(n) asm volatile("s_waitcnt vmcnt(" #n ")" ::: "memory")
; #define WAIT_L(n) asm volatile("s_waitcnt lgkmcnt(" #n ")" ::: "memory")
; #define BAR __builtin_amdgcn_s_barrier()
; __device__ __forceinline__ void gemm256(const u16* __restrict__ A, int lda, const u16* __restrict__ Bt, int ldb, int K,
;                                         f32x4 (&acc)[2][2][4][2], const int g_wid) {
;     ...
;     LDB(B1, 1, 1); WAIT_V(0); BAR; WAIT_L(0); MMA(0, 1, At, B1); BAR;
;     LDA(At, 1, 1); BAR; WAIT_L(0); MMA(1, 0, At, B0); MMA(1, 1, At, B1); BAR; }
;   if (wr == 0) BAR;
	ds_read_b128 v[130:133], v160
	ds_read_b128 v[238:241], v160 offset:1024
	ds_read_b128 v[242:245], v160 offset:2048
	ds_read_b128 v[246:249], v160 offset:3072
	s_waitcnt vmcnt(0)
	s_barrier
	s_waitcnt lgkmcnt(0)
	v_mfma_f32_16x16x32_bf16 v[26:29], v[18:21], v[130:133], v[218:221]
	v_mfma_f32_16x16x32_bf16 v[18:21], v[18:21], v[242:245], v[178:181]
	v_mfma_f32_16x16x32_bf16 v[58:61], v[22:25], v[238:241], v[26:29]
	v_mfma_f32_16x16x32_bf16 v[26:29], v[22:25], v[246:249], v[18:21]
	v_mfma_f32_16x16x32_bf16 v[18:21], v[30:33], v[130:133], v[182:185]
	v_mfma_f32_16x16x32_bf16 v[62:65], v[50:53], v[238:241], v[18:21]
	v_mfma_f32_16x16x32_bf16 v[18:21], v[30:33], v[242:245], v[186:189]
	v_mfma_f32_16x16x32_bf16 v[30:33], v[50:53], v[246:249], v[18:21]
	v_mfma_f32_16x16x32_bf16 v[18:21], v[198:201], v[130:133], v[78:81]
	v_mfma_f32_16x16x32_bf16 v[54:57], v[202:205], v[238:241], v[18:21]
	v_mfma_f32_16x16x32_bf16 v[18:21], v[198:201], v[242:245], v[74:77]
	v_mfma_f32_16x16x32_bf16 v[22:25], v[202:205], v[246:249], v[18:21]
	v_mfma_f32_16x16x32_bf16 v[18:21], v[210:213], v[130:133], v[70:73]
	v_mfma_f32_16x16x32_bf16 v[50:53], v[214:217], v[238:241], v[18:21]
	v_mfma_f32_16x16x32_bf16 v[18:21], v[210:213], v[242:245], v[66:69]
	v_mfma_f32_16x16x32_bf16 v[18:21], v[214:217], v[246:249], v[18:21]
	s_barrier
	ds_read_b128 v[176:179], v145 offset:49152
	ds_read_b128 v[180:183], v145 offset:50176
	ds_read_b128 v[184:187], v144 offset:49152
	ds_read_b128 v[144:147], v144 offset:50176
	ds_read_b128 v[198:201], v143 offset:49152
	ds_read_b128 v[202:205], v143 offset:50176
	ds_read_b128 v[210:213], v142 offset:49152
	ds_read_b128 v[214:217], v142 offset:50176
	s_barrier
	s_waitcnt lgkmcnt(0)
	v_mfma_f32_16x16x32_bf16 v[66:69], v[176:179], v[6:9], v[206:209]
	v_mfma_f32_16x16x32_bf16 v[110:113], v[180:183], v[10:13], v[66:69]
	v_mfma_f32_16x16x32_bf16 v[66:69], v[176:179], v[14:17], v[222:225]
	v_mfma_f32_16x16x32_bf16 v[78:81], v[180:183], v[194:197], v[66:69]
	v_mfma_f32_16x16x32_bf16 v[66:69], v[184:187], v[6:9], v[226:229]
	v_mfma_f32_16x16x32_bf16 v[46:49], v[198:201], v[6:9], v[46:49]
	v_mfma_f32_16x16x32_bf16 v[6:9], v[210:213], v[6:9], v[38:41]
	v_mfma_f32_16x16x32_bf16 v[106:109], v[144:147], v[10:13], v[66:69]
	v_mfma_f32_16x16x32_bf16 v[66:69], v[184:187], v[14:17], v[230:233]
	v_mfma_f32_16x16x32_bf16 v[42:45], v[198:201], v[14:17], v[42:45]
	v_mfma_f32_16x16x32_bf16 v[98:101], v[214:217], v[10:13], v[6:9]
	v_mfma_f32_16x16x32_bf16 v[6:9], v[210:213], v[14:17], v[34:37]
	v_mfma_f32_16x16x32_bf16 v[74:77], v[144:147], v[194:197], v[66:69]
	v_mfma_f32_16x16x32_bf16 v[102:105], v[202:205], v[10:13], v[46:49]
	v_mfma_f32_16x16x32_bf16 v[70:73], v[202:205], v[194:197], v[42:45]
	v_mfma_f32_16x16x32_bf16 v[66:69], v[214:217], v[194:197], v[6:9]
	v_mfma_f32_16x16x32_bf16 v[6:9], v[176:179], v[130:133], v[134:137]
	v_mfma_f32_16x16x32_bf16 v[46:49], v[180:183], v[238:241], v[6:9]
	v_mfma_f32_16x16x32_bf16 v[6:9], v[176:179], v[242:245], v[138:141]
	v_mfma_f32_16x16x32_bf16 v[14:17], v[180:183], v[246:249], v[6:9]
	v_mfma_f32_16x16x32_bf16 v[6:9], v[184:187], v[130:133], v[162:165]
	v_mfma_f32_16x16x32_bf16 v[42:45], v[144:147], v[238:241], v[6:9]
	v_mfma_f32_16x16x32_bf16 v[6:9], v[184:187], v[242:245], v[168:171]
	v_mfma_f32_16x16x32_bf16 v[10:13], v[144:147], v[246:249], v[6:9]
	v_mfma_f32_16x16x32_bf16 v[6:9], v[198:201], v[130:133], v[234:237]
	v_mfma_f32_16x16x32_bf16 v[38:41], v[202:205], v[238:241], v[6:9]
	v_mfma_f32_16x16x32_bf16 v[6:9], v[198:201], v[242:245], v[190:193]
	v_mfma_f32_16x16x32_bf16 v[34:37], v[210:213], v[130:133], v[172:175]
	v_mfma_f32_16x16x32_bf16 v[2:5], v[210:213], v[242:245], v[2:5]
	v_mfma_f32_16x16x32_bf16 v[6:9], v[202:205], v[246:249], v[6:9]
	v_mfma_f32_16x16x32_bf16 v[34:37], v[214:217], v[238:241], v[34:37]
	v_mfma_f32_16x16x32_bf16 v[2:5], v[214:217], v[246:249], v[2:5]
	s_setprio 0
	s_movk_i32 s2, 0x100
	v_cmp_gt_u32_e32 vcc, s2, v0
	s_barrier
	s_and_saveexec_b64 s[2:3], vcc
	s_cbranch_execz .LBB0_344
	s_barrier

; #define hw_tid() ((g_wid << 6) | hw_lane())
; #define STA(P, br, kt) STAGE(P, A, aoff0, aoff1, lda, br, kt)
; #define STB(P, br, kt) STAGE(P, Bt, boff0, boff1, ldb, br, kt)
; #define WAIT_V(n) asm volatile("s_waitcnt vmcnt(" #n ")" ::: "memory")
; #define BAR __builtin_amdgcn_s_barrier()
; __device__ __forceinline__ void gemm256(const u16* __restrict__ A, int lda, const u16* __restrict__ Bt, int ldb, int K,
;                                         f32x4 (&acc)[2][2][4][2], const int g_wid) {
;   int tid = hw_tid(); asm volatile("" : "+v"(tid));
;   const int wid = tid >> 6, lane = tid & 63, wr = wid >> 2, wc = wid & 3, fr = lane & 15, fq = lane >> 4;
;   int r0, c0, r1, c1;
;   stage_rc(tid * 16, r0, c0);
;   stage_rc(tid * 16 + 8192, r1, c1);
;   const int aoff0 = r0 * lda + c0, aoff1 = r1 * lda + c1, boff0 = r0 * ldb + c0, boff1 = r1 * ldb + c1;
;   bf16x8 At[4][2], B0[2][2], B1[2][2];
;   const int nt = K / BK;
;   STB(SB(0, 0), 0, 0); STA(SA(0, 0), 0, 0);
;   STB(SB(0, 1), HALF, 0); STA(SA(0, 1), HALF, 0);
;   if (wr == 1) BAR;
;   WAIT_V(4); BAR;
;   STB(SB(1, 0), 0, 1); STA(SA(1, 0), 0, 1); STB(SB(1, 1), HALF, 1);
;   WAIT_V(6); BAR;
.LBB0_464:
	s_or_b64 exec, exec, s[22:23]
	v_readlane_b32 s10, v254, 42
	s_mov_b64 s[22:23], 0x80
	v_lshl_add_u64 v[2:3], v[2:3], 0, s[22:23]
	v_add_u32_e32 v169, s10, v15
	v_add_u32_e32 v170, 0x2000, v169
	v_readfirstlane_b32 s9, v169
	s_mov_b32 m0, s9
	v_readfirstlane_b32 s9, v170
	v_add_u32_e32 v171, 0x8000, v162
	s_waitcnt vmcnt(4)
	s_barrier
	global_load_lds_dwordx4 v[2:3], off
	v_lshl_add_u64 v[2:3], v[6:7], 0, s[22:23]
	s_mov_b32 m0, s9
	v_readfirstlane_b32 s9, v171
	v_add_u32_e32 v172, 0xa000, v162
	v_readlane_b32 s11, v254, 43
	global_load_lds_dwordx4 v[2:3], off
	v_lshl_add_u64 v[2:3], v[8:9], 0, s[22:23]
	s_mov_b32 m0, s9
	v_readfirstlane_b32 s9, v172
	s_add_u32 s20, s20, 0x40080
	v_add_u32_e32 v173, s11, v15
	global_load_lds_dwordx4 v[2:3], off
	v_lshl_add_u64 v[2:3], v[4:5], 0, s[22:23]
	s_mov_b32 m0, s9
	s_addc_u32 s21, s21, 0
	v_readfirstlane_b32 s9, v173
	v_add_u32_e32 v174, 0x2000, v173
	global_load_lds_dwordx4 v[2:3], off
	v_lshl_add_u64 v[2:3], v[132:133], 1, s[20:21]
	s_mov_b32 m0, s9
	v_readfirstlane_b32 s9, v174
	global_load_lds_dwordx4 v[2:3], off
	v_lshl_add_u64 v[2:3], v[130:131], 1, s[20:21]
	s_mov_b32 m0, s9
	v_and_b32_e32 v20, 15, v0
	global_load_lds_dwordx4 v[2:3], off
	v_lshlrev_b32_e32 v3, 2, v0
	v_and_b32_e32 v21, 48, v0
	v_lshlrev_b32_e32 v2, 6, v20
	v_and_b32_e32 v3, 32, v3
	v_bitop3_b32 v2, v2, v3, v21 bitop3:0x36
	v_readlane_b32 s9, v254, 40
	v_lshlrev_b32_e32 v4, 6, v0
	v_add_u32_e32 v8, s10, v2
	v_add_u32_e32 v6, s9, v2
	v_readlane_b32 s9, v254, 41
	v_add_u32_e32 v9, s11, v2
	v_add_u32_e32 v20, 0, v2
	v_add_u32_e32 v7, s9, v2
	s_movk_i32 s9, 0x3c0
	v_and_or_b32 v2, v4, s9, v21
	v_xad_u32 v21, v2, v3, 0
	v_lshlrev_b32_e32 v2, 13, v14
	v_and_b32_e32 v15, 0x3000, v4
	v_and_b32_e32 v2, 0xffffc000, v2
	v_lshlrev_b32_e32 v4, 13, v10
	v_lshl_add_u32 v2, v16, 10, v2
	v_and_b32_e32 v4, 0xffffc000, v4
	v_or_b32_e32 v2, v2, v17
	s_add_u32 s18, s6, s18
	v_lshl_add_u32 v4, v11, 10, v4
	v_add_u32_sdwa v2, v2, sext(v18) dst_sel:DWORD dst_unused:UNUSED_PAD src0_sel:DWORD src1_sel:WORD_0
	s_addc_u32 s19, s7, s19
	v_or_b32_e32 v4, v4, v12
	v_ashrrev_i32_e32 v3, 31, v2
	v_add_u32_sdwa v4, v4, sext(v13) dst_sel:DWORD dst_unused:UNUSED_PAD src0_sel:DWORD src1_sel:WORD_0
	s_add_u32 s16, s4, s16
	s_waitcnt vmcnt(6)
	v_lshlrev_b32_e32 v19, 13, v19
	v_lshlrev_b64 v[2:3], 1, v[2:3]
	v_ashrrev_i32_e32 v5, 31, v4
	s_addc_u32 s17, s5, s17
	v_or_b32_e32 v22, 0x800, v19
	v_or_b32_e32 v23, 0x1000, v19
	v_or_b32_e32 v24, 0x1800, v19
	v_lshl_add_u64 v[134:135], s[18:19], 0, v[2:3]
	v_lshlrev_b64 v[4:5], 1, v[4:5]
	v_lshl_add_u64 v[138:139], s[16:17], 0, v[2:3]
	v_mov_b32_e32 v2, 0
	v_lshl_add_u64 v[136:137], s[18:19], 0, v[4:5]
	v_lshl_add_u64 v[140:141], s[16:17], 0, v[4:5]
	s_mov_b32 s9, -2
	s_mov_b64 s[16:17], 0
	v_add_u32_e32 v176, v6, v15
	v_add_u32_e32 v147, v20, v19
	v_add_u32_e32 v146, v21, v22
	v_add_u32_e32 v145, v21, v23
	v_add_u32_e32 v144, v21, v24
	v_add_u32_e32 v175, v7, v15
	v_add_u32_e32 v167, v8, v15
	v_add_u32_e32 v161, v9, v15
	v_mov_b32_e32 v3, v2
	v_mov_b32_e32 v4, v2
	v_mov_b32_e32 v5, v2
	v_mov_b32_e32 v6, v2
	v_mov_b32_e32 v7, v2
	v_mov_b32_e32 v8, v2
	v_mov_b32_e32 v9, v2
	v_mov_b32_e32 v10, v2
	v_mov_b32_e32 v11, v2
	v_mov_b32_e32 v12, v2
	v_mov_b32_e32 v13, v2
	v_mov_b32_e32 v14, v2
	v_mov_b32_e32 v15, v2
	v_mov_b32_e32 v16, v2
	v_mov_b32_e32 v17, v2
	v_mov_b32_e32 v18, v2
	v_mov_b32_e32 v19, v2
	v_mov_b32_e32 v20, v2
	v_mov_b32_e32 v21, v2
	v_mov_b32_e32 v22, v2
	v_mov_b32_e32 v23, v2
	v_mov_b32_e32 v24, v2
	v_mov_b32_e32 v25, v2
	v_mov_b32_e32 v26, v2
	v_mov_b32_e32 v27, v2
	v_mov_b32_e32 v28, v2
	v_mov_b32_e32 v29, v2
	v_mov_b32_e32 v30, v2
	v_mov_b32_e32 v31, v2
	v_mov_b32_e32 v32, v2
	v_mov_b32_e32 v33, v2
	v_mov_b32_e32 v34, v2
	v_mov_b32_e32 v35, v2
	v_mov_b32_e32 v36, v2
	v_mov_b32_e32 v37, v2
	v_mov_b32_e32 v38, v2
	v_mov_b32_e32 v39, v2
	v_mov_b32_e32 v40, v2
	v_mov_b32_e32 v41, v2
	v_mov_b32_e32 v42, v2
	v_mov_b32_e32 v43, v2
	v_mov_b32_e32 v44, v2
	v_mov_b32_e32 v45, v2
	v_mov_b32_e32 v46, v2
	v_mov_b32_e32 v47, v2
	v_mov_b32_e32 v48, v2
	v_mov_b32_e32 v49, v2
	v_mov_b32_e32 v50, v2
	v_mov_b32_e32 v51, v2
	v_mov_b32_e32 v52, v2
	v_mov_b32_e32 v53, v2
	v_mov_b32_e32 v54, v2
	v_mov_b32_e32 v55, v2
	v_mov_b32_e32 v56, v2
	v_mov_b32_e32 v57, v2
	v_mov_b32_e32 v58, v2
	v_mov_b32_e32 v59, v2
	v_mov_b32_e32 v60, v2
	v_mov_b32_e32 v61, v2
	v_mov_b32_e32 v62, v2
	v_mov_b32_e32 v63, v2
	v_mov_b32_e32 v64, v2
	v_mov_b32_e32 v65, v2
	v_mov_b32_e32 v66, v2
	v_mov_b32_e32 v67, v2
	v_mov_b32_e32 v68, v2
	v_mov_b32_e32 v69, v2
	v_mov_b32_e32 v70, v2
	v_mov_b32_e32 v71, v2
	v_mov_b32_e32 v72, v2
	v_mov_b32_e32 v73, v2
	v_mov_b32_e32 v74, v2
	v_mov_b32_e32 v75, v2
	v_mov_b32_e32 v76, v2
	v_mov_b32_e32 v77, v2
	v_mov_b32_e32 v78, v2
	v_mov_b32_e32 v79, v2
	v_mov_b32_e32 v80, v2
	v_mov_b32_e32 v81, v2
	v_mov_b32_e32 v82, v2
	v_mov_b32_e32 v83, v2
	v_mov_b32_e32 v84, v2
	v_mov_b32_e32 v85, v2
	v_mov_b32_e32 v86, v2
	v_mov_b32_e32 v87, v2
	v_mov_b32_e32 v88, v2
	v_mov_b32_e32 v89, v2
	v_mov_b32_e32 v90, v2
	v_mov_b32_e32 v91, v2
	v_mov_b32_e32 v92, v2
	v_mov_b32_e32 v93, v2
	v_mov_b32_e32 v94, v2
	v_mov_b32_e32 v95, v2
	v_mov_b32_e32 v96, v2
	v_mov_b32_e32 v97, v2
	v_mov_b32_e32 v98, v2
	v_mov_b32_e32 v99, v2
	v_mov_b32_e32 v100, v2
	v_mov_b32_e32 v101, v2
	v_mov_b32_e32 v102, v2
	v_mov_b32_e32 v103, v2
	v_mov_b32_e32 v104, v2
	v_mov_b32_e32 v105, v2
	v_mov_b32_e32 v106, v2
	v_mov_b32_e32 v107, v2
	v_mov_b32_e32 v108, v2
	v_mov_b32_e32 v109, v2
	v_mov_b32_e32 v110, v2
	v_mov_b32_e32 v111, v2
	v_mov_b32_e32 v112, v2
	v_mov_b32_e32 v113, v2
	v_mov_b32_e32 v114, v2
	v_mov_b32_e32 v115, v2
	v_mov_b32_e32 v116, v2
	v_mov_b32_e32 v117, v2
	v_mov_b32_e32 v118, v2
	v_mov_b32_e32 v119, v2
	v_mov_b32_e32 v120, v2
	v_mov_b32_e32 v121, v2
	v_mov_b32_e32 v122, v2
	v_mov_b32_e32 v123, v2
	v_mov_b32_e32 v124, v2
	v_mov_b32_e32 v125, v2
	v_mov_b32_e32 v126, v2
	v_mov_b32_e32 v127, v2
	v_mov_b32_e32 v128, v2
	v_mov_b32_e32 v129, v2
	.p2align 6
; #define STA(P, br, kt) STAGE(P, A, aoff0, aoff1, lda, br, kt)
; #define STB(P, br, kt) STAGE(P, Bt, boff0, boff1, ldb, br, kt)
; #define LDA(dst, b, h) _Pragma("unroll") for (int m = 0; m < 4; ++m) _Pragma("unroll") for (int k = 0; k < 2; ++k) \
;     dst[m][k] = *reinterpret_cast<const bf16x8*>((char*)SA(b, h) + lds_byte(wr * 64 + m * 16 + fr, k * 32 + fq * 8))
; #define LDB(dst, b, h) _Pragma("unroll") for (int n = 0; n < 2; ++n) _Pragma("unroll") for (int k = 0; k < 2; ++k) \
;     dst[n][k] = *reinterpret_cast<const bf16x8*>((char*)SB(b, h) + lds_byte(wc * 32 + n * 16 + fr, k * 32 + fq * 8))
; #define MMA(ai, bj, At, Bq) do { __builtin_amdgcn_s_setprio(1); \
;     _Pragma("unroll") for (int m = 0; m < 4; ++m) _Pragma("unroll") for (int n = 0; n < 2; ++n) _Pragma("unroll") for (int k = 0; k < 2; ++k) \
;       acc[ai][bj][m][n] = __builtin_amdgcn_mfma_f32_16x16x32_bf16(At[m][k], Bq[n][k], acc[ai][bj][m][n], 0, 0, 0); \
;     __builtin_amdgcn_s_setprio(0); } while (0)
; #define WAIT_L(n) asm volatile("s_waitcnt lgkmcnt(" #n ")" ::: "memory")
; #define BAR __builtin_amdgcn_s_barrier()
; #define SCHED __builtin_amdgcn_sched_barrier(0)
; __device__ __forceinline__ void gemm256(const u16* __restrict__ A, int lda, const u16* __restrict__ Bt, int ldb, int K,
;                                         f32x4 (&acc)[2][2][4][2], const int g_wid) {
;     ...
;     LDB(B0, 0, 0); SCHED; LDA(At, 0, 0); STA(SA(1, 1), HALF, t + 1);
;     WAIT_L(8); BAR; WAIT_L(0); MMA(0, 0, At, B0); BAR; SCHED;
;     LDB(B1, 0, 1); STB(SB(0, 0), 0, t + 2);
;     BAR; WAIT_L(0); MMA(0, 1, At, B1); BAR;
;     LDA(At, 0, 1); STA(SA(0, 0), 0, t + 2);
;     BAR; WAIT_L(0); MMA(1, 0, At, B0); BAR; SCHED;
.LBB0_465:
	s_barrier
	ds_read_b128 v[180:183], v176
	ds_read_b128 v[184:187], v176 offset:1024
	ds_read_b128 v[188:191], v176 offset:2048
	ds_read_b128 v[192:195], v176 offset:3072
	v_add_u32_e32 v177, 0xc000, v162
	v_lshl_add_u64 v[244:245], v[140:141], 0, s[16:17]
	v_readfirstlane_b32 s13, v177
	v_lshl_add_u64 v[178:179], v[244:245], 0, s[68:69]
	s_mov_b32 m0, s13
	ds_read_b128 v[196:199], v147
	ds_read_b128 v[200:203], v147 offset:1024
	ds_read_b128 v[204:207], v146
	ds_read_b128 v[208:211], v146 offset:1024
	ds_read_b128 v[212:215], v145
	ds_read_b128 v[216:219], v145 offset:1024
	ds_read_b128 v[220:223], v144
	ds_read_b128 v[224:227], v144 offset:1024
	global_load_lds_dwordx4 v[178:179], off
	v_add_u32_e32 v178, 0xe000, v162
	v_lshl_add_u64 v[246:247], v[138:139], 0, s[16:17]
	v_readfirstlane_b32 s13, v178
	v_lshl_add_u64 v[228:229], v[246:247], 0, s[68:69]
	s_mov_b32 m0, s13
	s_nop 0
	global_load_lds_dwordx4 v[228:229], off
	s_waitcnt lgkmcnt(8)
	s_barrier
	s_waitcnt lgkmcnt(0)
	v_mfma_f32_16x16x32_bf16 v[126:129], v[196:199], v[180:183], v[126:129]
	v_mfma_f32_16x16x32_bf16 v[122:125], v[196:199], v[188:191], v[122:125]
	v_mfma_f32_16x16x32_bf16 v[118:121], v[204:207], v[180:183], v[118:121]
	v_mfma_f32_16x16x32_bf16 v[114:117], v[204:207], v[188:191], v[114:117]
	v_mfma_f32_16x16x32_bf16 v[110:113], v[212:215], v[180:183], v[110:113]
	v_mfma_f32_16x16x32_bf16 v[106:109], v[212:215], v[188:191], v[106:109]
	v_mfma_f32_16x16x32_bf16 v[102:105], v[220:223], v[180:183], v[102:105]
	v_mfma_f32_16x16x32_bf16 v[98:101], v[220:223], v[188:191], v[98:101]
	v_mfma_f32_16x16x32_bf16 v[126:129], v[200:203], v[184:187], v[126:129]
	v_mfma_f32_16x16x32_bf16 v[122:125], v[200:203], v[192:195], v[122:125]
	v_mfma_f32_16x16x32_bf16 v[118:121], v[208:211], v[184:187], v[118:121]
	v_mfma_f32_16x16x32_bf16 v[114:117], v[208:211], v[192:195], v[114:117]
	v_mfma_f32_16x16x32_bf16 v[110:113], v[216:219], v[184:187], v[110:113]
	v_mfma_f32_16x16x32_bf16 v[106:109], v[216:219], v[192:195], v[106:109]
	v_mfma_f32_16x16x32_bf16 v[102:105], v[224:227], v[184:187], v[102:105]
	v_mfma_f32_16x16x32_bf16 v[98:101], v[224:227], v[192:195], v[98:101]
	s_barrier
	v_lshl_add_u64 v[248:249], v[136:137], 0, s[16:17]
	v_readfirstlane_b32 s13, v159
	v_lshl_add_u64 v[250:251], v[248:249], 0, s[74:75]
	s_mov_b32 m0, s13
	ds_read_b128 v[228:231], v175
	ds_read_b128 v[232:235], v175 offset:1024
	ds_read_b128 v[236:239], v175 offset:2048
	ds_read_b128 v[240:243], v175 offset:3072
	global_load_lds_dwordx4 v[250:251], off
	v_lshl_add_u64 v[250:251], v[134:135], 0, s[16:17]
	v_readfirstlane_b32 s13, v160
	v_lshl_add_u64 v[252:253], v[250:251], 0, s[74:75]
	s_mov_b32 m0, s13
	s_nop 0
	global_load_lds_dwordx4 v[252:253], off
	s_barrier
	s_waitcnt lgkmcnt(0)
	v_mfma_f32_16x16x32_bf16 v[94:97], v[196:199], v[228:231], v[94:97]
	v_mfma_f32_16x16x32_bf16 v[90:93], v[196:199], v[236:239], v[90:93]
	v_mfma_f32_16x16x32_bf16 v[86:89], v[204:207], v[228:231], v[86:89]
	v_mfma_f32_16x16x32_bf16 v[82:85], v[204:207], v[236:239], v[82:85]
	v_mfma_f32_16x16x32_bf16 v[78:81], v[212:215], v[228:231], v[78:81]
	v_mfma_f32_16x16x32_bf16 v[74:77], v[212:215], v[236:239], v[74:77]
	v_mfma_f32_16x16x32_bf16 v[70:73], v[220:223], v[228:231], v[70:73]
	v_mfma_f32_16x16x32_bf16 v[66:69], v[220:223], v[236:239], v[66:69]
	v_mfma_f32_16x16x32_bf16 v[94:97], v[200:203], v[232:235], v[94:97]
	v_mfma_f32_16x16x32_bf16 v[90:93], v[200:203], v[240:243], v[90:93]
	v_mfma_f32_16x16x32_bf16 v[86:89], v[208:211], v[232:235], v[86:89]
	v_mfma_f32_16x16x32_bf16 v[82:85], v[208:211], v[240:243], v[82:85]
	v_mfma_f32_16x16x32_bf16 v[78:81], v[216:219], v[232:235], v[78:81]
	v_mfma_f32_16x16x32_bf16 v[74:77], v[216:219], v[240:243], v[74:77]
	v_mfma_f32_16x16x32_bf16 v[70:73], v[224:227], v[232:235], v[70:73]
	v_mfma_f32_16x16x32_bf16 v[66:69], v[224:227], v[240:243], v[66:69]
	v_readfirstlane_b32 s13, v162
	v_lshl_add_u64 v[252:253], v[244:245], 0, s[74:75]
	s_mov_b32 m0, s13
	v_readfirstlane_b32 s13, v163
	s_barrier
	ds_read_b128 v[196:199], v147 offset:16384
	ds_read_b128 v[200:203], v147 offset:17408
	ds_read_b128 v[204:207], v146 offset:16384
	ds_read_b128 v[208:211], v146 offset:17408
	ds_read_b128 v[212:215], v145 offset:16384
	ds_read_b128 v[216:219], v145 offset:17408
	ds_read_b128 v[220:223], v144 offset:16384
	ds_read_b128 v[224:227], v144 offset:17408
	global_load_lds_dwordx4 v[252:253], off
	v_lshl_add_u64 v[252:253], v[246:247], 0, s[74:75]
	s_mov_b32 m0, s13
	s_nop 0
	global_load_lds_dwordx4 v[252:253], off
	s_barrier
	s_waitcnt lgkmcnt(0)
	v_mfma_f32_16x16x32_bf16 v[62:65], v[196:199], v[180:183], v[62:65]
	v_mfma_f32_16x16x32_bf16 v[58:61], v[196:199], v[188:191], v[58:61]
	v_mfma_f32_16x16x32_bf16 v[54:57], v[204:207], v[180:183], v[54:57]
	v_mfma_f32_16x16x32_bf16 v[50:53], v[204:207], v[188:191], v[50:53]
	v_mfma_f32_16x16x32_bf16 v[46:49], v[212:215], v[180:183], v[46:49]
	v_mfma_f32_16x16x32_bf16 v[42:45], v[212:215], v[188:191], v[42:45]
	v_mfma_f32_16x16x32_bf16 v[38:41], v[220:223], v[180:183], v[38:41]
	v_mfma_f32_16x16x32_bf16 v[34:37], v[220:223], v[188:191], v[34:37]
	v_mfma_f32_16x16x32_bf16 v[62:65], v[200:203], v[184:187], v[62:65]
	v_mfma_f32_16x16x32_bf16 v[58:61], v[200:203], v[192:195], v[58:61]
	v_mfma_f32_16x16x32_bf16 v[54:57], v[208:211], v[184:187], v[54:57]
	v_mfma_f32_16x16x32_bf16 v[50:53], v[208:211], v[192:195], v[50:53]
	v_mfma_f32_16x16x32_bf16 v[46:49], v[216:219], v[184:187], v[46:49]
	v_mfma_f32_16x16x32_bf16 v[42:45], v[216:219], v[192:195], v[42:45]
	v_mfma_f32_16x16x32_bf16 v[38:41], v[224:227], v[184:187], v[38:41]
	v_mfma_f32_16x16x32_bf16 v[34:37], v[224:227], v[192:195], v[34:37]
	s_barrier
; #define STA(P, br, kt) STAGE(P, A, aoff0, aoff1, lda, br, kt)
; #define STB(P, br, kt) STAGE(P, Bt, boff0, boff1, ldb, br, kt)
; #define LDA(dst, b, h) _Pragma("unroll") for (int m = 0; m < 4; ++m) _Pragma("unroll") for (int k = 0; k < 2; ++k) \
;     dst[m][k] = *reinterpret_cast<const bf16x8*>((char*)SA(b, h) + lds_byte(wr * 64 + m * 16 + fr, k * 32 + fq * 8))
; #define LDB(dst, b, h) _Pragma("unroll") for (int n = 0; n < 2; ++n) _Pragma("unroll") for (int k = 0; k < 2; ++k) \
;     dst[n][k] = *reinterpret_cast<const bf16x8*>((char*)SB(b, h) + lds_byte(wc * 32 + n * 16 + fr, k * 32 + fq * 8))
; #define MMA(ai, bj, At, Bq) do { __builtin_amdgcn_s_setprio(1); \
;     _Pragma("unroll") for (int m = 0; m < 4; ++m) _Pragma("unroll") for (int n = 0; n < 2; ++n) _Pragma("unroll") for (int k = 0; k < 2; ++k) \
;       acc[ai][bj][m][n] = __builtin_amdgcn_mfma_f32_16x16x32_bf16(At[m][k], Bq[n][k], acc[ai][bj][m][n], 0, 0, 0); \
;     __builtin_amdgcn_s_setprio(0); } while (0)
; #define WAIT_V(n) asm volatile("s_waitcnt vmcnt(" #n ")" ::: "memory")
; #define WAIT_L(n) asm volatile("s_waitcnt lgkmcnt(" #n ")" ::: "memory")
; #define BAR __builtin_amdgcn_s_barrier()
; #define SCHED __builtin_amdgcn_sched_barrier(0)
; __device__ __forceinline__ void gemm256(const u16* __restrict__ A, int lda, const u16* __restrict__ Bt, int ldb, int K,
;                                         f32x4 (&acc)[2][2][4][2], const int g_wid) {
;     ...
;     STB(SB(0, 1), HALF, t + 2);
;     WAIT_V(6); BAR; MMA(1, 1, At, B1); BAR;
;     LDB(B0, 1, 0); SCHED; LDA(At, 1, 0); STA(SA(0, 1), HALF, t + 2);
;     WAIT_L(8); BAR; WAIT_L(0); MMA(0, 0, At, B0); BAR; SCHED;
;     LDB(B1, 1, 1); STB(SB(1, 0), 0, t + 3);
;     BAR; WAIT_L(0); MMA(0, 1, At, B1); BAR;
;     LDA(At, 1, 1); STA(SA(1, 0), 0, t + 3);
;     BAR; WAIT_L(0); MMA(1, 0, At, B0); BAR; SCHED;
	v_readfirstlane_b32 s13, v164
	v_lshl_add_u64 v[180:181], v[248:249], 0, s[78:79]
	s_mov_b32 m0, s13
	v_readfirstlane_b32 s13, v165
	global_load_lds_dwordx4 v[180:181], off
	v_lshl_add_u64 v[180:181], v[250:251], 0, s[78:79]
	s_mov_b32 m0, s13
	s_nop 0
	global_load_lds_dwordx4 v[180:181], off
	s_waitcnt vmcnt(6)
	s_barrier
	v_mfma_f32_16x16x32_bf16 v[30:33], v[196:199], v[228:231], v[30:33]
	v_mfma_f32_16x16x32_bf16 v[26:29], v[196:199], v[236:239], v[26:29]
	v_mfma_f32_16x16x32_bf16 v[22:25], v[204:207], v[228:231], v[22:25]
	v_mfma_f32_16x16x32_bf16 v[18:21], v[204:207], v[236:239], v[18:21]
	v_mfma_f32_16x16x32_bf16 v[14:17], v[212:215], v[228:231], v[14:17]
	v_mfma_f32_16x16x32_bf16 v[10:13], v[212:215], v[236:239], v[10:13]
	v_mfma_f32_16x16x32_bf16 v[6:9], v[220:223], v[228:231], v[6:9]
	v_mfma_f32_16x16x32_bf16 v[2:5], v[220:223], v[236:239], v[2:5]
	v_mfma_f32_16x16x32_bf16 v[30:33], v[200:203], v[232:235], v[30:33]
	v_mfma_f32_16x16x32_bf16 v[26:29], v[200:203], v[240:243], v[26:29]
	v_mfma_f32_16x16x32_bf16 v[22:25], v[208:211], v[232:235], v[22:25]
	v_mfma_f32_16x16x32_bf16 v[18:21], v[208:211], v[240:243], v[18:21]
	v_mfma_f32_16x16x32_bf16 v[14:17], v[216:219], v[232:235], v[14:17]
	v_mfma_f32_16x16x32_bf16 v[10:13], v[216:219], v[240:243], v[10:13]
	v_mfma_f32_16x16x32_bf16 v[6:9], v[224:227], v[232:235], v[6:9]
	v_mfma_f32_16x16x32_bf16 v[2:5], v[224:227], v[240:243], v[2:5]
	s_barrier
	ds_read_b128 v[180:183], v167
	ds_read_b128 v[184:187], v167 offset:1024
	ds_read_b128 v[188:191], v167 offset:2048
	ds_read_b128 v[192:195], v167 offset:3072
	v_readfirstlane_b32 s13, v166
	v_lshl_add_u64 v[228:229], v[244:245], 0, s[78:79]
	s_mov_b32 m0, s13
	v_readfirstlane_b32 s13, v168
	ds_read_b128 v[196:199], v147 offset:32768
	ds_read_b128 v[200:203], v147 offset:33792
	ds_read_b128 v[204:207], v146 offset:32768
	ds_read_b128 v[208:211], v146 offset:33792
	ds_read_b128 v[212:215], v145 offset:32768
	ds_read_b128 v[216:219], v145 offset:33792
	ds_read_b128 v[220:223], v144 offset:32768
	ds_read_b128 v[224:227], v144 offset:33792
	global_load_lds_dwordx4 v[228:229], off
	v_lshl_add_u64 v[228:229], v[246:247], 0, s[78:79]
	s_mov_b32 m0, s13
	s_nop 0
	global_load_lds_dwordx4 v[228:229], off
	s_waitcnt lgkmcnt(8)
	s_barrier
	s_waitcnt lgkmcnt(0)
	v_mfma_f32_16x16x32_bf16 v[126:129], v[196:199], v[180:183], v[126:129]
	v_mfma_f32_16x16x32_bf16 v[122:125], v[196:199], v[188:191], v[122:125]
	v_mfma_f32_16x16x32_bf16 v[118:121], v[204:207], v[180:183], v[118:121]
	v_mfma_f32_16x16x32_bf16 v[114:117], v[204:207], v[188:191], v[114:117]
	v_mfma_f32_16x16x32_bf16 v[110:113], v[212:215], v[180:183], v[110:113]
	v_mfma_f32_16x16x32_bf16 v[106:109], v[212:215], v[188:191], v[106:109]
	v_mfma_f32_16x16x32_bf16 v[102:105], v[220:223], v[180:183], v[102:105]
	v_mfma_f32_16x16x32_bf16 v[98:101], v[220:223], v[188:191], v[98:101]
	v_mfma_f32_16x16x32_bf16 v[126:129], v[200:203], v[184:187], v[126:129]
	v_mfma_f32_16x16x32_bf16 v[122:125], v[200:203], v[192:195], v[122:125]
	v_mfma_f32_16x16x32_bf16 v[118:121], v[208:211], v[184:187], v[118:121]
	v_mfma_f32_16x16x32_bf16 v[114:117], v[208:211], v[192:195], v[114:117]
	v_mfma_f32_16x16x32_bf16 v[110:113], v[216:219], v[184:187], v[110:113]
	v_mfma_f32_16x16x32_bf16 v[106:109], v[216:219], v[192:195], v[106:109]
	v_mfma_f32_16x16x32_bf16 v[102:105], v[224:227], v[184:187], v[102:105]
	v_mfma_f32_16x16x32_bf16 v[98:101], v[224:227], v[192:195], v[98:101]
	s_barrier
	v_readfirstlane_b32 s13, v169
	v_lshl_add_u64 v[252:253], v[248:249], 0, s[82:83]
	s_mov_b32 m0, s13
	v_readfirstlane_b32 s13, v170
	ds_read_b128 v[228:231], v161
	ds_read_b128 v[232:235], v161 offset:1024
	ds_read_b128 v[236:239], v161 offset:2048
	ds_read_b128 v[240:243], v161 offset:3072
	global_load_lds_dwordx4 v[252:253], off
	v_lshl_add_u64 v[252:253], v[250:251], 0, s[82:83]
	s_mov_b32 m0, s13
	s_nop 0
	global_load_lds_dwordx4 v[252:253], off
	s_barrier
	s_waitcnt lgkmcnt(0)
	v_mfma_f32_16x16x32_bf16 v[94:97], v[196:199], v[228:231], v[94:97]
	v_mfma_f32_16x16x32_bf16 v[90:93], v[196:199], v[236:239], v[90:93]
	v_mfma_f32_16x16x32_bf16 v[86:89], v[204:207], v[228:231], v[86:89]
	v_mfma_f32_16x16x32_bf16 v[82:85], v[204:207], v[236:239], v[82:85]
	v_mfma_f32_16x16x32_bf16 v[78:81], v[212:215], v[228:231], v[78:81]
	v_mfma_f32_16x16x32_bf16 v[74:77], v[212:215], v[236:239], v[74:77]
	v_mfma_f32_16x16x32_bf16 v[70:73], v[220:223], v[228:231], v[70:73]
	v_mfma_f32_16x16x32_bf16 v[66:69], v[220:223], v[236:239], v[66:69]
	v_mfma_f32_16x16x32_bf16 v[94:97], v[200:203], v[232:235], v[94:97]
	v_mfma_f32_16x16x32_bf16 v[90:93], v[200:203], v[240:243], v[90:93]
	v_mfma_f32_16x16x32_bf16 v[86:89], v[208:211], v[232:235], v[86:89]
	v_mfma_f32_16x16x32_bf16 v[82:85], v[208:211], v[240:243], v[82:85]
	v_mfma_f32_16x16x32_bf16 v[78:81], v[216:219], v[232:235], v[78:81]
	v_mfma_f32_16x16x32_bf16 v[74:77], v[216:219], v[240:243], v[74:77]
	v_mfma_f32_16x16x32_bf16 v[70:73], v[224:227], v[232:235], v[70:73]
	v_mfma_f32_16x16x32_bf16 v[66:69], v[224:227], v[240:243], v[66:69]
	v_readfirstlane_b32 s13, v171
	v_lshl_add_u64 v[244:245], v[244:245], 0, s[82:83]
	s_mov_b32 m0, s13
	v_readfirstlane_b32 s13, v172
	s_barrier
	ds_read_b128 v[196:199], v147 offset:49152
	ds_read_b128 v[200:203], v147 offset:50176
	ds_read_b128 v[204:207], v146 offset:49152
	ds_read_b128 v[208:211], v146 offset:50176
	ds_read_b128 v[212:215], v145 offset:49152
	ds_read_b128 v[216:219], v145 offset:50176
	ds_read_b128 v[220:223], v144 offset:49152
	ds_read_b128 v[224:227], v144 offset:50176
	global_load_lds_dwordx4 v[244:245], off
	v_lshl_add_u64 v[244:245], v[246:247], 0, s[82:83]
	s_mov_b32 m0, s13
	s_nop 0
	global_load_lds_dwordx4 v[244:245], off
	s_barrier
; #define STA(P, br, kt) STAGE(P, A, aoff0, aoff1, lda, br, kt)
; #define STB(P, br, kt) STAGE(P, Bt, boff0, boff1, ldb, br, kt)
; #define LDA(dst, b, h) _Pragma("unroll") for (int m = 0; m < 4; ++m) _Pragma("unroll") for (int k = 0; k < 2; ++k) \
;     dst[m][k] = *reinterpret_cast<const bf16x8*>((char*)SA(b, h) + lds_byte(wr * 64 + m * 16 + fr, k * 32 + fq * 8))
; #define LDB(dst, b, h) _Pragma("unroll") for (int n = 0; n < 2; ++n) _Pragma("unroll") for (int k = 0; k < 2; ++k) \
;     dst[n][k] = *reinterpret_cast<const bf16x8*>((char*)SB(b, h) + lds_byte(wc * 32 + n * 16 + fr, k * 32 + fq * 8))
; #define MMA(ai, bj, At, Bq) do { __builtin_amdgcn_s_setprio(1); \
;     _Pragma("unroll") for (int m = 0; m < 4; ++m) _Pragma("unroll") for (int n = 0; n < 2; ++n) _Pragma("unroll") for (int k = 0; k < 2; ++k) \
;       acc[ai][bj][m][n] = __builtin_amdgcn_mfma_f32_16x16x32_bf16(At[m][k], Bq[n][k], acc[ai][bj][m][n], 0, 0, 0); \
;     __builtin_amdgcn_s_setprio(0); } while (0)
; #define WAIT_V(n) asm volatile("s_waitcnt vmcnt(" #n ")" ::: "memory")
; #define WAIT_L(n) asm volatile("s_waitcnt lgkmcnt(" #n ")" ::: "memory")
; #define BAR __builtin_amdgcn_s_barrier()
; #define SCHED __builtin_amdgcn_sched_barrier(0)
; __device__ __forceinline__ void gemm256(const u16* __restrict__ A, int lda, const u16* __restrict__ Bt, int ldb, int K,
;                                         f32x4 (&acc)[2][2][4][2], const int g_wid) {
;     ...
;     BAR; WAIT_L(0); MMA(1, 0, At, B0); BAR; SCHED;
;     STB(SB(1, 1), HALF, t + 3);
;     WAIT_V(6); BAR; MMA(1, 1, At, B1); BAR;
;   }
;   { LDB(B0, 0, 0); LDA(At, 0, 0); STA(SA(1, 1), HALF, nt - 1);
;     BAR; WAIT_L(0); MMA(0, 0, At, B0); BAR;
;     LDB(B1, 0, 1); BAR; WAIT_L(0); MMA(0, 1, At, B1); BAR;
	s_waitcnt lgkmcnt(0)
	v_mfma_f32_16x16x32_bf16 v[62:65], v[196:199], v[180:183], v[62:65]
	v_mfma_f32_16x16x32_bf16 v[58:61], v[196:199], v[188:191], v[58:61]
	v_mfma_f32_16x16x32_bf16 v[54:57], v[204:207], v[180:183], v[54:57]
	v_mfma_f32_16x16x32_bf16 v[50:53], v[204:207], v[188:191], v[50:53]
	v_mfma_f32_16x16x32_bf16 v[46:49], v[212:215], v[180:183], v[46:49]
	v_mfma_f32_16x16x32_bf16 v[42:45], v[212:215], v[188:191], v[42:45]
	v_mfma_f32_16x16x32_bf16 v[38:41], v[220:223], v[180:183], v[38:41]
	v_mfma_f32_16x16x32_bf16 v[34:37], v[220:223], v[188:191], v[34:37]
	v_mfma_f32_16x16x32_bf16 v[62:65], v[200:203], v[184:187], v[62:65]
	v_mfma_f32_16x16x32_bf16 v[58:61], v[200:203], v[192:195], v[58:61]
	v_mfma_f32_16x16x32_bf16 v[54:57], v[208:211], v[184:187], v[54:57]
	v_mfma_f32_16x16x32_bf16 v[50:53], v[208:211], v[192:195], v[50:53]
	v_mfma_f32_16x16x32_bf16 v[46:49], v[216:219], v[184:187], v[46:49]
	v_mfma_f32_16x16x32_bf16 v[42:45], v[216:219], v[192:195], v[42:45]
	v_mfma_f32_16x16x32_bf16 v[38:41], v[224:227], v[184:187], v[38:41]
	v_mfma_f32_16x16x32_bf16 v[34:37], v[224:227], v[192:195], v[34:37]
	s_barrier
	v_readfirstlane_b32 s13, v173
	v_lshl_add_u64 v[180:181], v[248:249], 0, s[86:87]
	s_mov_b32 m0, s13
	v_readfirstlane_b32 s13, v174
	global_load_lds_dwordx4 v[180:181], off
	v_lshl_add_u64 v[180:181], v[250:251], 0, s[86:87]
	s_mov_b32 m0, s13
	s_nop 0
	global_load_lds_dwordx4 v[180:181], off
	s_waitcnt vmcnt(6)
	s_barrier
	v_mfma_f32_16x16x32_bf16 v[30:33], v[196:199], v[228:231], v[30:33]
	v_mfma_f32_16x16x32_bf16 v[26:29], v[196:199], v[236:239], v[26:29]
	v_mfma_f32_16x16x32_bf16 v[22:25], v[204:207], v[228:231], v[22:25]
	v_mfma_f32_16x16x32_bf16 v[18:21], v[204:207], v[236:239], v[18:21]
	v_mfma_f32_16x16x32_bf16 v[14:17], v[212:215], v[228:231], v[14:17]
	v_mfma_f32_16x16x32_bf16 v[10:13], v[212:215], v[236:239], v[10:13]
	v_mfma_f32_16x16x32_bf16 v[6:9], v[220:223], v[228:231], v[6:9]
	v_mfma_f32_16x16x32_bf16 v[2:5], v[220:223], v[236:239], v[2:5]
	v_mfma_f32_16x16x32_bf16 v[30:33], v[200:203], v[232:235], v[30:33]
	v_mfma_f32_16x16x32_bf16 v[26:29], v[200:203], v[240:243], v[26:29]
	v_mfma_f32_16x16x32_bf16 v[22:25], v[208:211], v[232:235], v[22:25]
	v_mfma_f32_16x16x32_bf16 v[18:21], v[208:211], v[240:243], v[18:21]
	v_mfma_f32_16x16x32_bf16 v[14:17], v[216:219], v[232:235], v[14:17]
	v_mfma_f32_16x16x32_bf16 v[10:13], v[216:219], v[240:243], v[10:13]
	v_mfma_f32_16x16x32_bf16 v[6:9], v[224:227], v[232:235], v[6:9]
	v_mfma_f32_16x16x32_bf16 v[2:5], v[224:227], v[240:243], v[2:5]
	s_add_i32 s9, s9, 2
	s_add_u32 s16, s16, 0x100
	s_addc_u32 s17, s17, 0
	s_cmp_lt_u32 s9, 12
	s_cbranch_scc1 .LBB0_465
	s_barrier
	s_add_u32 s14, s14, 0x40780
	s_addc_u32 s15, s15, 0
	v_readfirstlane_b32 s9, v177
	v_lshl_add_u64 v[132:133], v[132:133], 1, s[14:15]
	s_mov_b32 m0, s9
	v_readfirstlane_b32 s9, v178
	ds_read_b128 v[134:137], v176
	ds_read_b128 v[138:141], v176 offset:1024
	ds_read_b128 v[162:165], v176 offset:2048
	ds_read_b128 v[168:171], v176 offset:3072
	ds_read_b128 v[180:183], v147
	ds_read_b128 v[184:187], v147 offset:1024
	ds_read_b128 v[188:191], v146
	ds_read_b128 v[192:195], v146 offset:1024
	ds_read_b128 v[196:199], v145
	ds_read_b128 v[200:203], v145 offset:1024
	ds_read_b128 v[204:207], v144
	ds_read_b128 v[208:211], v144 offset:1024
	global_load_lds_dwordx4 v[132:133], off
	v_lshl_add_u64 v[130:131], v[130:131], 1, s[14:15]
	s_mov_b32 m0, s9
	s_nop 0
	global_load_lds_dwordx4 v[130:131], off
	s_barrier
	s_waitcnt lgkmcnt(0)
	v_mfma_f32_16x16x32_bf16 v[126:129], v[180:183], v[134:137], v[126:129]
	v_mfma_f32_16x16x32_bf16 v[118:121], v[188:191], v[134:137], v[118:121]
	v_mfma_f32_16x16x32_bf16 v[114:117], v[188:191], v[162:165], v[114:117]
	v_mfma_f32_16x16x32_bf16 v[102:105], v[204:207], v[134:137], v[102:105]
	v_mfma_f32_16x16x32_bf16 v[126:129], v[184:187], v[138:141], v[126:129]
	v_mfma_f32_16x16x32_bf16 v[122:125], v[180:183], v[162:165], v[122:125]
	v_mfma_f32_16x16x32_bf16 v[118:121], v[192:195], v[138:141], v[118:121]
	v_mfma_f32_16x16x32_bf16 v[114:117], v[192:195], v[168:171], v[114:117]
	v_mfma_f32_16x16x32_bf16 v[110:113], v[196:199], v[134:137], v[110:113]
	v_mfma_f32_16x16x32_bf16 v[106:109], v[196:199], v[162:165], v[106:109]
	v_mfma_f32_16x16x32_bf16 v[102:105], v[208:211], v[138:141], v[102:105]
	v_mfma_f32_16x16x32_bf16 v[98:101], v[204:207], v[162:165], v[98:101]
	v_mfma_f32_16x16x32_bf16 v[130:133], v[184:187], v[168:171], v[122:125]
	v_mfma_f32_16x16x32_bf16 v[176:179], v[200:203], v[138:141], v[110:113]
	v_mfma_f32_16x16x32_bf16 v[212:215], v[200:203], v[168:171], v[106:109]
	v_mfma_f32_16x16x32_bf16 v[216:219], v[208:211], v[168:171], v[98:101]
	s_barrier
	s_nop 1
	ds_read_b128 v[98:101], v175
	ds_read_b128 v[106:109], v175 offset:1024
	ds_read_b128 v[110:113], v175 offset:2048
	ds_read_b128 v[122:125], v175 offset:3072
	s_barrier
	s_waitcnt lgkmcnt(0)
	v_mfma_f32_16x16x32_bf16 v[94:97], v[180:183], v[98:101], v[94:97]
	v_mfma_f32_16x16x32_bf16 v[86:89], v[188:191], v[98:101], v[86:89]
	v_mfma_f32_16x16x32_bf16 v[82:85], v[188:191], v[110:113], v[82:85]
	v_mfma_f32_16x16x32_bf16 v[70:73], v[204:207], v[98:101], v[70:73]
	v_mfma_f32_16x16x32_bf16 v[94:97], v[184:187], v[106:109], v[94:97]
	v_mfma_f32_16x16x32_bf16 v[90:93], v[180:183], v[110:113], v[90:93]
	v_mfma_f32_16x16x32_bf16 v[86:89], v[192:195], v[106:109], v[86:89]
	v_mfma_f32_16x16x32_bf16 v[82:85], v[192:195], v[122:125], v[82:85]
	v_mfma_f32_16x16x32_bf16 v[78:81], v[196:199], v[98:101], v[78:81]
	v_mfma_f32_16x16x32_bf16 v[74:77], v[196:199], v[110:113], v[74:77]
	v_mfma_f32_16x16x32_bf16 v[70:73], v[208:211], v[106:109], v[70:73]
	v_mfma_f32_16x16x32_bf16 v[66:69], v[204:207], v[110:113], v[66:69]
	v_mfma_f32_16x16x32_bf16 v[172:175], v[184:187], v[122:125], v[90:93]
	v_mfma_f32_16x16x32_bf16 v[180:183], v[200:203], v[106:109], v[78:81]
	v_mfma_f32_16x16x32_bf16 v[184:187], v[200:203], v[122:125], v[74:77]
	v_mfma_f32_16x16x32_bf16 v[188:191], v[208:211], v[122:125], v[66:69]
	s_barrier
; #define STA(P, br, kt) STAGE(P, A, aoff0, aoff1, lda, br, kt)
; #define LDA(dst, b, h) _Pragma("unroll") for (int m = 0; m < 4; ++m) _Pragma("unroll") for (int k = 0; k < 2; ++k) \
;     dst[m][k] = *reinterpret_cast<const bf16x8*>((char*)SA(b, h) + lds_byte(wr * 64 + m * 16 + fr, k * 32 + fq * 8))
; #define LDB(dst, b, h) _Pragma("unroll") for (int n = 0; n < 2; ++n) _Pragma("unroll") for (int k = 0; k < 2; ++k) \
;     dst[n][k] = *reinterpret_cast<const bf16x8*>((char*)SB(b, h) + lds_byte(wc * 32 + n * 16 + fr, k * 32 + fq * 8))
; #define MMA(ai, bj, At, Bq) do { __builtin_amdgcn_s_setprio(1); \
;     _Pragma("unroll") for (int m = 0; m < 4; ++m) _Pragma("unroll") for (int n = 0; n < 2; ++n) _Pragma("unroll") for (int k = 0; k < 2; ++k) \
;       acc[ai][bj][m][n] = __builtin_amdgcn_mfma_f32_16x16x32_bf16(At[m][k], Bq[n][k], acc[ai][bj][m][n], 0, 0, 0); \
;     __builtin_amdgcn_s_setprio(0); } while (0)
; #define WAIT_V(n) asm volatile("s_waitcnt vmcnt(" #n ")" ::: "memory")
; #define WAIT_L(n) asm volatile("s_waitcnt lgkmcnt(" #n ")" ::: "memory")
; #define BAR __builtin_amdgcn_s_barrier()
; __device__ __forceinline__ void gemm256(const u16* __restrict__ A, int lda, const u16* __restrict__ Bt, int ldb, int K,
;                                         f32x4 (&acc)[2][2][4][2], const int g_wid) {
;     ...
;   { LDB(B0, 0, 0); LDA(At, 0, 0); STA(SA(1, 1), HALF, nt - 1);
;     BAR; WAIT_L(0); MMA(0, 0, At, B0); BAR;
;     LDB(B1, 0, 1); BAR; WAIT_L(0); MMA(0, 1, At, B1); BAR;
;     LDA(At, 0, 1); WAIT_V(4); BAR; WAIT_L(0); MMA(1, 0, At, B0); MMA(1, 1, At, B1); BAR; }
;   { LDB(B0, 1, 0); LDA(At, 1, 0); WAIT_V(2); BAR; WAIT_L(0); MMA(0, 0, At, B0); BAR;
;     LDB(B1, 1, 1); WAIT_V(0); BAR; WAIT_L(0); MMA(0, 1, At, B1); BAR;
;     LDA(At, 1, 1); BAR; WAIT_L(0); MMA(1, 0, At, B0); MMA(1, 1, At, B1); BAR; }
	s_nop 1
	ds_read_b128 v[66:69], v147 offset:16384
	ds_read_b128 v[74:77], v147 offset:17408
	ds_read_b128 v[78:81], v146 offset:16384
	ds_read_b128 v[90:93], v146 offset:17408
	ds_read_b128 v[192:195], v145 offset:16384
	ds_read_b128 v[196:199], v145 offset:17408
	ds_read_b128 v[200:203], v144 offset:16384
	ds_read_b128 v[204:207], v144 offset:17408
	s_waitcnt vmcnt(4)
	s_barrier
	s_waitcnt lgkmcnt(0)
	v_mfma_f32_16x16x32_bf16 v[62:65], v[66:69], v[134:137], v[62:65]
	v_mfma_f32_16x16x32_bf16 v[54:57], v[78:81], v[134:137], v[54:57]
	v_mfma_f32_16x16x32_bf16 v[46:49], v[192:195], v[134:137], v[46:49]
	v_mfma_f32_16x16x32_bf16 v[38:41], v[200:203], v[134:137], v[38:41]
	v_mfma_f32_16x16x32_bf16 v[62:65], v[74:77], v[138:141], v[62:65]
	v_mfma_f32_16x16x32_bf16 v[58:61], v[66:69], v[162:165], v[58:61]
	v_mfma_f32_16x16x32_bf16 v[54:57], v[90:93], v[138:141], v[54:57]
	v_mfma_f32_16x16x32_bf16 v[50:53], v[78:81], v[162:165], v[50:53]
	v_mfma_f32_16x16x32_bf16 v[46:49], v[196:199], v[138:141], v[46:49]
	v_mfma_f32_16x16x32_bf16 v[42:45], v[192:195], v[162:165], v[42:45]
	v_mfma_f32_16x16x32_bf16 v[38:41], v[204:207], v[138:141], v[38:41]
	v_mfma_f32_16x16x32_bf16 v[34:37], v[200:203], v[162:165], v[34:37]
	v_mfma_f32_16x16x32_bf16 v[208:211], v[74:77], v[168:171], v[58:61]
	v_mfma_f32_16x16x32_bf16 v[220:223], v[90:93], v[168:171], v[50:53]
	v_mfma_f32_16x16x32_bf16 v[224:227], v[196:199], v[168:171], v[42:45]
	v_mfma_f32_16x16x32_bf16 v[134:137], v[204:207], v[168:171], v[34:37]
	v_mfma_f32_16x16x32_bf16 v[30:33], v[66:69], v[98:101], v[30:33]
	v_mfma_f32_16x16x32_bf16 v[22:25], v[78:81], v[98:101], v[22:25]
	v_mfma_f32_16x16x32_bf16 v[14:17], v[192:195], v[98:101], v[14:17]
	v_mfma_f32_16x16x32_bf16 v[6:9], v[200:203], v[98:101], v[6:9]
	v_mfma_f32_16x16x32_bf16 v[30:33], v[74:77], v[106:109], v[30:33]
	v_mfma_f32_16x16x32_bf16 v[26:29], v[66:69], v[110:113], v[26:29]
	v_mfma_f32_16x16x32_bf16 v[22:25], v[90:93], v[106:109], v[22:25]
	v_mfma_f32_16x16x32_bf16 v[18:21], v[78:81], v[110:113], v[18:21]
	v_mfma_f32_16x16x32_bf16 v[14:17], v[196:199], v[106:109], v[14:17]
	v_mfma_f32_16x16x32_bf16 v[10:13], v[192:195], v[110:113], v[10:13]
	v_mfma_f32_16x16x32_bf16 v[6:9], v[204:207], v[106:109], v[6:9]
	v_mfma_f32_16x16x32_bf16 v[2:5], v[200:203], v[110:113], v[2:5]
	v_mfma_f32_16x16x32_bf16 v[138:141], v[74:77], v[122:125], v[26:29]
	v_mfma_f32_16x16x32_bf16 v[162:165], v[90:93], v[122:125], v[18:21]
	v_mfma_f32_16x16x32_bf16 v[168:171], v[196:199], v[122:125], v[10:13]
	v_mfma_f32_16x16x32_bf16 v[192:195], v[204:207], v[122:125], v[2:5]
	s_barrier
	ds_read_b128 v[196:199], v167
	ds_read_b128 v[200:203], v167 offset:1024
	ds_read_b128 v[204:207], v167 offset:2048
	ds_read_b128 v[228:231], v167 offset:3072
	ds_read_b128 v[2:5], v147 offset:32768
	ds_read_b128 v[10:13], v147 offset:33792
	ds_read_b128 v[18:21], v146 offset:32768
	ds_read_b128 v[34:37], v146 offset:33792
	ds_read_b128 v[232:235], v145 offset:32768
	ds_read_b128 v[236:239], v145 offset:33792
	ds_read_b128 v[240:243], v144 offset:32768
	ds_read_b128 v[244:247], v144 offset:33792
	s_waitcnt vmcnt(2)
	s_barrier
	s_waitcnt lgkmcnt(0)
	v_mfma_f32_16x16x32_bf16 v[26:29], v[2:5], v[196:199], v[126:129]
	v_mfma_f32_16x16x32_bf16 v[122:125], v[10:13], v[200:203], v[26:29]
	v_mfma_f32_16x16x32_bf16 v[26:29], v[2:5], v[204:207], v[130:133]
	v_mfma_f32_16x16x32_bf16 v[90:93], v[10:13], v[228:231], v[26:29]
	v_mfma_f32_16x16x32_bf16 v[26:29], v[18:21], v[196:199], v[118:121]
	v_mfma_f32_16x16x32_bf16 v[110:113], v[34:37], v[200:203], v[26:29]
	v_mfma_f32_16x16x32_bf16 v[26:29], v[18:21], v[204:207], v[114:117]
	v_mfma_f32_16x16x32_bf16 v[78:81], v[34:37], v[228:231], v[26:29]
	v_mfma_f32_16x16x32_bf16 v[26:29], v[232:235], v[196:199], v[176:179]
	v_mfma_f32_16x16x32_bf16 v[106:109], v[236:239], v[200:203], v[26:29]
	v_mfma_f32_16x16x32_bf16 v[26:29], v[232:235], v[204:207], v[212:215]
	v_mfma_f32_16x16x32_bf16 v[74:77], v[236:239], v[228:231], v[26:29]
	v_mfma_f32_16x16x32_bf16 v[26:29], v[240:243], v[196:199], v[102:105]
	v_mfma_f32_16x16x32_bf16 v[98:101], v[244:247], v[200:203], v[26:29]
	v_mfma_f32_16x16x32_bf16 v[26:29], v[240:243], v[204:207], v[216:219]
	v_mfma_f32_16x16x32_bf16 v[66:69], v[244:247], v[228:231], v[26:29]
	s_barrier
; #define LDA(dst, b, h) _Pragma("unroll") for (int m = 0; m < 4; ++m) _Pragma("unroll") for (int k = 0; k < 2; ++k) \
;     dst[m][k] = *reinterpret_cast<const bf16x8*>((char*)SA(b, h) + lds_byte(wr * 64 + m * 16 + fr, k * 32 + fq * 8))
; #define LDB(dst, b, h) _Pragma("unroll") for (int n = 0; n < 2; ++n) _Pragma("unroll") for (int k = 0; k < 2; ++k) \
;     dst[n][k] = *reinterpret_cast<const bf16x8*>((char*)SB(b, h) + lds_byte(wc * 32 + n * 16 + fr, k * 32 + fq * 8))
; #define MMA(ai, bj, At, Bq) do { __builtin_amdgcn_s_setprio(1); \
;     _Pragma("unroll") for (int m = 0; m < 4; ++m) _Pragma("unroll") for (int n = 0; n < 2; ++n) _Pragma("unroll") for (int k = 0; k < 2; ++k) \
;       acc[ai][bj][m][n] = __builtin_amdgcn_mfma_f32_16x16x32_bf16(At[m][k], Bq[n][k], acc[ai][bj][m][n], 0, 0, 0); \
;     __builtin_amdgcn_s_setprio(0); } while (0)
; #define WAIT_V(n) asm volatile("s_waitcnt vmcnt(" #n ")" ::: "memory")
; #define WAIT_L(n) asm volatile("s_waitcnt lgkmcnt(" #n ")" ::: "memory")
; #define BAR __builtin_amdgcn_s_barrier()
; __device__ __forceinline__ void gemm256(const u16* __restrict__ A, int lda, const u16* __restrict__ Bt, int ldb, int K,
;                                         f32x4 (&acc)[2][2][4][2], const int g_wid) {
;     ...
;   { LDB(B0, 1, 0); LDA(At, 1, 0); WAIT_V(2); BAR; WAIT_L(0); MMA(0, 0, At, B0); BAR;
;     LDB(B1, 1, 1); WAIT_V(0); BAR; WAIT_L(0); MMA(0, 1, At, B1); BAR;
;     LDA(At, 1, 1); BAR; WAIT_L(0); MMA(1, 0, At, B0); MMA(1, 1, At, B1); BAR; }
;   if (wr == 0) BAR;
	ds_read_b128 v[130:133], v161
	ds_read_b128 v[176:179], v161 offset:1024
	ds_read_b128 v[212:215], v161 offset:2048
	ds_read_b128 v[216:219], v161 offset:3072
	s_waitcnt vmcnt(0)
	s_barrier
	s_waitcnt lgkmcnt(0)
	v_mfma_f32_16x16x32_bf16 v[26:29], v[2:5], v[130:133], v[94:97]
	v_mfma_f32_16x16x32_bf16 v[2:5], v[2:5], v[212:215], v[172:175]
	v_mfma_f32_16x16x32_bf16 v[58:61], v[10:13], v[176:179], v[26:29]
	v_mfma_f32_16x16x32_bf16 v[26:29], v[10:13], v[216:219], v[2:5]
	v_mfma_f32_16x16x32_bf16 v[2:5], v[18:21], v[130:133], v[86:89]
	v_mfma_f32_16x16x32_bf16 v[50:53], v[34:37], v[176:179], v[2:5]
	v_mfma_f32_16x16x32_bf16 v[2:5], v[18:21], v[212:215], v[82:85]
	v_mfma_f32_16x16x32_bf16 v[18:21], v[34:37], v[216:219], v[2:5]
	v_mfma_f32_16x16x32_bf16 v[2:5], v[232:235], v[130:133], v[180:183]
	v_mfma_f32_16x16x32_bf16 v[42:45], v[236:239], v[176:179], v[2:5]
	v_mfma_f32_16x16x32_bf16 v[2:5], v[232:235], v[212:215], v[184:187]
	v_mfma_f32_16x16x32_bf16 v[10:13], v[236:239], v[216:219], v[2:5]
	v_mfma_f32_16x16x32_bf16 v[2:5], v[240:243], v[130:133], v[70:73]
	v_mfma_f32_16x16x32_bf16 v[34:37], v[244:247], v[176:179], v[2:5]
	v_mfma_f32_16x16x32_bf16 v[2:5], v[240:243], v[212:215], v[188:191]
	v_mfma_f32_16x16x32_bf16 v[2:5], v[244:247], v[216:219], v[2:5]
	s_barrier
	ds_read_b128 v[172:175], v147 offset:49152
	ds_read_b128 v[180:183], v147 offset:50176
	ds_read_b128 v[184:187], v146 offset:49152
	ds_read_b128 v[188:191], v146 offset:50176
	ds_read_b128 v[232:235], v145 offset:49152
	ds_read_b128 v[236:239], v145 offset:50176
	ds_read_b128 v[240:243], v144 offset:49152
	ds_read_b128 v[144:147], v144 offset:50176
	s_barrier
	s_waitcnt lgkmcnt(0)
	v_mfma_f32_16x16x32_bf16 v[62:65], v[172:175], v[196:199], v[62:65]
	v_mfma_f32_16x16x32_bf16 v[54:57], v[184:187], v[196:199], v[54:57]
	v_mfma_f32_16x16x32_bf16 v[46:49], v[232:235], v[196:199], v[46:49]
	v_mfma_f32_16x16x32_bf16 v[38:41], v[240:243], v[196:199], v[38:41]
	v_mfma_f32_16x16x32_bf16 v[126:129], v[180:183], v[200:203], v[62:65]
	v_mfma_f32_16x16x32_bf16 v[62:65], v[172:175], v[204:207], v[208:211]
	v_mfma_f32_16x16x32_bf16 v[118:121], v[188:191], v[200:203], v[54:57]
	v_mfma_f32_16x16x32_bf16 v[54:57], v[184:187], v[204:207], v[220:223]
	v_mfma_f32_16x16x32_bf16 v[114:117], v[236:239], v[200:203], v[46:49]
	v_mfma_f32_16x16x32_bf16 v[46:49], v[232:235], v[204:207], v[224:227]
	v_mfma_f32_16x16x32_bf16 v[102:105], v[144:147], v[200:203], v[38:41]
	v_mfma_f32_16x16x32_bf16 v[38:41], v[240:243], v[204:207], v[134:137]
	v_mfma_f32_16x16x32_bf16 v[94:97], v[180:183], v[228:231], v[62:65]
	v_mfma_f32_16x16x32_bf16 v[86:89], v[188:191], v[228:231], v[54:57]
	v_mfma_f32_16x16x32_bf16 v[82:85], v[236:239], v[228:231], v[46:49]
	v_mfma_f32_16x16x32_bf16 v[70:73], v[144:147], v[228:231], v[38:41]
	v_mfma_f32_16x16x32_bf16 v[30:33], v[172:175], v[130:133], v[30:33]
	v_mfma_f32_16x16x32_bf16 v[22:25], v[184:187], v[130:133], v[22:25]
	v_mfma_f32_16x16x32_bf16 v[14:17], v[232:235], v[130:133], v[14:17]
	v_mfma_f32_16x16x32_bf16 v[6:9], v[240:243], v[130:133], v[6:9]
	v_mfma_f32_16x16x32_bf16 v[62:65], v[180:183], v[176:179], v[30:33]
	v_mfma_f32_16x16x32_bf16 v[30:33], v[172:175], v[212:215], v[138:141]
	v_mfma_f32_16x16x32_bf16 v[54:57], v[188:191], v[176:179], v[22:25]
	v_mfma_f32_16x16x32_bf16 v[22:25], v[184:187], v[212:215], v[162:165]
	v_mfma_f32_16x16x32_bf16 v[46:49], v[236:239], v[176:179], v[14:17]
	v_mfma_f32_16x16x32_bf16 v[14:17], v[232:235], v[212:215], v[168:171]
	v_mfma_f32_16x16x32_bf16 v[38:41], v[144:147], v[176:179], v[6:9]
	v_mfma_f32_16x16x32_bf16 v[6:9], v[240:243], v[212:215], v[192:195]
	v_mfma_f32_16x16x32_bf16 v[30:33], v[180:183], v[216:219], v[30:33]
	v_mfma_f32_16x16x32_bf16 v[22:25], v[188:191], v[216:219], v[22:25]
	v_mfma_f32_16x16x32_bf16 v[14:17], v[236:239], v[216:219], v[14:17]
	v_mfma_f32_16x16x32_bf16 v[6:9], v[144:147], v[216:219], v[6:9]
	s_setprio 0
	s_movk_i32 s9, 0x100
	v_cmp_gt_u32_e32 vcc, s9, v0
	s_barrier
	s_and_saveexec_b64 s[14:15], vcc
	s_cbranch_execz .LBB0_455
	s_barrier
	s_branch .LBB0_455

; #define hw_tid() ((g_wid << 6) | hw_lane())
; #define STA(P, br, kt) STAGE(P, A, aoff0, aoff1, lda, br, kt)
; #define STB(P, br, kt) STAGE(P, Bt, boff0, boff1, ldb, br, kt)
; #define WAIT_V(n) asm volatile("s_waitcnt vmcnt(" #n ")" ::: "memory")
; #define BAR __builtin_amdgcn_s_barrier()
; __device__ __forceinline__ void gemm256(const u16* __restrict__ A, int lda, const u16* __restrict__ Bt, int ldb, int K,
;                                         f32x4 (&acc)[2][2][4][2], const int g_wid) {
;   int tid = hw_tid(); asm volatile("" : "+v"(tid));
;   const int wid = tid >> 6, lane = tid & 63, wr = wid >> 2, wc = wid & 3, fr = lane & 15, fq = lane >> 4;
;   int r0, c0, r1, c1;
;   stage_rc(tid * 16, r0, c0);
;   stage_rc(tid * 16 + 8192, r1, c1);
;   const int aoff0 = r0 * lda + c0, aoff1 = r1 * lda + c1, boff0 = r0 * ldb + c0, boff1 = r1 * ldb + c1;
;   bf16x8 At[4][2], B0[2][2], B1[2][2];
;   const int nt = K / BK;
;   STB(SB(0, 0), 0, 0); STA(SA(0, 0), 0, 0);
;   STB(SB(0, 1), HALF, 0); STA(SA(0, 1), HALF, 0);
;   if (wr == 1) BAR;
;   WAIT_V(4); BAR;
;   STB(SB(1, 0), 0, 1); STA(SA(1, 0), 0, 1); STB(SB(1, 1), HALF, 1);
;   WAIT_V(6); BAR;
.LBB0_487:
	s_or_b64 exec, exec, s[18:19]
	v_readlane_b32 s9, v254, 42
	s_mov_b64 s[18:19], 0x80
	v_lshl_add_u64 v[2:3], v[2:3], 0, s[18:19]
	v_add_u32_e32 v167, s9, v19
	v_add_u32_e32 v168, 0x2000, v167
	v_readfirstlane_b32 s3, v167
	s_mov_b32 m0, s3
	v_readfirstlane_b32 s3, v168
	v_add_u32_e32 v169, 0x8000, v159
	s_waitcnt vmcnt(4)
	s_barrier
	global_load_lds_dwordx4 v[2:3], off
	v_lshl_add_u64 v[2:3], v[6:7], 0, s[18:19]
	s_mov_b32 m0, s3
	v_readfirstlane_b32 s3, v169
	global_load_lds_dwordx4 v[2:3], off
	v_lshl_add_u64 v[2:3], v[8:9], 0, s[18:19]
	s_mov_b32 m0, s3
	v_add_u32_e32 v170, 0xa000, v159
	global_load_lds_dwordx4 v[2:3], off
	v_lshl_add_u64 v[2:3], v[4:5], 0, s[18:19]
	v_readlane_b32 s18, v254, 43
	v_readfirstlane_b32 s3, v170
	s_add_u32 s16, s16, 0x40080
	v_add_u32_e32 v171, s18, v19
	s_mov_b32 m0, s3
	s_addc_u32 s17, s17, 0
	v_readfirstlane_b32 s3, v171
	v_add_u32_e32 v172, 0x2000, v171
	global_load_lds_dwordx4 v[2:3], off
	v_lshl_add_u64 v[2:3], v[132:133], 1, s[16:17]
	s_mov_b32 m0, s3
	v_readfirstlane_b32 s3, v172
	global_load_lds_dwordx4 v[2:3], off
	v_lshl_add_u64 v[2:3], v[130:131], 1, s[16:17]
	s_mov_b32 m0, s3
	v_and_b32_e32 v20, 15, v0
	global_load_lds_dwordx4 v[2:3], off
	v_lshlrev_b32_e32 v3, 2, v0
	v_and_b32_e32 v21, 48, v0
	v_lshlrev_b32_e32 v2, 6, v20
	v_and_b32_e32 v3, 32, v3
	v_bitop3_b32 v2, v2, v3, v21 bitop3:0x36
	v_readlane_b32 s3, v254, 40
	v_lshlrev_b32_e32 v4, 6, v0
	v_add_u32_e32 v8, s9, v2
	v_add_u32_e32 v6, s3, v2
	v_readlane_b32 s3, v254, 41
	v_add_u32_e32 v9, s18, v2
	v_add_u32_e32 v20, 0, v2
	v_add_u32_e32 v7, s3, v2
	s_movk_i32 s3, 0x3c0
	v_and_or_b32 v2, v4, s3, v21
	v_xad_u32 v21, v2, v3, 0
	v_lshlrev_b32_e32 v2, 13, v11
	v_and_b32_e32 v19, 0x3000, v4
	v_and_b32_e32 v2, 0xffffc000, v2
	v_lshlrev_b32_e32 v4, 13, v12
	v_lshl_add_u32 v2, v13, 10, v2
	v_and_b32_e32 v4, 0xffffc000, v4
	v_or_b32_e32 v2, v2, v14
	s_add_u32 s14, s4, s14
	v_lshl_add_u32 v4, v16, 10, v4
	v_add_u32_sdwa v2, v2, sext(v15) dst_sel:DWORD dst_unused:UNUSED_PAD src0_sel:DWORD src1_sel:WORD_0
	s_addc_u32 s15, s5, s15
	v_or_b32_e32 v4, v4, v17
	v_ashrrev_i32_e32 v3, 31, v2
	v_add_u32_sdwa v4, v4, sext(v18) dst_sel:DWORD dst_unused:UNUSED_PAD src0_sel:DWORD src1_sel:WORD_0
	s_add_u32 s12, s6, s12
	s_waitcnt vmcnt(6)
	v_lshlrev_b32_e32 v10, 13, v10
	v_lshlrev_b64 v[2:3], 1, v[2:3]
	v_ashrrev_i32_e32 v5, 31, v4
	s_addc_u32 s13, s7, s13
	v_or_b32_e32 v22, 0x800, v10
	v_or_b32_e32 v23, 0x1000, v10
	v_or_b32_e32 v24, 0x1800, v10
	v_lshl_add_u64 v[134:135], s[14:15], 0, v[2:3]
	v_lshlrev_b64 v[4:5], 1, v[4:5]
	v_lshl_add_u64 v[138:139], s[12:13], 0, v[2:3]
	v_mov_b32_e32 v2, 0
	v_lshl_add_u64 v[136:137], s[14:15], 0, v[4:5]
	v_lshl_add_u64 v[140:141], s[12:13], 0, v[4:5]
	s_mov_b32 s3, -2
	s_mov_b64 s[12:13], 0
	v_add_u32_e32 v174, v6, v19
	v_add_u32_e32 v145, v20, v10
	v_add_u32_e32 v144, v21, v22
	v_add_u32_e32 v143, v21, v23
	v_add_u32_e32 v142, v21, v24
	v_add_u32_e32 v173, v7, v19
	v_add_u32_e32 v166, v8, v19
	v_add_u32_e32 v160, v9, v19
	v_mov_b32_e32 v3, v2
	v_mov_b32_e32 v4, v2
	v_mov_b32_e32 v5, v2
	v_mov_b32_e32 v6, v2
	v_mov_b32_e32 v7, v2
	v_mov_b32_e32 v8, v2
	v_mov_b32_e32 v9, v2
	v_mov_b32_e32 v10, v2
	v_mov_b32_e32 v11, v2
	v_mov_b32_e32 v12, v2
	v_mov_b32_e32 v13, v2
	v_mov_b32_e32 v14, v2
	v_mov_b32_e32 v15, v2
	v_mov_b32_e32 v16, v2
	v_mov_b32_e32 v17, v2
	v_mov_b32_e32 v18, v2
	v_mov_b32_e32 v19, v2
	v_mov_b32_e32 v20, v2
	v_mov_b32_e32 v21, v2
	v_mov_b32_e32 v22, v2
	v_mov_b32_e32 v23, v2
	v_mov_b32_e32 v24, v2
	v_mov_b32_e32 v25, v2
	v_mov_b32_e32 v26, v2
	v_mov_b32_e32 v27, v2
	v_mov_b32_e32 v28, v2
	v_mov_b32_e32 v29, v2
	v_mov_b32_e32 v30, v2
	v_mov_b32_e32 v31, v2
	v_mov_b32_e32 v32, v2
	v_mov_b32_e32 v33, v2
	v_mov_b32_e32 v34, v2
	v_mov_b32_e32 v35, v2
	v_mov_b32_e32 v36, v2
	v_mov_b32_e32 v37, v2
	v_mov_b32_e32 v38, v2
	v_mov_b32_e32 v39, v2
	v_mov_b32_e32 v40, v2
	v_mov_b32_e32 v41, v2
	v_mov_b32_e32 v42, v2
	v_mov_b32_e32 v43, v2
	v_mov_b32_e32 v44, v2
	v_mov_b32_e32 v45, v2
	v_mov_b32_e32 v46, v2
	v_mov_b32_e32 v47, v2
	v_mov_b32_e32 v48, v2
	v_mov_b32_e32 v49, v2
	v_mov_b32_e32 v50, v2
	v_mov_b32_e32 v51, v2
	v_mov_b32_e32 v52, v2
	v_mov_b32_e32 v53, v2
	v_mov_b32_e32 v54, v2
	v_mov_b32_e32 v55, v2
	v_mov_b32_e32 v56, v2
	v_mov_b32_e32 v57, v2
	v_mov_b32_e32 v58, v2
	v_mov_b32_e32 v59, v2
	v_mov_b32_e32 v60, v2
	v_mov_b32_e32 v61, v2
	v_mov_b32_e32 v62, v2
	v_mov_b32_e32 v63, v2
	v_mov_b32_e32 v64, v2
	v_mov_b32_e32 v65, v2
	v_mov_b32_e32 v66, v2
	v_mov_b32_e32 v67, v2
	v_mov_b32_e32 v68, v2
	v_mov_b32_e32 v69, v2
	v_mov_b32_e32 v70, v2
	v_mov_b32_e32 v71, v2
	v_mov_b32_e32 v72, v2
	v_mov_b32_e32 v73, v2
	v_mov_b32_e32 v74, v2
	v_mov_b32_e32 v75, v2
	v_mov_b32_e32 v76, v2
	v_mov_b32_e32 v77, v2
	v_mov_b32_e32 v78, v2
	v_mov_b32_e32 v79, v2
	v_mov_b32_e32 v80, v2
	v_mov_b32_e32 v81, v2
	v_mov_b32_e32 v82, v2
	v_mov_b32_e32 v83, v2
	v_mov_b32_e32 v84, v2
	v_mov_b32_e32 v85, v2
	v_mov_b32_e32 v86, v2
	v_mov_b32_e32 v87, v2
	v_mov_b32_e32 v88, v2
	v_mov_b32_e32 v89, v2
	v_mov_b32_e32 v90, v2
	v_mov_b32_e32 v91, v2
	v_mov_b32_e32 v92, v2
	v_mov_b32_e32 v93, v2
	v_mov_b32_e32 v94, v2
	v_mov_b32_e32 v95, v2
	v_mov_b32_e32 v96, v2
	v_mov_b32_e32 v97, v2
	v_mov_b32_e32 v98, v2
	v_mov_b32_e32 v99, v2
	v_mov_b32_e32 v100, v2
	v_mov_b32_e32 v101, v2
	v_mov_b32_e32 v102, v2
	v_mov_b32_e32 v103, v2
	v_mov_b32_e32 v104, v2
	v_mov_b32_e32 v105, v2
	v_mov_b32_e32 v106, v2
	v_mov_b32_e32 v107, v2
	v_mov_b32_e32 v108, v2
	v_mov_b32_e32 v109, v2
	v_mov_b32_e32 v110, v2
	v_mov_b32_e32 v111, v2
	v_mov_b32_e32 v112, v2
	v_mov_b32_e32 v113, v2
	v_mov_b32_e32 v114, v2
	v_mov_b32_e32 v115, v2
	v_mov_b32_e32 v116, v2
	v_mov_b32_e32 v117, v2
	v_mov_b32_e32 v118, v2
	v_mov_b32_e32 v119, v2
	v_mov_b32_e32 v120, v2
	v_mov_b32_e32 v121, v2
	v_mov_b32_e32 v122, v2
	v_mov_b32_e32 v123, v2
	v_mov_b32_e32 v124, v2
	v_mov_b32_e32 v125, v2
	v_mov_b32_e32 v126, v2
	v_mov_b32_e32 v127, v2
	v_mov_b32_e32 v128, v2
	v_mov_b32_e32 v129, v2
	.p2align 6
; #define STA(P, br, kt) STAGE(P, A, aoff0, aoff1, lda, br, kt)
; #define STB(P, br, kt) STAGE(P, Bt, boff0, boff1, ldb, br, kt)
; #define LDA(dst, b, h) _Pragma("unroll") for (int m = 0; m < 4; ++m) _Pragma("unroll") for (int k = 0; k < 2; ++k) \
;     dst[m][k] = *reinterpret_cast<const bf16x8*>((char*)SA(b, h) + lds_byte(wr * 64 + m * 16 + fr, k * 32 + fq * 8))
; #define LDB(dst, b, h) _Pragma("unroll") for (int n = 0; n < 2; ++n) _Pragma("unroll") for (int k = 0; k < 2; ++k) \
;     dst[n][k] = *reinterpret_cast<const bf16x8*>((char*)SB(b, h) + lds_byte(wc * 32 + n * 16 + fr, k * 32 + fq * 8))
; #define MMA(ai, bj, At, Bq) do { __builtin_amdgcn_s_setprio(1); \
;     _Pragma("unroll") for (int m = 0; m < 4; ++m) _Pragma("unroll") for (int n = 0; n < 2; ++n) _Pragma("unroll") for (int k = 0; k < 2; ++k) \
;       acc[ai][bj][m][n] = __builtin_amdgcn_mfma_f32_16x16x32_bf16(At[m][k], Bq[n][k], acc[ai][bj][m][n], 0, 0, 0); \
;     __builtin_amdgcn_s_setprio(0); } while (0)
; #define WAIT_V(n) asm volatile("s_waitcnt vmcnt(" #n ")" ::: "memory")
; #define WAIT_L(n) asm volatile("s_waitcnt lgkmcnt(" #n ")" ::: "memory")
; #define BAR __builtin_amdgcn_s_barrier()
; #define SCHED __builtin_amdgcn_sched_barrier(0)
; __device__ __forceinline__ void gemm256(const u16* __restrict__ A, int lda, const u16* __restrict__ Bt, int ldb, int K,
;                                         f32x4 (&acc)[2][2][4][2], const int g_wid) {
;     ...
;   for (int t = 0; t < nt - 2; t += 2) {
;     LDB(B0, 0, 0); SCHED; LDA(At, 0, 0); STA(SA(1, 1), HALF, t + 1);
;     WAIT_L(8); BAR; WAIT_L(0); MMA(0, 0, At, B0); BAR; SCHED;
;     LDB(B1, 0, 1); STB(SB(0, 0), 0, t + 2);
;     BAR; WAIT_L(0); MMA(0, 1, At, B1); BAR;
;     LDA(At, 0, 1); STA(SA(0, 0), 0, t + 2);
;     BAR; WAIT_L(0); MMA(1, 0, At, B0); BAR; SCHED;
;     STB(SB(0, 1), HALF, t + 2);
;     WAIT_V(6); BAR; MMA(1, 1, At, B1); BAR;
.LBB0_488:
	s_barrier
	ds_read_b128 v[178:181], v174
	ds_read_b128 v[182:185], v174 offset:1024
	ds_read_b128 v[186:189], v174 offset:2048
	ds_read_b128 v[190:193], v174 offset:3072
	v_add_u32_e32 v175, 0xc000, v159
	v_lshl_add_u64 v[242:243], v[138:139], 0, s[12:13]
	v_readfirstlane_b32 s9, v175
	v_lshl_add_u64 v[176:177], v[242:243], 0, s[44:45]
	s_mov_b32 m0, s9
	ds_read_b128 v[194:197], v145
	ds_read_b128 v[198:201], v145 offset:1024
	ds_read_b128 v[202:205], v144
	ds_read_b128 v[206:209], v144 offset:1024
	ds_read_b128 v[210:213], v143
	ds_read_b128 v[214:217], v143 offset:1024
	ds_read_b128 v[218:221], v142
	ds_read_b128 v[222:225], v142 offset:1024
	global_load_lds_dwordx4 v[176:177], off
	v_add_u32_e32 v176, 0xe000, v159
	v_lshl_add_u64 v[244:245], v[140:141], 0, s[12:13]
	v_readfirstlane_b32 s9, v176
	v_lshl_add_u64 v[226:227], v[244:245], 0, s[44:45]
	s_mov_b32 m0, s9
	s_nop 0
	global_load_lds_dwordx4 v[226:227], off
	s_waitcnt lgkmcnt(8)
	s_barrier
	s_waitcnt lgkmcnt(0)
	v_mfma_f32_16x16x32_bf16 v[126:129], v[194:197], v[178:181], v[126:129]
	v_mfma_f32_16x16x32_bf16 v[122:125], v[194:197], v[186:189], v[122:125]
	v_mfma_f32_16x16x32_bf16 v[118:121], v[202:205], v[178:181], v[118:121]
	v_mfma_f32_16x16x32_bf16 v[114:117], v[202:205], v[186:189], v[114:117]
	v_mfma_f32_16x16x32_bf16 v[110:113], v[210:213], v[178:181], v[110:113]
	v_mfma_f32_16x16x32_bf16 v[106:109], v[210:213], v[186:189], v[106:109]
	v_mfma_f32_16x16x32_bf16 v[102:105], v[218:221], v[178:181], v[102:105]
	v_mfma_f32_16x16x32_bf16 v[98:101], v[218:221], v[186:189], v[98:101]
	v_mfma_f32_16x16x32_bf16 v[126:129], v[198:201], v[182:185], v[126:129]
	v_mfma_f32_16x16x32_bf16 v[122:125], v[198:201], v[190:193], v[122:125]
	v_mfma_f32_16x16x32_bf16 v[118:121], v[206:209], v[182:185], v[118:121]
	v_mfma_f32_16x16x32_bf16 v[114:117], v[206:209], v[190:193], v[114:117]
	v_mfma_f32_16x16x32_bf16 v[110:113], v[214:217], v[182:185], v[110:113]
	v_mfma_f32_16x16x32_bf16 v[106:109], v[214:217], v[190:193], v[106:109]
	v_mfma_f32_16x16x32_bf16 v[102:105], v[222:225], v[182:185], v[102:105]
	v_mfma_f32_16x16x32_bf16 v[98:101], v[222:225], v[190:193], v[98:101]
	s_barrier
	v_lshl_add_u64 v[246:247], v[134:135], 0, s[12:13]
	v_readfirstlane_b32 s9, v146
	v_lshl_add_u64 v[248:249], v[246:247], 0, s[64:65]
	s_mov_b32 m0, s9
	ds_read_b128 v[226:229], v173
	ds_read_b128 v[230:233], v173 offset:1024
	ds_read_b128 v[234:237], v173 offset:2048
	ds_read_b128 v[238:241], v173 offset:3072
	global_load_lds_dwordx4 v[248:249], off
	v_lshl_add_u64 v[248:249], v[136:137], 0, s[12:13]
	v_readfirstlane_b32 s9, v147
	v_lshl_add_u64 v[250:251], v[248:249], 0, s[64:65]
	s_mov_b32 m0, s9
	s_nop 0
	global_load_lds_dwordx4 v[250:251], off
	s_barrier
	s_waitcnt lgkmcnt(0)
	v_mfma_f32_16x16x32_bf16 v[94:97], v[194:197], v[226:229], v[94:97]
	v_mfma_f32_16x16x32_bf16 v[90:93], v[194:197], v[234:237], v[90:93]
	v_mfma_f32_16x16x32_bf16 v[86:89], v[202:205], v[226:229], v[86:89]
	v_mfma_f32_16x16x32_bf16 v[82:85], v[202:205], v[234:237], v[82:85]
	v_mfma_f32_16x16x32_bf16 v[78:81], v[210:213], v[226:229], v[78:81]
	v_mfma_f32_16x16x32_bf16 v[74:77], v[210:213], v[234:237], v[74:77]
	v_mfma_f32_16x16x32_bf16 v[70:73], v[218:221], v[226:229], v[70:73]
	v_mfma_f32_16x16x32_bf16 v[66:69], v[218:221], v[234:237], v[66:69]
	v_mfma_f32_16x16x32_bf16 v[94:97], v[198:201], v[230:233], v[94:97]
	v_mfma_f32_16x16x32_bf16 v[90:93], v[198:201], v[238:241], v[90:93]
	v_mfma_f32_16x16x32_bf16 v[86:89], v[206:209], v[230:233], v[86:89]
	v_mfma_f32_16x16x32_bf16 v[82:85], v[206:209], v[238:241], v[82:85]
	v_mfma_f32_16x16x32_bf16 v[78:81], v[214:217], v[230:233], v[78:81]
	v_mfma_f32_16x16x32_bf16 v[74:77], v[214:217], v[238:241], v[74:77]
	v_mfma_f32_16x16x32_bf16 v[70:73], v[222:225], v[230:233], v[70:73]
	v_mfma_f32_16x16x32_bf16 v[66:69], v[222:225], v[238:241], v[66:69]
	v_readfirstlane_b32 s9, v159
	v_lshl_add_u64 v[250:251], v[242:243], 0, s[70:71]
	s_mov_b32 m0, s9
	v_readfirstlane_b32 s9, v161
	s_barrier
	ds_read_b128 v[194:197], v145 offset:16384
	ds_read_b128 v[198:201], v145 offset:17408
	ds_read_b128 v[202:205], v144 offset:16384
	ds_read_b128 v[206:209], v144 offset:17408
	ds_read_b128 v[210:213], v143 offset:16384
	ds_read_b128 v[214:217], v143 offset:17408
	ds_read_b128 v[218:221], v142 offset:16384
	ds_read_b128 v[222:225], v142 offset:17408
	global_load_lds_dwordx4 v[250:251], off
	v_lshl_add_u64 v[250:251], v[244:245], 0, s[70:71]
	s_mov_b32 m0, s9
	s_nop 0
	global_load_lds_dwordx4 v[250:251], off
	s_barrier
	s_waitcnt lgkmcnt(0)
	v_mfma_f32_16x16x32_bf16 v[62:65], v[194:197], v[178:181], v[62:65]
	v_mfma_f32_16x16x32_bf16 v[58:61], v[194:197], v[186:189], v[58:61]
	v_mfma_f32_16x16x32_bf16 v[54:57], v[202:205], v[178:181], v[54:57]
	v_mfma_f32_16x16x32_bf16 v[50:53], v[202:205], v[186:189], v[50:53]
	v_mfma_f32_16x16x32_bf16 v[46:49], v[210:213], v[178:181], v[46:49]
	v_mfma_f32_16x16x32_bf16 v[42:45], v[210:213], v[186:189], v[42:45]
	v_mfma_f32_16x16x32_bf16 v[38:41], v[218:221], v[178:181], v[38:41]
	v_mfma_f32_16x16x32_bf16 v[34:37], v[218:221], v[186:189], v[34:37]
	v_mfma_f32_16x16x32_bf16 v[62:65], v[198:201], v[182:185], v[62:65]
	v_mfma_f32_16x16x32_bf16 v[58:61], v[198:201], v[190:193], v[58:61]
	v_mfma_f32_16x16x32_bf16 v[54:57], v[206:209], v[182:185], v[54:57]
	v_mfma_f32_16x16x32_bf16 v[50:53], v[206:209], v[190:193], v[50:53]
	v_mfma_f32_16x16x32_bf16 v[46:49], v[214:217], v[182:185], v[46:49]
	v_mfma_f32_16x16x32_bf16 v[42:45], v[214:217], v[190:193], v[42:45]
	v_mfma_f32_16x16x32_bf16 v[38:41], v[222:225], v[182:185], v[38:41]
	v_mfma_f32_16x16x32_bf16 v[34:37], v[222:225], v[190:193], v[34:37]
	s_barrier
; #define STA(P, br, kt) STAGE(P, A, aoff0, aoff1, lda, br, kt)
; #define STB(P, br, kt) STAGE(P, Bt, boff0, boff1, ldb, br, kt)
; #define LDA(dst, b, h) _Pragma("unroll") for (int m = 0; m < 4; ++m) _Pragma("unroll") for (int k = 0; k < 2; ++k) \
;     dst[m][k] = *reinterpret_cast<const bf16x8*>((char*)SA(b, h) + lds_byte(wr * 64 + m * 16 + fr, k * 32 + fq * 8))
; #define LDB(dst, b, h) _Pragma("unroll") for (int n = 0; n < 2; ++n) _Pragma("unroll") for (int k = 0; k < 2; ++k) \
;     dst[n][k] = *reinterpret_cast<const bf16x8*>((char*)SB(b, h) + lds_byte(wc * 32 + n * 16 + fr, k * 32 + fq * 8))
; #define MMA(ai, bj, At, Bq) do { __builtin_amdgcn_s_setprio(1); \
;     _Pragma("unroll") for (int m = 0; m < 4; ++m) _Pragma("unroll") for (int n = 0; n < 2; ++n) _Pragma("unroll") for (int k = 0; k < 2; ++k) \
;       acc[ai][bj][m][n] = __builtin_amdgcn_mfma_f32_16x16x32_bf16(At[m][k], Bq[n][k], acc[ai][bj][m][n], 0, 0, 0); \
;     __builtin_amdgcn_s_setprio(0); } while (0)
; #define WAIT_V(n) asm volatile("s_waitcnt vmcnt(" #n ")" ::: "memory")
; #define WAIT_L(n) asm volatile("s_waitcnt lgkmcnt(" #n ")" ::: "memory")
; #define BAR __builtin_amdgcn_s_barrier()
; #define SCHED __builtin_amdgcn_sched_barrier(0)
; __device__ __forceinline__ void gemm256(const u16* __restrict__ A, int lda, const u16* __restrict__ Bt, int ldb, int K,
;                                         f32x4 (&acc)[2][2][4][2], const int g_wid) {
;     ...
;     LDA(At, 0, 1); STA(SA(0, 0), 0, t + 2);
;     BAR; WAIT_L(0); MMA(1, 0, At, B0); BAR; SCHED;
;     STB(SB(0, 1), HALF, t + 2);
;     WAIT_V(6); BAR; MMA(1, 1, At, B1); BAR;
;     LDB(B0, 1, 0); SCHED; LDA(At, 1, 0); STA(SA(0, 1), HALF, t + 2);
;     WAIT_L(8); BAR; WAIT_L(0); MMA(0, 0, At, B0); BAR; SCHED;
;     LDB(B1, 1, 1); STB(SB(1, 0), 0, t + 3);
;     BAR; WAIT_L(0); MMA(0, 1, At, B1); BAR;
	v_readfirstlane_b32 s9, v162
	v_lshl_add_u64 v[178:179], v[246:247], 0, s[0:1]
	s_mov_b32 m0, s9
	v_readfirstlane_b32 s9, v163
	global_load_lds_dwordx4 v[178:179], off
	v_lshl_add_u64 v[178:179], v[248:249], 0, s[0:1]
	s_mov_b32 m0, s9
	s_nop 0
	global_load_lds_dwordx4 v[178:179], off
	s_waitcnt vmcnt(6)
	s_barrier
	v_mfma_f32_16x16x32_bf16 v[30:33], v[194:197], v[226:229], v[30:33]
	v_mfma_f32_16x16x32_bf16 v[26:29], v[194:197], v[234:237], v[26:29]
	v_mfma_f32_16x16x32_bf16 v[22:25], v[202:205], v[226:229], v[22:25]
	v_mfma_f32_16x16x32_bf16 v[18:21], v[202:205], v[234:237], v[18:21]
	v_mfma_f32_16x16x32_bf16 v[14:17], v[210:213], v[226:229], v[14:17]
	v_mfma_f32_16x16x32_bf16 v[10:13], v[210:213], v[234:237], v[10:13]
	v_mfma_f32_16x16x32_bf16 v[6:9], v[218:221], v[226:229], v[6:9]
	v_mfma_f32_16x16x32_bf16 v[2:5], v[218:221], v[234:237], v[2:5]
	v_mfma_f32_16x16x32_bf16 v[30:33], v[198:201], v[230:233], v[30:33]
	v_mfma_f32_16x16x32_bf16 v[26:29], v[198:201], v[238:241], v[26:29]
	v_mfma_f32_16x16x32_bf16 v[22:25], v[206:209], v[230:233], v[22:25]
	v_mfma_f32_16x16x32_bf16 v[18:21], v[206:209], v[238:241], v[18:21]
	v_mfma_f32_16x16x32_bf16 v[14:17], v[214:217], v[230:233], v[14:17]
	v_mfma_f32_16x16x32_bf16 v[10:13], v[214:217], v[238:241], v[10:13]
	v_mfma_f32_16x16x32_bf16 v[6:9], v[222:225], v[230:233], v[6:9]
	v_mfma_f32_16x16x32_bf16 v[2:5], v[222:225], v[238:241], v[2:5]
	s_barrier
	ds_read_b128 v[178:181], v166
	ds_read_b128 v[182:185], v166 offset:1024
	ds_read_b128 v[186:189], v166 offset:2048
	ds_read_b128 v[190:193], v166 offset:3072
	v_readfirstlane_b32 s9, v164
	v_lshl_add_u64 v[226:227], v[242:243], 0, s[52:53]
	s_mov_b32 m0, s9
	v_readfirstlane_b32 s9, v165
	ds_read_b128 v[194:197], v145 offset:32768
	ds_read_b128 v[198:201], v145 offset:33792
	ds_read_b128 v[202:205], v144 offset:32768
	ds_read_b128 v[206:209], v144 offset:33792
	ds_read_b128 v[210:213], v143 offset:32768
	ds_read_b128 v[214:217], v143 offset:33792
	ds_read_b128 v[218:221], v142 offset:32768
	ds_read_b128 v[222:225], v142 offset:33792
	global_load_lds_dwordx4 v[226:227], off
	v_lshl_add_u64 v[226:227], v[244:245], 0, s[52:53]
	s_mov_b32 m0, s9
	s_nop 0
	global_load_lds_dwordx4 v[226:227], off
	s_waitcnt lgkmcnt(8)
	s_barrier
	s_waitcnt lgkmcnt(0)
	v_mfma_f32_16x16x32_bf16 v[126:129], v[194:197], v[178:181], v[126:129]
	v_mfma_f32_16x16x32_bf16 v[122:125], v[194:197], v[186:189], v[122:125]
	v_mfma_f32_16x16x32_bf16 v[118:121], v[202:205], v[178:181], v[118:121]
	v_mfma_f32_16x16x32_bf16 v[114:117], v[202:205], v[186:189], v[114:117]
	v_mfma_f32_16x16x32_bf16 v[110:113], v[210:213], v[178:181], v[110:113]
	v_mfma_f32_16x16x32_bf16 v[106:109], v[210:213], v[186:189], v[106:109]
	v_mfma_f32_16x16x32_bf16 v[102:105], v[218:221], v[178:181], v[102:105]
	v_mfma_f32_16x16x32_bf16 v[98:101], v[218:221], v[186:189], v[98:101]
	v_mfma_f32_16x16x32_bf16 v[126:129], v[198:201], v[182:185], v[126:129]
	v_mfma_f32_16x16x32_bf16 v[122:125], v[198:201], v[190:193], v[122:125]
	v_mfma_f32_16x16x32_bf16 v[118:121], v[206:209], v[182:185], v[118:121]
	v_mfma_f32_16x16x32_bf16 v[114:117], v[206:209], v[190:193], v[114:117]
	v_mfma_f32_16x16x32_bf16 v[110:113], v[214:217], v[182:185], v[110:113]
	v_mfma_f32_16x16x32_bf16 v[106:109], v[214:217], v[190:193], v[106:109]
	v_mfma_f32_16x16x32_bf16 v[102:105], v[222:225], v[182:185], v[102:105]
	v_mfma_f32_16x16x32_bf16 v[98:101], v[222:225], v[190:193], v[98:101]
	s_barrier
	v_readfirstlane_b32 s9, v167
	v_lshl_add_u64 v[250:251], v[246:247], 0, s[58:59]
	s_mov_b32 m0, s9
	v_readfirstlane_b32 s9, v168
	ds_read_b128 v[226:229], v160
	ds_read_b128 v[230:233], v160 offset:1024
	ds_read_b128 v[234:237], v160 offset:2048
	ds_read_b128 v[238:241], v160 offset:3072
	global_load_lds_dwordx4 v[250:251], off
	v_lshl_add_u64 v[250:251], v[248:249], 0, s[58:59]
	s_mov_b32 m0, s9
	s_nop 0
	global_load_lds_dwordx4 v[250:251], off
	s_barrier
	s_waitcnt lgkmcnt(0)
	v_mfma_f32_16x16x32_bf16 v[94:97], v[194:197], v[226:229], v[94:97]
	v_mfma_f32_16x16x32_bf16 v[90:93], v[194:197], v[234:237], v[90:93]
	v_mfma_f32_16x16x32_bf16 v[86:89], v[202:205], v[226:229], v[86:89]
	v_mfma_f32_16x16x32_bf16 v[82:85], v[202:205], v[234:237], v[82:85]
	v_mfma_f32_16x16x32_bf16 v[78:81], v[210:213], v[226:229], v[78:81]
	v_mfma_f32_16x16x32_bf16 v[74:77], v[210:213], v[234:237], v[74:77]
	v_mfma_f32_16x16x32_bf16 v[70:73], v[218:221], v[226:229], v[70:73]
	v_mfma_f32_16x16x32_bf16 v[66:69], v[218:221], v[234:237], v[66:69]
	v_mfma_f32_16x16x32_bf16 v[94:97], v[198:201], v[230:233], v[94:97]
	v_mfma_f32_16x16x32_bf16 v[90:93], v[198:201], v[238:241], v[90:93]
	v_mfma_f32_16x16x32_bf16 v[86:89], v[206:209], v[230:233], v[86:89]
	v_mfma_f32_16x16x32_bf16 v[82:85], v[206:209], v[238:241], v[82:85]
	v_mfma_f32_16x16x32_bf16 v[78:81], v[214:217], v[230:233], v[78:81]
	v_mfma_f32_16x16x32_bf16 v[74:77], v[214:217], v[238:241], v[74:77]
	v_mfma_f32_16x16x32_bf16 v[70:73], v[222:225], v[230:233], v[70:73]
	v_mfma_f32_16x16x32_bf16 v[66:69], v[222:225], v[238:241], v[66:69]
	v_readfirstlane_b32 s9, v169
	v_lshl_add_u64 v[242:243], v[242:243], 0, s[60:61]
	s_mov_b32 m0, s9
	v_readfirstlane_b32 s9, v170
	s_barrier
	ds_read_b128 v[194:197], v145 offset:49152
	ds_read_b128 v[198:201], v145 offset:50176
	ds_read_b128 v[202:205], v144 offset:49152
	ds_read_b128 v[206:209], v144 offset:50176
	ds_read_b128 v[210:213], v143 offset:49152
	ds_read_b128 v[214:217], v143 offset:50176
	ds_read_b128 v[218:221], v142 offset:49152
	ds_read_b128 v[222:225], v142 offset:50176
	global_load_lds_dwordx4 v[242:243], off
	v_lshl_add_u64 v[242:243], v[244:245], 0, s[60:61]
	s_mov_b32 m0, s9
	s_nop 0
	global_load_lds_dwordx4 v[242:243], off
	s_barrier
; #define STA(P, br, kt) STAGE(P, A, aoff0, aoff1, lda, br, kt)
; #define STB(P, br, kt) STAGE(P, Bt, boff0, boff1, ldb, br, kt)
; #define LDA(dst, b, h) _Pragma("unroll") for (int m = 0; m < 4; ++m) _Pragma("unroll") for (int k = 0; k < 2; ++k) \
;     dst[m][k] = *reinterpret_cast<const bf16x8*>((char*)SA(b, h) + lds_byte(wr * 64 + m * 16 + fr, k * 32 + fq * 8))
; #define LDB(dst, b, h) _Pragma("unroll") for (int n = 0; n < 2; ++n) _Pragma("unroll") for (int k = 0; k < 2; ++k) \
;     dst[n][k] = *reinterpret_cast<const bf16x8*>((char*)SB(b, h) + lds_byte(wc * 32 + n * 16 + fr, k * 32 + fq * 8))
; #define MMA(ai, bj, At, Bq) do { __builtin_amdgcn_s_setprio(1); \
;     _Pragma("unroll") for (int m = 0; m < 4; ++m) _Pragma("unroll") for (int n = 0; n < 2; ++n) _Pragma("unroll") for (int k = 0; k < 2; ++k) \
;       acc[ai][bj][m][n] = __builtin_amdgcn_mfma_f32_16x16x32_bf16(At[m][k], Bq[n][k], acc[ai][bj][m][n], 0, 0, 0); \
;     __builtin_amdgcn_s_setprio(0); } while (0)
; #define WAIT_V(n) asm volatile("s_waitcnt vmcnt(" #n ")" ::: "memory")
; #define WAIT_L(n) asm volatile("s_waitcnt lgkmcnt(" #n ")" ::: "memory")
; #define BAR __builtin_amdgcn_s_barrier()
; #define SCHED __builtin_amdgcn_sched_barrier(0)
; __device__ __forceinline__ void gemm256(const u16* __restrict__ A, int lda, const u16* __restrict__ Bt, int ldb, int K,
;                                         f32x4 (&acc)[2][2][4][2], const int g_wid) {
;     ...
;     WAIT_L(8); BAR; WAIT_L(0); MMA(0, 0, At, B0); BAR; SCHED;
;     LDB(B1, 1, 1); STB(SB(1, 0), 0, t + 3);
;     BAR; WAIT_L(0); MMA(0, 1, At, B1); BAR;
;     LDA(At, 1, 1); STA(SA(1, 0), 0, t + 3);
;     BAR; WAIT_L(0); MMA(1, 0, At, B0); BAR; SCHED;
;     STB(SB(1, 1), HALF, t + 3);
;     WAIT_V(6); BAR; MMA(1, 1, At, B1); BAR;
;   }
;   { LDB(B0, 0, 0); LDA(At, 0, 0); STA(SA(1, 1), HALF, nt - 1);
;     BAR; WAIT_L(0); MMA(0, 0, At, B0); BAR;
	s_waitcnt lgkmcnt(0)
	v_mfma_f32_16x16x32_bf16 v[62:65], v[194:197], v[178:181], v[62:65]
	v_mfma_f32_16x16x32_bf16 v[58:61], v[194:197], v[186:189], v[58:61]
	v_mfma_f32_16x16x32_bf16 v[54:57], v[202:205], v[178:181], v[54:57]
	v_mfma_f32_16x16x32_bf16 v[50:53], v[202:205], v[186:189], v[50:53]
	v_mfma_f32_16x16x32_bf16 v[46:49], v[210:213], v[178:181], v[46:49]
	v_mfma_f32_16x16x32_bf16 v[42:45], v[210:213], v[186:189], v[42:45]
	v_mfma_f32_16x16x32_bf16 v[38:41], v[218:221], v[178:181], v[38:41]
	v_mfma_f32_16x16x32_bf16 v[34:37], v[218:221], v[186:189], v[34:37]
	v_mfma_f32_16x16x32_bf16 v[62:65], v[198:201], v[182:185], v[62:65]
	v_mfma_f32_16x16x32_bf16 v[58:61], v[198:201], v[190:193], v[58:61]
	v_mfma_f32_16x16x32_bf16 v[54:57], v[206:209], v[182:185], v[54:57]
	v_mfma_f32_16x16x32_bf16 v[50:53], v[206:209], v[190:193], v[50:53]
	v_mfma_f32_16x16x32_bf16 v[46:49], v[214:217], v[182:185], v[46:49]
	v_mfma_f32_16x16x32_bf16 v[42:45], v[214:217], v[190:193], v[42:45]
	v_mfma_f32_16x16x32_bf16 v[38:41], v[222:225], v[182:185], v[38:41]
	v_mfma_f32_16x16x32_bf16 v[34:37], v[222:225], v[190:193], v[34:37]
	s_barrier
	v_readfirstlane_b32 s9, v171
	v_lshl_add_u64 v[178:179], v[246:247], 0, s[48:49]
	s_mov_b32 m0, s9
	v_readfirstlane_b32 s9, v172
	global_load_lds_dwordx4 v[178:179], off
	v_lshl_add_u64 v[178:179], v[248:249], 0, s[48:49]
	s_mov_b32 m0, s9
	s_nop 0
	global_load_lds_dwordx4 v[178:179], off
	s_waitcnt vmcnt(6)
	s_barrier
	v_mfma_f32_16x16x32_bf16 v[30:33], v[194:197], v[226:229], v[30:33]
	v_mfma_f32_16x16x32_bf16 v[26:29], v[194:197], v[234:237], v[26:29]
	v_mfma_f32_16x16x32_bf16 v[22:25], v[202:205], v[226:229], v[22:25]
	v_mfma_f32_16x16x32_bf16 v[18:21], v[202:205], v[234:237], v[18:21]
	v_mfma_f32_16x16x32_bf16 v[14:17], v[210:213], v[226:229], v[14:17]
	v_mfma_f32_16x16x32_bf16 v[10:13], v[210:213], v[234:237], v[10:13]
	v_mfma_f32_16x16x32_bf16 v[6:9], v[218:221], v[226:229], v[6:9]
	v_mfma_f32_16x16x32_bf16 v[2:5], v[218:221], v[234:237], v[2:5]
	v_mfma_f32_16x16x32_bf16 v[30:33], v[198:201], v[230:233], v[30:33]
	v_mfma_f32_16x16x32_bf16 v[26:29], v[198:201], v[238:241], v[26:29]
	v_mfma_f32_16x16x32_bf16 v[22:25], v[206:209], v[230:233], v[22:25]
	v_mfma_f32_16x16x32_bf16 v[18:21], v[206:209], v[238:241], v[18:21]
	v_mfma_f32_16x16x32_bf16 v[14:17], v[214:217], v[230:233], v[14:17]
	v_mfma_f32_16x16x32_bf16 v[10:13], v[214:217], v[238:241], v[10:13]
	v_mfma_f32_16x16x32_bf16 v[6:9], v[222:225], v[230:233], v[6:9]
	v_mfma_f32_16x16x32_bf16 v[2:5], v[222:225], v[238:241], v[2:5]
	s_add_i32 s3, s3, 2
	s_add_u32 s12, s12, 0x100
	s_addc_u32 s13, s13, 0
	s_cmp_lt_u32 s3, 12
	s_cbranch_scc1 .LBB0_488
	s_barrier
	s_add_u32 s10, s10, 0x40780
	s_addc_u32 s11, s11, 0
	v_readfirstlane_b32 s3, v175
	v_lshl_add_u64 v[132:133], v[132:133], 1, s[10:11]
	s_mov_b32 m0, s3
	v_readfirstlane_b32 s3, v176
	ds_read_b128 v[134:137], v174
	ds_read_b128 v[138:141], v174 offset:1024
	ds_read_b128 v[162:165], v174 offset:2048
	ds_read_b128 v[168:171], v174 offset:3072
	ds_read_b128 v[178:181], v145
	ds_read_b128 v[182:185], v145 offset:1024
	ds_read_b128 v[186:189], v144
	ds_read_b128 v[190:193], v144 offset:1024
	ds_read_b128 v[194:197], v143
	ds_read_b128 v[198:201], v143 offset:1024
	ds_read_b128 v[202:205], v142
	ds_read_b128 v[206:209], v142 offset:1024
	global_load_lds_dwordx4 v[132:133], off
	v_lshl_add_u64 v[130:131], v[130:131], 1, s[10:11]
	s_mov_b32 m0, s3
	s_nop 0
	global_load_lds_dwordx4 v[130:131], off
	s_barrier
	s_waitcnt lgkmcnt(0)
	v_mfma_f32_16x16x32_bf16 v[126:129], v[178:181], v[134:137], v[126:129]
	v_mfma_f32_16x16x32_bf16 v[118:121], v[186:189], v[134:137], v[118:121]
	v_mfma_f32_16x16x32_bf16 v[114:117], v[186:189], v[162:165], v[114:117]
	v_mfma_f32_16x16x32_bf16 v[110:113], v[194:197], v[134:137], v[110:113]
	v_mfma_f32_16x16x32_bf16 v[106:109], v[194:197], v[162:165], v[106:109]
	v_mfma_f32_16x16x32_bf16 v[102:105], v[202:205], v[134:137], v[102:105]
	v_mfma_f32_16x16x32_bf16 v[98:101], v[202:205], v[162:165], v[98:101]
	v_mfma_f32_16x16x32_bf16 v[126:129], v[182:185], v[138:141], v[126:129]
	v_mfma_f32_16x16x32_bf16 v[122:125], v[178:181], v[162:165], v[122:125]
	v_mfma_f32_16x16x32_bf16 v[118:121], v[190:193], v[138:141], v[118:121]
	v_mfma_f32_16x16x32_bf16 v[114:117], v[190:193], v[168:171], v[114:117]
	v_mfma_f32_16x16x32_bf16 v[110:113], v[198:201], v[138:141], v[110:113]
	v_mfma_f32_16x16x32_bf16 v[106:109], v[198:201], v[168:171], v[106:109]
	v_mfma_f32_16x16x32_bf16 v[102:105], v[206:209], v[138:141], v[102:105]
	v_mfma_f32_16x16x32_bf16 v[98:101], v[206:209], v[168:171], v[98:101]
	v_mfma_f32_16x16x32_bf16 v[130:133], v[182:185], v[168:171], v[122:125]
	s_barrier
	s_nop 0
	ds_read_b128 v[122:125], v173
	ds_read_b128 v[174:177], v173 offset:1024
	ds_read_b128 v[210:213], v173 offset:2048
	ds_read_b128 v[214:217], v173 offset:3072
	s_barrier
	s_waitcnt lgkmcnt(0)
	v_mfma_f32_16x16x32_bf16 v[78:81], v[194:197], v[122:125], v[78:81]
	v_mfma_f32_16x16x32_bf16 v[74:77], v[194:197], v[210:213], v[74:77]
	v_mfma_f32_16x16x32_bf16 v[70:73], v[202:205], v[122:125], v[70:73]
	v_mfma_f32_16x16x32_bf16 v[66:69], v[202:205], v[210:213], v[66:69]
	v_mfma_f32_16x16x32_bf16 v[94:97], v[178:181], v[122:125], v[94:97]
	v_mfma_f32_16x16x32_bf16 v[90:93], v[178:181], v[210:213], v[90:93]
	v_mfma_f32_16x16x32_bf16 v[86:89], v[186:189], v[122:125], v[86:89]
	v_mfma_f32_16x16x32_bf16 v[82:85], v[186:189], v[210:213], v[82:85]
	v_mfma_f32_16x16x32_bf16 v[78:81], v[198:201], v[174:177], v[78:81]
	v_mfma_f32_16x16x32_bf16 v[74:77], v[198:201], v[214:217], v[74:77]
	v_mfma_f32_16x16x32_bf16 v[70:73], v[206:209], v[174:177], v[70:73]
	v_mfma_f32_16x16x32_bf16 v[66:69], v[206:209], v[214:217], v[66:69]
	v_mfma_f32_16x16x32_bf16 v[218:221], v[182:185], v[174:177], v[94:97]
	v_mfma_f32_16x16x32_bf16 v[178:181], v[182:185], v[214:217], v[90:93]
	v_mfma_f32_16x16x32_bf16 v[182:185], v[190:193], v[174:177], v[86:89]
	v_mfma_f32_16x16x32_bf16 v[186:189], v[190:193], v[214:217], v[82:85]
	s_barrier
; #define LDA(dst, b, h) _Pragma("unroll") for (int m = 0; m < 4; ++m) _Pragma("unroll") for (int k = 0; k < 2; ++k) \
;     dst[m][k] = *reinterpret_cast<const bf16x8*>((char*)SA(b, h) + lds_byte(wr * 64 + m * 16 + fr, k * 32 + fq * 8))
; #define LDB(dst, b, h) _Pragma("unroll") for (int n = 0; n < 2; ++n) _Pragma("unroll") for (int k = 0; k < 2; ++k) \
;     dst[n][k] = *reinterpret_cast<const bf16x8*>((char*)SB(b, h) + lds_byte(wc * 32 + n * 16 + fr, k * 32 + fq * 8))
; #define MMA(ai, bj, At, Bq) do { __builtin_amdgcn_s_setprio(1); \
;     _Pragma("unroll") for (int m = 0; m < 4; ++m) _Pragma("unroll") for (int n = 0; n < 2; ++n) _Pragma("unroll") for (int k = 0; k < 2; ++k) \
;       acc[ai][bj][m][n] = __builtin_amdgcn_mfma_f32_16x16x32_bf16(At[m][k], Bq[n][k], acc[ai][bj][m][n], 0, 0, 0); \
;     __builtin_amdgcn_s_setprio(0); } while (0)
; #define WAIT_V(n) asm volatile("s_waitcnt vmcnt(" #n ")" ::: "memory")
; #define WAIT_L(n) asm volatile("s_waitcnt lgkmcnt(" #n ")" ::: "memory")
; #define BAR __builtin_amdgcn_s_barrier()
; __device__ __forceinline__ void gemm256(const u16* __restrict__ A, int lda, const u16* __restrict__ Bt, int ldb, int K,
;                                         f32x4 (&acc)[2][2][4][2], const int g_wid) {
;     ...
;     BAR; WAIT_L(0); MMA(0, 0, At, B0); BAR;
;     LDB(B1, 0, 1); BAR; WAIT_L(0); MMA(0, 1, At, B1); BAR;
;     LDA(At, 0, 1); WAIT_V(4); BAR; WAIT_L(0); MMA(1, 0, At, B0); MMA(1, 1, At, B1); BAR; }
;   { LDB(B0, 1, 0); LDA(At, 1, 0); WAIT_V(2); BAR; WAIT_L(0); MMA(0, 0, At, B0); BAR;
	s_nop 0
	ds_read_b128 v[82:85], v145 offset:16384
	ds_read_b128 v[86:89], v145 offset:17408
	ds_read_b128 v[90:93], v144 offset:16384
	ds_read_b128 v[94:97], v144 offset:17408
	ds_read_b128 v[190:193], v143 offset:16384
	ds_read_b128 v[194:197], v143 offset:17408
	ds_read_b128 v[198:201], v142 offset:16384
	ds_read_b128 v[202:205], v142 offset:17408
	s_waitcnt vmcnt(4)
	s_barrier
	s_waitcnt lgkmcnt(0)
	v_mfma_f32_16x16x32_bf16 v[46:49], v[190:193], v[134:137], v[46:49]
	v_mfma_f32_16x16x32_bf16 v[42:45], v[190:193], v[162:165], v[42:45]
	v_mfma_f32_16x16x32_bf16 v[38:41], v[198:201], v[134:137], v[38:41]
	v_mfma_f32_16x16x32_bf16 v[34:37], v[198:201], v[162:165], v[34:37]
	v_mfma_f32_16x16x32_bf16 v[62:65], v[82:85], v[134:137], v[62:65]
	v_mfma_f32_16x16x32_bf16 v[58:61], v[82:85], v[162:165], v[58:61]
	v_mfma_f32_16x16x32_bf16 v[54:57], v[90:93], v[134:137], v[54:57]
	v_mfma_f32_16x16x32_bf16 v[50:53], v[90:93], v[162:165], v[50:53]
	v_mfma_f32_16x16x32_bf16 v[46:49], v[194:197], v[138:141], v[46:49]
	v_mfma_f32_16x16x32_bf16 v[42:45], v[194:197], v[168:171], v[42:45]
	v_mfma_f32_16x16x32_bf16 v[38:41], v[202:205], v[138:141], v[38:41]
	v_mfma_f32_16x16x32_bf16 v[34:37], v[202:205], v[168:171], v[34:37]
	v_mfma_f32_16x16x32_bf16 v[206:209], v[86:89], v[138:141], v[62:65]
	v_mfma_f32_16x16x32_bf16 v[222:225], v[86:89], v[168:171], v[58:61]
	v_mfma_f32_16x16x32_bf16 v[226:229], v[94:97], v[138:141], v[54:57]
	v_mfma_f32_16x16x32_bf16 v[230:233], v[94:97], v[168:171], v[50:53]
	v_mfma_f32_16x16x32_bf16 v[2:5], v[198:201], v[210:213], v[2:5]
	v_mfma_f32_16x16x32_bf16 v[30:33], v[82:85], v[122:125], v[30:33]
	v_mfma_f32_16x16x32_bf16 v[26:29], v[82:85], v[210:213], v[26:29]
	v_mfma_f32_16x16x32_bf16 v[22:25], v[90:93], v[122:125], v[22:25]
	v_mfma_f32_16x16x32_bf16 v[18:21], v[90:93], v[210:213], v[18:21]
	v_mfma_f32_16x16x32_bf16 v[14:17], v[190:193], v[122:125], v[14:17]
	v_mfma_f32_16x16x32_bf16 v[10:13], v[190:193], v[210:213], v[10:13]
	v_mfma_f32_16x16x32_bf16 v[6:9], v[198:201], v[122:125], v[6:9]
	v_mfma_f32_16x16x32_bf16 v[2:5], v[202:205], v[214:217], v[2:5]
	v_mfma_f32_16x16x32_bf16 v[134:137], v[86:89], v[174:177], v[30:33]
	v_mfma_f32_16x16x32_bf16 v[138:141], v[86:89], v[214:217], v[26:29]
	v_mfma_f32_16x16x32_bf16 v[162:165], v[94:97], v[174:177], v[22:25]
	v_mfma_f32_16x16x32_bf16 v[168:171], v[94:97], v[214:217], v[18:21]
	v_mfma_f32_16x16x32_bf16 v[234:237], v[194:197], v[174:177], v[14:17]
	v_mfma_f32_16x16x32_bf16 v[190:193], v[194:197], v[214:217], v[10:13]
	v_mfma_f32_16x16x32_bf16 v[172:175], v[202:205], v[174:177], v[6:9]
	s_barrier
	s_nop 0
	ds_read_b128 v[6:9], v166
	ds_read_b128 v[10:13], v166 offset:1024
	ds_read_b128 v[14:17], v166 offset:2048
	ds_read_b128 v[194:197], v166 offset:3072
	ds_read_b128 v[18:21], v145 offset:32768
	ds_read_b128 v[22:25], v145 offset:33792
	ds_read_b128 v[30:33], v144 offset:32768
	ds_read_b128 v[50:53], v144 offset:33792
	ds_read_b128 v[198:201], v143 offset:32768
	ds_read_b128 v[202:205], v143 offset:33792
	ds_read_b128 v[210:213], v142 offset:32768
	ds_read_b128 v[214:217], v142 offset:33792
	s_waitcnt vmcnt(2)
	s_barrier
	s_waitcnt lgkmcnt(0)
	v_mfma_f32_16x16x32_bf16 v[26:29], v[18:21], v[6:9], v[126:129]
	v_mfma_f32_16x16x32_bf16 v[122:125], v[22:25], v[10:13], v[26:29]
	v_mfma_f32_16x16x32_bf16 v[26:29], v[18:21], v[14:17], v[130:133]
	v_mfma_f32_16x16x32_bf16 v[90:93], v[22:25], v[194:197], v[26:29]
	v_mfma_f32_16x16x32_bf16 v[26:29], v[30:33], v[6:9], v[118:121]
	v_mfma_f32_16x16x32_bf16 v[126:129], v[50:53], v[10:13], v[26:29]
	v_mfma_f32_16x16x32_bf16 v[26:29], v[30:33], v[14:17], v[114:117]
	v_mfma_f32_16x16x32_bf16 v[94:97], v[50:53], v[194:197], v[26:29]
	v_mfma_f32_16x16x32_bf16 v[26:29], v[198:201], v[6:9], v[110:113]
	v_mfma_f32_16x16x32_bf16 v[118:121], v[202:205], v[10:13], v[26:29]
	v_mfma_f32_16x16x32_bf16 v[26:29], v[198:201], v[14:17], v[106:109]
	v_mfma_f32_16x16x32_bf16 v[86:89], v[202:205], v[194:197], v[26:29]
	v_mfma_f32_16x16x32_bf16 v[26:29], v[210:213], v[6:9], v[102:105]
	v_mfma_f32_16x16x32_bf16 v[114:117], v[214:217], v[10:13], v[26:29]
	v_mfma_f32_16x16x32_bf16 v[26:29], v[210:213], v[14:17], v[98:101]
	v_mfma_f32_16x16x32_bf16 v[82:85], v[214:217], v[194:197], v[26:29]
	s_barrier
; #define LDA(dst, b, h) _Pragma("unroll") for (int m = 0; m < 4; ++m) _Pragma("unroll") for (int k = 0; k < 2; ++k) \
;     dst[m][k] = *reinterpret_cast<const bf16x8*>((char*)SA(b, h) + lds_byte(wr * 64 + m * 16 + fr, k * 32 + fq * 8))
; #define LDB(dst, b, h) _Pragma("unroll") for (int n = 0; n < 2; ++n) _Pragma("unroll") for (int k = 0; k < 2; ++k) \
;     dst[n][k] = *reinterpret_cast<const bf16x8*>((char*)SB(b, h) + lds_byte(wc * 32 + n * 16 + fr, k * 32 + fq * 8))
; #define MMA(ai, bj, At, Bq) do { __builtin_amdgcn_s_setprio(1); \
;     _Pragma("unroll") for (int m = 0; m < 4; ++m) _Pragma("unroll") for (int n = 0; n < 2; ++n) _Pragma("unroll") for (int k = 0; k < 2; ++k) \
;       acc[ai][bj][m][n] = __builtin_amdgcn_mfma_f32_16x16x32_bf16(At[m][k], Bq[n][k], acc[ai][bj][m][n], 0, 0, 0); \
;     __builtin_amdgcn_s_setprio(0); } while (0)
; #define WAIT_V(n) asm volatile("s_waitcnt vmcnt(" #n ")" ::: "memory")
; #define WAIT_L(n) asm volatile("s_waitcnt lgkmcnt(" #n ")" ::: "memory")
; #define BAR __builtin_amdgcn_s_barrier()
; __device__ __forceinline__ void gemm256(const u16* __restrict__ A, int lda, const u16* __restrict__ Bt, int ldb, int K,
;                                         f32x4 (&acc)[2][2][4][2], const int g_wid) {
;     ...
;   { LDB(B0, 1, 0); LDA(At, 1, 0); WAIT_V(2); BAR; WAIT_L(0); MMA(0, 0, At, B0); BAR;
;     LDB(B1, 1, 1); WAIT_V(0); BAR; WAIT_L(0); MMA(0, 1, At, B1); BAR;
;     LDA(At, 1, 1); BAR; WAIT_L(0); MMA(1, 0, At, B0); MMA(1, 1, At, B1); BAR; }
;   if (wr == 0) BAR;
	ds_read_b128 v[130:133], v160
	ds_read_b128 v[238:241], v160 offset:1024
	ds_read_b128 v[242:245], v160 offset:2048
	ds_read_b128 v[246:249], v160 offset:3072
	s_waitcnt vmcnt(0)
	s_barrier
	s_waitcnt lgkmcnt(0)
	v_mfma_f32_16x16x32_bf16 v[26:29], v[18:21], v[130:133], v[218:221]
	v_mfma_f32_16x16x32_bf16 v[18:21], v[18:21], v[242:245], v[178:181]
	v_mfma_f32_16x16x32_bf16 v[58:61], v[22:25], v[238:241], v[26:29]
	v_mfma_f32_16x16x32_bf16 v[26:29], v[22:25], v[246:249], v[18:21]
	v_mfma_f32_16x16x32_bf16 v[18:21], v[30:33], v[130:133], v[182:185]
	v_mfma_f32_16x16x32_bf16 v[62:65], v[50:53], v[238:241], v[18:21]
	v_mfma_f32_16x16x32_bf16 v[18:21], v[30:33], v[242:245], v[186:189]
	v_mfma_f32_16x16x32_bf16 v[30:33], v[50:53], v[246:249], v[18:21]
	v_mfma_f32_16x16x32_bf16 v[18:21], v[198:201], v[130:133], v[78:81]
	v_mfma_f32_16x16x32_bf16 v[54:57], v[202:205], v[238:241], v[18:21]
	v_mfma_f32_16x16x32_bf16 v[18:21], v[198:201], v[242:245], v[74:77]
	v_mfma_f32_16x16x32_bf16 v[22:25], v[202:205], v[246:249], v[18:21]
	v_mfma_f32_16x16x32_bf16 v[18:21], v[210:213], v[130:133], v[70:73]
	v_mfma_f32_16x16x32_bf16 v[50:53], v[214:217], v[238:241], v[18:21]
	v_mfma_f32_16x16x32_bf16 v[18:21], v[210:213], v[242:245], v[66:69]
	v_mfma_f32_16x16x32_bf16 v[18:21], v[214:217], v[246:249], v[18:21]
	s_barrier
	ds_read_b128 v[176:179], v145 offset:49152
	ds_read_b128 v[180:183], v145 offset:50176
	ds_read_b128 v[184:187], v144 offset:49152
	ds_read_b128 v[144:147], v144 offset:50176
	ds_read_b128 v[198:201], v143 offset:49152
	ds_read_b128 v[202:205], v143 offset:50176
	ds_read_b128 v[210:213], v142 offset:49152
	ds_read_b128 v[214:217], v142 offset:50176
	s_barrier
	s_waitcnt lgkmcnt(0)
	v_mfma_f32_16x16x32_bf16 v[66:69], v[176:179], v[6:9], v[206:209]
	v_mfma_f32_16x16x32_bf16 v[110:113], v[180:183], v[10:13], v[66:69]
	v_mfma_f32_16x16x32_bf16 v[66:69], v[176:179], v[14:17], v[222:225]
	v_mfma_f32_16x16x32_bf16 v[78:81], v[180:183], v[194:197], v[66:69]
	v_mfma_f32_16x16x32_bf16 v[66:69], v[184:187], v[6:9], v[226:229]
	v_mfma_f32_16x16x32_bf16 v[46:49], v[198:201], v[6:9], v[46:49]
	v_mfma_f32_16x16x32_bf16 v[6:9], v[210:213], v[6:9], v[38:41]
	v_mfma_f32_16x16x32_bf16 v[106:109], v[144:147], v[10:13], v[66:69]
	v_mfma_f32_16x16x32_bf16 v[66:69], v[184:187], v[14:17], v[230:233]
	v_mfma_f32_16x16x32_bf16 v[42:45], v[198:201], v[14:17], v[42:45]
	v_mfma_f32_16x16x32_bf16 v[98:101], v[214:217], v[10:13], v[6:9]
	v_mfma_f32_16x16x32_bf16 v[6:9], v[210:213], v[14:17], v[34:37]
	v_mfma_f32_16x16x32_bf16 v[74:77], v[144:147], v[194:197], v[66:69]
	v_mfma_f32_16x16x32_bf16 v[102:105], v[202:205], v[10:13], v[46:49]
	v_mfma_f32_16x16x32_bf16 v[70:73], v[202:205], v[194:197], v[42:45]
	v_mfma_f32_16x16x32_bf16 v[66:69], v[214:217], v[194:197], v[6:9]
	v_mfma_f32_16x16x32_bf16 v[6:9], v[176:179], v[130:133], v[134:137]
	v_mfma_f32_16x16x32_bf16 v[46:49], v[180:183], v[238:241], v[6:9]
	v_mfma_f32_16x16x32_bf16 v[6:9], v[176:179], v[242:245], v[138:141]
	v_mfma_f32_16x16x32_bf16 v[14:17], v[180:183], v[246:249], v[6:9]
	v_mfma_f32_16x16x32_bf16 v[6:9], v[184:187], v[130:133], v[162:165]
	v_mfma_f32_16x16x32_bf16 v[42:45], v[144:147], v[238:241], v[6:9]
	v_mfma_f32_16x16x32_bf16 v[6:9], v[184:187], v[242:245], v[168:171]
	v_mfma_f32_16x16x32_bf16 v[10:13], v[144:147], v[246:249], v[6:9]
	v_mfma_f32_16x16x32_bf16 v[6:9], v[198:201], v[130:133], v[234:237]
	v_mfma_f32_16x16x32_bf16 v[38:41], v[202:205], v[238:241], v[6:9]
	v_mfma_f32_16x16x32_bf16 v[6:9], v[198:201], v[242:245], v[190:193]
	v_mfma_f32_16x16x32_bf16 v[34:37], v[210:213], v[130:133], v[172:175]
	v_mfma_f32_16x16x32_bf16 v[2:5], v[210:213], v[242:245], v[2:5]
	v_mfma_f32_16x16x32_bf16 v[6:9], v[202:205], v[246:249], v[6:9]
	v_mfma_f32_16x16x32_bf16 v[34:37], v[214:217], v[238:241], v[34:37]
	v_mfma_f32_16x16x32_bf16 v[2:5], v[214:217], v[246:249], v[2:5]
	s_setprio 0
	s_movk_i32 s3, 0x100
	v_cmp_gt_u32_e32 vcc, s3, v0
	s_barrier
	s_and_saveexec_b64 s[10:11], vcc
	s_cbranch_execz .LBB0_491
	s_barrier
